# GEMM epilogues: per-row rstd/base/pp global loads hoisted and batched (one vmcnt wait per batch instead of one per load) in SwiGLU, EpiResid<0> x2, EpiProj, EpiResid<1>; FFN-up LDS-DMA issue moved int
# speedup vs baseline: 1.0510x; 1.0510x over previous
; #define PG8_STAGE(bufoff, gbase, voff) do { _Pragma("unroll") for (int _i = 0; _i < 2; ++_i) \
;         __builtin_amdgcn_global_load_lds((const unsigned*)((const char*)(gbase) + (voff)[_i]), (LAS unsigned*)(lds + (bufoff) + ldsw + _i * 8192), 16, 0, 0); } while (0)
; #define PG8_LDA(dst, b, h) do { _Pragma("unroll") for (int m = 0; m < 4; ++m) _Pragma("unroll") for (int k = 0; k < 2; ++k) dst[m][k] = *(const LAS bf16x8*)(lds + PG8_SA(b, h) + aoff + m * 2048 + k * 1024); } while (0)
; #define PG8_LDB(dst, b, h) do { _Pragma("unroll") for (int n = 0; n < 2; ++n) _Pragma("unroll") for (int k = 0; k < 2; ++k) dst[n][k] = *(const LAS bf16x8*)(lds + PG8_SB(b, h) + boff + n * 2048 + k * 1024); } while (0)
; #define PG8_WAIT_V(n) asm volatile("s_waitcnt vmcnt(" #n ")" ::: "memory")
; #define PG8_WAIT_L(n) asm volatile("s_waitcnt lgkmcnt(" #n ")" ::: "memory")
; #define PG8_BAR __builtin_amdgcn_s_barrier()
; #define PG8_SCHED __builtin_amdgcn_sched_barrier(0)
; template <class Epi, int KK, int LDA, int LDB, int NN, bool AGRP>
; __device__ __forceinline__ void gemm_phase(LAS unsigned char* lds, const bf16_t* gA, const bf16_t* gBt, int G_, int bid_, int tid) {
;     ...
;         for (int t = 0; t < nt; t += 2) {
;             const bool last = (t == nt - 2);
;             const char* a1 = cA + (size_t)(t + 1) * kstep;
;             const char* a2 = last ? nA : cA + (size_t)(t + 2) * kstep; const char* b2 = last ? nB : cB + (size_t)(t + 2) * kstep;
;             const char* a3 = a2 + kstep; const char* b3 = b2 + kstep;
;             PG8_LDB(B0, 0, 0); PG8_SCHED; PG8_LDA(At, 0, 0); PG8_STAGE(PG8_SA(1, 1), a1 + hstepA, voffA);
;             PG8_WAIT_L(8); PG8_BAR; PG8_WAIT_L(0); PG8_MMA(0, 0, At, B0); PG8_BAR; PG8_SCHED;
;             PG8_LDB(B1, 0, 1); PG8_STAGE(PG8_SB(0, 0), b2, voffB);
;             PG8_BAR; PG8_WAIT_L(0); PG8_MMA(0, 1, At, B1); PG8_BAR;
;             PG8_LDA(At, 0, 1); PG8_STAGE(PG8_SA(0, 0), a2, voffA);
;             PG8_BAR; PG8_WAIT_L(0); PG8_MMA(1, 0, At, B0); PG8_BAR; PG8_SCHED;
;             PG8_STAGE(PG8_SB(0, 1), b2 + hstepB, voffB);
;             PG8_WAIT_V(6); PG8_BAR; PG8_MMA(1, 1, At, B1); PG8_BAR;
;             PG8_LDB(B0, 1, 0); PG8_SCHED; PG8_LDA(At, 1, 0); PG8_STAGE(PG8_SA(0, 1), a2 + hstepA, voffA);
;             PG8_WAIT_L(8); PG8_BAR; PG8_WAIT_L(0); PG8_MMA(0, 0, At, B0); PG8_BAR; PG8_SCHED;
.LBB1_23:
	ds_read_b128 v[142:145], v153
	ds_read_b128 v[146:149], v153 offset:1024
	ds_read_b128 v[158:161], v153 offset:2048
	ds_read_b128 v[162:165], v153 offset:3072
	s_add_u32 s20, s16, 0xfffc0080
	s_addc_u32 s21, s17, -1
	s_cmp_eq_u32 s70, 12
	s_cselect_b32 s23, s1, s21
	s_cselect_b32 s22, s19, s20
	s_cselect_b32 s21, s9, s65
	s_cselect_b32 s20, s24, s25
	v_lshl_add_u64 v[208:209], s[16:17], 0, v[140:141]
	s_add_i32 m0, s31, 0xc000
	ds_read_b128 v[166:169], v154
	ds_read_b128 v[176:179], v154 offset:1024
	ds_read_b128 v[180:183], v154 offset:2048
	ds_read_b128 v[184:187], v154 offset:3072
	ds_read_b128 v[188:191], v154 offset:4096
	ds_read_b128 v[194:197], v154 offset:5120
	ds_read_b128 v[200:203], v154 offset:6144
	ds_read_b128 v[204:207], v154 offset:7168
	global_load_lds_dwordx4 v[208:209], off
	v_lshl_add_u64 v[208:209], s[16:17], 0, v[138:139]
	s_add_i32 m0, s31, 0xe000
	s_nop 0
	global_load_lds_dwordx4 v[208:209], off
	s_waitcnt lgkmcnt(8)
	s_barrier
	s_waitcnt lgkmcnt(0)
	s_setprio 1
	s_waitcnt lgkmcnt(0)
	v_mfma_f32_16x16x32_bf16 v[126:129], v[142:145], v[166:169], v[126:129]
	v_mfma_f32_16x16x32_bf16 v[122:125], v[158:161], v[166:169], v[122:125]
	v_mfma_f32_16x16x32_bf16 v[110:113], v[142:145], v[180:183], v[110:113]
	v_mfma_f32_16x16x32_bf16 v[106:109], v[158:161], v[180:183], v[106:109]
	v_mfma_f32_16x16x32_bf16 v[94:97], v[142:145], v[188:191], v[94:97]
	v_mfma_f32_16x16x32_bf16 v[90:93], v[158:161], v[188:191], v[90:93]
	v_mfma_f32_16x16x32_bf16 v[78:81], v[142:145], v[200:203], v[78:81]
	v_mfma_f32_16x16x32_bf16 v[74:77], v[158:161], v[200:203], v[74:77]
	v_mfma_f32_16x16x32_bf16 v[126:129], v[146:149], v[176:179], v[126:129]
	v_mfma_f32_16x16x32_bf16 v[122:125], v[162:165], v[176:179], v[122:125]
	v_mfma_f32_16x16x32_bf16 v[110:113], v[146:149], v[184:187], v[110:113]
	v_mfma_f32_16x16x32_bf16 v[106:109], v[162:165], v[184:187], v[106:109]
	v_mfma_f32_16x16x32_bf16 v[94:97], v[146:149], v[194:197], v[94:97]
	v_mfma_f32_16x16x32_bf16 v[90:93], v[162:165], v[194:197], v[90:93]
	v_mfma_f32_16x16x32_bf16 v[78:81], v[146:149], v[204:207], v[78:81]
	v_mfma_f32_16x16x32_bf16 v[74:77], v[162:165], v[204:207], v[74:77]
	s_setprio 0
	s_barrier
	s_mov_b32 m0, s29
	v_lshl_add_u64 v[224:225], s[20:21], 0, v[134:135]
	ds_read_b128 v[208:211], v155
	ds_read_b128 v[212:215], v155 offset:1024
	ds_read_b128 v[216:219], v155 offset:2048
	ds_read_b128 v[220:223], v155 offset:3072
	global_load_lds_dwordx4 v[224:225], off
	v_lshl_add_u64 v[226:227], s[20:21], 0, v[130:131]
	s_mov_b32 m0, s30
	s_nop 0
	global_load_lds_dwordx4 v[226:227], off
	s_barrier
	s_waitcnt lgkmcnt(0)
	s_setprio 1
	s_waitcnt lgkmcnt(0)
	v_mfma_f32_16x16x32_bf16 v[118:121], v[208:211], v[166:169], v[118:121]
	v_mfma_f32_16x16x32_bf16 v[114:117], v[216:219], v[166:169], v[114:117]
	v_mfma_f32_16x16x32_bf16 v[102:105], v[208:211], v[180:183], v[102:105]
	v_mfma_f32_16x16x32_bf16 v[98:101], v[216:219], v[180:183], v[98:101]
	v_mfma_f32_16x16x32_bf16 v[86:89], v[208:211], v[188:191], v[86:89]
	v_mfma_f32_16x16x32_bf16 v[82:85], v[216:219], v[188:191], v[82:85]
	v_mfma_f32_16x16x32_bf16 v[70:73], v[208:211], v[200:203], v[70:73]
	v_mfma_f32_16x16x32_bf16 v[66:69], v[216:219], v[200:203], v[66:69]
	v_mfma_f32_16x16x32_bf16 v[118:121], v[212:215], v[176:179], v[118:121]
	v_mfma_f32_16x16x32_bf16 v[114:117], v[220:223], v[176:179], v[114:117]
	v_mfma_f32_16x16x32_bf16 v[102:105], v[212:215], v[184:187], v[102:105]
	v_mfma_f32_16x16x32_bf16 v[98:101], v[220:223], v[184:187], v[98:101]
	v_mfma_f32_16x16x32_bf16 v[86:89], v[212:215], v[194:197], v[86:89]
	v_mfma_f32_16x16x32_bf16 v[82:85], v[220:223], v[194:197], v[82:85]
	v_mfma_f32_16x16x32_bf16 v[70:73], v[212:215], v[204:207], v[70:73]
	v_mfma_f32_16x16x32_bf16 v[66:69], v[220:223], v[204:207], v[66:69]
	s_setprio 0
	s_mov_b32 m0, s31
	v_lshl_add_u64 v[228:229], s[22:23], 0, v[136:137]
	s_barrier
	ds_read_b128 v[166:169], v154 offset:16384
	ds_read_b128 v[176:179], v154 offset:17408
	ds_read_b128 v[180:183], v154 offset:18432
	ds_read_b128 v[184:187], v154 offset:19456
	ds_read_b128 v[188:191], v154 offset:20480
	ds_read_b128 v[194:197], v154 offset:21504
	ds_read_b128 v[200:203], v154 offset:22528
	ds_read_b128 v[204:207], v154 offset:23552
	global_load_lds_dwordx4 v[228:229], off
	v_lshl_add_u64 v[230:231], s[22:23], 0, v[132:133]
	s_mov_b32 m0, s34
	s_nop 0
	global_load_lds_dwordx4 v[230:231], off
	s_barrier
	s_waitcnt lgkmcnt(0)
	s_setprio 1
	s_waitcnt lgkmcnt(0)
	v_mfma_f32_16x16x32_bf16 v[62:65], v[142:145], v[166:169], v[62:65]
	v_mfma_f32_16x16x32_bf16 v[58:61], v[158:161], v[166:169], v[58:61]
	v_mfma_f32_16x16x32_bf16 v[46:49], v[142:145], v[180:183], v[46:49]
	v_mfma_f32_16x16x32_bf16 v[42:45], v[158:161], v[180:183], v[42:45]
	v_mfma_f32_16x16x32_bf16 v[30:33], v[142:145], v[188:191], v[30:33]
	v_mfma_f32_16x16x32_bf16 v[26:29], v[158:161], v[188:191], v[26:29]
	v_mfma_f32_16x16x32_bf16 v[14:17], v[142:145], v[200:203], v[14:17]
	v_mfma_f32_16x16x32_bf16 v[10:13], v[158:161], v[200:203], v[10:13]
	v_mfma_f32_16x16x32_bf16 v[62:65], v[146:149], v[176:179], v[62:65]
	v_mfma_f32_16x16x32_bf16 v[58:61], v[162:165], v[176:179], v[58:61]
	v_mfma_f32_16x16x32_bf16 v[46:49], v[146:149], v[184:187], v[46:49]
	v_mfma_f32_16x16x32_bf16 v[42:45], v[162:165], v[184:187], v[42:45]
	v_mfma_f32_16x16x32_bf16 v[30:33], v[146:149], v[194:197], v[30:33]
	v_mfma_f32_16x16x32_bf16 v[26:29], v[162:165], v[194:197], v[26:29]
	v_mfma_f32_16x16x32_bf16 v[14:17], v[146:149], v[204:207], v[14:17]
	v_mfma_f32_16x16x32_bf16 v[10:13], v[162:165], v[204:207], v[10:13]
	s_setprio 0
	s_barrier
; #define PG8_STAGE(bufoff, gbase, voff) do { _Pragma("unroll") for (int _i = 0; _i < 2; ++_i) \
;         __builtin_amdgcn_global_load_lds((const unsigned*)((const char*)(gbase) + (voff)[_i]), (LAS unsigned*)(lds + (bufoff) + ldsw + _i * 8192), 16, 0, 0); } while (0)
; #define PG8_LDA(dst, b, h) do { _Pragma("unroll") for (int m = 0; m < 4; ++m) _Pragma("unroll") for (int k = 0; k < 2; ++k) dst[m][k] = *(const LAS bf16x8*)(lds + PG8_SA(b, h) + aoff + m * 2048 + k * 1024); } while (0)
; #define PG8_LDB(dst, b, h) do { _Pragma("unroll") for (int n = 0; n < 2; ++n) _Pragma("unroll") for (int k = 0; k < 2; ++k) dst[n][k] = *(const LAS bf16x8*)(lds + PG8_SB(b, h) + boff + n * 2048 + k * 1024); } while (0)
; #define PG8_MMA(ai, bj, At, Bt) do { __builtin_amdgcn_s_setprio(1); _Pragma("unroll") for (int m = 0; m < 4; ++m) _Pragma("unroll") for (int n = 0; n < 2; ++n) _Pragma("unroll") for (int k = 0; k < 2; ++k) \
;         acc[ai][bj][m][n] = __builtin_amdgcn_mfma_f32_16x16x32_bf16(Bt[n][k], At[m][k], acc[ai][bj][m][n], 0, 0, 0); __builtin_amdgcn_s_setprio(0); } while (0)
; #define PG8_WAIT_V(n) asm volatile("s_waitcnt vmcnt(" #n ")" ::: "memory")
; #define PG8_WAIT_L(n) asm volatile("s_waitcnt lgkmcnt(" #n ")" ::: "memory")
; #define PG8_BAR __builtin_amdgcn_s_barrier()
; #define PG8_SCHED __builtin_amdgcn_sched_barrier(0)
; template <class Epi, int KK, int LDA, int LDB, int NN, bool AGRP>
; __device__ __forceinline__ void gemm_phase(LAS unsigned char* lds, const bf16_t* gA, const bf16_t* gBt, int G_, int bid_, int tid) {
;     ...
;             PG8_STAGE(PG8_SB(0, 1), b2 + hstepB, voffB);
;             PG8_WAIT_V(6); PG8_BAR; PG8_MMA(1, 1, At, B1); PG8_BAR;
;             PG8_LDB(B0, 1, 0); PG8_SCHED; PG8_LDA(At, 1, 0); PG8_STAGE(PG8_SA(0, 1), a2 + hstepA, voffA);
;             PG8_WAIT_L(8); PG8_BAR; PG8_WAIT_L(0); PG8_MMA(0, 0, At, B0); PG8_BAR; PG8_SCHED;
;             PG8_LDB(B1, 1, 1); PG8_STAGE(PG8_SB(1, 0), b3, voffB);
;             PG8_BAR; PG8_WAIT_L(0); PG8_MMA(0, 1, At, B1); PG8_BAR;
;             PG8_LDA(At, 1, 1); PG8_STAGE(PG8_SA(1, 0), a3, voffA);
;             PG8_BAR; PG8_WAIT_L(0); PG8_MMA(1, 0, At, B0); PG8_BAR; PG8_SCHED;
	s_add_u32 s66, s20, 0x40000
	s_addc_u32 s67, s21, 0
	s_mov_b32 m0, s35
	v_lshl_add_u64 v[142:143], s[66:67], 0, v[134:135]
	global_load_lds_dwordx4 v[142:143], off
	v_lshl_add_u64 v[142:143], s[66:67], 0, v[130:131]
	s_mov_b32 m0, s36
	s_nop 0
	global_load_lds_dwordx4 v[142:143], off
	s_waitcnt vmcnt(6)
	s_barrier
	s_setprio 1
	v_mfma_f32_16x16x32_bf16 v[54:57], v[208:211], v[166:169], v[54:57]
	v_mfma_f32_16x16x32_bf16 v[50:53], v[216:219], v[166:169], v[50:53]
	v_mfma_f32_16x16x32_bf16 v[38:41], v[208:211], v[180:183], v[38:41]
	v_mfma_f32_16x16x32_bf16 v[34:37], v[216:219], v[180:183], v[34:37]
	v_mfma_f32_16x16x32_bf16 v[22:25], v[208:211], v[188:191], v[22:25]
	v_mfma_f32_16x16x32_bf16 v[18:21], v[216:219], v[188:191], v[18:21]
	v_mfma_f32_16x16x32_bf16 v[6:9], v[208:211], v[200:203], v[6:9]
	v_mfma_f32_16x16x32_bf16 v[0:3], v[216:219], v[200:203], v[0:3]
	v_mfma_f32_16x16x32_bf16 v[54:57], v[212:215], v[176:179], v[54:57]
	v_mfma_f32_16x16x32_bf16 v[50:53], v[220:223], v[176:179], v[50:53]
	v_mfma_f32_16x16x32_bf16 v[38:41], v[212:215], v[184:187], v[38:41]
	v_mfma_f32_16x16x32_bf16 v[34:37], v[220:223], v[184:187], v[34:37]
	v_mfma_f32_16x16x32_bf16 v[22:25], v[212:215], v[194:197], v[22:25]
	v_mfma_f32_16x16x32_bf16 v[18:21], v[220:223], v[194:197], v[18:21]
	v_mfma_f32_16x16x32_bf16 v[6:9], v[212:215], v[204:207], v[6:9]
	v_mfma_f32_16x16x32_bf16 v[0:3], v[220:223], v[204:207], v[0:3]
	s_setprio 0
	s_barrier
	ds_read_b128 v[142:145], v156
	ds_read_b128 v[146:149], v156 offset:1024
	ds_read_b128 v[158:161], v156 offset:2048
	ds_read_b128 v[162:165], v156 offset:3072
	s_add_u32 s22, s22, 0x40000
	s_addc_u32 s23, s23, 0
	s_mov_b32 m0, s37
	v_lshl_add_u64 v[208:209], s[22:23], 0, v[136:137]
	ds_read_b128 v[166:169], v154 offset:32768
	ds_read_b128 v[176:179], v154 offset:33792
	ds_read_b128 v[180:183], v154 offset:34816
	ds_read_b128 v[184:187], v154 offset:35840
	ds_read_b128 v[188:191], v154 offset:36864
	ds_read_b128 v[194:197], v154 offset:37888
	ds_read_b128 v[200:203], v154 offset:38912
	ds_read_b128 v[204:207], v154 offset:39936
	global_load_lds_dwordx4 v[208:209], off
	v_lshl_add_u64 v[208:209], s[22:23], 0, v[132:133]
	s_mov_b32 m0, s39
	s_nop 0
	global_load_lds_dwordx4 v[208:209], off
	s_waitcnt lgkmcnt(8)
	s_barrier
	s_waitcnt lgkmcnt(0)
	s_setprio 1
	s_waitcnt lgkmcnt(0)
	v_mfma_f32_16x16x32_bf16 v[126:129], v[142:145], v[166:169], v[126:129]
	v_mfma_f32_16x16x32_bf16 v[122:125], v[158:161], v[166:169], v[122:125]
	v_mfma_f32_16x16x32_bf16 v[110:113], v[142:145], v[180:183], v[110:113]
	v_mfma_f32_16x16x32_bf16 v[106:109], v[158:161], v[180:183], v[106:109]
	v_mfma_f32_16x16x32_bf16 v[94:97], v[142:145], v[188:191], v[94:97]
	v_mfma_f32_16x16x32_bf16 v[90:93], v[158:161], v[188:191], v[90:93]
	v_mfma_f32_16x16x32_bf16 v[78:81], v[142:145], v[200:203], v[78:81]
	v_mfma_f32_16x16x32_bf16 v[74:77], v[158:161], v[200:203], v[74:77]
	v_mfma_f32_16x16x32_bf16 v[126:129], v[146:149], v[176:179], v[126:129]
	v_mfma_f32_16x16x32_bf16 v[122:125], v[162:165], v[176:179], v[122:125]
	v_mfma_f32_16x16x32_bf16 v[110:113], v[146:149], v[184:187], v[110:113]
	v_mfma_f32_16x16x32_bf16 v[106:109], v[162:165], v[184:187], v[106:109]
	v_mfma_f32_16x16x32_bf16 v[94:97], v[146:149], v[194:197], v[94:97]
	v_mfma_f32_16x16x32_bf16 v[90:93], v[162:165], v[194:197], v[90:93]
	v_mfma_f32_16x16x32_bf16 v[78:81], v[146:149], v[204:207], v[78:81]
	v_mfma_f32_16x16x32_bf16 v[74:77], v[162:165], v[204:207], v[74:77]
	s_setprio 0
	s_barrier
	s_mov_b32 m0, s43
	v_lshl_add_u64 v[224:225], v[224:225], 0, s[76:77]
	ds_read_b128 v[208:211], v157
	ds_read_b128 v[212:215], v157 offset:1024
	ds_read_b128 v[216:219], v157 offset:2048
	ds_read_b128 v[220:223], v157 offset:3072
	global_load_lds_dwordx4 v[224:225], off
	v_lshl_add_u64 v[224:225], v[226:227], 0, s[76:77]
	s_mov_b32 m0, s44
	s_nop 0
	global_load_lds_dwordx4 v[224:225], off
	s_barrier
	s_waitcnt lgkmcnt(0)
	s_setprio 1
	s_waitcnt lgkmcnt(0)
	v_mfma_f32_16x16x32_bf16 v[118:121], v[208:211], v[166:169], v[118:121]
	v_mfma_f32_16x16x32_bf16 v[114:117], v[216:219], v[166:169], v[114:117]
	v_mfma_f32_16x16x32_bf16 v[102:105], v[208:211], v[180:183], v[102:105]
	v_mfma_f32_16x16x32_bf16 v[98:101], v[216:219], v[180:183], v[98:101]
	v_mfma_f32_16x16x32_bf16 v[86:89], v[208:211], v[188:191], v[86:89]
	v_mfma_f32_16x16x32_bf16 v[82:85], v[216:219], v[188:191], v[82:85]
	v_mfma_f32_16x16x32_bf16 v[70:73], v[208:211], v[200:203], v[70:73]
	v_mfma_f32_16x16x32_bf16 v[66:69], v[216:219], v[200:203], v[66:69]
	v_mfma_f32_16x16x32_bf16 v[118:121], v[212:215], v[176:179], v[118:121]
	v_mfma_f32_16x16x32_bf16 v[114:117], v[220:223], v[176:179], v[114:117]
	v_mfma_f32_16x16x32_bf16 v[102:105], v[212:215], v[184:187], v[102:105]
	v_mfma_f32_16x16x32_bf16 v[98:101], v[220:223], v[184:187], v[98:101]
	v_mfma_f32_16x16x32_bf16 v[86:89], v[212:215], v[194:197], v[86:89]
	v_mfma_f32_16x16x32_bf16 v[82:85], v[220:223], v[194:197], v[82:85]
	v_mfma_f32_16x16x32_bf16 v[70:73], v[212:215], v[204:207], v[70:73]
	v_mfma_f32_16x16x32_bf16 v[66:69], v[220:223], v[204:207], v[66:69]
	s_setprio 0
	s_mov_b32 m0, s45
	v_lshl_add_u64 v[224:225], v[228:229], 0, s[76:77]
	s_barrier
	ds_read_b128 v[166:169], v154 offset:49152
	ds_read_b128 v[176:179], v154 offset:50176
	ds_read_b128 v[180:183], v154 offset:51200
	ds_read_b128 v[184:187], v154 offset:52224
	ds_read_b128 v[188:191], v154 offset:53248
	ds_read_b128 v[194:197], v154 offset:54272
	ds_read_b128 v[200:203], v154 offset:55296
	ds_read_b128 v[204:207], v154 offset:56320
	global_load_lds_dwordx4 v[224:225], off
	v_lshl_add_u64 v[224:225], v[230:231], 0, s[76:77]
	s_mov_b32 m0, s46
	s_nop 0
	global_load_lds_dwordx4 v[224:225], off
	s_barrier
; #define LAS __attribute__((address_space(3)))
; __device__ __forceinline__ float bflo(unsigned w) { return __uint_as_float(w << 16); }
; __device__ __forceinline__ float bfhi(unsigned w) { return __uint_as_float(w & 0xffff0000u); }
; #define PG8_STAGE(bufoff, gbase, voff) do { _Pragma("unroll") for (int _i = 0; _i < 2; ++_i) \
;         __builtin_amdgcn_global_load_lds((const unsigned*)((const char*)(gbase) + (voff)[_i]), (LAS unsigned*)(lds + (bufoff) + ldsw + _i * 8192), 16, 0, 0); } while (0)
; template <class Epi, int KK, int LDA, int LDB, int NN, bool AGRP>
; __device__ __forceinline__ void gemm_phase(LAS unsigned char* lds, const bf16_t* gA, const bf16_t* gBt, int G_, int bid_, int tid) {
;     ...
;             PG8_BAR; PG8_WAIT_L(0); PG8_MMA(1, 0, At, B0); PG8_BAR; PG8_SCHED;
;             PG8_STAGE(PG8_SB(1, 1), b3 + hstepB, voffB);
;             PG8_WAIT_V(6); PG8_BAR; PG8_MMA(1, 1, At, B1); PG8_BAR;
;         }
;     __device__ __forceinline__ void operator()(const f32x4 (&acc)[2][2][4][2], const Unit& u, int wr, int wc, int fr, int fq, LAS unsigned char* lds) const {
;         const float* rss_in = EPP(const float*, 1); const float* bias = EPP(const float*, 2);
;         const bf16_t* base = EPP(const bf16_t*, 3);
;         bf16_t* hb = EPP(bf16_t*, 5); float* rss_out = EPP(float*, 6); const bf16_t* pp = EPP(const bf16_t*, 7); const float scale = __uint_as_float((unsigned)ep64(lds, 8));
;         const int row0 = u.pm * BM + wr * 64 + fr, col0 = u.pn * BM + wc * 32 + 8 * fq;
;         f32x4 bv[2][2];
; #pragma unroll
;         for (int bj = 0; bj < 2; ++bj)
; #pragma unroll
;             for (int n = 0; n < 2; ++n) bv[bj][n] = (MODE == 0 && bias) ? *(const f32x4*)(bias + col0 + bj * HALF + 4 * n) : (f32x4){0.f, 0.f, 0.f, 0.f};
; #pragma unroll
;         for (int ai = 0; ai < 2; ++ai)
; #pragma unroll
;             for (int m = 0; m < 4; ++m) { const int row = row0 + ai * HALF + m * 16; const size_t off = (size_t)row * D + col0;
;                 float rs = 1.0f; if (MODE == 1) rs = rstd_of4(rss_in, row, fq);
;                 float ss = 0.f;
; #pragma unroll
;                 for (int bj = 0; bj < 2; ++bj) { const size_t o = off + bj * HALF; const u32x4 bw = *(const u32x4*)(base + o);
;                     const float bs[8] = {bflo(bw.x), bfhi(bw.x), bflo(bw.y), bfhi(bw.y), bflo(bw.z), bfhi(bw.z), bflo(bw.w), bfhi(bw.w)};
	s_waitcnt lgkmcnt(0)
	s_setprio 1
	s_waitcnt lgkmcnt(0)
	v_mfma_f32_16x16x32_bf16 v[62:65], v[142:145], v[166:169], v[62:65]
	v_mfma_f32_16x16x32_bf16 v[58:61], v[158:161], v[166:169], v[58:61]
	v_mfma_f32_16x16x32_bf16 v[46:49], v[142:145], v[180:183], v[46:49]
	v_mfma_f32_16x16x32_bf16 v[42:45], v[158:161], v[180:183], v[42:45]
	v_mfma_f32_16x16x32_bf16 v[30:33], v[142:145], v[188:191], v[30:33]
	v_mfma_f32_16x16x32_bf16 v[26:29], v[158:161], v[188:191], v[26:29]
	v_mfma_f32_16x16x32_bf16 v[14:17], v[142:145], v[200:203], v[14:17]
	v_mfma_f32_16x16x32_bf16 v[10:13], v[158:161], v[200:203], v[10:13]
	v_mfma_f32_16x16x32_bf16 v[62:65], v[146:149], v[176:179], v[62:65]
	v_mfma_f32_16x16x32_bf16 v[58:61], v[162:165], v[176:179], v[58:61]
	v_mfma_f32_16x16x32_bf16 v[46:49], v[146:149], v[184:187], v[46:49]
	v_mfma_f32_16x16x32_bf16 v[42:45], v[162:165], v[184:187], v[42:45]
	v_mfma_f32_16x16x32_bf16 v[30:33], v[146:149], v[194:197], v[30:33]
	v_mfma_f32_16x16x32_bf16 v[26:29], v[162:165], v[194:197], v[26:29]
	v_mfma_f32_16x16x32_bf16 v[14:17], v[146:149], v[204:207], v[14:17]
	v_mfma_f32_16x16x32_bf16 v[10:13], v[162:165], v[204:207], v[10:13]
	s_setprio 0
	s_barrier
	s_add_u32 s20, s20, 0x40080
	s_addc_u32 s21, s21, 0
	s_mov_b32 m0, s47
	v_lshl_add_u64 v[142:143], s[20:21], 0, v[134:135]
	global_load_lds_dwordx4 v[142:143], off
	v_lshl_add_u64 v[142:143], s[20:21], 0, v[130:131]
	s_mov_b32 m0, s48
	s_nop 0
	global_load_lds_dwordx4 v[142:143], off
	s_waitcnt vmcnt(6)
	s_barrier
	s_setprio 1
	v_mfma_f32_16x16x32_bf16 v[54:57], v[208:211], v[166:169], v[54:57]
	v_mfma_f32_16x16x32_bf16 v[50:53], v[216:219], v[166:169], v[50:53]
	v_mfma_f32_16x16x32_bf16 v[38:41], v[208:211], v[180:183], v[38:41]
	v_mfma_f32_16x16x32_bf16 v[34:37], v[216:219], v[180:183], v[34:37]
	v_mfma_f32_16x16x32_bf16 v[22:25], v[208:211], v[188:191], v[22:25]
	v_mfma_f32_16x16x32_bf16 v[18:21], v[216:219], v[188:191], v[18:21]
	v_mfma_f32_16x16x32_bf16 v[6:9], v[208:211], v[200:203], v[6:9]
	v_mfma_f32_16x16x32_bf16 v[0:3], v[216:219], v[200:203], v[0:3]
	v_mfma_f32_16x16x32_bf16 v[54:57], v[212:215], v[176:179], v[54:57]
	v_mfma_f32_16x16x32_bf16 v[50:53], v[220:223], v[176:179], v[50:53]
	v_mfma_f32_16x16x32_bf16 v[38:41], v[212:215], v[184:187], v[38:41]
	v_mfma_f32_16x16x32_bf16 v[34:37], v[220:223], v[184:187], v[34:37]
	v_mfma_f32_16x16x32_bf16 v[22:25], v[212:215], v[194:197], v[22:25]
	v_mfma_f32_16x16x32_bf16 v[18:21], v[220:223], v[194:197], v[18:21]
	v_mfma_f32_16x16x32_bf16 v[6:9], v[212:215], v[204:207], v[6:9]
	v_mfma_f32_16x16x32_bf16 v[0:3], v[220:223], v[204:207], v[0:3]
	s_setprio 0
	s_add_i32 s70, s70, 2
	s_add_u32 s25, s25, 0x100
	s_addc_u32 s65, s65, 0
	s_add_u32 s16, s16, 0x100
	s_addc_u32 s17, s17, 0
	s_cmp_gt_u32 s70, 13
	s_barrier
	s_cbranch_scc0 .LBB1_23
	v_mov_b32_e32 v142, s49
	ds_read_b32 v142, v142
	v_mov_b32_e32 v143, s50
	ds_read_b32 v148, v143
	v_mov_b32_e32 v143, s51
	ds_read_b32 v143, v143
	s_waitcnt lgkmcnt(0)
	v_mov_b32_e32 v143, s52
	ds_read_b32 v143, v143
	s_waitcnt lgkmcnt(0)
	v_mov_b32_e32 v143, s53
	v_mov_b32_e32 v144, s54
	v_readfirstlane_b32 s20, v142
	v_mov_b32_e32 v142, s55
	ds_read_b32 v143, v143
	ds_read_b32 v144, v144
	ds_read_b32 v175, v142
	v_mov_b32_e32 v142, s56
	ds_read_b32 v184, v142
	v_mov_b32_e32 v142, s57
	ds_read_b32 v185, v142
	v_mov_b32_e32 v142, s58
	ds_read_b32 v186, v142
	v_mov_b32_e32 v142, s59
	ds_read_b32 v176, v142
	v_mov_b32_e32 v142, s60
	ds_read_b32 v177, v142
	v_mov_b32_e32 v142, s61
	ds_read_b32 v142, v142
	s_waitcnt lgkmcnt(0)
	v_mov_b32_e32 v142, s62
	v_readfirstlane_b32 s17, v144
	ds_read_b32 v142, v142
	v_lshl_add_u32 v144, s18, 8, v151
	s_waitcnt lgkmcnt(0)
	v_lshl_or_b32 v142, s41, 8, v152
	v_ashrrev_i32_e32 v145, 31, v144
	v_readfirstlane_b32 s16, v143
	v_ashrrev_i32_e32 v143, 31, v142
	v_lshlrev_b64 v[146:147], 10, v[144:145]
	v_lshl_add_u64 v[146:147], v[146:147], 0, v[142:143]
	v_readfirstlane_b32 s21, v148
	v_lshlrev_b64 v[168:169], 1, v[146:147]
	v_lshlrev_b64 v[148:149], 6, v[144:145]
	v_lshl_add_u64 v[146:147], s[20:21], 0, v[4:5]
	v_lshl_add_u64 v[180:181], s[16:17], 0, v[168:169]
	v_lshl_add_u64 v[158:159], v[146:147], 0, v[148:149]
	global_load_dwordx4 v[160:163], v[180:181], off
	global_load_dwordx4 v[164:167], v[158:159], off
	v_readfirstlane_b32 s22, v176
	v_readfirstlane_b32 s23, v177
	v_and_b32_e32 v158, 64, v171
	v_xor_b32_e32 v145, 16, v171
	v_lshl_add_u64 v[182:183], s[22:23], 0, v[168:169]
	global_load_dwordx4 v[176:179], v[182:183], off
	global_load_dwordx4 v[200:203], v[180:181], off offset:256
	global_load_dwordx4 v[204:207], v[182:183], off offset:256
	v_add_u32_e32 v158, 64, v158
	v_xor_b32_e32 v159, 32, v171
	v_cmp_lt_i32_e32 vcc, v145, v158
	v_readfirstlane_b32 s18, v175
	v_readfirstlane_b32 s19, v184
	v_cndmask_b32_e32 v145, v171, v145, vcc
	v_cmp_lt_i32_e32 vcc, v159, v158
	v_lshlrev_b32_e32 v158, 2, v145
	v_readfirstlane_b32 s20, v185
	v_cndmask_b32_e32 v159, v171, v159, vcc
	v_lshlrev_b32_e32 v145, 2, v159
	v_readfirstlane_b32 s21, v186
	s_waitcnt vmcnt(0)
	v_lshlrev_b32_e32 v159, 16, v160
	v_and_b32_e32 v175, 0xffff0000, v160
	v_lshlrev_b32_e32 v184, 16, v161
	v_and_b32_e32 v187, 0xffff0000, v161
	v_mov_b32_e32 v160, v165
	v_mov_b32_e32 v161, v166
	v_mov_b32_e32 v165, v167
	v_pk_add_f32 v[160:161], v[160:161], v[164:165]
	v_lshlrev_b32_e32 v164, 16, v163
	v_add_f32_e32 v160, v160, v161
	ds_bpermute_b32 v161, v158, v160
	v_lshlrev_b32_e32 v165, 16, v176
	v_and_b32_e32 v166, 0xffff0000, v176
	v_lshlrev_b32_e32 v167, 16, v177
	v_and_b32_e32 v176, 0xffff0000, v177
	s_waitcnt lgkmcnt(0)
; __device__ __forceinline__ unsigned cvt_pk_bf16(float lo, float hi) { unsigned r; asm volatile("v_cvt_pk_bf16_f32 %0, %1, %2" : "=v"(r) : "v"(lo), "v"(hi)); return r; }
; __device__ __forceinline__ float bflo(unsigned w) { return __uint_as_float(w << 16); }
;     __device__ __forceinline__ void operator()(const f32x4 (&acc)[2][2][4][2], const Unit& u, int wr, int wc, int fr, int fq, LAS unsigned char* lds) const {
;     ...
;             for (int m = 0; m < 4; ++m) { const int row = row0 + ai * HALF + m * 16; const size_t off = (size_t)row * D + col0;
;                 float rs = 1.0f; if (MODE == 1) rs = rstd_of4(rss_in, row, fq);
;                 float ss = 0.f;
; #pragma unroll
;                 for (int bj = 0; bj < 2; ++bj) { const size_t o = off + bj * HALF; const u32x4 bw = *(const u32x4*)(base + o);
;                     const float bs[8] = {bflo(bw.x), bfhi(bw.x), bflo(bw.y), bfhi(bw.y), bflo(bw.z), bfhi(bw.z), bflo(bw.w), bfhi(bw.w)};
;                     float hn[8];
;                     if (MODE == 0) {
; #pragma unroll
;                         for (int n = 0; n < 2; ++n)
; #pragma unroll
;                             for (int e = 0; e < 4; ++e) hn[4 * n + e] = bs[4 * n + e] + (acc[ai][bj][m][n][e] + bv[bj][n][e]) * scale;
;                     } else { const u32x4 pw = *(const u32x4*)(pp + o);
;                         const float pv[8] = {bflo(pw.x), bfhi(pw.x), bflo(pw.y), bfhi(pw.y), bflo(pw.z), bfhi(pw.z), bflo(pw.w), bfhi(pw.w)};
; #pragma unroll
;                         for (int n = 0; n < 2; ++n)
; #pragma unroll
;                             for (int e = 0; e < 4; ++e) hn[4 * n + e] = bs[4 * n + e] + fast_sigmoid(acc[ai][bj][m][n][e] * rs) * pv[4 * n + e]; }
;                     u32x4 w; w.x = cvt_pk_bf16(hn[0], hn[1]); w.y = cvt_pk_bf16(hn[2], hn[3]); w.z = cvt_pk_bf16(hn[4], hn[5]); w.w = cvt_pk_bf16(hn[6], hn[7]); *(u32x4*)(hb + o) = w;
;                     const float hr[8] = {bflo(w.x), bfhi(w.x), bflo(w.y), bfhi(w.y), bflo(w.z), bfhi(w.z), bflo(w.w), bfhi(w.w)};
;                     ss += ((hr[0] * hr[0] + hr[1] * hr[1]) + (hr[2] * hr[2] + hr[3] * hr[3])) + ((hr[4] * hr[4] + hr[5] * hr[5]) + (hr[6] * hr[6] + hr[7] * hr[7])); }
;                 ss += __shfl_xor(ss, 16); ss += __shfl_xor(ss, 32);
;                 if (fq == 0) rss_out[(size_t)row * 16 + u.pn * 4 + wc] = ss; }
	v_add_f32_e32 v160, v160, v161
	ds_bpermute_b32 v161, v145, v160
	v_lshlrev_b32_e32 v177, 16, v178
	v_lshlrev_b32_e32 v188, 16, v162
	v_and_b32_e32 v162, 0xffff0000, v162
	v_and_b32_e32 v163, 0xffff0000, v163
	s_waitcnt lgkmcnt(0)
	v_add_f32_e32 v160, v160, v161
	v_fmamk_f32 v160, v160, 0x3a800000, v173
	v_mul_f32_e32 v161, 0x4b800000, v160
	v_cmp_gt_f32_e32 vcc, s64, v160
	s_nop 1
	v_cndmask_b32_e32 v160, v160, v161, vcc
	v_rsq_f32_e32 v160, v160
	v_and_b32_e32 v161, 0xffff0000, v178
	v_lshlrev_b32_e32 v178, 16, v179
	v_and_b32_e32 v179, 0xffff0000, v179
	v_mul_f32_e32 v189, 0x45800000, v160
	v_cndmask_b32_e32 v189, v160, v189, vcc
	v_mul_f32_e32 v124, v124, v189
	v_mul_f32_e32 v126, v126, v189
	v_mul_f32_e32 v127, v127, v189
	v_mul_f32_e32 v128, v128, v189
	v_mul_f32_e32 v129, v129, v189
	v_mul_f32_e32 v122, v122, v189
	v_mul_f32_e32 v123, v123, v189
	v_mul_f32_e32 v124, 0xbfb8aa3b, v124
	v_mul_f32_e32 v125, v125, v189
	v_mul_f32_e32 v126, 0xbfb8aa3b, v126
	v_mul_f32_e32 v127, 0xbfb8aa3b, v127
	v_mul_f32_e32 v128, 0xbfb8aa3b, v128
	v_mul_f32_e32 v129, 0xbfb8aa3b, v129
	v_mul_f32_e32 v122, 0xbfb8aa3b, v122
	v_mul_f32_e32 v123, 0xbfb8aa3b, v123
	v_exp_f32_e32 v124, v124
	v_mul_f32_e32 v125, 0xbfb8aa3b, v125
	v_exp_f32_e32 v126, v126
	v_exp_f32_e32 v127, v127
	v_exp_f32_e32 v128, v128
	v_exp_f32_e32 v129, v129
	v_exp_f32_e32 v122, v122
	v_exp_f32_e32 v123, v123
	v_exp_f32_e32 v125, v125
	v_add_f32_e32 v124, 1.0, v124
	v_add_f32_e32 v126, 1.0, v126
	v_add_f32_e32 v127, 1.0, v127
	v_add_f32_e32 v128, 1.0, v128
	v_add_f32_e32 v129, 1.0, v129
	v_add_f32_e32 v122, 1.0, v122
	v_add_f32_e32 v123, 1.0, v123
	v_rcp_f32_e32 v124, v124
	v_add_f32_e32 v125, 1.0, v125
	v_rcp_f32_e32 v126, v126
	v_rcp_f32_e32 v127, v127
	v_rcp_f32_e32 v128, v128
	v_rcp_f32_e32 v129, v129
	v_rcp_f32_e32 v122, v122
	v_rcp_f32_e32 v123, v123
	v_rcp_f32_e32 v125, v125
	v_fmac_f32_e32 v164, v124, v178
	v_fmac_f32_e32 v159, v126, v165
	v_fmac_f32_e32 v175, v127, v166
	v_fmac_f32_e32 v184, v128, v167
	v_fmac_f32_e32 v187, v129, v176
	v_fmac_f32_e32 v188, v122, v177
	v_fmac_f32_e32 v162, v123, v161
	v_fmac_f32_e32 v163, v125, v179
	v_cvt_pk_bf16_f32 v122, v159, v175
	v_cvt_pk_bf16_f32 v123, v184, v187
	v_cvt_pk_bf16_f32 v124, v188, v162
	v_cvt_pk_bf16_f32 v125, v164, v163
	v_lshl_add_u64 v[164:165], s[18:19], 0, v[168:169]
	global_store_dwordx4 v[164:165], v[122:125], off
	v_mov_b32_e32 v126, v200
	v_mov_b32_e32 v127, v201
	v_mov_b32_e32 v128, v202
	v_mov_b32_e32 v129, v203
	v_mov_b32_e32 v160, v204
	v_mov_b32_e32 v161, v205
	v_mov_b32_e32 v162, v206
	v_mov_b32_e32 v163, v207
	v_mul_f32_e32 v118, v118, v189
	v_mul_f32_e32 v119, v119, v189
	v_mul_f32_e32 v115, v115, v189
	v_mul_f32_e32 v116, v116, v189
	v_mul_f32_e32 v120, v120, v189
	v_mul_f32_e32 v121, v121, v189
	v_mul_f32_e32 v114, v114, v189
	v_mul_f32_e32 v118, 0xbfb8aa3b, v118
	v_mul_f32_e32 v119, 0xbfb8aa3b, v119
	v_mul_f32_e32 v115, 0xbfb8aa3b, v115
	v_mul_f32_e32 v116, 0xbfb8aa3b, v116
	v_mul_f32_e32 v117, v117, v189
	v_mul_f32_e32 v120, 0xbfb8aa3b, v120
	v_mul_f32_e32 v121, 0xbfb8aa3b, v121
	v_mul_f32_e32 v114, 0xbfb8aa3b, v114
	v_exp_f32_e32 v118, v118
	v_exp_f32_e32 v119, v119
	v_exp_f32_e32 v115, v115
	v_exp_f32_e32 v116, v116
	v_mul_f32_e32 v117, 0xbfb8aa3b, v117
	v_exp_f32_e32 v120, v120
	v_exp_f32_e32 v121, v121
	v_exp_f32_e32 v114, v114
	v_exp_f32_e32 v117, v117
	v_add_f32_e32 v118, 1.0, v118
	v_add_f32_e32 v119, 1.0, v119
	v_lshlrev_b32_e32 v159, 16, v122
	v_and_b32_e32 v122, 0xffff0000, v122
	v_lshlrev_b32_e32 v166, 16, v123
	v_and_b32_e32 v123, 0xffff0000, v123
	v_lshlrev_b32_e32 v167, 16, v124
	v_and_b32_e32 v124, 0xffff0000, v124
	v_lshlrev_b32_e32 v168, 16, v125
	v_and_b32_e32 v125, 0xffff0000, v125
	v_add_f32_e32 v115, 1.0, v115
	v_add_f32_e32 v116, 1.0, v116
	v_add_f32_e32 v120, 1.0, v120
	v_add_f32_e32 v121, 1.0, v121
	v_rcp_f32_e32 v118, v118
	v_rcp_f32_e32 v119, v119
	v_mul_f32_e32 v122, v122, v122
	v_mul_f32_e32 v123, v123, v123
	v_mul_f32_e32 v124, v124, v124
	v_mul_f32_e32 v125, v125, v125
	v_add_f32_e32 v114, 1.0, v114
	v_rcp_f32_e32 v115, v115
	v_rcp_f32_e32 v116, v116
	v_add_f32_e32 v117, 1.0, v117
	v_rcp_f32_e32 v120, v120
	v_rcp_f32_e32 v121, v121
	v_fmac_f32_e32 v122, v159, v159
	v_fmac_f32_e32 v123, v166, v166
	v_fmac_f32_e32 v124, v167, v167
	v_fmac_f32_e32 v125, v168, v168
	v_rcp_f32_e32 v114, v114
	v_rcp_f32_e32 v117, v117
	v_add_f32_e32 v122, v122, v123
	v_add_f32_e32 v123, v124, v125
	v_add_f32_e32 v122, v122, v123
	s_nop 0
	v_lshlrev_b32_e32 v123, 16, v126
	v_and_b32_e32 v124, 0xffff0000, v126
	v_lshlrev_b32_e32 v125, 16, v127
	v_and_b32_e32 v126, 0xffff0000, v127
	v_lshlrev_b32_e32 v127, 16, v128
	v_and_b32_e32 v128, 0xffff0000, v128
	v_lshlrev_b32_e32 v159, 16, v129
	s_nop 0
	v_lshlrev_b32_e32 v166, 16, v160
	v_and_b32_e32 v160, 0xffff0000, v160
	v_lshlrev_b32_e32 v168, 16, v162
	v_and_b32_e32 v162, 0xffff0000, v162
	v_lshlrev_b32_e32 v169, 16, v163
	v_and_b32_e32 v129, 0xffff0000, v129
	v_lshlrev_b32_e32 v167, 16, v161
	v_and_b32_e32 v161, 0xffff0000, v161
	v_and_b32_e32 v163, 0xffff0000, v163
	v_fmac_f32_e32 v123, v118, v166
	v_fmac_f32_e32 v124, v119, v160
	v_fmac_f32_e32 v128, v115, v162
	v_fmac_f32_e32 v159, v116, v169
	v_cvt_pk_bf16_f32 v116, v123, v124
	v_fmac_f32_e32 v125, v120, v167
	v_and_b32_e32 v115, 0xffff0000, v116
	v_fmac_f32_e32 v126, v121, v161
	v_fmac_f32_e32 v127, v114, v168
	v_fmac_f32_e32 v129, v117, v163
	v_cvt_pk_bf16_f32 v117, v125, v126
	v_lshlrev_b32_e32 v114, 16, v116
	v_and_b32_e32 v121, 0xffff0000, v117
	v_mul_f32_e32 v115, v115, v115
	v_lshlrev_b32_e32 v120, 16, v117
	v_fmac_f32_e32 v115, v114, v114
	v_mul_f32_e32 v114, v121, v121
	v_cvt_pk_bf16_f32 v118, v127, v128
	v_cvt_pk_bf16_f32 v119, v159, v129
	v_fmac_f32_e32 v114, v120, v120
	v_and_b32_e32 v124, 0xffff0000, v118
	v_and_b32_e32 v126, 0xffff0000, v119
	v_lshlrev_b32_e32 v123, 16, v118
	v_lshlrev_b32_e32 v125, 16, v119
	v_add_f32_e32 v114, v115, v114
	v_mul_f32_e32 v115, v124, v124
	v_mul_f32_e32 v120, v126, v126
	v_fmac_f32_e32 v115, v123, v123
	v_fmac_f32_e32 v120, v125, v125
	v_add_f32_e32 v115, v115, v120
	v_add_f32_e32 v114, v114, v115
	v_add_f32_e32 v114, v122, v114
	ds_bpermute_b32 v115, v158, v114
	global_store_dwordx4 v[164:165], v[116:119], off offset:256
	s_waitcnt lgkmcnt(0)
	v_add_f32_e32 v114, v114, v115
	ds_bpermute_b32 v115, v145, v114
	s_and_saveexec_b64 s[24:25], s[6:7]
	s_cbranch_execz .LBB1_26
	s_lshl_b32 s66, s41, 2
	v_lshl_add_u64 v[116:117], s[20:21], 0, v[148:149]
	s_ashr_i32 s67, s66, 31
	v_lshl_add_u64 v[116:117], s[66:67], 2, v[116:117]
	s_lshl_b32 s74, s40, 2
	v_lshl_add_u64 v[116:117], v[116:117], 0, s[74:75]
	s_waitcnt lgkmcnt(0)
	v_add_f32_e32 v114, v114, v115
	global_store_dword v[116:117], v114, off
; __device__ __forceinline__ unsigned cvt_pk_bf16(float lo, float hi) { unsigned r; asm volatile("v_cvt_pk_bf16_f32 %0, %1, %2" : "=v"(r) : "v"(lo), "v"(hi)); return r; }
; __device__ __forceinline__ float bflo(unsigned w) { return __uint_as_float(w << 16); }
;     __device__ __forceinline__ void operator()(const f32x4 (&acc)[2][2][4][2], const Unit& u, int wr, int wc, int fr, int fq, LAS unsigned char* lds) const {
;     ...
;             for (int m = 0; m < 4; ++m) { const int row = row0 + ai * HALF + m * 16; const size_t off = (size_t)row * D + col0;
;                 float rs = 1.0f; if (MODE == 1) rs = rstd_of4(rss_in, row, fq);
;                 float ss = 0.f;
; #pragma unroll
;                 for (int bj = 0; bj < 2; ++bj) { const size_t o = off + bj * HALF; const u32x4 bw = *(const u32x4*)(base + o);
;                     const float bs[8] = {bflo(bw.x), bfhi(bw.x), bflo(bw.y), bfhi(bw.y), bflo(bw.z), bfhi(bw.z), bflo(bw.w), bfhi(bw.w)};
;                     float hn[8];
;                     if (MODE == 0) {
; #pragma unroll
;                         for (int n = 0; n < 2; ++n)
; #pragma unroll
;                             for (int e = 0; e < 4; ++e) hn[4 * n + e] = bs[4 * n + e] + (acc[ai][bj][m][n][e] + bv[bj][n][e]) * scale;
;                     } else { const u32x4 pw = *(const u32x4*)(pp + o);
;                         const float pv[8] = {bflo(pw.x), bfhi(pw.x), bflo(pw.y), bfhi(pw.y), bflo(pw.z), bfhi(pw.z), bflo(pw.w), bfhi(pw.w)};
; #pragma unroll
;                         for (int n = 0; n < 2; ++n)
; #pragma unroll
;                             for (int e = 0; e < 4; ++e) hn[4 * n + e] = bs[4 * n + e] + fast_sigmoid(acc[ai][bj][m][n][e] * rs) * pv[4 * n + e]; }
;                     u32x4 w; w.x = cvt_pk_bf16(hn[0], hn[1]); w.y = cvt_pk_bf16(hn[2], hn[3]); w.z = cvt_pk_bf16(hn[4], hn[5]); w.w = cvt_pk_bf16(hn[6], hn[7]); *(u32x4*)(hb + o) = w;
;                     const float hr[8] = {bflo(w.x), bfhi(w.x), bflo(w.y), bfhi(w.y), bflo(w.z), bfhi(w.z), bflo(w.w), bfhi(w.w)};
;                     ss += ((hr[0] * hr[0] + hr[1] * hr[1]) + (hr[2] * hr[2] + hr[3] * hr[3])) + ((hr[4] * hr[4] + hr[5] * hr[5]) + (hr[6] * hr[6] + hr[7] * hr[7])); }
;                 ss += __shfl_xor(ss, 16); ss += __shfl_xor(ss, 32);
;                 if (fq == 0) rss_out[(size_t)row * 16 + u.pn * 4 + wc] = ss; }
.LBB1_26:
	s_or_b64 exec, exec, s[24:25]
	v_or_b32_e32 v114, 16, v144
	s_waitcnt lgkmcnt(0)
	v_ashrrev_i32_e32 v115, 31, v114
	v_lshlrev_b64 v[116:117], 10, v[114:115]
	v_lshlrev_b64 v[114:115], 6, v[114:115]
	v_lshl_add_u64 v[120:121], v[116:117], 0, v[142:143]
	v_lshl_add_u64 v[116:117], v[146:147], 0, v[114:115]
	global_load_dwordx4 v[116:119], v[116:117], off
	v_lshlrev_b64 v[120:121], 1, v[120:121]
	v_lshl_add_u64 v[216:217], s[16:17], 0, v[120:121]
	v_lshl_add_u64 v[218:219], s[22:23], 0, v[120:121]
	global_load_dwordx4 v[200:203], v[216:217], off
	global_load_dwordx4 v[204:207], v[218:219], off
	global_load_dwordx4 v[208:211], v[216:217], off offset:256
	global_load_dwordx4 v[212:215], v[218:219], off offset:256
	s_waitcnt vmcnt(0)
	v_mov_b32_e32 v122, v117
	v_mov_b32_e32 v123, v118
	v_mov_b32_e32 v117, v119
	v_pk_add_f32 v[116:117], v[122:123], v[116:117]
	v_lshl_add_u64 v[118:119], s[22:23], 0, v[120:121]
	v_add_f32_e32 v116, v116, v117
	ds_bpermute_b32 v117, v158, v116
	s_waitcnt lgkmcnt(0)
	v_add_f32_e32 v116, v116, v117
	ds_bpermute_b32 v117, v145, v116
	s_waitcnt lgkmcnt(0)
	v_add_f32_e32 v116, v116, v117
	v_fmamk_f32 v116, v116, 0x3a800000, v173
	v_cmp_gt_f32_e32 vcc, s64, v116
	v_mul_f32_e32 v117, 0x4b800000, v116
	s_nop 0
	v_cndmask_b32_e32 v116, v116, v117, vcc
	v_rsq_f32_e32 v116, v116
	s_nop 0
	v_mul_f32_e32 v117, 0x45800000, v116
	v_cndmask_b32_e32 v122, v116, v117, vcc
	v_lshl_add_u64 v[116:117], s[16:17], 0, v[120:121]
	v_mov_b32_e32 v124, v200
	v_mov_b32_e32 v125, v201
	v_mov_b32_e32 v126, v202
	v_mov_b32_e32 v127, v203
	v_mul_f32_e32 v110, v110, v122
	v_mul_f32_e32 v110, 0xbfb8aa3b, v110
	v_mul_f32_e32 v106, v106, v122
	v_exp_f32_e32 v110, v110
	v_mul_f32_e32 v106, 0xbfb8aa3b, v106
	v_exp_f32_e32 v106, v106
	v_mul_f32_e32 v102, v102, v122
	v_add_f32_e32 v110, 1.0, v110
	v_rcp_f32_e32 v110, v110
	v_add_f32_e32 v106, 1.0, v106
	v_rcp_f32_e32 v106, v106
	v_mul_f32_e32 v98, v98, v122
	v_mul_f32_e32 v102, 0xbfb8aa3b, v102
	v_mul_f32_e32 v98, 0xbfb8aa3b, v98
	v_exp_f32_e32 v102, v102
	v_exp_f32_e32 v98, v98
	v_add_f32_e32 v102, 1.0, v102
	v_add_f32_e32 v98, 1.0, v98
	v_rcp_f32_e32 v102, v102
	v_rcp_f32_e32 v98, v98
	s_nop 0
	v_lshlrev_b32_e32 v123, 16, v124
	v_and_b32_e32 v128, 0xffff0000, v124
	v_lshlrev_b32_e32 v129, 16, v125
	v_and_b32_e32 v148, 0xffff0000, v125
	v_lshlrev_b32_e32 v149, 16, v126
	v_and_b32_e32 v159, 0xffff0000, v126
	v_lshlrev_b32_e32 v160, 16, v127
	v_and_b32_e32 v161, 0xffff0000, v127
	v_mov_b32_e32 v124, v204
	v_mov_b32_e32 v125, v205
	v_mov_b32_e32 v126, v206
	v_mov_b32_e32 v127, v207
	s_nop 0
	v_lshlrev_b32_e32 v162, 16, v124
	v_lshlrev_b32_e32 v164, 16, v126
	v_fmac_f32_e32 v123, v110, v162
	v_mul_f32_e32 v110, v111, v122
	v_mul_f32_e32 v110, 0xbfb8aa3b, v110
	v_fmac_f32_e32 v149, v106, v164
	v_mul_f32_e32 v106, v107, v122
	v_exp_f32_e32 v110, v110
	v_mul_f32_e32 v106, 0xbfb8aa3b, v106
	v_exp_f32_e32 v106, v106
	v_and_b32_e32 v124, 0xffff0000, v124
	v_add_f32_e32 v110, 1.0, v110
	v_rcp_f32_e32 v110, v110
	v_add_f32_e32 v106, 1.0, v106
	v_rcp_f32_e32 v106, v106
	v_and_b32_e32 v126, 0xffff0000, v126
	v_fmac_f32_e32 v128, v110, v124
	v_mul_f32_e32 v110, v112, v122
	v_mul_f32_e32 v110, 0xbfb8aa3b, v110
	v_fmac_f32_e32 v159, v106, v126
	v_mul_f32_e32 v106, v108, v122
	v_exp_f32_e32 v110, v110
	v_mul_f32_e32 v106, 0xbfb8aa3b, v106
	v_exp_f32_e32 v106, v106
	v_lshlrev_b32_e32 v163, 16, v125
	v_add_f32_e32 v110, 1.0, v110
	v_rcp_f32_e32 v110, v110
	v_add_f32_e32 v106, 1.0, v106
	v_rcp_f32_e32 v106, v106
	v_lshlrev_b32_e32 v165, 16, v127
	v_fmac_f32_e32 v129, v110, v163
	v_mul_f32_e32 v110, v113, v122
	v_mul_f32_e32 v110, 0xbfb8aa3b, v110
	v_fmac_f32_e32 v160, v106, v165
	v_mul_f32_e32 v106, v109, v122
	v_exp_f32_e32 v110, v110
	v_mul_f32_e32 v106, 0xbfb8aa3b, v106
	v_exp_f32_e32 v106, v106
	v_and_b32_e32 v125, 0xffff0000, v125
	v_add_f32_e32 v110, 1.0, v110
	v_rcp_f32_e32 v110, v110
	v_add_f32_e32 v106, 1.0, v106
	v_rcp_f32_e32 v106, v106
	v_and_b32_e32 v127, 0xffff0000, v127
	v_fmac_f32_e32 v148, v110, v125
	v_lshl_add_u64 v[110:111], s[18:19], 0, v[120:121]
	v_fmac_f32_e32 v161, v106, v127
	v_cvt_pk_bf16_f32 v106, v123, v128
	v_cvt_pk_bf16_f32 v107, v129, v148
	v_cvt_pk_bf16_f32 v108, v149, v159
	v_cvt_pk_bf16_f32 v109, v160, v161
	global_store_dwordx4 v[110:111], v[106:109], off
	v_mov_b32_e32 v124, v208
	v_mov_b32_e32 v125, v209
	v_mov_b32_e32 v126, v210
	v_mov_b32_e32 v127, v211
	v_lshlrev_b32_e32 v112, 16, v106
	v_and_b32_e32 v106, 0xffff0000, v106
	v_lshlrev_b32_e32 v113, 16, v107
	v_and_b32_e32 v107, 0xffff0000, v107
	v_mul_f32_e32 v106, v106, v106
	v_mul_f32_e32 v107, v107, v107
	v_lshlrev_b32_e32 v120, 16, v108
	v_and_b32_e32 v108, 0xffff0000, v108
	v_lshlrev_b32_e32 v121, 16, v109
	v_and_b32_e32 v109, 0xffff0000, v109
	v_fmac_f32_e32 v106, v112, v112
	v_fmac_f32_e32 v107, v113, v113
	v_add_f32_e32 v106, v106, v107
	v_mul_f32_e32 v107, v108, v108
	v_mul_f32_e32 v108, v109, v109
	v_fmac_f32_e32 v107, v120, v120
	v_fmac_f32_e32 v108, v121, v121
	v_add_f32_e32 v107, v107, v108
	v_add_f32_e32 v106, v106, v107
	s_nop 0
	v_lshlrev_b32_e32 v107, 16, v124
	v_and_b32_e32 v108, 0xffff0000, v124
	v_lshlrev_b32_e32 v109, 16, v125
	v_and_b32_e32 v112, 0xffff0000, v125
	v_lshlrev_b32_e32 v113, 16, v126
	v_and_b32_e32 v116, 0xffff0000, v126
	v_lshlrev_b32_e32 v117, 16, v127
	v_and_b32_e32 v120, 0xffff0000, v127
	v_mov_b32_e32 v124, v212
	v_mov_b32_e32 v125, v213
	v_mov_b32_e32 v126, v214
	v_mov_b32_e32 v127, v215
	s_nop 0
	v_lshlrev_b32_e32 v118, 16, v124
	v_and_b32_e32 v119, 0xffff0000, v124
	v_lshlrev_b32_e32 v124, 16, v126
	v_fmac_f32_e32 v107, v102, v118
	v_mul_f32_e32 v102, v103, v122
; __device__ __forceinline__ unsigned cvt_pk_bf16(float lo, float hi) { unsigned r; asm volatile("v_cvt_pk_bf16_f32 %0, %1, %2" : "=v"(r) : "v"(lo), "v"(hi)); return r; }
; __device__ __forceinline__ float bflo(unsigned w) { return __uint_as_float(w << 16); }
;     __device__ __forceinline__ void operator()(const f32x4 (&acc)[2][2][4][2], const Unit& u, int wr, int wc, int fr, int fq, LAS unsigned char* lds) const {
;     ...
;             for (int m = 0; m < 4; ++m) { const int row = row0 + ai * HALF + m * 16; const size_t off = (size_t)row * D + col0;
;                 float rs = 1.0f; if (MODE == 1) rs = rstd_of4(rss_in, row, fq);
;                 float ss = 0.f;
; #pragma unroll
;                 for (int bj = 0; bj < 2; ++bj) { const size_t o = off + bj * HALF; const u32x4 bw = *(const u32x4*)(base + o);
;                     const float bs[8] = {bflo(bw.x), bfhi(bw.x), bflo(bw.y), bfhi(bw.y), bflo(bw.z), bfhi(bw.z), bflo(bw.w), bfhi(bw.w)};
;                     float hn[8];
;                     if (MODE == 0) {
; #pragma unroll
;                         for (int n = 0; n < 2; ++n)
; #pragma unroll
;                             for (int e = 0; e < 4; ++e) hn[4 * n + e] = bs[4 * n + e] + (acc[ai][bj][m][n][e] + bv[bj][n][e]) * scale;
;                     } else { const u32x4 pw = *(const u32x4*)(pp + o);
;                         const float pv[8] = {bflo(pw.x), bfhi(pw.x), bflo(pw.y), bfhi(pw.y), bflo(pw.z), bfhi(pw.z), bflo(pw.w), bfhi(pw.w)};
; #pragma unroll
;                         for (int n = 0; n < 2; ++n)
; #pragma unroll
;                             for (int e = 0; e < 4; ++e) hn[4 * n + e] = bs[4 * n + e] + fast_sigmoid(acc[ai][bj][m][n][e] * rs) * pv[4 * n + e]; }
;                     u32x4 w; w.x = cvt_pk_bf16(hn[0], hn[1]); w.y = cvt_pk_bf16(hn[2], hn[3]); w.z = cvt_pk_bf16(hn[4], hn[5]); w.w = cvt_pk_bf16(hn[6], hn[7]); *(u32x4*)(hb + o) = w;
;                     const float hr[8] = {bflo(w.x), bfhi(w.x), bflo(w.y), bfhi(w.y), bflo(w.z), bfhi(w.z), bflo(w.w), bfhi(w.w)};
;                     ss += ((hr[0] * hr[0] + hr[1] * hr[1]) + (hr[2] * hr[2] + hr[3] * hr[3])) + ((hr[4] * hr[4] + hr[5] * hr[5]) + (hr[6] * hr[6] + hr[7] * hr[7])); }
;                 ss += __shfl_xor(ss, 16); ss += __shfl_xor(ss, 32);
;                 if (fq == 0) rss_out[(size_t)row * 16 + u.pn * 4 + wc] = ss; }
	v_fmac_f32_e32 v113, v98, v124
	v_mul_f32_e32 v98, v99, v122
	v_mul_f32_e32 v102, 0xbfb8aa3b, v102
	v_mul_f32_e32 v98, 0xbfb8aa3b, v98
	v_exp_f32_e32 v102, v102
	v_exp_f32_e32 v98, v98
	v_lshlrev_b32_e32 v121, 16, v125
	v_and_b32_e32 v123, 0xffff0000, v125
	v_add_f32_e32 v102, 1.0, v102
	v_add_f32_e32 v98, 1.0, v98
	v_rcp_f32_e32 v102, v102
	v_rcp_f32_e32 v98, v98
	v_and_b32_e32 v125, 0xffff0000, v126
	v_lshlrev_b32_e32 v126, 16, v127
	v_fmac_f32_e32 v108, v102, v119
	v_mul_f32_e32 v102, v104, v122
	v_fmac_f32_e32 v116, v98, v125
	v_mul_f32_e32 v98, v100, v122
	v_mul_f32_e32 v102, 0xbfb8aa3b, v102
	v_mul_f32_e32 v98, 0xbfb8aa3b, v98
	v_exp_f32_e32 v102, v102
	v_exp_f32_e32 v98, v98
	v_and_b32_e32 v127, 0xffff0000, v127
	v_add_f32_e32 v102, 1.0, v102
	v_add_f32_e32 v98, 1.0, v98
	v_rcp_f32_e32 v102, v102
	v_rcp_f32_e32 v98, v98
	v_fmac_f32_e32 v109, v102, v121
	v_mul_f32_e32 v102, v105, v122
	v_fmac_f32_e32 v117, v98, v126
	v_mul_f32_e32 v98, v101, v122
	v_mul_f32_e32 v102, 0xbfb8aa3b, v102
	v_mul_f32_e32 v98, 0xbfb8aa3b, v98
	v_exp_f32_e32 v102, v102
	v_exp_f32_e32 v98, v98
	v_add_f32_e32 v102, 1.0, v102
	v_add_f32_e32 v98, 1.0, v98
	v_rcp_f32_e32 v102, v102
	v_rcp_f32_e32 v98, v98
	v_fmac_f32_e32 v112, v102, v123
	v_fmac_f32_e32 v120, v98, v127
	v_cvt_pk_bf16_f32 v98, v107, v108
	v_cvt_pk_bf16_f32 v99, v109, v112
	v_cvt_pk_bf16_f32 v100, v113, v116
	v_cvt_pk_bf16_f32 v101, v117, v120
	global_store_dwordx4 v[110:111], v[98:101], off offset:256
	v_lshlrev_b32_e32 v102, 16, v98
	v_lshlrev_b32_e32 v103, 16, v99
	v_and_b32_e32 v98, 0xffff0000, v98
	v_and_b32_e32 v99, 0xffff0000, v99
	v_mul_f32_e32 v98, v98, v98
	v_mul_f32_e32 v99, v99, v99
	v_lshlrev_b32_e32 v104, 16, v100
	v_and_b32_e32 v100, 0xffff0000, v100
	v_lshlrev_b32_e32 v105, 16, v101
	v_and_b32_e32 v101, 0xffff0000, v101
	v_fmac_f32_e32 v98, v102, v102
	v_fmac_f32_e32 v99, v103, v103
	v_add_f32_e32 v98, v98, v99
	v_mul_f32_e32 v99, v100, v100
	v_mul_f32_e32 v100, v101, v101
	v_fmac_f32_e32 v99, v104, v104
	v_fmac_f32_e32 v100, v105, v105
	v_add_f32_e32 v99, v99, v100
	v_add_f32_e32 v98, v98, v99
	v_add_f32_e32 v98, v106, v98
	ds_bpermute_b32 v99, v158, v98
	s_waitcnt lgkmcnt(0)
	v_add_f32_e32 v98, v98, v99
	ds_bpermute_b32 v99, v145, v98
	s_and_saveexec_b64 s[24:25], s[6:7]
	s_cbranch_execz .LBB1_28
	s_lshl_b32 s66, s41, 2
	v_lshl_add_u64 v[100:101], s[20:21], 0, v[114:115]
	s_ashr_i32 s67, s66, 31
	v_lshl_add_u64 v[100:101], s[66:67], 2, v[100:101]
	s_lshl_b32 s74, s40, 2
	v_lshl_add_u64 v[100:101], v[100:101], 0, s[74:75]
	s_waitcnt lgkmcnt(0)
	v_add_f32_e32 v98, v98, v99
	global_store_dword v[100:101], v98, off
.LBB1_28:
	s_or_b64 exec, exec, s[24:25]
	v_or_b32_e32 v98, 32, v144
	s_waitcnt lgkmcnt(0)
	v_ashrrev_i32_e32 v99, 31, v98
	v_lshlrev_b64 v[100:101], 10, v[98:99]
	v_lshlrev_b64 v[98:99], 6, v[98:99]
	v_lshl_add_u64 v[104:105], v[100:101], 0, v[142:143]
	v_lshl_add_u64 v[100:101], v[146:147], 0, v[98:99]
	global_load_dwordx4 v[100:103], v[100:101], off
	v_lshlrev_b64 v[104:105], 1, v[104:105]
	v_lshl_add_u64 v[216:217], s[16:17], 0, v[104:105]
	v_lshl_add_u64 v[218:219], s[22:23], 0, v[104:105]
	global_load_dwordx4 v[200:203], v[216:217], off
	global_load_dwordx4 v[204:207], v[218:219], off
	global_load_dwordx4 v[208:211], v[216:217], off offset:256
	global_load_dwordx4 v[212:215], v[218:219], off offset:256
	s_waitcnt vmcnt(0)
	v_mov_b32_e32 v106, v101
	v_mov_b32_e32 v107, v102
	v_mov_b32_e32 v101, v103
	v_pk_add_f32 v[100:101], v[106:107], v[100:101]
	v_lshl_add_u64 v[102:103], s[22:23], 0, v[104:105]
	v_add_f32_e32 v100, v100, v101
	ds_bpermute_b32 v101, v158, v100
	s_waitcnt lgkmcnt(0)
	v_add_f32_e32 v100, v100, v101
	ds_bpermute_b32 v101, v145, v100
	s_waitcnt lgkmcnt(0)
	v_add_f32_e32 v100, v100, v101
	v_fmamk_f32 v100, v100, 0x3a800000, v173
	v_cmp_gt_f32_e32 vcc, s64, v100
	v_mul_f32_e32 v101, 0x4b800000, v100
	s_nop 0
	v_cndmask_b32_e32 v100, v100, v101, vcc
	v_rsq_f32_e32 v100, v100
	s_nop 0
	v_mul_f32_e32 v101, 0x45800000, v100
	v_cndmask_b32_e32 v106, v100, v101, vcc
	v_lshl_add_u64 v[100:101], s[16:17], 0, v[104:105]
	v_mov_b32_e32 v108, v200
	v_mov_b32_e32 v109, v201
	v_mov_b32_e32 v110, v202
	v_mov_b32_e32 v111, v203
	v_mul_f32_e32 v94, v94, v106
	v_mul_f32_e32 v94, 0xbfb8aa3b, v94
	v_mul_f32_e32 v90, v90, v106
	v_exp_f32_e32 v94, v94
	v_mul_f32_e32 v90, 0xbfb8aa3b, v90
	v_exp_f32_e32 v90, v90
	v_mul_f32_e32 v86, v86, v106
	v_add_f32_e32 v94, 1.0, v94
	v_rcp_f32_e32 v94, v94
	v_add_f32_e32 v90, 1.0, v90
	v_rcp_f32_e32 v90, v90
	v_mul_f32_e32 v82, v82, v106
	v_mul_f32_e32 v86, 0xbfb8aa3b, v86
	v_mul_f32_e32 v82, 0xbfb8aa3b, v82
	v_exp_f32_e32 v86, v86
	v_exp_f32_e32 v82, v82
	v_add_f32_e32 v86, 1.0, v86
	v_add_f32_e32 v82, 1.0, v82
	v_rcp_f32_e32 v86, v86
	v_rcp_f32_e32 v82, v82
	s_nop 0
	v_lshlrev_b32_e32 v107, 16, v108
	v_and_b32_e32 v112, 0xffff0000, v108
	v_lshlrev_b32_e32 v113, 16, v109
	v_and_b32_e32 v114, 0xffff0000, v109
	v_lshlrev_b32_e32 v115, 16, v110
	v_and_b32_e32 v116, 0xffff0000, v110
	v_lshlrev_b32_e32 v117, 16, v111
	v_and_b32_e32 v118, 0xffff0000, v111
	v_mov_b32_e32 v108, v204
	v_mov_b32_e32 v109, v205
	v_mov_b32_e32 v110, v206
	v_mov_b32_e32 v111, v207
	s_nop 0
	v_lshlrev_b32_e32 v119, 16, v108
	v_lshlrev_b32_e32 v121, 16, v110
	v_fmac_f32_e32 v107, v94, v119
	v_mul_f32_e32 v94, v95, v106
	v_mul_f32_e32 v94, 0xbfb8aa3b, v94
	v_fmac_f32_e32 v115, v90, v121
	v_mul_f32_e32 v90, v91, v106
	v_exp_f32_e32 v94, v94
	v_mul_f32_e32 v90, 0xbfb8aa3b, v90
	v_exp_f32_e32 v90, v90
	v_and_b32_e32 v108, 0xffff0000, v108
	v_add_f32_e32 v94, 1.0, v94
	v_rcp_f32_e32 v94, v94
	v_add_f32_e32 v90, 1.0, v90
	v_rcp_f32_e32 v90, v90
	v_and_b32_e32 v110, 0xffff0000, v110
; __device__ __forceinline__ unsigned cvt_pk_bf16(float lo, float hi) { unsigned r; asm volatile("v_cvt_pk_bf16_f32 %0, %1, %2" : "=v"(r) : "v"(lo), "v"(hi)); return r; }
; __device__ __forceinline__ float bflo(unsigned w) { return __uint_as_float(w << 16); }
;     __device__ __forceinline__ void operator()(const f32x4 (&acc)[2][2][4][2], const Unit& u, int wr, int wc, int fr, int fq, LAS unsigned char* lds) const {
;     ...
;             for (int m = 0; m < 4; ++m) { const int row = row0 + ai * HALF + m * 16; const size_t off = (size_t)row * D + col0;
;                 float rs = 1.0f; if (MODE == 1) rs = rstd_of4(rss_in, row, fq);
;                 float ss = 0.f;
; #pragma unroll
;                 for (int bj = 0; bj < 2; ++bj) { const size_t o = off + bj * HALF; const u32x4 bw = *(const u32x4*)(base + o);
;                     const float bs[8] = {bflo(bw.x), bfhi(bw.x), bflo(bw.y), bfhi(bw.y), bflo(bw.z), bfhi(bw.z), bflo(bw.w), bfhi(bw.w)};
;                     float hn[8];
;                     if (MODE == 0) {
; #pragma unroll
;                         for (int n = 0; n < 2; ++n)
; #pragma unroll
;                             for (int e = 0; e < 4; ++e) hn[4 * n + e] = bs[4 * n + e] + (acc[ai][bj][m][n][e] + bv[bj][n][e]) * scale;
;                     } else { const u32x4 pw = *(const u32x4*)(pp + o);
;                         const float pv[8] = {bflo(pw.x), bfhi(pw.x), bflo(pw.y), bfhi(pw.y), bflo(pw.z), bfhi(pw.z), bflo(pw.w), bfhi(pw.w)};
; #pragma unroll
;                         for (int n = 0; n < 2; ++n)
; #pragma unroll
;                             for (int e = 0; e < 4; ++e) hn[4 * n + e] = bs[4 * n + e] + fast_sigmoid(acc[ai][bj][m][n][e] * rs) * pv[4 * n + e]; }
;                     u32x4 w; w.x = cvt_pk_bf16(hn[0], hn[1]); w.y = cvt_pk_bf16(hn[2], hn[3]); w.z = cvt_pk_bf16(hn[4], hn[5]); w.w = cvt_pk_bf16(hn[6], hn[7]); *(u32x4*)(hb + o) = w;
;                     const float hr[8] = {bflo(w.x), bfhi(w.x), bflo(w.y), bfhi(w.y), bflo(w.z), bfhi(w.z), bflo(w.w), bfhi(w.w)};
;                     ss += ((hr[0] * hr[0] + hr[1] * hr[1]) + (hr[2] * hr[2] + hr[3] * hr[3])) + ((hr[4] * hr[4] + hr[5] * hr[5]) + (hr[6] * hr[6] + hr[7] * hr[7])); }
;                 ss += __shfl_xor(ss, 16); ss += __shfl_xor(ss, 32);
;                 if (fq == 0) rss_out[(size_t)row * 16 + u.pn * 4 + wc] = ss; }
	v_fmac_f32_e32 v112, v94, v108
	v_mul_f32_e32 v94, v96, v106
	v_mul_f32_e32 v94, 0xbfb8aa3b, v94
	v_fmac_f32_e32 v116, v90, v110
	v_mul_f32_e32 v90, v92, v106
	v_exp_f32_e32 v94, v94
	v_mul_f32_e32 v90, 0xbfb8aa3b, v90
	v_exp_f32_e32 v90, v90
	v_lshlrev_b32_e32 v120, 16, v109
	v_add_f32_e32 v94, 1.0, v94
	v_rcp_f32_e32 v94, v94
	v_add_f32_e32 v90, 1.0, v90
	v_rcp_f32_e32 v90, v90
	v_lshlrev_b32_e32 v122, 16, v111
	v_fmac_f32_e32 v113, v94, v120
	v_mul_f32_e32 v94, v97, v106
	v_mul_f32_e32 v94, 0xbfb8aa3b, v94
	v_fmac_f32_e32 v117, v90, v122
	v_mul_f32_e32 v90, v93, v106
	v_exp_f32_e32 v94, v94
	v_mul_f32_e32 v90, 0xbfb8aa3b, v90
	v_exp_f32_e32 v90, v90
	v_and_b32_e32 v109, 0xffff0000, v109
	v_add_f32_e32 v94, 1.0, v94
	v_rcp_f32_e32 v94, v94
	v_add_f32_e32 v90, 1.0, v90
	v_rcp_f32_e32 v90, v90
	v_and_b32_e32 v111, 0xffff0000, v111
	v_fmac_f32_e32 v114, v94, v109
	v_lshl_add_u64 v[94:95], s[18:19], 0, v[104:105]
	v_fmac_f32_e32 v118, v90, v111
	v_cvt_pk_bf16_f32 v90, v107, v112
	v_cvt_pk_bf16_f32 v91, v113, v114
	v_cvt_pk_bf16_f32 v92, v115, v116
	v_cvt_pk_bf16_f32 v93, v117, v118
	global_store_dwordx4 v[94:95], v[90:93], off
	v_mov_b32_e32 v108, v208
	v_mov_b32_e32 v109, v209
	v_mov_b32_e32 v110, v210
	v_mov_b32_e32 v111, v211
	v_lshlrev_b32_e32 v96, 16, v90
	v_and_b32_e32 v90, 0xffff0000, v90
	v_lshlrev_b32_e32 v97, 16, v91
	v_and_b32_e32 v91, 0xffff0000, v91
	v_mul_f32_e32 v90, v90, v90
	v_mul_f32_e32 v91, v91, v91
	v_lshlrev_b32_e32 v104, 16, v92
	v_and_b32_e32 v92, 0xffff0000, v92
	v_lshlrev_b32_e32 v105, 16, v93
	v_and_b32_e32 v93, 0xffff0000, v93
	v_fmac_f32_e32 v90, v96, v96
	v_fmac_f32_e32 v91, v97, v97
	v_add_f32_e32 v90, v90, v91
	v_mul_f32_e32 v91, v92, v92
	v_mul_f32_e32 v92, v93, v93
	v_fmac_f32_e32 v91, v104, v104
	v_fmac_f32_e32 v92, v105, v105
	v_add_f32_e32 v91, v91, v92
	v_add_f32_e32 v90, v90, v91
	s_nop 0
	v_lshlrev_b32_e32 v91, 16, v108
	v_and_b32_e32 v92, 0xffff0000, v108
	v_lshlrev_b32_e32 v93, 16, v109
	v_and_b32_e32 v96, 0xffff0000, v109
	v_lshlrev_b32_e32 v97, 16, v110
	v_and_b32_e32 v100, 0xffff0000, v110
	v_lshlrev_b32_e32 v101, 16, v111
	v_and_b32_e32 v104, 0xffff0000, v111
	v_mov_b32_e32 v108, v212
	v_mov_b32_e32 v109, v213
	v_mov_b32_e32 v110, v214
	v_mov_b32_e32 v111, v215
	s_nop 0
	v_lshlrev_b32_e32 v102, 16, v108
	v_and_b32_e32 v103, 0xffff0000, v108
	v_lshlrev_b32_e32 v108, 16, v110
	v_fmac_f32_e32 v91, v86, v102
	v_mul_f32_e32 v86, v87, v106
	v_fmac_f32_e32 v97, v82, v108
	v_mul_f32_e32 v82, v83, v106
	v_mul_f32_e32 v86, 0xbfb8aa3b, v86
	v_mul_f32_e32 v82, 0xbfb8aa3b, v82
	v_exp_f32_e32 v86, v86
	v_exp_f32_e32 v82, v82
	v_lshlrev_b32_e32 v105, 16, v109
	v_and_b32_e32 v107, 0xffff0000, v109
	v_add_f32_e32 v86, 1.0, v86
	v_add_f32_e32 v82, 1.0, v82
	v_rcp_f32_e32 v86, v86
	v_rcp_f32_e32 v82, v82
	v_and_b32_e32 v109, 0xffff0000, v110
	v_lshlrev_b32_e32 v110, 16, v111
	v_fmac_f32_e32 v92, v86, v103
	v_mul_f32_e32 v86, v88, v106
	v_fmac_f32_e32 v100, v82, v109
	v_mul_f32_e32 v82, v84, v106
	v_mul_f32_e32 v86, 0xbfb8aa3b, v86
	v_mul_f32_e32 v82, 0xbfb8aa3b, v82
	v_exp_f32_e32 v86, v86
	v_exp_f32_e32 v82, v82
	v_and_b32_e32 v111, 0xffff0000, v111
	v_add_f32_e32 v86, 1.0, v86
	v_add_f32_e32 v82, 1.0, v82
	v_rcp_f32_e32 v86, v86
	v_rcp_f32_e32 v82, v82
	v_fmac_f32_e32 v93, v86, v105
	v_mul_f32_e32 v86, v89, v106
	v_fmac_f32_e32 v101, v82, v110
	v_mul_f32_e32 v82, v85, v106
	v_mul_f32_e32 v86, 0xbfb8aa3b, v86
	v_mul_f32_e32 v82, 0xbfb8aa3b, v82
	v_exp_f32_e32 v86, v86
	v_exp_f32_e32 v82, v82
	v_add_f32_e32 v86, 1.0, v86
	v_add_f32_e32 v82, 1.0, v82
	v_rcp_f32_e32 v86, v86
	v_rcp_f32_e32 v82, v82
	v_fmac_f32_e32 v96, v86, v107
	v_fmac_f32_e32 v104, v82, v111
	v_cvt_pk_bf16_f32 v82, v91, v92
	v_cvt_pk_bf16_f32 v83, v93, v96
	v_cvt_pk_bf16_f32 v84, v97, v100
	v_cvt_pk_bf16_f32 v85, v101, v104
	global_store_dwordx4 v[94:95], v[82:85], off offset:256
	v_lshlrev_b32_e32 v86, 16, v82
	v_lshlrev_b32_e32 v87, 16, v83
	v_and_b32_e32 v82, 0xffff0000, v82
	v_and_b32_e32 v83, 0xffff0000, v83
	v_mul_f32_e32 v82, v82, v82
	v_mul_f32_e32 v83, v83, v83
	v_lshlrev_b32_e32 v88, 16, v84
	v_and_b32_e32 v84, 0xffff0000, v84
	v_lshlrev_b32_e32 v89, 16, v85
	v_and_b32_e32 v85, 0xffff0000, v85
	v_fmac_f32_e32 v82, v86, v86
	v_fmac_f32_e32 v83, v87, v87
	v_add_f32_e32 v82, v82, v83
	v_mul_f32_e32 v83, v84, v84
	v_mul_f32_e32 v84, v85, v85
	v_fmac_f32_e32 v83, v88, v88
	v_fmac_f32_e32 v84, v89, v89
	v_add_f32_e32 v83, v83, v84
	v_add_f32_e32 v82, v82, v83
	v_add_f32_e32 v82, v90, v82
	ds_bpermute_b32 v83, v158, v82
	s_waitcnt lgkmcnt(0)
	v_add_f32_e32 v82, v82, v83
	ds_bpermute_b32 v83, v145, v82
	s_and_saveexec_b64 s[24:25], s[6:7]
	s_cbranch_execz .LBB1_30
	s_lshl_b32 s66, s41, 2
	v_lshl_add_u64 v[84:85], s[20:21], 0, v[98:99]
	s_ashr_i32 s67, s66, 31
	v_lshl_add_u64 v[84:85], s[66:67], 2, v[84:85]
	s_lshl_b32 s74, s40, 2
	v_lshl_add_u64 v[84:85], v[84:85], 0, s[74:75]
	s_waitcnt lgkmcnt(0)
	v_add_f32_e32 v82, v82, v83
	global_store_dword v[84:85], v82, off
; __device__ __forceinline__ unsigned cvt_pk_bf16(float lo, float hi) { unsigned r; asm volatile("v_cvt_pk_bf16_f32 %0, %1, %2" : "=v"(r) : "v"(lo), "v"(hi)); return r; }
; __device__ __forceinline__ float bflo(unsigned w) { return __uint_as_float(w << 16); }
;     __device__ __forceinline__ void operator()(const f32x4 (&acc)[2][2][4][2], const Unit& u, int wr, int wc, int fr, int fq, LAS unsigned char* lds) const {
;     ...
;             for (int m = 0; m < 4; ++m) { const int row = row0 + ai * HALF + m * 16; const size_t off = (size_t)row * D + col0;
;                 float rs = 1.0f; if (MODE == 1) rs = rstd_of4(rss_in, row, fq);
;                 float ss = 0.f;
; #pragma unroll
;                 for (int bj = 0; bj < 2; ++bj) { const size_t o = off + bj * HALF; const u32x4 bw = *(const u32x4*)(base + o);
;                     const float bs[8] = {bflo(bw.x), bfhi(bw.x), bflo(bw.y), bfhi(bw.y), bflo(bw.z), bfhi(bw.z), bflo(bw.w), bfhi(bw.w)};
;                     float hn[8];
;                     if (MODE == 0) {
; #pragma unroll
;                         for (int n = 0; n < 2; ++n)
; #pragma unroll
;                             for (int e = 0; e < 4; ++e) hn[4 * n + e] = bs[4 * n + e] + (acc[ai][bj][m][n][e] + bv[bj][n][e]) * scale;
;                     } else { const u32x4 pw = *(const u32x4*)(pp + o);
;                         const float pv[8] = {bflo(pw.x), bfhi(pw.x), bflo(pw.y), bfhi(pw.y), bflo(pw.z), bfhi(pw.z), bflo(pw.w), bfhi(pw.w)};
; #pragma unroll
;                         for (int n = 0; n < 2; ++n)
; #pragma unroll
;                             for (int e = 0; e < 4; ++e) hn[4 * n + e] = bs[4 * n + e] + fast_sigmoid(acc[ai][bj][m][n][e] * rs) * pv[4 * n + e]; }
;                     u32x4 w; w.x = cvt_pk_bf16(hn[0], hn[1]); w.y = cvt_pk_bf16(hn[2], hn[3]); w.z = cvt_pk_bf16(hn[4], hn[5]); w.w = cvt_pk_bf16(hn[6], hn[7]); *(u32x4*)(hb + o) = w;
;                     const float hr[8] = {bflo(w.x), bfhi(w.x), bflo(w.y), bfhi(w.y), bflo(w.z), bfhi(w.z), bflo(w.w), bfhi(w.w)};
;                     ss += ((hr[0] * hr[0] + hr[1] * hr[1]) + (hr[2] * hr[2] + hr[3] * hr[3])) + ((hr[4] * hr[4] + hr[5] * hr[5]) + (hr[6] * hr[6] + hr[7] * hr[7])); }
;                 ss += __shfl_xor(ss, 16); ss += __shfl_xor(ss, 32);
;                 if (fq == 0) rss_out[(size_t)row * 16 + u.pn * 4 + wc] = ss; }
.LBB1_30:
	s_or_b64 exec, exec, s[24:25]
	v_or_b32_e32 v82, 48, v144
	s_waitcnt lgkmcnt(0)
	v_ashrrev_i32_e32 v83, 31, v82
	v_lshlrev_b64 v[84:85], 10, v[82:83]
	v_lshlrev_b64 v[82:83], 6, v[82:83]
	v_lshl_add_u64 v[88:89], v[84:85], 0, v[142:143]
	v_lshl_add_u64 v[84:85], v[146:147], 0, v[82:83]
	global_load_dwordx4 v[84:87], v[84:85], off
	v_lshlrev_b64 v[88:89], 1, v[88:89]
	v_lshl_add_u64 v[216:217], s[16:17], 0, v[88:89]
	v_lshl_add_u64 v[218:219], s[22:23], 0, v[88:89]
	global_load_dwordx4 v[200:203], v[216:217], off
	global_load_dwordx4 v[204:207], v[218:219], off
	global_load_dwordx4 v[208:211], v[216:217], off offset:256
	global_load_dwordx4 v[212:215], v[218:219], off offset:256
	s_waitcnt vmcnt(0)
	v_mov_b32_e32 v90, v85
	v_mov_b32_e32 v91, v86
	v_mov_b32_e32 v85, v87
	v_pk_add_f32 v[84:85], v[90:91], v[84:85]
	v_lshl_add_u64 v[86:87], s[22:23], 0, v[88:89]
	v_add_f32_e32 v84, v84, v85
	ds_bpermute_b32 v85, v158, v84
	s_waitcnt lgkmcnt(0)
	v_add_f32_e32 v84, v84, v85
	ds_bpermute_b32 v85, v145, v84
	s_waitcnt lgkmcnt(0)
	v_add_f32_e32 v84, v84, v85
	v_fmamk_f32 v84, v84, 0x3a800000, v173
	v_cmp_gt_f32_e32 vcc, s64, v84
	v_mul_f32_e32 v85, 0x4b800000, v84
	s_nop 0
	v_cndmask_b32_e32 v84, v84, v85, vcc
	v_rsq_f32_e32 v84, v84
	s_nop 0
	v_mul_f32_e32 v85, 0x45800000, v84
	v_cndmask_b32_e32 v90, v84, v85, vcc
	v_lshl_add_u64 v[84:85], s[16:17], 0, v[88:89]
	v_mov_b32_e32 v92, v200
	v_mov_b32_e32 v93, v201
	v_mov_b32_e32 v94, v202
	v_mov_b32_e32 v95, v203
	v_mul_f32_e32 v78, v78, v90
	v_mul_f32_e32 v78, 0xbfb8aa3b, v78
	v_mul_f32_e32 v74, v74, v90
	v_exp_f32_e32 v78, v78
	v_mul_f32_e32 v74, 0xbfb8aa3b, v74
	v_exp_f32_e32 v74, v74
	v_mul_f32_e32 v70, v70, v90
	v_add_f32_e32 v78, 1.0, v78
	v_rcp_f32_e32 v78, v78
	v_add_f32_e32 v74, 1.0, v74
	v_rcp_f32_e32 v74, v74
	v_mul_f32_e32 v66, v66, v90
	v_mul_f32_e32 v70, 0xbfb8aa3b, v70
	v_mul_f32_e32 v66, 0xbfb8aa3b, v66
	v_exp_f32_e32 v70, v70
	v_exp_f32_e32 v66, v66
	v_add_f32_e32 v70, 1.0, v70
	v_add_f32_e32 v66, 1.0, v66
	v_rcp_f32_e32 v70, v70
	v_rcp_f32_e32 v66, v66
	s_nop 0
	v_lshlrev_b32_e32 v91, 16, v92
	v_and_b32_e32 v96, 0xffff0000, v92
	v_lshlrev_b32_e32 v97, 16, v93
	v_and_b32_e32 v98, 0xffff0000, v93
	v_lshlrev_b32_e32 v99, 16, v94
	v_and_b32_e32 v100, 0xffff0000, v94
	v_lshlrev_b32_e32 v101, 16, v95
	v_and_b32_e32 v102, 0xffff0000, v95
	v_mov_b32_e32 v92, v204
	v_mov_b32_e32 v93, v205
	v_mov_b32_e32 v94, v206
	v_mov_b32_e32 v95, v207
	s_nop 0
	v_lshlrev_b32_e32 v103, 16, v92
	v_lshlrev_b32_e32 v105, 16, v94
	v_fmac_f32_e32 v91, v78, v103
	v_mul_f32_e32 v78, v79, v90
	v_mul_f32_e32 v78, 0xbfb8aa3b, v78
	v_fmac_f32_e32 v99, v74, v105
	v_mul_f32_e32 v74, v75, v90
	v_exp_f32_e32 v78, v78
	v_mul_f32_e32 v74, 0xbfb8aa3b, v74
	v_exp_f32_e32 v74, v74
	v_and_b32_e32 v92, 0xffff0000, v92
	v_add_f32_e32 v78, 1.0, v78
	v_rcp_f32_e32 v78, v78
	v_add_f32_e32 v74, 1.0, v74
	v_rcp_f32_e32 v74, v74
	v_and_b32_e32 v94, 0xffff0000, v94
	v_fmac_f32_e32 v96, v78, v92
	v_mul_f32_e32 v78, v80, v90
	v_mul_f32_e32 v78, 0xbfb8aa3b, v78
	v_fmac_f32_e32 v100, v74, v94
	v_mul_f32_e32 v74, v76, v90
	v_exp_f32_e32 v78, v78
	v_mul_f32_e32 v74, 0xbfb8aa3b, v74
	v_exp_f32_e32 v74, v74
	v_lshlrev_b32_e32 v104, 16, v93
	v_add_f32_e32 v78, 1.0, v78
	v_rcp_f32_e32 v78, v78
	v_add_f32_e32 v74, 1.0, v74
	v_rcp_f32_e32 v74, v74
	v_lshlrev_b32_e32 v106, 16, v95
	v_fmac_f32_e32 v97, v78, v104
	v_mul_f32_e32 v78, v81, v90
	v_mul_f32_e32 v78, 0xbfb8aa3b, v78
	v_fmac_f32_e32 v101, v74, v106
	v_mul_f32_e32 v74, v77, v90
	v_exp_f32_e32 v78, v78
	v_mul_f32_e32 v74, 0xbfb8aa3b, v74
	v_exp_f32_e32 v74, v74
	v_and_b32_e32 v93, 0xffff0000, v93
	v_add_f32_e32 v78, 1.0, v78
	v_rcp_f32_e32 v78, v78
	v_add_f32_e32 v74, 1.0, v74
	v_rcp_f32_e32 v74, v74
	v_and_b32_e32 v95, 0xffff0000, v95
	v_fmac_f32_e32 v98, v78, v93
	v_lshl_add_u64 v[78:79], s[18:19], 0, v[88:89]
	v_fmac_f32_e32 v102, v74, v95
	v_cvt_pk_bf16_f32 v74, v91, v96
	v_cvt_pk_bf16_f32 v75, v97, v98
	v_cvt_pk_bf16_f32 v76, v99, v100
	v_cvt_pk_bf16_f32 v77, v101, v102
	global_store_dwordx4 v[78:79], v[74:77], off
	v_mov_b32_e32 v92, v208
	v_mov_b32_e32 v93, v209
	v_mov_b32_e32 v94, v210
	v_mov_b32_e32 v95, v211
	v_lshlrev_b32_e32 v80, 16, v74
	v_and_b32_e32 v74, 0xffff0000, v74
	v_lshlrev_b32_e32 v81, 16, v75
	v_and_b32_e32 v75, 0xffff0000, v75
	v_mul_f32_e32 v74, v74, v74
	v_mul_f32_e32 v75, v75, v75
	v_lshlrev_b32_e32 v88, 16, v76
	v_and_b32_e32 v76, 0xffff0000, v76
	v_lshlrev_b32_e32 v89, 16, v77
	v_and_b32_e32 v77, 0xffff0000, v77
	v_fmac_f32_e32 v74, v80, v80
	v_fmac_f32_e32 v75, v81, v81
	v_add_f32_e32 v74, v74, v75
	v_mul_f32_e32 v75, v76, v76
	v_mul_f32_e32 v76, v77, v77
	v_fmac_f32_e32 v75, v88, v88
	v_fmac_f32_e32 v76, v89, v89
	v_add_f32_e32 v75, v75, v76
	v_add_f32_e32 v74, v74, v75
	s_nop 0
	v_lshlrev_b32_e32 v75, 16, v92
	v_and_b32_e32 v76, 0xffff0000, v92
	v_lshlrev_b32_e32 v77, 16, v93
	v_and_b32_e32 v80, 0xffff0000, v93
	v_lshlrev_b32_e32 v81, 16, v94
	v_and_b32_e32 v84, 0xffff0000, v94
	v_lshlrev_b32_e32 v85, 16, v95
	v_and_b32_e32 v88, 0xffff0000, v95
	v_mov_b32_e32 v92, v212
	v_mov_b32_e32 v93, v213
	v_mov_b32_e32 v94, v214
	v_mov_b32_e32 v95, v215
	s_nop 0
	v_lshlrev_b32_e32 v86, 16, v92
	v_and_b32_e32 v87, 0xffff0000, v92
	v_lshlrev_b32_e32 v92, 16, v94
	v_fmac_f32_e32 v75, v70, v86
	v_mul_f32_e32 v70, v71, v90
	v_fmac_f32_e32 v81, v66, v92
	v_mul_f32_e32 v66, v67, v90
	v_mul_f32_e32 v70, 0xbfb8aa3b, v70
	v_mul_f32_e32 v66, 0xbfb8aa3b, v66
	v_exp_f32_e32 v70, v70
	v_exp_f32_e32 v66, v66
	v_lshlrev_b32_e32 v89, 16, v93
	v_and_b32_e32 v91, 0xffff0000, v93
	v_add_f32_e32 v70, 1.0, v70
	v_add_f32_e32 v66, 1.0, v66
	v_rcp_f32_e32 v70, v70
	v_rcp_f32_e32 v66, v66
; __device__ __forceinline__ unsigned cvt_pk_bf16(float lo, float hi) { unsigned r; asm volatile("v_cvt_pk_bf16_f32 %0, %1, %2" : "=v"(r) : "v"(lo), "v"(hi)); return r; }
; __device__ __forceinline__ float bflo(unsigned w) { return __uint_as_float(w << 16); }
;     __device__ __forceinline__ void operator()(const f32x4 (&acc)[2][2][4][2], const Unit& u, int wr, int wc, int fr, int fq, LAS unsigned char* lds) const {
;     ...
;             for (int m = 0; m < 4; ++m) { const int row = row0 + ai * HALF + m * 16; const size_t off = (size_t)row * D + col0;
;                 float rs = 1.0f; if (MODE == 1) rs = rstd_of4(rss_in, row, fq);
;                 float ss = 0.f;
; #pragma unroll
;                 for (int bj = 0; bj < 2; ++bj) { const size_t o = off + bj * HALF; const u32x4 bw = *(const u32x4*)(base + o);
;                     const float bs[8] = {bflo(bw.x), bfhi(bw.x), bflo(bw.y), bfhi(bw.y), bflo(bw.z), bfhi(bw.z), bflo(bw.w), bfhi(bw.w)};
;                     float hn[8];
;                     if (MODE == 0) {
; #pragma unroll
;                         for (int n = 0; n < 2; ++n)
; #pragma unroll
;                             for (int e = 0; e < 4; ++e) hn[4 * n + e] = bs[4 * n + e] + (acc[ai][bj][m][n][e] + bv[bj][n][e]) * scale;
;                     } else { const u32x4 pw = *(const u32x4*)(pp + o);
;                         const float pv[8] = {bflo(pw.x), bfhi(pw.x), bflo(pw.y), bfhi(pw.y), bflo(pw.z), bfhi(pw.z), bflo(pw.w), bfhi(pw.w)};
; #pragma unroll
;                         for (int n = 0; n < 2; ++n)
; #pragma unroll
;                             for (int e = 0; e < 4; ++e) hn[4 * n + e] = bs[4 * n + e] + fast_sigmoid(acc[ai][bj][m][n][e] * rs) * pv[4 * n + e]; }
;                     u32x4 w; w.x = cvt_pk_bf16(hn[0], hn[1]); w.y = cvt_pk_bf16(hn[2], hn[3]); w.z = cvt_pk_bf16(hn[4], hn[5]); w.w = cvt_pk_bf16(hn[6], hn[7]); *(u32x4*)(hb + o) = w;
;                     const float hr[8] = {bflo(w.x), bfhi(w.x), bflo(w.y), bfhi(w.y), bflo(w.z), bfhi(w.z), bflo(w.w), bfhi(w.w)};
;                     ss += ((hr[0] * hr[0] + hr[1] * hr[1]) + (hr[2] * hr[2] + hr[3] * hr[3])) + ((hr[4] * hr[4] + hr[5] * hr[5]) + (hr[6] * hr[6] + hr[7] * hr[7])); }
;                 ss += __shfl_xor(ss, 16); ss += __shfl_xor(ss, 32);
;                 if (fq == 0) rss_out[(size_t)row * 16 + u.pn * 4 + wc] = ss; }
	v_and_b32_e32 v93, 0xffff0000, v94
	v_lshlrev_b32_e32 v94, 16, v95
	v_fmac_f32_e32 v76, v70, v87
	v_mul_f32_e32 v70, v72, v90
	v_fmac_f32_e32 v84, v66, v93
	v_mul_f32_e32 v66, v68, v90
	v_mul_f32_e32 v70, 0xbfb8aa3b, v70
	v_mul_f32_e32 v66, 0xbfb8aa3b, v66
	v_exp_f32_e32 v70, v70
	v_exp_f32_e32 v66, v66
	v_and_b32_e32 v95, 0xffff0000, v95
	v_add_f32_e32 v70, 1.0, v70
	v_add_f32_e32 v66, 1.0, v66
	v_rcp_f32_e32 v70, v70
	v_rcp_f32_e32 v66, v66
	v_fmac_f32_e32 v77, v70, v89
	v_mul_f32_e32 v70, v73, v90
	v_fmac_f32_e32 v85, v66, v94
	v_mul_f32_e32 v66, v69, v90
	v_mul_f32_e32 v70, 0xbfb8aa3b, v70
	v_mul_f32_e32 v66, 0xbfb8aa3b, v66
	v_exp_f32_e32 v70, v70
	v_exp_f32_e32 v66, v66
	v_add_f32_e32 v70, 1.0, v70
	v_add_f32_e32 v66, 1.0, v66
	v_rcp_f32_e32 v70, v70
	v_rcp_f32_e32 v66, v66
	v_fmac_f32_e32 v80, v70, v91
	v_fmac_f32_e32 v88, v66, v95
	v_cvt_pk_bf16_f32 v66, v75, v76
	v_cvt_pk_bf16_f32 v67, v77, v80
	v_cvt_pk_bf16_f32 v68, v81, v84
	v_cvt_pk_bf16_f32 v69, v85, v88
	global_store_dwordx4 v[78:79], v[66:69], off offset:256
	v_lshlrev_b32_e32 v70, 16, v66
	v_lshlrev_b32_e32 v71, 16, v67
	v_and_b32_e32 v66, 0xffff0000, v66
	v_and_b32_e32 v67, 0xffff0000, v67
	v_mul_f32_e32 v66, v66, v66
	v_mul_f32_e32 v67, v67, v67
	v_lshlrev_b32_e32 v72, 16, v68
	v_and_b32_e32 v68, 0xffff0000, v68
	v_lshlrev_b32_e32 v73, 16, v69
	v_and_b32_e32 v69, 0xffff0000, v69
	v_fmac_f32_e32 v66, v70, v70
	v_fmac_f32_e32 v67, v71, v71
	v_add_f32_e32 v66, v66, v67
	v_mul_f32_e32 v67, v68, v68
	v_mul_f32_e32 v68, v69, v69
	v_fmac_f32_e32 v67, v72, v72
	v_fmac_f32_e32 v68, v73, v73
	v_add_f32_e32 v67, v67, v68
	v_add_f32_e32 v66, v66, v67
	v_add_f32_e32 v66, v74, v66
	ds_bpermute_b32 v67, v158, v66
	s_waitcnt lgkmcnt(0)
	v_add_f32_e32 v66, v66, v67
	ds_bpermute_b32 v67, v145, v66
	s_and_saveexec_b64 s[24:25], s[6:7]
	s_cbranch_execz .LBB1_32
	s_lshl_b32 s66, s41, 2
	v_lshl_add_u64 v[68:69], s[20:21], 0, v[82:83]
	s_ashr_i32 s67, s66, 31
	v_lshl_add_u64 v[68:69], s[66:67], 2, v[68:69]
	s_lshl_b32 s74, s40, 2
	v_lshl_add_u64 v[68:69], v[68:69], 0, s[74:75]
	s_waitcnt lgkmcnt(0)
	v_add_f32_e32 v66, v66, v67
	global_store_dword v[68:69], v66, off
.LBB1_32:
	s_or_b64 exec, exec, s[24:25]
	v_add_u32_e32 v66, 0x80, v144
	s_waitcnt lgkmcnt(0)
	v_ashrrev_i32_e32 v67, 31, v66
	v_lshlrev_b64 v[68:69], 10, v[66:67]
	v_lshlrev_b64 v[66:67], 6, v[66:67]
	v_lshl_add_u64 v[72:73], v[68:69], 0, v[142:143]
	v_lshl_add_u64 v[68:69], v[146:147], 0, v[66:67]
	global_load_dwordx4 v[68:71], v[68:69], off
	v_lshlrev_b64 v[72:73], 1, v[72:73]
	v_lshl_add_u64 v[216:217], s[16:17], 0, v[72:73]
	v_lshl_add_u64 v[218:219], s[22:23], 0, v[72:73]
	global_load_dwordx4 v[200:203], v[216:217], off
	global_load_dwordx4 v[204:207], v[218:219], off
	global_load_dwordx4 v[208:211], v[216:217], off offset:256
	global_load_dwordx4 v[212:215], v[218:219], off offset:256
	s_waitcnt vmcnt(0)
	v_mov_b32_e32 v74, v69
	v_mov_b32_e32 v75, v70
	v_mov_b32_e32 v69, v71
	v_pk_add_f32 v[68:69], v[74:75], v[68:69]
	v_lshl_add_u64 v[70:71], s[22:23], 0, v[72:73]
	v_add_f32_e32 v68, v68, v69
	ds_bpermute_b32 v69, v158, v68
	s_waitcnt lgkmcnt(0)
	v_add_f32_e32 v68, v68, v69
	ds_bpermute_b32 v69, v145, v68
	s_waitcnt lgkmcnt(0)
	v_add_f32_e32 v68, v68, v69
	v_fmamk_f32 v68, v68, 0x3a800000, v173
	v_cmp_gt_f32_e32 vcc, s64, v68
	v_mul_f32_e32 v69, 0x4b800000, v68
	s_nop 0
	v_cndmask_b32_e32 v68, v68, v69, vcc
	v_rsq_f32_e32 v68, v68
	s_nop 0
	v_mul_f32_e32 v69, 0x45800000, v68
	v_cndmask_b32_e32 v74, v68, v69, vcc
	v_lshl_add_u64 v[68:69], s[16:17], 0, v[72:73]
	v_mov_b32_e32 v76, v200
	v_mov_b32_e32 v77, v201
	v_mov_b32_e32 v78, v202
	v_mov_b32_e32 v79, v203
	v_mul_f32_e32 v62, v62, v74
	v_mul_f32_e32 v62, 0xbfb8aa3b, v62
	v_mul_f32_e32 v58, v58, v74
	v_exp_f32_e32 v62, v62
	v_mul_f32_e32 v58, 0xbfb8aa3b, v58
	v_exp_f32_e32 v58, v58
	v_mul_f32_e32 v54, v54, v74
	v_add_f32_e32 v62, 1.0, v62
	v_rcp_f32_e32 v62, v62
	v_add_f32_e32 v58, 1.0, v58
	v_rcp_f32_e32 v58, v58
	v_mul_f32_e32 v50, v50, v74
	v_mul_f32_e32 v54, 0xbfb8aa3b, v54
	v_mul_f32_e32 v50, 0xbfb8aa3b, v50
	v_exp_f32_e32 v54, v54
	v_exp_f32_e32 v50, v50
	v_add_f32_e32 v54, 1.0, v54
	v_add_f32_e32 v50, 1.0, v50
	v_rcp_f32_e32 v54, v54
	v_rcp_f32_e32 v50, v50
	s_nop 0
	v_lshlrev_b32_e32 v75, 16, v76
	v_and_b32_e32 v80, 0xffff0000, v76
	v_lshlrev_b32_e32 v81, 16, v77
	v_and_b32_e32 v82, 0xffff0000, v77
	v_lshlrev_b32_e32 v83, 16, v78
	v_and_b32_e32 v84, 0xffff0000, v78
	v_lshlrev_b32_e32 v85, 16, v79
	v_and_b32_e32 v86, 0xffff0000, v79
	v_mov_b32_e32 v76, v204
	v_mov_b32_e32 v77, v205
	v_mov_b32_e32 v78, v206
	v_mov_b32_e32 v79, v207
	s_nop 0
	v_lshlrev_b32_e32 v87, 16, v76
	v_lshlrev_b32_e32 v89, 16, v78
	v_fmac_f32_e32 v75, v62, v87
	v_mul_f32_e32 v62, v63, v74
	v_mul_f32_e32 v62, 0xbfb8aa3b, v62
	v_fmac_f32_e32 v83, v58, v89
	v_mul_f32_e32 v58, v59, v74
	v_exp_f32_e32 v62, v62
	v_mul_f32_e32 v58, 0xbfb8aa3b, v58
	v_exp_f32_e32 v58, v58
	v_and_b32_e32 v76, 0xffff0000, v76
	v_add_f32_e32 v62, 1.0, v62
	v_rcp_f32_e32 v62, v62
	v_add_f32_e32 v58, 1.0, v58
	v_rcp_f32_e32 v58, v58
	v_and_b32_e32 v78, 0xffff0000, v78
	v_fmac_f32_e32 v80, v62, v76
	v_mul_f32_e32 v62, v64, v74
	v_mul_f32_e32 v62, 0xbfb8aa3b, v62
	v_fmac_f32_e32 v84, v58, v78
	v_mul_f32_e32 v58, v60, v74
	v_exp_f32_e32 v62, v62
	v_mul_f32_e32 v58, 0xbfb8aa3b, v58
	v_exp_f32_e32 v58, v58
	v_lshlrev_b32_e32 v88, 16, v77
	v_add_f32_e32 v62, 1.0, v62
	v_rcp_f32_e32 v62, v62
	v_add_f32_e32 v58, 1.0, v58
	v_rcp_f32_e32 v58, v58
	v_lshlrev_b32_e32 v90, 16, v79
	v_fmac_f32_e32 v81, v62, v88
	v_mul_f32_e32 v62, v65, v74
	v_mul_f32_e32 v62, 0xbfb8aa3b, v62
	v_fmac_f32_e32 v85, v58, v90
	v_mul_f32_e32 v58, v61, v74
; __device__ __forceinline__ unsigned cvt_pk_bf16(float lo, float hi) { unsigned r; asm volatile("v_cvt_pk_bf16_f32 %0, %1, %2" : "=v"(r) : "v"(lo), "v"(hi)); return r; }
; __device__ __forceinline__ float bflo(unsigned w) { return __uint_as_float(w << 16); }
;     __device__ __forceinline__ void operator()(const f32x4 (&acc)[2][2][4][2], const Unit& u, int wr, int wc, int fr, int fq, LAS unsigned char* lds) const {
;     ...
;             for (int m = 0; m < 4; ++m) { const int row = row0 + ai * HALF + m * 16; const size_t off = (size_t)row * D + col0;
;                 float rs = 1.0f; if (MODE == 1) rs = rstd_of4(rss_in, row, fq);
;                 float ss = 0.f;
; #pragma unroll
;                 for (int bj = 0; bj < 2; ++bj) { const size_t o = off + bj * HALF; const u32x4 bw = *(const u32x4*)(base + o);
;                     const float bs[8] = {bflo(bw.x), bfhi(bw.x), bflo(bw.y), bfhi(bw.y), bflo(bw.z), bfhi(bw.z), bflo(bw.w), bfhi(bw.w)};
;                     float hn[8];
;                     if (MODE == 0) {
; #pragma unroll
;                         for (int n = 0; n < 2; ++n)
; #pragma unroll
;                             for (int e = 0; e < 4; ++e) hn[4 * n + e] = bs[4 * n + e] + (acc[ai][bj][m][n][e] + bv[bj][n][e]) * scale;
;                     } else { const u32x4 pw = *(const u32x4*)(pp + o);
;                         const float pv[8] = {bflo(pw.x), bfhi(pw.x), bflo(pw.y), bfhi(pw.y), bflo(pw.z), bfhi(pw.z), bflo(pw.w), bfhi(pw.w)};
; #pragma unroll
;                         for (int n = 0; n < 2; ++n)
; #pragma unroll
;                             for (int e = 0; e < 4; ++e) hn[4 * n + e] = bs[4 * n + e] + fast_sigmoid(acc[ai][bj][m][n][e] * rs) * pv[4 * n + e]; }
;                     u32x4 w; w.x = cvt_pk_bf16(hn[0], hn[1]); w.y = cvt_pk_bf16(hn[2], hn[3]); w.z = cvt_pk_bf16(hn[4], hn[5]); w.w = cvt_pk_bf16(hn[6], hn[7]); *(u32x4*)(hb + o) = w;
;                     const float hr[8] = {bflo(w.x), bfhi(w.x), bflo(w.y), bfhi(w.y), bflo(w.z), bfhi(w.z), bflo(w.w), bfhi(w.w)};
;                     ss += ((hr[0] * hr[0] + hr[1] * hr[1]) + (hr[2] * hr[2] + hr[3] * hr[3])) + ((hr[4] * hr[4] + hr[5] * hr[5]) + (hr[6] * hr[6] + hr[7] * hr[7])); }
;                 ss += __shfl_xor(ss, 16); ss += __shfl_xor(ss, 32);
;                 if (fq == 0) rss_out[(size_t)row * 16 + u.pn * 4 + wc] = ss; }
	v_exp_f32_e32 v62, v62
	v_mul_f32_e32 v58, 0xbfb8aa3b, v58
	v_exp_f32_e32 v58, v58
	v_and_b32_e32 v77, 0xffff0000, v77
	v_add_f32_e32 v62, 1.0, v62
	v_rcp_f32_e32 v62, v62
	v_add_f32_e32 v58, 1.0, v58
	v_rcp_f32_e32 v58, v58
	v_and_b32_e32 v79, 0xffff0000, v79
	v_fmac_f32_e32 v82, v62, v77
	v_lshl_add_u64 v[62:63], s[18:19], 0, v[72:73]
	v_fmac_f32_e32 v86, v58, v79
	v_cvt_pk_bf16_f32 v58, v75, v80
	v_cvt_pk_bf16_f32 v59, v81, v82
	v_cvt_pk_bf16_f32 v60, v83, v84
	v_cvt_pk_bf16_f32 v61, v85, v86
	global_store_dwordx4 v[62:63], v[58:61], off
	v_mov_b32_e32 v76, v208
	v_mov_b32_e32 v77, v209
	v_mov_b32_e32 v78, v210
	v_mov_b32_e32 v79, v211
	v_lshlrev_b32_e32 v64, 16, v58
	v_and_b32_e32 v58, 0xffff0000, v58
	v_lshlrev_b32_e32 v65, 16, v59
	v_and_b32_e32 v59, 0xffff0000, v59
	v_mul_f32_e32 v58, v58, v58
	v_mul_f32_e32 v59, v59, v59
	v_lshlrev_b32_e32 v72, 16, v60
	v_and_b32_e32 v60, 0xffff0000, v60
	v_lshlrev_b32_e32 v73, 16, v61
	v_and_b32_e32 v61, 0xffff0000, v61
	v_fmac_f32_e32 v58, v64, v64
	v_fmac_f32_e32 v59, v65, v65
	v_add_f32_e32 v58, v58, v59
	v_mul_f32_e32 v59, v60, v60
	v_mul_f32_e32 v60, v61, v61
	v_fmac_f32_e32 v59, v72, v72
	v_fmac_f32_e32 v60, v73, v73
	v_add_f32_e32 v59, v59, v60
	v_add_f32_e32 v58, v58, v59
	s_nop 0
	v_lshlrev_b32_e32 v59, 16, v76
	v_and_b32_e32 v60, 0xffff0000, v76
	v_lshlrev_b32_e32 v61, 16, v77
	v_and_b32_e32 v64, 0xffff0000, v77
	v_lshlrev_b32_e32 v65, 16, v78
	v_and_b32_e32 v68, 0xffff0000, v78
	v_lshlrev_b32_e32 v69, 16, v79
	v_and_b32_e32 v72, 0xffff0000, v79
	v_mov_b32_e32 v76, v212
	v_mov_b32_e32 v77, v213
	v_mov_b32_e32 v78, v214
	v_mov_b32_e32 v79, v215
	s_nop 0
	v_lshlrev_b32_e32 v70, 16, v76
	v_and_b32_e32 v71, 0xffff0000, v76
	v_lshlrev_b32_e32 v76, 16, v78
	v_fmac_f32_e32 v59, v54, v70
	v_mul_f32_e32 v54, v55, v74
	v_fmac_f32_e32 v65, v50, v76
	v_mul_f32_e32 v50, v51, v74
	v_mul_f32_e32 v54, 0xbfb8aa3b, v54
	v_mul_f32_e32 v50, 0xbfb8aa3b, v50
	v_exp_f32_e32 v54, v54
	v_exp_f32_e32 v50, v50
	v_lshlrev_b32_e32 v73, 16, v77
	v_and_b32_e32 v75, 0xffff0000, v77
	v_add_f32_e32 v54, 1.0, v54
	v_add_f32_e32 v50, 1.0, v50
	v_rcp_f32_e32 v54, v54
	v_rcp_f32_e32 v50, v50
	v_and_b32_e32 v77, 0xffff0000, v78
	v_lshlrev_b32_e32 v78, 16, v79
	v_fmac_f32_e32 v60, v54, v71
	v_mul_f32_e32 v54, v56, v74
	v_fmac_f32_e32 v68, v50, v77
	v_mul_f32_e32 v50, v52, v74
	v_mul_f32_e32 v54, 0xbfb8aa3b, v54
	v_mul_f32_e32 v50, 0xbfb8aa3b, v50
	v_exp_f32_e32 v54, v54
	v_exp_f32_e32 v50, v50
	v_and_b32_e32 v79, 0xffff0000, v79
	v_add_f32_e32 v54, 1.0, v54
	v_add_f32_e32 v50, 1.0, v50
	v_rcp_f32_e32 v54, v54
	v_rcp_f32_e32 v50, v50
	v_fmac_f32_e32 v61, v54, v73
	v_mul_f32_e32 v54, v57, v74
	v_fmac_f32_e32 v69, v50, v78
	v_mul_f32_e32 v50, v53, v74
	v_mul_f32_e32 v54, 0xbfb8aa3b, v54
	v_mul_f32_e32 v50, 0xbfb8aa3b, v50
	v_exp_f32_e32 v54, v54
	v_exp_f32_e32 v50, v50
	v_add_f32_e32 v54, 1.0, v54
	v_add_f32_e32 v50, 1.0, v50
	v_rcp_f32_e32 v54, v54
	v_rcp_f32_e32 v50, v50
	v_fmac_f32_e32 v64, v54, v75
	v_fmac_f32_e32 v72, v50, v79
	v_cvt_pk_bf16_f32 v50, v59, v60
	v_cvt_pk_bf16_f32 v51, v61, v64
	v_cvt_pk_bf16_f32 v52, v65, v68
	v_cvt_pk_bf16_f32 v53, v69, v72
	global_store_dwordx4 v[62:63], v[50:53], off offset:256
	v_lshlrev_b32_e32 v54, 16, v50
	v_lshlrev_b32_e32 v55, 16, v51
	v_and_b32_e32 v50, 0xffff0000, v50
	v_and_b32_e32 v51, 0xffff0000, v51
	v_mul_f32_e32 v50, v50, v50
	v_mul_f32_e32 v51, v51, v51
	v_lshlrev_b32_e32 v56, 16, v52
	v_and_b32_e32 v52, 0xffff0000, v52
	v_lshlrev_b32_e32 v57, 16, v53
	v_and_b32_e32 v53, 0xffff0000, v53
	v_fmac_f32_e32 v50, v54, v54
	v_fmac_f32_e32 v51, v55, v55
	v_add_f32_e32 v50, v50, v51
	v_mul_f32_e32 v51, v52, v52
	v_mul_f32_e32 v52, v53, v53
	v_fmac_f32_e32 v51, v56, v56
	v_fmac_f32_e32 v52, v57, v57
	v_add_f32_e32 v51, v51, v52
	v_add_f32_e32 v50, v50, v51
	v_add_f32_e32 v50, v58, v50
	ds_bpermute_b32 v51, v158, v50
	s_waitcnt lgkmcnt(0)
	v_add_f32_e32 v50, v50, v51
	ds_bpermute_b32 v51, v145, v50
	s_and_saveexec_b64 s[24:25], s[6:7]
	s_cbranch_execz .LBB1_34
	s_lshl_b32 s66, s41, 2
	v_lshl_add_u64 v[52:53], s[20:21], 0, v[66:67]
	s_ashr_i32 s67, s66, 31
	v_lshl_add_u64 v[52:53], s[66:67], 2, v[52:53]
	s_lshl_b32 s74, s40, 2
	v_lshl_add_u64 v[52:53], v[52:53], 0, s[74:75]
	s_waitcnt lgkmcnt(0)
	v_add_f32_e32 v50, v50, v51
	global_store_dword v[52:53], v50, off
; __device__ __forceinline__ unsigned cvt_pk_bf16(float lo, float hi) { unsigned r; asm volatile("v_cvt_pk_bf16_f32 %0, %1, %2" : "=v"(r) : "v"(lo), "v"(hi)); return r; }
; __device__ __forceinline__ float bflo(unsigned w) { return __uint_as_float(w << 16); }
;     __device__ __forceinline__ void operator()(const f32x4 (&acc)[2][2][4][2], const Unit& u, int wr, int wc, int fr, int fq, LAS unsigned char* lds) const {
;     ...
;             for (int m = 0; m < 4; ++m) { const int row = row0 + ai * HALF + m * 16; const size_t off = (size_t)row * D + col0;
;                 float rs = 1.0f; if (MODE == 1) rs = rstd_of4(rss_in, row, fq);
;                 float ss = 0.f;
; #pragma unroll
;                 for (int bj = 0; bj < 2; ++bj) { const size_t o = off + bj * HALF; const u32x4 bw = *(const u32x4*)(base + o);
;                     const float bs[8] = {bflo(bw.x), bfhi(bw.x), bflo(bw.y), bfhi(bw.y), bflo(bw.z), bfhi(bw.z), bflo(bw.w), bfhi(bw.w)};
;                     float hn[8];
;                     if (MODE == 0) {
; #pragma unroll
;                         for (int n = 0; n < 2; ++n)
; #pragma unroll
;                             for (int e = 0; e < 4; ++e) hn[4 * n + e] = bs[4 * n + e] + (acc[ai][bj][m][n][e] + bv[bj][n][e]) * scale;
;                     } else { const u32x4 pw = *(const u32x4*)(pp + o);
;                         const float pv[8] = {bflo(pw.x), bfhi(pw.x), bflo(pw.y), bfhi(pw.y), bflo(pw.z), bfhi(pw.z), bflo(pw.w), bfhi(pw.w)};
; #pragma unroll
;                         for (int n = 0; n < 2; ++n)
; #pragma unroll
;                             for (int e = 0; e < 4; ++e) hn[4 * n + e] = bs[4 * n + e] + fast_sigmoid(acc[ai][bj][m][n][e] * rs) * pv[4 * n + e]; }
;                     u32x4 w; w.x = cvt_pk_bf16(hn[0], hn[1]); w.y = cvt_pk_bf16(hn[2], hn[3]); w.z = cvt_pk_bf16(hn[4], hn[5]); w.w = cvt_pk_bf16(hn[6], hn[7]); *(u32x4*)(hb + o) = w;
;                     const float hr[8] = {bflo(w.x), bfhi(w.x), bflo(w.y), bfhi(w.y), bflo(w.z), bfhi(w.z), bflo(w.w), bfhi(w.w)};
;                     ss += ((hr[0] * hr[0] + hr[1] * hr[1]) + (hr[2] * hr[2] + hr[3] * hr[3])) + ((hr[4] * hr[4] + hr[5] * hr[5]) + (hr[6] * hr[6] + hr[7] * hr[7])); }
;                 ss += __shfl_xor(ss, 16); ss += __shfl_xor(ss, 32);
;                 if (fq == 0) rss_out[(size_t)row * 16 + u.pn * 4 + wc] = ss; }
.LBB1_34:
	s_or_b64 exec, exec, s[24:25]
	v_add_u32_e32 v50, 0x90, v144
	s_waitcnt lgkmcnt(0)
	v_ashrrev_i32_e32 v51, 31, v50
	v_lshlrev_b64 v[52:53], 10, v[50:51]
	v_lshlrev_b64 v[50:51], 6, v[50:51]
	v_lshl_add_u64 v[56:57], v[52:53], 0, v[142:143]
	v_lshl_add_u64 v[52:53], v[146:147], 0, v[50:51]
	global_load_dwordx4 v[52:55], v[52:53], off
	v_lshlrev_b64 v[56:57], 1, v[56:57]
	v_lshl_add_u64 v[216:217], s[16:17], 0, v[56:57]
	v_lshl_add_u64 v[218:219], s[22:23], 0, v[56:57]
	global_load_dwordx4 v[200:203], v[216:217], off
	global_load_dwordx4 v[204:207], v[218:219], off
	global_load_dwordx4 v[208:211], v[216:217], off offset:256
	global_load_dwordx4 v[212:215], v[218:219], off offset:256
	s_waitcnt vmcnt(0)
	v_mov_b32_e32 v58, v53
	v_mov_b32_e32 v59, v54
	v_mov_b32_e32 v53, v55
	v_pk_add_f32 v[52:53], v[58:59], v[52:53]
	v_lshl_add_u64 v[54:55], s[22:23], 0, v[56:57]
	v_add_f32_e32 v52, v52, v53
	ds_bpermute_b32 v53, v158, v52
	s_waitcnt lgkmcnt(0)
	v_add_f32_e32 v52, v52, v53
	ds_bpermute_b32 v53, v145, v52
	s_waitcnt lgkmcnt(0)
	v_add_f32_e32 v52, v52, v53
	v_fmamk_f32 v52, v52, 0x3a800000, v173
	v_cmp_gt_f32_e32 vcc, s64, v52
	v_mul_f32_e32 v53, 0x4b800000, v52
	s_nop 0
	v_cndmask_b32_e32 v52, v52, v53, vcc
	v_rsq_f32_e32 v52, v52
	s_nop 0
	v_mul_f32_e32 v53, 0x45800000, v52
	v_cndmask_b32_e32 v58, v52, v53, vcc
	v_lshl_add_u64 v[52:53], s[16:17], 0, v[56:57]
	v_mov_b32_e32 v60, v200
	v_mov_b32_e32 v61, v201
	v_mov_b32_e32 v62, v202
	v_mov_b32_e32 v63, v203
	v_mul_f32_e32 v46, v46, v58
	v_mul_f32_e32 v46, 0xbfb8aa3b, v46
	v_mul_f32_e32 v42, v42, v58
	v_exp_f32_e32 v46, v46
	v_mul_f32_e32 v42, 0xbfb8aa3b, v42
	v_exp_f32_e32 v42, v42
	v_mul_f32_e32 v38, v38, v58
	v_add_f32_e32 v46, 1.0, v46
	v_rcp_f32_e32 v46, v46
	v_add_f32_e32 v42, 1.0, v42
	v_rcp_f32_e32 v42, v42
	v_mul_f32_e32 v34, v34, v58
	v_mul_f32_e32 v38, 0xbfb8aa3b, v38
	v_mul_f32_e32 v34, 0xbfb8aa3b, v34
	v_exp_f32_e32 v38, v38
	v_exp_f32_e32 v34, v34
	v_add_f32_e32 v38, 1.0, v38
	v_add_f32_e32 v34, 1.0, v34
	v_rcp_f32_e32 v38, v38
	v_rcp_f32_e32 v34, v34
	s_nop 0
	v_lshlrev_b32_e32 v59, 16, v60
	v_and_b32_e32 v64, 0xffff0000, v60
	v_lshlrev_b32_e32 v65, 16, v61
	v_and_b32_e32 v66, 0xffff0000, v61
	v_lshlrev_b32_e32 v67, 16, v62
	v_and_b32_e32 v68, 0xffff0000, v62
	v_lshlrev_b32_e32 v69, 16, v63
	v_and_b32_e32 v70, 0xffff0000, v63
	v_mov_b32_e32 v60, v204
	v_mov_b32_e32 v61, v205
	v_mov_b32_e32 v62, v206
	v_mov_b32_e32 v63, v207
	s_nop 0
	v_lshlrev_b32_e32 v71, 16, v60
	v_lshlrev_b32_e32 v73, 16, v62
	v_fmac_f32_e32 v59, v46, v71
	v_mul_f32_e32 v46, v47, v58
	v_mul_f32_e32 v46, 0xbfb8aa3b, v46
	v_fmac_f32_e32 v67, v42, v73
	v_mul_f32_e32 v42, v43, v58
	v_exp_f32_e32 v46, v46
	v_mul_f32_e32 v42, 0xbfb8aa3b, v42
	v_exp_f32_e32 v42, v42
	v_and_b32_e32 v60, 0xffff0000, v60
	v_add_f32_e32 v46, 1.0, v46
	v_rcp_f32_e32 v46, v46
	v_add_f32_e32 v42, 1.0, v42
	v_rcp_f32_e32 v42, v42
	v_and_b32_e32 v62, 0xffff0000, v62
	v_fmac_f32_e32 v64, v46, v60
	v_mul_f32_e32 v46, v48, v58
	v_mul_f32_e32 v46, 0xbfb8aa3b, v46
	v_fmac_f32_e32 v68, v42, v62
	v_mul_f32_e32 v42, v44, v58
	v_exp_f32_e32 v46, v46
	v_mul_f32_e32 v42, 0xbfb8aa3b, v42
	v_exp_f32_e32 v42, v42
	v_lshlrev_b32_e32 v72, 16, v61
	v_add_f32_e32 v46, 1.0, v46
	v_rcp_f32_e32 v46, v46
	v_add_f32_e32 v42, 1.0, v42
	v_rcp_f32_e32 v42, v42
	v_lshlrev_b32_e32 v74, 16, v63
	v_fmac_f32_e32 v65, v46, v72
	v_mul_f32_e32 v46, v49, v58
	v_mul_f32_e32 v46, 0xbfb8aa3b, v46
	v_fmac_f32_e32 v69, v42, v74
	v_mul_f32_e32 v42, v45, v58
	v_exp_f32_e32 v46, v46
	v_mul_f32_e32 v42, 0xbfb8aa3b, v42
	v_exp_f32_e32 v42, v42
	v_and_b32_e32 v61, 0xffff0000, v61
	v_add_f32_e32 v46, 1.0, v46
	v_rcp_f32_e32 v46, v46
	v_add_f32_e32 v42, 1.0, v42
	v_rcp_f32_e32 v42, v42
	v_and_b32_e32 v63, 0xffff0000, v63
	v_fmac_f32_e32 v66, v46, v61
	v_lshl_add_u64 v[46:47], s[18:19], 0, v[56:57]
	v_fmac_f32_e32 v70, v42, v63
	v_cvt_pk_bf16_f32 v42, v59, v64
	v_cvt_pk_bf16_f32 v43, v65, v66
	v_cvt_pk_bf16_f32 v44, v67, v68
	v_cvt_pk_bf16_f32 v45, v69, v70
	global_store_dwordx4 v[46:47], v[42:45], off
	v_mov_b32_e32 v60, v208
	v_mov_b32_e32 v61, v209
	v_mov_b32_e32 v62, v210
	v_mov_b32_e32 v63, v211
	v_lshlrev_b32_e32 v48, 16, v42
	v_and_b32_e32 v42, 0xffff0000, v42
	v_lshlrev_b32_e32 v49, 16, v43
	v_and_b32_e32 v43, 0xffff0000, v43
	v_mul_f32_e32 v42, v42, v42
	v_mul_f32_e32 v43, v43, v43
	v_lshlrev_b32_e32 v56, 16, v44
	v_and_b32_e32 v44, 0xffff0000, v44
	v_lshlrev_b32_e32 v57, 16, v45
	v_and_b32_e32 v45, 0xffff0000, v45
	v_fmac_f32_e32 v42, v48, v48
	v_fmac_f32_e32 v43, v49, v49
	v_add_f32_e32 v42, v42, v43
	v_mul_f32_e32 v43, v44, v44
	v_mul_f32_e32 v44, v45, v45
	v_fmac_f32_e32 v43, v56, v56
	v_fmac_f32_e32 v44, v57, v57
	v_add_f32_e32 v43, v43, v44
	v_add_f32_e32 v42, v42, v43
	s_nop 0
	v_lshlrev_b32_e32 v43, 16, v60
	v_and_b32_e32 v44, 0xffff0000, v60
	v_lshlrev_b32_e32 v45, 16, v61
	v_and_b32_e32 v48, 0xffff0000, v61
	v_lshlrev_b32_e32 v49, 16, v62
	v_and_b32_e32 v52, 0xffff0000, v62
	v_lshlrev_b32_e32 v53, 16, v63
	v_and_b32_e32 v56, 0xffff0000, v63
	v_mov_b32_e32 v60, v212
	v_mov_b32_e32 v61, v213
	v_mov_b32_e32 v62, v214
	v_mov_b32_e32 v63, v215
	s_nop 0
	v_lshlrev_b32_e32 v54, 16, v60
	v_and_b32_e32 v55, 0xffff0000, v60
	v_lshlrev_b32_e32 v60, 16, v62
	v_fmac_f32_e32 v43, v38, v54
	v_mul_f32_e32 v38, v39, v58
	v_fmac_f32_e32 v49, v34, v60
	v_mul_f32_e32 v34, v35, v58
	v_mul_f32_e32 v38, 0xbfb8aa3b, v38
	v_mul_f32_e32 v34, 0xbfb8aa3b, v34
	v_exp_f32_e32 v38, v38
	v_exp_f32_e32 v34, v34
	v_lshlrev_b32_e32 v57, 16, v61
	v_and_b32_e32 v59, 0xffff0000, v61
	v_add_f32_e32 v38, 1.0, v38
	v_add_f32_e32 v34, 1.0, v34
	v_rcp_f32_e32 v38, v38
	v_rcp_f32_e32 v34, v34
; __device__ __forceinline__ unsigned cvt_pk_bf16(float lo, float hi) { unsigned r; asm volatile("v_cvt_pk_bf16_f32 %0, %1, %2" : "=v"(r) : "v"(lo), "v"(hi)); return r; }
; __device__ __forceinline__ float bflo(unsigned w) { return __uint_as_float(w << 16); }
;     __device__ __forceinline__ void operator()(const f32x4 (&acc)[2][2][4][2], const Unit& u, int wr, int wc, int fr, int fq, LAS unsigned char* lds) const {
;     ...
;             for (int m = 0; m < 4; ++m) { const int row = row0 + ai * HALF + m * 16; const size_t off = (size_t)row * D + col0;
;                 float rs = 1.0f; if (MODE == 1) rs = rstd_of4(rss_in, row, fq);
;                 float ss = 0.f;
; #pragma unroll
;                 for (int bj = 0; bj < 2; ++bj) { const size_t o = off + bj * HALF; const u32x4 bw = *(const u32x4*)(base + o);
;                     const float bs[8] = {bflo(bw.x), bfhi(bw.x), bflo(bw.y), bfhi(bw.y), bflo(bw.z), bfhi(bw.z), bflo(bw.w), bfhi(bw.w)};
;                     float hn[8];
;                     if (MODE == 0) {
; #pragma unroll
;                         for (int n = 0; n < 2; ++n)
; #pragma unroll
;                             for (int e = 0; e < 4; ++e) hn[4 * n + e] = bs[4 * n + e] + (acc[ai][bj][m][n][e] + bv[bj][n][e]) * scale;
;                     } else { const u32x4 pw = *(const u32x4*)(pp + o);
;                         const float pv[8] = {bflo(pw.x), bfhi(pw.x), bflo(pw.y), bfhi(pw.y), bflo(pw.z), bfhi(pw.z), bflo(pw.w), bfhi(pw.w)};
; #pragma unroll
;                         for (int n = 0; n < 2; ++n)
; #pragma unroll
;                             for (int e = 0; e < 4; ++e) hn[4 * n + e] = bs[4 * n + e] + fast_sigmoid(acc[ai][bj][m][n][e] * rs) * pv[4 * n + e]; }
;                     u32x4 w; w.x = cvt_pk_bf16(hn[0], hn[1]); w.y = cvt_pk_bf16(hn[2], hn[3]); w.z = cvt_pk_bf16(hn[4], hn[5]); w.w = cvt_pk_bf16(hn[6], hn[7]); *(u32x4*)(hb + o) = w;
;                     const float hr[8] = {bflo(w.x), bfhi(w.x), bflo(w.y), bfhi(w.y), bflo(w.z), bfhi(w.z), bflo(w.w), bfhi(w.w)};
;                     ss += ((hr[0] * hr[0] + hr[1] * hr[1]) + (hr[2] * hr[2] + hr[3] * hr[3])) + ((hr[4] * hr[4] + hr[5] * hr[5]) + (hr[6] * hr[6] + hr[7] * hr[7])); }
;                 ss += __shfl_xor(ss, 16); ss += __shfl_xor(ss, 32);
;                 if (fq == 0) rss_out[(size_t)row * 16 + u.pn * 4 + wc] = ss; }
	v_and_b32_e32 v61, 0xffff0000, v62
	v_lshlrev_b32_e32 v62, 16, v63
	v_fmac_f32_e32 v44, v38, v55
	v_mul_f32_e32 v38, v40, v58
	v_fmac_f32_e32 v52, v34, v61
	v_mul_f32_e32 v34, v36, v58
	v_mul_f32_e32 v38, 0xbfb8aa3b, v38
	v_mul_f32_e32 v34, 0xbfb8aa3b, v34
	v_exp_f32_e32 v38, v38
	v_exp_f32_e32 v34, v34
	v_and_b32_e32 v63, 0xffff0000, v63
	v_add_f32_e32 v38, 1.0, v38
	v_add_f32_e32 v34, 1.0, v34
	v_rcp_f32_e32 v38, v38
	v_rcp_f32_e32 v34, v34
	v_fmac_f32_e32 v45, v38, v57
	v_mul_f32_e32 v38, v41, v58
	v_fmac_f32_e32 v53, v34, v62
	v_mul_f32_e32 v34, v37, v58
	v_mul_f32_e32 v38, 0xbfb8aa3b, v38
	v_mul_f32_e32 v34, 0xbfb8aa3b, v34
	v_exp_f32_e32 v38, v38
	v_exp_f32_e32 v34, v34
	v_add_f32_e32 v38, 1.0, v38
	v_add_f32_e32 v34, 1.0, v34
	v_rcp_f32_e32 v38, v38
	v_rcp_f32_e32 v34, v34
	v_fmac_f32_e32 v48, v38, v59
	v_fmac_f32_e32 v56, v34, v63
	v_cvt_pk_bf16_f32 v34, v43, v44
	v_cvt_pk_bf16_f32 v35, v45, v48
	v_cvt_pk_bf16_f32 v36, v49, v52
	v_cvt_pk_bf16_f32 v37, v53, v56
	global_store_dwordx4 v[46:47], v[34:37], off offset:256
	v_lshlrev_b32_e32 v38, 16, v34
	v_lshlrev_b32_e32 v39, 16, v35
	v_and_b32_e32 v34, 0xffff0000, v34
	v_and_b32_e32 v35, 0xffff0000, v35
	v_mul_f32_e32 v34, v34, v34
	v_mul_f32_e32 v35, v35, v35
	v_lshlrev_b32_e32 v40, 16, v36
	v_and_b32_e32 v36, 0xffff0000, v36
	v_lshlrev_b32_e32 v41, 16, v37
	v_and_b32_e32 v37, 0xffff0000, v37
	v_fmac_f32_e32 v34, v38, v38
	v_fmac_f32_e32 v35, v39, v39
	v_add_f32_e32 v34, v34, v35
	v_mul_f32_e32 v35, v36, v36
	v_mul_f32_e32 v36, v37, v37
	v_fmac_f32_e32 v35, v40, v40
	v_fmac_f32_e32 v36, v41, v41
	v_add_f32_e32 v35, v35, v36
	v_add_f32_e32 v34, v34, v35
	v_add_f32_e32 v34, v42, v34
	ds_bpermute_b32 v35, v158, v34
	s_waitcnt lgkmcnt(0)
	v_add_f32_e32 v34, v34, v35
	ds_bpermute_b32 v35, v145, v34
	s_and_saveexec_b64 s[24:25], s[6:7]
	s_cbranch_execz .LBB1_36
	s_lshl_b32 s66, s41, 2
	v_lshl_add_u64 v[36:37], s[20:21], 0, v[50:51]
	s_ashr_i32 s67, s66, 31
	v_lshl_add_u64 v[36:37], s[66:67], 2, v[36:37]
	s_lshl_b32 s74, s40, 2
	v_lshl_add_u64 v[36:37], v[36:37], 0, s[74:75]
	s_waitcnt lgkmcnt(0)
	v_add_f32_e32 v34, v34, v35
	global_store_dword v[36:37], v34, off
.LBB1_36:
	s_or_b64 exec, exec, s[24:25]
	v_add_u32_e32 v34, 0xa0, v144
	s_waitcnt lgkmcnt(0)
	v_ashrrev_i32_e32 v35, 31, v34
	v_lshlrev_b64 v[36:37], 10, v[34:35]
	v_lshlrev_b64 v[34:35], 6, v[34:35]
	v_lshl_add_u64 v[40:41], v[36:37], 0, v[142:143]
	v_lshl_add_u64 v[36:37], v[146:147], 0, v[34:35]
	global_load_dwordx4 v[36:39], v[36:37], off
	v_lshlrev_b64 v[40:41], 1, v[40:41]
	v_lshl_add_u64 v[216:217], s[16:17], 0, v[40:41]
	v_lshl_add_u64 v[218:219], s[22:23], 0, v[40:41]
	global_load_dwordx4 v[200:203], v[216:217], off
	global_load_dwordx4 v[204:207], v[218:219], off
	global_load_dwordx4 v[208:211], v[216:217], off offset:256
	global_load_dwordx4 v[212:215], v[218:219], off offset:256
	s_waitcnt vmcnt(0)
	v_mov_b32_e32 v42, v37
	v_mov_b32_e32 v43, v38
	v_mov_b32_e32 v37, v39
	v_pk_add_f32 v[36:37], v[42:43], v[36:37]
	v_lshl_add_u64 v[38:39], s[22:23], 0, v[40:41]
	v_add_f32_e32 v36, v36, v37
	ds_bpermute_b32 v37, v158, v36
	s_waitcnt lgkmcnt(0)
	v_add_f32_e32 v36, v36, v37
	ds_bpermute_b32 v37, v145, v36
	s_waitcnt lgkmcnt(0)
; __device__ __forceinline__ unsigned cvt_pk_bf16(float lo, float hi) { unsigned r; asm volatile("v_cvt_pk_bf16_f32 %0, %1, %2" : "=v"(r) : "v"(lo), "v"(hi)); return r; }
; __device__ __forceinline__ float bflo(unsigned w) { return __uint_as_float(w << 16); }
;     __device__ __forceinline__ void operator()(const f32x4 (&acc)[2][2][4][2], const Unit& u, int wr, int wc, int fr, int fq, LAS unsigned char* lds) const {
;     ...
;             for (int m = 0; m < 4; ++m) { const int row = row0 + ai * HALF + m * 16; const size_t off = (size_t)row * D + col0;
;                 float rs = 1.0f; if (MODE == 1) rs = rstd_of4(rss_in, row, fq);
;                 float ss = 0.f;
; #pragma unroll
;                 for (int bj = 0; bj < 2; ++bj) { const size_t o = off + bj * HALF; const u32x4 bw = *(const u32x4*)(base + o);
;                     const float bs[8] = {bflo(bw.x), bfhi(bw.x), bflo(bw.y), bfhi(bw.y), bflo(bw.z), bfhi(bw.z), bflo(bw.w), bfhi(bw.w)};
;                     float hn[8];
;                     if (MODE == 0) {
; #pragma unroll
;                         for (int n = 0; n < 2; ++n)
; #pragma unroll
;                             for (int e = 0; e < 4; ++e) hn[4 * n + e] = bs[4 * n + e] + (acc[ai][bj][m][n][e] + bv[bj][n][e]) * scale;
;                     } else { const u32x4 pw = *(const u32x4*)(pp + o);
;                         const float pv[8] = {bflo(pw.x), bfhi(pw.x), bflo(pw.y), bfhi(pw.y), bflo(pw.z), bfhi(pw.z), bflo(pw.w), bfhi(pw.w)};
; #pragma unroll
;                         for (int n = 0; n < 2; ++n)
; #pragma unroll
;                             for (int e = 0; e < 4; ++e) hn[4 * n + e] = bs[4 * n + e] + fast_sigmoid(acc[ai][bj][m][n][e] * rs) * pv[4 * n + e]; }
;                     u32x4 w; w.x = cvt_pk_bf16(hn[0], hn[1]); w.y = cvt_pk_bf16(hn[2], hn[3]); w.z = cvt_pk_bf16(hn[4], hn[5]); w.w = cvt_pk_bf16(hn[6], hn[7]); *(u32x4*)(hb + o) = w;
;                     const float hr[8] = {bflo(w.x), bfhi(w.x), bflo(w.y), bfhi(w.y), bflo(w.z), bfhi(w.z), bflo(w.w), bfhi(w.w)};
;                     ss += ((hr[0] * hr[0] + hr[1] * hr[1]) + (hr[2] * hr[2] + hr[3] * hr[3])) + ((hr[4] * hr[4] + hr[5] * hr[5]) + (hr[6] * hr[6] + hr[7] * hr[7])); }
;                 ss += __shfl_xor(ss, 16); ss += __shfl_xor(ss, 32);
;                 if (fq == 0) rss_out[(size_t)row * 16 + u.pn * 4 + wc] = ss; }
	v_add_f32_e32 v36, v36, v37
	v_fmamk_f32 v36, v36, 0x3a800000, v173
	v_cmp_gt_f32_e32 vcc, s64, v36
	v_mul_f32_e32 v37, 0x4b800000, v36
	s_nop 0
	v_cndmask_b32_e32 v36, v36, v37, vcc
	v_rsq_f32_e32 v36, v36
	s_nop 0
	v_mul_f32_e32 v37, 0x45800000, v36
	v_cndmask_b32_e32 v42, v36, v37, vcc
	v_lshl_add_u64 v[36:37], s[16:17], 0, v[40:41]
	v_mov_b32_e32 v44, v200
	v_mov_b32_e32 v45, v201
	v_mov_b32_e32 v46, v202
	v_mov_b32_e32 v47, v203
	v_mul_f32_e32 v30, v30, v42
	v_mul_f32_e32 v30, 0xbfb8aa3b, v30
	v_mul_f32_e32 v26, v26, v42
	v_exp_f32_e32 v30, v30
	v_mul_f32_e32 v26, 0xbfb8aa3b, v26
	v_exp_f32_e32 v26, v26
	v_mul_f32_e32 v22, v22, v42
	v_add_f32_e32 v30, 1.0, v30
	v_rcp_f32_e32 v30, v30
	v_add_f32_e32 v26, 1.0, v26
	v_rcp_f32_e32 v26, v26
	v_mul_f32_e32 v18, v18, v42
	v_mul_f32_e32 v22, 0xbfb8aa3b, v22
	v_mul_f32_e32 v18, 0xbfb8aa3b, v18
	v_exp_f32_e32 v22, v22
	v_exp_f32_e32 v18, v18
	v_add_f32_e32 v22, 1.0, v22
	v_add_f32_e32 v18, 1.0, v18
	v_rcp_f32_e32 v22, v22
	v_rcp_f32_e32 v18, v18
	s_nop 0
	v_lshlrev_b32_e32 v43, 16, v44
	v_and_b32_e32 v48, 0xffff0000, v44
	v_lshlrev_b32_e32 v49, 16, v45
	v_and_b32_e32 v50, 0xffff0000, v45
	v_lshlrev_b32_e32 v51, 16, v46
	v_and_b32_e32 v52, 0xffff0000, v46
	v_lshlrev_b32_e32 v53, 16, v47
	v_and_b32_e32 v54, 0xffff0000, v47
	v_mov_b32_e32 v44, v204
	v_mov_b32_e32 v45, v205
	v_mov_b32_e32 v46, v206
	v_mov_b32_e32 v47, v207
	s_nop 0
	v_lshlrev_b32_e32 v55, 16, v44
	v_lshlrev_b32_e32 v57, 16, v46
	v_fmac_f32_e32 v43, v30, v55
	v_mul_f32_e32 v30, v31, v42
	v_mul_f32_e32 v30, 0xbfb8aa3b, v30
	v_fmac_f32_e32 v51, v26, v57
	v_mul_f32_e32 v26, v27, v42
	v_exp_f32_e32 v30, v30
	v_mul_f32_e32 v26, 0xbfb8aa3b, v26
	v_exp_f32_e32 v26, v26
	v_and_b32_e32 v44, 0xffff0000, v44
	v_add_f32_e32 v30, 1.0, v30
	v_rcp_f32_e32 v30, v30
	v_add_f32_e32 v26, 1.0, v26
	v_rcp_f32_e32 v26, v26
	v_and_b32_e32 v46, 0xffff0000, v46
	v_fmac_f32_e32 v48, v30, v44
	v_mul_f32_e32 v30, v32, v42
	v_mul_f32_e32 v30, 0xbfb8aa3b, v30
	v_fmac_f32_e32 v52, v26, v46
	v_mul_f32_e32 v26, v28, v42
	v_exp_f32_e32 v30, v30
	v_mul_f32_e32 v26, 0xbfb8aa3b, v26
	v_exp_f32_e32 v26, v26
	v_lshlrev_b32_e32 v56, 16, v45
	v_add_f32_e32 v30, 1.0, v30
	v_rcp_f32_e32 v30, v30
	v_add_f32_e32 v26, 1.0, v26
	v_rcp_f32_e32 v26, v26
	v_lshlrev_b32_e32 v58, 16, v47
	v_fmac_f32_e32 v49, v30, v56
	v_mul_f32_e32 v30, v33, v42
	v_mul_f32_e32 v30, 0xbfb8aa3b, v30
	v_fmac_f32_e32 v53, v26, v58
	v_mul_f32_e32 v26, v29, v42
	v_exp_f32_e32 v30, v30
	v_mul_f32_e32 v26, 0xbfb8aa3b, v26
	v_exp_f32_e32 v26, v26
	v_and_b32_e32 v45, 0xffff0000, v45
	v_add_f32_e32 v30, 1.0, v30
	v_rcp_f32_e32 v30, v30
	v_add_f32_e32 v26, 1.0, v26
	v_rcp_f32_e32 v26, v26
	v_and_b32_e32 v47, 0xffff0000, v47
	v_fmac_f32_e32 v50, v30, v45
	v_lshl_add_u64 v[30:31], s[18:19], 0, v[40:41]
	v_fmac_f32_e32 v54, v26, v47
	v_cvt_pk_bf16_f32 v26, v43, v48
	v_cvt_pk_bf16_f32 v27, v49, v50
	v_cvt_pk_bf16_f32 v28, v51, v52
	v_cvt_pk_bf16_f32 v29, v53, v54
	global_store_dwordx4 v[30:31], v[26:29], off
	v_mov_b32_e32 v44, v208
	v_mov_b32_e32 v45, v209
	v_mov_b32_e32 v46, v210
	v_mov_b32_e32 v47, v211
	v_lshlrev_b32_e32 v32, 16, v26
	v_and_b32_e32 v26, 0xffff0000, v26
	v_lshlrev_b32_e32 v33, 16, v27
	v_and_b32_e32 v27, 0xffff0000, v27
	v_mul_f32_e32 v26, v26, v26
	v_mul_f32_e32 v27, v27, v27
	v_lshlrev_b32_e32 v40, 16, v28
	v_and_b32_e32 v28, 0xffff0000, v28
	v_lshlrev_b32_e32 v41, 16, v29
	v_and_b32_e32 v29, 0xffff0000, v29
	v_fmac_f32_e32 v26, v32, v32
	v_fmac_f32_e32 v27, v33, v33
	v_add_f32_e32 v26, v26, v27
	v_mul_f32_e32 v27, v28, v28
	v_mul_f32_e32 v28, v29, v29
	v_fmac_f32_e32 v27, v40, v40
	v_fmac_f32_e32 v28, v41, v41
	v_add_f32_e32 v27, v27, v28
	v_add_f32_e32 v26, v26, v27
	s_nop 0
	v_lshlrev_b32_e32 v27, 16, v44
	v_and_b32_e32 v28, 0xffff0000, v44
	v_lshlrev_b32_e32 v29, 16, v45
	v_and_b32_e32 v32, 0xffff0000, v45
	v_lshlrev_b32_e32 v33, 16, v46
	v_and_b32_e32 v36, 0xffff0000, v46
	v_lshlrev_b32_e32 v37, 16, v47
	v_and_b32_e32 v40, 0xffff0000, v47
	v_mov_b32_e32 v44, v212
	v_mov_b32_e32 v45, v213
	v_mov_b32_e32 v46, v214
	v_mov_b32_e32 v47, v215
	s_nop 0
	v_lshlrev_b32_e32 v38, 16, v44
	v_and_b32_e32 v39, 0xffff0000, v44
	v_lshlrev_b32_e32 v44, 16, v46
	v_fmac_f32_e32 v27, v22, v38
	v_mul_f32_e32 v22, v23, v42
	v_fmac_f32_e32 v33, v18, v44
	v_mul_f32_e32 v18, v19, v42
	v_mul_f32_e32 v22, 0xbfb8aa3b, v22
	v_mul_f32_e32 v18, 0xbfb8aa3b, v18
	v_exp_f32_e32 v22, v22
	v_exp_f32_e32 v18, v18
	v_lshlrev_b32_e32 v41, 16, v45
	v_and_b32_e32 v43, 0xffff0000, v45
	v_add_f32_e32 v22, 1.0, v22
	v_add_f32_e32 v18, 1.0, v18
	v_rcp_f32_e32 v22, v22
	v_rcp_f32_e32 v18, v18
	v_and_b32_e32 v45, 0xffff0000, v46
	v_lshlrev_b32_e32 v46, 16, v47
	v_fmac_f32_e32 v28, v22, v39
	v_mul_f32_e32 v22, v24, v42
	v_fmac_f32_e32 v36, v18, v45
	v_mul_f32_e32 v18, v20, v42
	v_mul_f32_e32 v22, 0xbfb8aa3b, v22
	v_mul_f32_e32 v18, 0xbfb8aa3b, v18
	v_exp_f32_e32 v22, v22
	v_exp_f32_e32 v18, v18
	v_and_b32_e32 v47, 0xffff0000, v47
	v_add_f32_e32 v22, 1.0, v22
	v_add_f32_e32 v18, 1.0, v18
	v_rcp_f32_e32 v22, v22
	v_rcp_f32_e32 v18, v18
	v_fmac_f32_e32 v29, v22, v41
	v_mul_f32_e32 v22, v25, v42
	v_fmac_f32_e32 v37, v18, v46
	v_mul_f32_e32 v18, v21, v42
	v_mul_f32_e32 v22, 0xbfb8aa3b, v22
	v_mul_f32_e32 v18, 0xbfb8aa3b, v18
	v_exp_f32_e32 v22, v22
	v_exp_f32_e32 v18, v18
	v_add_f32_e32 v22, 1.0, v22
	v_add_f32_e32 v18, 1.0, v18
	v_rcp_f32_e32 v22, v22
	v_rcp_f32_e32 v18, v18
	v_fmac_f32_e32 v32, v22, v43
	v_fmac_f32_e32 v40, v18, v47
	v_cvt_pk_bf16_f32 v18, v27, v28
	v_cvt_pk_bf16_f32 v19, v29, v32
	v_cvt_pk_bf16_f32 v20, v33, v36
	v_cvt_pk_bf16_f32 v21, v37, v40
	global_store_dwordx4 v[30:31], v[18:21], off offset:256
	v_lshlrev_b32_e32 v22, 16, v18
	v_lshlrev_b32_e32 v23, 16, v19
	v_and_b32_e32 v18, 0xffff0000, v18
	v_and_b32_e32 v19, 0xffff0000, v19
	v_mul_f32_e32 v18, v18, v18
	v_mul_f32_e32 v19, v19, v19
	v_lshlrev_b32_e32 v24, 16, v20
	v_and_b32_e32 v20, 0xffff0000, v20
	v_lshlrev_b32_e32 v25, 16, v21
	v_and_b32_e32 v21, 0xffff0000, v21
	v_fmac_f32_e32 v18, v22, v22
	v_fmac_f32_e32 v19, v23, v23
	v_add_f32_e32 v18, v18, v19
	v_mul_f32_e32 v19, v20, v20
	v_mul_f32_e32 v20, v21, v21
	v_fmac_f32_e32 v19, v24, v24
	v_fmac_f32_e32 v20, v25, v25
	v_add_f32_e32 v19, v19, v20
	v_add_f32_e32 v18, v18, v19
	v_add_f32_e32 v18, v26, v18
	ds_bpermute_b32 v19, v158, v18
	s_waitcnt lgkmcnt(0)
	v_add_f32_e32 v18, v18, v19
	ds_bpermute_b32 v19, v145, v18
	s_and_saveexec_b64 s[24:25], s[6:7]
	s_cbranch_execz .LBB1_38
	s_lshl_b32 s66, s41, 2
	v_lshl_add_u64 v[20:21], s[20:21], 0, v[34:35]
	s_ashr_i32 s67, s66, 31
	v_lshl_add_u64 v[20:21], s[66:67], 2, v[20:21]
	s_lshl_b32 s74, s40, 2
	v_lshl_add_u64 v[20:21], v[20:21], 0, s[74:75]
	s_waitcnt lgkmcnt(0)
	v_add_f32_e32 v18, v18, v19
	global_store_dword v[20:21], v18, off

; #define LAS __attribute__((address_space(3)))
; __device__ __forceinline__ unsigned cvt_pk_bf16(float lo, float hi) { unsigned r; asm volatile("v_cvt_pk_bf16_f32 %0, %1, %2" : "=v"(r) : "v"(lo), "v"(hi)); return r; }
; #define EPP(T_, k) ((T_)(__attribute__((address_space(1))) char*)ep64(lds, (k)))
;     __device__ __forceinline__ void operator()(const f32x4 (&acc)[2][2][4][2], const Unit& u, int wr, int wc, int fr, int fq, LAS unsigned char* lds) const {
;         bf16_t* O = EPP(bf16_t*, 0); const float* rss = EPP(const float*, 1); const float* bias = EPP(const float*, 2); const int ldc = (int)ep64(lds, 3);
;         const int row0 = u.pm * BM + wr * 64 + fr, col0 = u.pn * BM + wc * 32 + 8 * fq;
;         f32x4 bv[2][2];
; #pragma unroll
;         for (int bj = 0; bj < 2; ++bj)
; #pragma unroll
;             for (int n = 0; n < 2; ++n) bv[bj][n] = bias ? *(const f32x4*)(bias + col0 + bj * HALF + 4 * n) : (f32x4){0.f, 0.f, 0.f, 0.f};
; #pragma unroll
;         for (int ai = 0; ai < 2; ++ai)
; #pragma unroll
;             for (int m = 0; m < 4; ++m) { const int row = row0 + ai * HALF + m * 16; const float rs = rss ? rstd_of4(rss, row, fq) : 1.0f;
; #pragma unroll
;                 for (int bj = 0; bj < 2; ++bj) { const f32x4 v0 = acc[ai][bj][m][0] * rs + bv[bj][0], v1 = acc[ai][bj][m][1] * rs + bv[bj][1];
;                     u32x4 w; w.x = cvt_pk_bf16(v0[0], v0[1]); w.y = cvt_pk_bf16(v0[2], v0[3]); w.z = cvt_pk_bf16(v1[0], v1[1]); w.w = cvt_pk_bf16(v1[2], v1[3]);
;                     *(u32x4*)(O + (size_t)row * ldc + col0 + bj * HALF) = w; } }
.LBB1_677:
	v_readfirstlane_b32 s1, v160
	v_lshl_add_u32 v160, s16, 8, v183
	s_cmp_lg_u64 s[18:19], 0
	s_cselect_b64 s[16:17], -1, 0
	s_cmp_eq_u64 s[18:19], 0
	v_lshl_add_u64 v[158:159], s[18:19], 0, v[4:5]
	v_ashrrev_i32_e32 v161, 31, v160
	v_mov_b32_e32 v164, 1.0
	v_mov_b32_e32 v166, 1.0
	s_cbranch_scc1 .LBB1_679
	v_lshlrev_b64 v[188:189], 6, v[160:161]
	v_lshl_add_u64 v[188:189], v[158:159], 0, v[188:189]
	global_load_dwordx4 v[188:191], v[188:189], off
	v_or_b32_e32 v228, 16, v160
	v_ashrrev_i32_e32 v229, 31, v228
	v_lshlrev_b64 v[228:229], 6, v[228:229]
	v_lshl_add_u64 v[228:229], v[158:159], 0, v[228:229]
	global_load_dwordx4 v[200:203], v[228:229], off
	v_or_b32_e32 v228, 32, v160
	v_ashrrev_i32_e32 v229, 31, v228
	v_lshlrev_b64 v[228:229], 6, v[228:229]
	v_lshl_add_u64 v[228:229], v[158:159], 0, v[228:229]
	global_load_dwordx4 v[204:207], v[228:229], off
	v_or_b32_e32 v228, 48, v160
	v_ashrrev_i32_e32 v229, 31, v228
	v_lshlrev_b64 v[228:229], 6, v[228:229]
	v_lshl_add_u64 v[228:229], v[158:159], 0, v[228:229]
	global_load_dwordx4 v[208:211], v[228:229], off
	v_add_u32_e32 v228, 0x80, v160
	v_ashrrev_i32_e32 v229, 31, v228
	v_lshlrev_b64 v[228:229], 6, v[228:229]
	v_lshl_add_u64 v[228:229], v[158:159], 0, v[228:229]
	global_load_dwordx4 v[212:215], v[228:229], off
	v_add_u32_e32 v228, 0x90, v160
	v_ashrrev_i32_e32 v229, 31, v228
	v_lshlrev_b64 v[228:229], 6, v[228:229]
	v_lshl_add_u64 v[228:229], v[158:159], 0, v[228:229]
	global_load_dwordx4 v[216:219], v[228:229], off
	v_add_u32_e32 v228, 0xa0, v160
	v_ashrrev_i32_e32 v229, 31, v228
	v_lshlrev_b64 v[228:229], 6, v[228:229]
	v_lshl_add_u64 v[228:229], v[158:159], 0, v[228:229]
	global_load_dwordx4 v[220:223], v[228:229], off
	v_add_u32_e32 v228, 0xb0, v160
	v_ashrrev_i32_e32 v229, 31, v228
	v_lshlrev_b64 v[228:229], 6, v[228:229]
	v_lshl_add_u64 v[228:229], v[158:159], 0, v[228:229]
	global_load_dwordx4 v[224:227], v[228:229], off
	v_and_b32_e32 v187, 64, v171
	v_xor_b32_e32 v166, 16, v171
	v_add_u32_e32 v187, 64, v187
	v_cmp_lt_i32_e32 vcc, v166, v187
	s_waitcnt vmcnt(0)
	v_mov_b32_e32 v194, v189
	v_mov_b32_e32 v195, v190
	v_mov_b32_e32 v189, v191
	v_pk_add_f32 v[188:189], v[194:195], v[188:189]
	v_cndmask_b32_e32 v166, v171, v166, vcc
	v_add_f32_e32 v161, v188, v189
	v_lshlrev_b32_e32 v166, 2, v166
	ds_bpermute_b32 v166, v166, v161
	s_waitcnt lgkmcnt(0)
	v_add_f32_e32 v161, v161, v166
	v_xor_b32_e32 v166, 32, v171
	v_cmp_lt_i32_e32 vcc, v166, v187
	s_nop 1
	v_cndmask_b32_e32 v166, v171, v166, vcc
	v_lshlrev_b32_e32 v166, 2, v166
	ds_bpermute_b32 v166, v166, v161
	s_waitcnt lgkmcnt(0)
	v_add_f32_e32 v161, v161, v166
	v_fmamk_f32 v161, v161, 0x3a800000, v173
	v_cmp_gt_f32_e32 vcc, s64, v161
	v_mul_f32_e32 v166, 0x4b800000, v161
	s_nop 0
	v_cndmask_b32_e32 v161, v161, v166, vcc
	v_rsq_f32_e32 v161, v161
	s_nop 0
	v_mul_f32_e32 v166, 0x45800000, v161
	v_cndmask_b32_e32 v166, v161, v166, vcc
.LBB1_679:
	v_mov_b32_e32 v188, s9
	v_mov_b32_e32 v189, s22
	v_lshl_add_u64 v[162:163], v[162:163], 1, v[188:189]
	v_mad_i64_i32 v[188:189], s[6:7], s1, v160, 0
	v_lshl_add_u64 v[188:189], v[188:189], 1, v[162:163]
	v_pk_fma_f32 v[142:143], v[142:143], v[166:167], v[156:157] op_sel_hi:[1,0,1]
	v_pk_fma_f32 v[140:141], v[140:141], v[166:167], v[94:95] op_sel_hi:[1,0,1]
	s_waitcnt vmcnt(0)
	v_pk_fma_f32 v[190:191], v[138:139], v[166:167], v[92:93] op_sel_hi:[1,0,1]
	v_pk_fma_f32 v[138:139], v[136:137], v[166:167], v[90:91] op_sel_hi:[1,0,1]
	v_cvt_pk_bf16_f32 v136, v140, v141
	v_cvt_pk_bf16_f32 v137, v142, v143
	v_pk_fma_f32 v[134:135], v[134:135], v[166:167], v[102:103] op_sel_hi:[1,0,1]
	v_cvt_pk_bf16_f32 v138, v138, v139
	v_cvt_pk_bf16_f32 v139, v190, v191
	global_store_dwordx4 v[188:189], v[136:139], off
	v_pk_fma_f32 v[132:133], v[132:133], v[166:167], v[100:101] op_sel_hi:[1,0,1]
	s_andn2_b64 vcc, exec, s[16:17]
	v_pk_fma_f32 v[136:137], v[130:131], v[166:167], v[98:99] op_sel_hi:[1,0,1]
	v_pk_fma_f32 v[130:131], v[128:129], v[166:167], v[96:97] op_sel_hi:[1,0,1]
	v_cvt_pk_bf16_f32 v128, v132, v133
	v_cvt_pk_bf16_f32 v129, v134, v135
	s_nop 0
	v_cvt_pk_bf16_f32 v130, v130, v131
	v_cvt_pk_bf16_f32 v131, v136, v137
	global_store_dwordx4 v[188:189], v[128:131], off offset:256
	s_nop 1
	v_or_b32_e32 v128, 16, v160
	v_cndmask_b32_e64 v129, 0, 1, s[16:17]
	v_cmp_ne_u32_e64 s[6:7], 1, v129
	v_ashrrev_i32_e32 v129, 31, v128
	s_cbranch_vccnz .LBB1_681
	v_lshlrev_b64 v[130:131], 6, v[128:129]
	v_lshl_add_u64 v[130:131], v[158:159], 0, v[130:131]
	v_mov_b32_e32 v130, v200
	v_mov_b32_e32 v131, v201
	v_mov_b32_e32 v132, v202
	v_mov_b32_e32 v133, v203
	s_nop 0
	v_mov_b32_e32 v134, v131
	v_mov_b32_e32 v135, v132
	v_mov_b32_e32 v131, v133
	v_pk_add_f32 v[130:131], v[134:135], v[130:131]
	s_nop 0
	v_add_f32_e32 v129, v130, v131
	v_and_b32_e32 v131, 64, v171
	v_xor_b32_e32 v130, 16, v171
	v_add_u32_e32 v131, 64, v131
	v_cmp_lt_i32_e32 vcc, v130, v131
	s_nop 1
	v_cndmask_b32_e32 v130, v171, v130, vcc
	v_lshlrev_b32_e32 v130, 2, v130
	ds_bpermute_b32 v130, v130, v129
	s_waitcnt lgkmcnt(0)
	v_add_f32_e32 v129, v129, v130
	v_xor_b32_e32 v130, 32, v171
	v_cmp_lt_i32_e32 vcc, v130, v131
	s_nop 1
	v_cndmask_b32_e32 v130, v171, v130, vcc
	v_lshlrev_b32_e32 v130, 2, v130
	ds_bpermute_b32 v130, v130, v129
	s_waitcnt lgkmcnt(0)
	v_add_f32_e32 v129, v129, v130
	v_fmamk_f32 v129, v129, 0x3a800000, v173
	v_cmp_gt_f32_e32 vcc, s64, v129
	v_mul_f32_e32 v130, 0x4b800000, v129
	s_nop 0
	v_cndmask_b32_e32 v129, v129, v130, vcc
	v_rsq_f32_e32 v129, v129
	s_nop 0
	v_mul_f32_e32 v130, 0x45800000, v129
	v_cndmask_b32_e32 v164, v129, v130, vcc
; __device__ __forceinline__ unsigned cvt_pk_bf16(float lo, float hi) { unsigned r; asm volatile("v_cvt_pk_bf16_f32 %0, %1, %2" : "=v"(r) : "v"(lo), "v"(hi)); return r; }
;     __device__ __forceinline__ void operator()(const f32x4 (&acc)[2][2][4][2], const Unit& u, int wr, int wc, int fr, int fq, LAS unsigned char* lds) const {
;     ...
;         for (int ai = 0; ai < 2; ++ai)
; #pragma unroll
;             for (int m = 0; m < 4; ++m) { const int row = row0 + ai * HALF + m * 16; const float rs = rss ? rstd_of4(rss, row, fq) : 1.0f;
; #pragma unroll
;                 for (int bj = 0; bj < 2; ++bj) { const f32x4 v0 = acc[ai][bj][m][0] * rs + bv[bj][0], v1 = acc[ai][bj][m][1] * rs + bv[bj][1];
;                     u32x4 w; w.x = cvt_pk_bf16(v0[0], v0[1]); w.y = cvt_pk_bf16(v0[2], v0[3]); w.z = cvt_pk_bf16(v1[0], v1[1]); w.w = cvt_pk_bf16(v1[2], v1[3]);
;                     *(u32x4*)(O + (size_t)row * ldc + col0 + bj * HALF) = w; } }
.LBB1_681:
	v_mad_i64_i32 v[128:129], s[16:17], s1, v128, 0
	v_lshl_add_u64 v[128:129], v[128:129], 1, v[162:163]
	v_pk_fma_f32 v[126:127], v[126:127], v[164:165], v[156:157] op_sel_hi:[1,0,1]
	v_pk_fma_f32 v[124:125], v[124:125], v[164:165], v[94:95] op_sel_hi:[1,0,1]
	v_pk_fma_f32 v[130:131], v[122:123], v[164:165], v[92:93] op_sel_hi:[1,0,1]
	v_pk_fma_f32 v[122:123], v[120:121], v[164:165], v[90:91] op_sel_hi:[1,0,1]
	v_cvt_pk_bf16_f32 v120, v124, v125
	v_cvt_pk_bf16_f32 v121, v126, v127
	v_pk_fma_f32 v[118:119], v[118:119], v[164:165], v[102:103] op_sel_hi:[1,0,1]
	v_cvt_pk_bf16_f32 v122, v122, v123
	v_cvt_pk_bf16_f32 v123, v130, v131
	global_store_dwordx4 v[128:129], v[120:123], off
	v_pk_fma_f32 v[116:117], v[116:117], v[164:165], v[100:101] op_sel_hi:[1,0,1]
	s_and_b64 vcc, exec, s[6:7]
	v_pk_fma_f32 v[120:121], v[114:115], v[164:165], v[98:99] op_sel_hi:[1,0,1]
	v_pk_fma_f32 v[114:115], v[112:113], v[164:165], v[96:97] op_sel_hi:[1,0,1]
	v_cvt_pk_bf16_f32 v112, v116, v117
	v_cvt_pk_bf16_f32 v113, v118, v119
	v_mov_b32_e32 v116, 1.0
	v_cvt_pk_bf16_f32 v114, v114, v115
	v_cvt_pk_bf16_f32 v115, v120, v121
	global_store_dwordx4 v[128:129], v[112:115], off offset:256
	s_nop 1
	v_or_b32_e32 v114, 32, v160
	v_ashrrev_i32_e32 v115, 31, v114
	v_mov_b32_e32 v112, 1.0
	s_cbranch_vccnz .LBB1_683
	v_lshlrev_b64 v[116:117], 6, v[114:115]
	v_lshl_add_u64 v[116:117], v[158:159], 0, v[116:117]
	v_mov_b32_e32 v116, v204
	v_mov_b32_e32 v117, v205
	v_mov_b32_e32 v118, v206
	v_mov_b32_e32 v119, v207
	v_xor_b32_e32 v115, 16, v171
	s_nop 0
	v_mov_b32_e32 v120, v117
	v_mov_b32_e32 v121, v118
	v_mov_b32_e32 v117, v119
	v_pk_add_f32 v[116:117], v[120:121], v[116:117]
	s_nop 0
	v_add_f32_e32 v113, v116, v117
	v_and_b32_e32 v116, 64, v171
	v_add_u32_e32 v116, 64, v116
	v_cmp_lt_i32_e32 vcc, v115, v116
	s_nop 1
	v_cndmask_b32_e32 v115, v171, v115, vcc
	v_lshlrev_b32_e32 v115, 2, v115
	ds_bpermute_b32 v115, v115, v113
	s_waitcnt lgkmcnt(0)
	v_add_f32_e32 v113, v113, v115
	v_xor_b32_e32 v115, 32, v171
	v_cmp_lt_i32_e32 vcc, v115, v116
	s_nop 1
	v_cndmask_b32_e32 v115, v171, v115, vcc
	v_lshlrev_b32_e32 v115, 2, v115
	ds_bpermute_b32 v115, v115, v113
	s_waitcnt lgkmcnt(0)
	v_add_f32_e32 v113, v113, v115
	v_fmamk_f32 v113, v113, 0x3a800000, v173
	v_cmp_gt_f32_e32 vcc, s64, v113
	v_mul_f32_e32 v115, 0x4b800000, v113
	s_nop 0
	v_cndmask_b32_e32 v113, v113, v115, vcc
	v_rsq_f32_e32 v113, v113
	s_nop 0
	v_mul_f32_e32 v115, 0x45800000, v113
	v_cndmask_b32_e32 v116, v113, v115, vcc
.LBB1_683:
	v_mad_i64_i32 v[114:115], s[16:17], s1, v114, 0
	v_lshl_add_u64 v[114:115], v[114:115], 1, v[162:163]
	v_pk_fma_f32 v[110:111], v[110:111], v[116:117], v[156:157] op_sel_hi:[1,0,1]
	v_pk_fma_f32 v[108:109], v[108:109], v[116:117], v[94:95] op_sel_hi:[1,0,1]
	v_pk_fma_f32 v[118:119], v[106:107], v[116:117], v[92:93] op_sel_hi:[1,0,1]
	v_pk_fma_f32 v[106:107], v[104:105], v[116:117], v[90:91] op_sel_hi:[1,0,1]
	v_cvt_pk_bf16_f32 v104, v108, v109
	v_cvt_pk_bf16_f32 v105, v110, v111
	v_pk_fma_f32 v[86:87], v[86:87], v[116:117], v[100:101] op_sel_hi:[1,0,1]
	v_cvt_pk_bf16_f32 v106, v106, v107
	v_cvt_pk_bf16_f32 v107, v118, v119
	global_store_dwordx4 v[114:115], v[104:107], off
	v_pk_fma_f32 v[88:89], v[88:89], v[116:117], v[102:103] op_sel_hi:[1,0,1]
	s_and_b64 vcc, exec, s[6:7]
	v_pk_fma_f32 v[104:105], v[84:85], v[116:117], v[98:99] op_sel_hi:[1,0,1]
	v_pk_fma_f32 v[84:85], v[82:83], v[116:117], v[96:97] op_sel_hi:[1,0,1]
	v_cvt_pk_bf16_f32 v82, v86, v87
	v_cvt_pk_bf16_f32 v83, v88, v89
	s_nop 0
	v_cvt_pk_bf16_f32 v84, v84, v85
	v_cvt_pk_bf16_f32 v85, v104, v105
	global_store_dwordx4 v[114:115], v[82:85], off offset:256
	s_nop 1
	v_or_b32_e32 v82, 48, v160
	v_ashrrev_i32_e32 v83, 31, v82
	s_cbranch_vccnz .LBB1_685
	v_lshlrev_b64 v[84:85], 6, v[82:83]
	v_lshl_add_u64 v[84:85], v[158:159], 0, v[84:85]
	v_mov_b32_e32 v84, v208
	v_mov_b32_e32 v85, v209
	v_mov_b32_e32 v86, v210
	v_mov_b32_e32 v87, v211
	s_nop 0
	v_mov_b32_e32 v88, v85
	v_mov_b32_e32 v89, v86
	v_mov_b32_e32 v85, v87
	v_pk_add_f32 v[84:85], v[88:89], v[84:85]
	s_nop 0
	v_add_f32_e32 v83, v84, v85
	v_and_b32_e32 v85, 64, v171
	v_xor_b32_e32 v84, 16, v171
	v_add_u32_e32 v85, 64, v85
	v_cmp_lt_i32_e32 vcc, v84, v85
	s_nop 1
	v_cndmask_b32_e32 v84, v171, v84, vcc
	v_lshlrev_b32_e32 v84, 2, v84
	ds_bpermute_b32 v84, v84, v83
	s_waitcnt lgkmcnt(0)
	v_add_f32_e32 v83, v83, v84
	v_xor_b32_e32 v84, 32, v171
	v_cmp_lt_i32_e32 vcc, v84, v85
	s_nop 1
	v_cndmask_b32_e32 v84, v171, v84, vcc
	v_lshlrev_b32_e32 v84, 2, v84
	ds_bpermute_b32 v84, v84, v83
	s_waitcnt lgkmcnt(0)
	v_add_f32_e32 v83, v83, v84
	v_fmamk_f32 v83, v83, 0x3a800000, v173
	v_cmp_gt_f32_e32 vcc, s64, v83
	v_mul_f32_e32 v84, 0x4b800000, v83
	s_nop 0
	v_cndmask_b32_e32 v83, v83, v84, vcc
	v_rsq_f32_e32 v83, v83
	s_nop 0
	v_mul_f32_e32 v84, 0x45800000, v83
	v_cndmask_b32_e32 v112, v83, v84, vcc
; __device__ __forceinline__ unsigned cvt_pk_bf16(float lo, float hi) { unsigned r; asm volatile("v_cvt_pk_bf16_f32 %0, %1, %2" : "=v"(r) : "v"(lo), "v"(hi)); return r; }
;     __device__ __forceinline__ void operator()(const f32x4 (&acc)[2][2][4][2], const Unit& u, int wr, int wc, int fr, int fq, LAS unsigned char* lds) const {
;     ...
;         for (int ai = 0; ai < 2; ++ai)
; #pragma unroll
;             for (int m = 0; m < 4; ++m) { const int row = row0 + ai * HALF + m * 16; const float rs = rss ? rstd_of4(rss, row, fq) : 1.0f;
; #pragma unroll
;                 for (int bj = 0; bj < 2; ++bj) { const f32x4 v0 = acc[ai][bj][m][0] * rs + bv[bj][0], v1 = acc[ai][bj][m][1] * rs + bv[bj][1];
;                     u32x4 w; w.x = cvt_pk_bf16(v0[0], v0[1]); w.y = cvt_pk_bf16(v0[2], v0[3]); w.z = cvt_pk_bf16(v1[0], v1[1]); w.w = cvt_pk_bf16(v1[2], v1[3]);
;                     *(u32x4*)(O + (size_t)row * ldc + col0 + bj * HALF) = w; } }
.LBB1_685:
	v_mad_i64_i32 v[82:83], s[16:17], s1, v82, 0
	v_lshl_add_u64 v[82:83], v[82:83], 1, v[162:163]
	v_pk_fma_f32 v[80:81], v[80:81], v[112:113], v[156:157] op_sel_hi:[1,0,1]
	v_pk_fma_f32 v[78:79], v[78:79], v[112:113], v[94:95] op_sel_hi:[1,0,1]
	v_pk_fma_f32 v[84:85], v[76:77], v[112:113], v[92:93] op_sel_hi:[1,0,1]
	v_pk_fma_f32 v[76:77], v[74:75], v[112:113], v[90:91] op_sel_hi:[1,0,1]
	v_cvt_pk_bf16_f32 v74, v78, v79
	v_cvt_pk_bf16_f32 v75, v80, v81
	v_pk_fma_f32 v[72:73], v[72:73], v[112:113], v[102:103] op_sel_hi:[1,0,1]
	v_cvt_pk_bf16_f32 v76, v76, v77
	v_cvt_pk_bf16_f32 v77, v84, v85
	global_store_dwordx4 v[82:83], v[74:77], off
	v_pk_fma_f32 v[70:71], v[70:71], v[112:113], v[100:101] op_sel_hi:[1,0,1]
	s_and_b64 vcc, exec, s[6:7]
	v_pk_fma_f32 v[74:75], v[68:69], v[112:113], v[98:99] op_sel_hi:[1,0,1]
	v_pk_fma_f32 v[68:69], v[66:67], v[112:113], v[96:97] op_sel_hi:[1,0,1]
	v_cvt_pk_bf16_f32 v66, v70, v71
	v_cvt_pk_bf16_f32 v67, v72, v73
	v_mov_b32_e32 v70, 1.0
	v_cvt_pk_bf16_f32 v68, v68, v69
	v_cvt_pk_bf16_f32 v69, v74, v75
	global_store_dwordx4 v[82:83], v[66:69], off offset:256
	s_nop 1
	v_add_u32_e32 v68, 0x80, v160
	v_ashrrev_i32_e32 v69, 31, v68
	v_mov_b32_e32 v66, 1.0
	s_cbranch_vccnz .LBB1_687
	v_lshlrev_b64 v[70:71], 6, v[68:69]
	v_lshl_add_u64 v[70:71], v[158:159], 0, v[70:71]
	v_mov_b32_e32 v70, v212
	v_mov_b32_e32 v71, v213
	v_mov_b32_e32 v72, v214
	v_mov_b32_e32 v73, v215
	v_xor_b32_e32 v69, 16, v171
	s_nop 0
	v_mov_b32_e32 v74, v71
	v_mov_b32_e32 v75, v72
	v_mov_b32_e32 v71, v73
	v_pk_add_f32 v[70:71], v[74:75], v[70:71]
	s_nop 0
	v_add_f32_e32 v67, v70, v71
	v_and_b32_e32 v70, 64, v171
	v_add_u32_e32 v70, 64, v70
	v_cmp_lt_i32_e32 vcc, v69, v70
	s_nop 1
	v_cndmask_b32_e32 v69, v171, v69, vcc
	v_lshlrev_b32_e32 v69, 2, v69
	ds_bpermute_b32 v69, v69, v67
	s_waitcnt lgkmcnt(0)
	v_add_f32_e32 v67, v67, v69
	v_xor_b32_e32 v69, 32, v171
	v_cmp_lt_i32_e32 vcc, v69, v70
	s_nop 1
	v_cndmask_b32_e32 v69, v171, v69, vcc
	v_lshlrev_b32_e32 v69, 2, v69
	ds_bpermute_b32 v69, v69, v67
	s_waitcnt lgkmcnt(0)
	v_add_f32_e32 v67, v67, v69
	v_fmamk_f32 v67, v67, 0x3a800000, v173
	v_cmp_gt_f32_e32 vcc, s64, v67
	v_mul_f32_e32 v69, 0x4b800000, v67
	s_nop 0
	v_cndmask_b32_e32 v67, v67, v69, vcc
	v_rsq_f32_e32 v67, v67
	s_nop 0
	v_mul_f32_e32 v69, 0x45800000, v67
	v_cndmask_b32_e32 v70, v67, v69, vcc
.LBB1_687:
	v_mad_i64_i32 v[68:69], s[16:17], s1, v68, 0
	v_lshl_add_u64 v[68:69], v[68:69], 1, v[162:163]
	v_pk_fma_f32 v[64:65], v[64:65], v[70:71], v[156:157] op_sel_hi:[1,0,1]
	v_pk_fma_f32 v[62:63], v[62:63], v[70:71], v[94:95] op_sel_hi:[1,0,1]
	v_pk_fma_f32 v[72:73], v[60:61], v[70:71], v[92:93] op_sel_hi:[1,0,1]
	v_pk_fma_f32 v[60:61], v[58:59], v[70:71], v[90:91] op_sel_hi:[1,0,1]
	v_cvt_pk_bf16_f32 v58, v62, v63
	v_cvt_pk_bf16_f32 v59, v64, v65
	v_pk_fma_f32 v[54:55], v[54:55], v[70:71], v[100:101] op_sel_hi:[1,0,1]
	v_cvt_pk_bf16_f32 v60, v60, v61
	v_cvt_pk_bf16_f32 v61, v72, v73
	global_store_dwordx4 v[68:69], v[58:61], off
	v_pk_fma_f32 v[56:57], v[56:57], v[70:71], v[102:103] op_sel_hi:[1,0,1]
	s_and_b64 vcc, exec, s[6:7]
	v_pk_fma_f32 v[58:59], v[52:53], v[70:71], v[98:99] op_sel_hi:[1,0,1]
	v_pk_fma_f32 v[52:53], v[50:51], v[70:71], v[96:97] op_sel_hi:[1,0,1]
	v_cvt_pk_bf16_f32 v50, v54, v55
	v_cvt_pk_bf16_f32 v51, v56, v57
	s_nop 0
	v_cvt_pk_bf16_f32 v52, v52, v53
	v_cvt_pk_bf16_f32 v53, v58, v59
	global_store_dwordx4 v[68:69], v[50:53], off offset:256
	s_nop 1
	v_add_u32_e32 v50, 0x90, v160
	v_ashrrev_i32_e32 v51, 31, v50
	s_cbranch_vccnz .LBB1_689
	v_lshlrev_b64 v[52:53], 6, v[50:51]
	v_lshl_add_u64 v[52:53], v[158:159], 0, v[52:53]
	v_mov_b32_e32 v52, v216
	v_mov_b32_e32 v53, v217
	v_mov_b32_e32 v54, v218
	v_mov_b32_e32 v55, v219
	s_nop 0
	v_mov_b32_e32 v56, v53
	v_mov_b32_e32 v57, v54
	v_mov_b32_e32 v53, v55
	v_pk_add_f32 v[52:53], v[56:57], v[52:53]
	s_nop 0
	v_add_f32_e32 v51, v52, v53
	v_and_b32_e32 v53, 64, v171
	v_xor_b32_e32 v52, 16, v171
	v_add_u32_e32 v53, 64, v53
	v_cmp_lt_i32_e32 vcc, v52, v53
	s_nop 1
	v_cndmask_b32_e32 v52, v171, v52, vcc
	v_lshlrev_b32_e32 v52, 2, v52
	ds_bpermute_b32 v52, v52, v51
	s_waitcnt lgkmcnt(0)
	v_add_f32_e32 v51, v51, v52
	v_xor_b32_e32 v52, 32, v171
	v_cmp_lt_i32_e32 vcc, v52, v53
	s_nop 1
	v_cndmask_b32_e32 v52, v171, v52, vcc
	v_lshlrev_b32_e32 v52, 2, v52
	ds_bpermute_b32 v52, v52, v51
	s_waitcnt lgkmcnt(0)
	v_add_f32_e32 v51, v51, v52
	v_fmamk_f32 v51, v51, 0x3a800000, v173
	v_cmp_gt_f32_e32 vcc, s64, v51
	v_mul_f32_e32 v52, 0x4b800000, v51
	s_nop 0
	v_cndmask_b32_e32 v51, v51, v52, vcc
	v_rsq_f32_e32 v51, v51
	s_nop 0
	v_mul_f32_e32 v52, 0x45800000, v51
	v_cndmask_b32_e32 v66, v51, v52, vcc
; __device__ __forceinline__ unsigned cvt_pk_bf16(float lo, float hi) { unsigned r; asm volatile("v_cvt_pk_bf16_f32 %0, %1, %2" : "=v"(r) : "v"(lo), "v"(hi)); return r; }
;     __device__ __forceinline__ void operator()(const f32x4 (&acc)[2][2][4][2], const Unit& u, int wr, int wc, int fr, int fq, LAS unsigned char* lds) const {
;     ...
;         for (int ai = 0; ai < 2; ++ai)
; #pragma unroll
;             for (int m = 0; m < 4; ++m) { const int row = row0 + ai * HALF + m * 16; const float rs = rss ? rstd_of4(rss, row, fq) : 1.0f;
; #pragma unroll
;                 for (int bj = 0; bj < 2; ++bj) { const f32x4 v0 = acc[ai][bj][m][0] * rs + bv[bj][0], v1 = acc[ai][bj][m][1] * rs + bv[bj][1];
;                     u32x4 w; w.x = cvt_pk_bf16(v0[0], v0[1]); w.y = cvt_pk_bf16(v0[2], v0[3]); w.z = cvt_pk_bf16(v1[0], v1[1]); w.w = cvt_pk_bf16(v1[2], v1[3]);
;                     *(u32x4*)(O + (size_t)row * ldc + col0 + bj * HALF) = w; } }
.LBB1_689:
	v_mad_i64_i32 v[50:51], s[16:17], s1, v50, 0
	v_lshl_add_u64 v[50:51], v[50:51], 1, v[162:163]
	v_pk_fma_f32 v[48:49], v[48:49], v[66:67], v[156:157] op_sel_hi:[1,0,1]
	v_pk_fma_f32 v[46:47], v[46:47], v[66:67], v[94:95] op_sel_hi:[1,0,1]
	v_pk_fma_f32 v[52:53], v[44:45], v[66:67], v[92:93] op_sel_hi:[1,0,1]
	v_pk_fma_f32 v[44:45], v[42:43], v[66:67], v[90:91] op_sel_hi:[1,0,1]
	v_cvt_pk_bf16_f32 v42, v46, v47
	v_cvt_pk_bf16_f32 v43, v48, v49
	v_pk_fma_f32 v[40:41], v[40:41], v[66:67], v[102:103] op_sel_hi:[1,0,1]
	v_cvt_pk_bf16_f32 v44, v44, v45
	v_cvt_pk_bf16_f32 v45, v52, v53
	global_store_dwordx4 v[50:51], v[42:45], off
	v_pk_fma_f32 v[38:39], v[38:39], v[66:67], v[100:101] op_sel_hi:[1,0,1]
	s_and_b64 vcc, exec, s[6:7]
	v_pk_fma_f32 v[42:43], v[36:37], v[66:67], v[98:99] op_sel_hi:[1,0,1]
	v_pk_fma_f32 v[36:37], v[34:35], v[66:67], v[96:97] op_sel_hi:[1,0,1]
	v_cvt_pk_bf16_f32 v34, v38, v39
	v_cvt_pk_bf16_f32 v35, v40, v41
	v_mov_b32_e32 v38, 1.0
	v_cvt_pk_bf16_f32 v36, v36, v37
	v_cvt_pk_bf16_f32 v37, v42, v43
	global_store_dwordx4 v[50:51], v[34:37], off offset:256
	s_nop 1
	v_add_u32_e32 v36, 0xa0, v160
	v_ashrrev_i32_e32 v37, 31, v36
	v_mov_b32_e32 v34, 1.0
	s_cbranch_vccnz .LBB1_691
	v_lshlrev_b64 v[38:39], 6, v[36:37]
	v_lshl_add_u64 v[38:39], v[158:159], 0, v[38:39]
	v_mov_b32_e32 v38, v220
	v_mov_b32_e32 v39, v221
	v_mov_b32_e32 v40, v222
	v_mov_b32_e32 v41, v223
	v_xor_b32_e32 v37, 16, v171
	s_nop 0
	v_mov_b32_e32 v42, v39
	v_mov_b32_e32 v43, v40
	v_mov_b32_e32 v39, v41
	v_pk_add_f32 v[38:39], v[42:43], v[38:39]
	s_nop 0
	v_add_f32_e32 v35, v38, v39
	v_and_b32_e32 v38, 64, v171
	v_add_u32_e32 v38, 64, v38
	v_cmp_lt_i32_e32 vcc, v37, v38
	s_nop 1
	v_cndmask_b32_e32 v37, v171, v37, vcc
	v_lshlrev_b32_e32 v37, 2, v37
	ds_bpermute_b32 v37, v37, v35
	s_waitcnt lgkmcnt(0)
	v_add_f32_e32 v35, v35, v37
	v_xor_b32_e32 v37, 32, v171
	v_cmp_lt_i32_e32 vcc, v37, v38
	s_nop 1
	v_cndmask_b32_e32 v37, v171, v37, vcc
	v_lshlrev_b32_e32 v37, 2, v37
	ds_bpermute_b32 v37, v37, v35
	s_waitcnt lgkmcnt(0)
	v_add_f32_e32 v35, v35, v37
	v_fmamk_f32 v35, v35, 0x3a800000, v173
	v_cmp_gt_f32_e32 vcc, s64, v35
	v_mul_f32_e32 v37, 0x4b800000, v35
	s_nop 0
	v_cndmask_b32_e32 v35, v35, v37, vcc
	v_rsq_f32_e32 v35, v35
	s_nop 0
	v_mul_f32_e32 v37, 0x45800000, v35
	v_cndmask_b32_e32 v38, v35, v37, vcc
.LBB1_691:
	v_mad_i64_i32 v[36:37], s[16:17], s1, v36, 0
	v_lshl_add_u64 v[36:37], v[36:37], 1, v[162:163]
	v_pk_fma_f32 v[32:33], v[32:33], v[38:39], v[156:157] op_sel_hi:[1,0,1]
	v_pk_fma_f32 v[30:31], v[30:31], v[38:39], v[94:95] op_sel_hi:[1,0,1]
	v_pk_fma_f32 v[40:41], v[28:29], v[38:39], v[92:93] op_sel_hi:[1,0,1]
	v_pk_fma_f32 v[28:29], v[26:27], v[38:39], v[90:91] op_sel_hi:[1,0,1]
	v_cvt_pk_bf16_f32 v26, v30, v31
	v_cvt_pk_bf16_f32 v27, v32, v33
	v_pk_fma_f32 v[22:23], v[22:23], v[38:39], v[100:101] op_sel_hi:[1,0,1]
	v_cvt_pk_bf16_f32 v28, v28, v29
	v_cvt_pk_bf16_f32 v29, v40, v41
	global_store_dwordx4 v[36:37], v[26:29], off
	v_pk_fma_f32 v[24:25], v[24:25], v[38:39], v[102:103] op_sel_hi:[1,0,1]
	s_and_b64 vcc, exec, s[6:7]
	v_pk_fma_f32 v[26:27], v[20:21], v[38:39], v[98:99] op_sel_hi:[1,0,1]
	v_pk_fma_f32 v[20:21], v[18:19], v[38:39], v[96:97] op_sel_hi:[1,0,1]
	v_cvt_pk_bf16_f32 v18, v22, v23
	v_cvt_pk_bf16_f32 v19, v24, v25
	s_nop 0
	v_cvt_pk_bf16_f32 v20, v20, v21
	v_cvt_pk_bf16_f32 v21, v26, v27
	global_store_dwordx4 v[36:37], v[18:21], off offset:256
	s_nop 1
	v_add_u32_e32 v18, 0xb0, v160
	v_ashrrev_i32_e32 v19, 31, v18
	s_cbranch_vccnz .LBB1_664
	v_lshlrev_b64 v[20:21], 6, v[18:19]
	v_lshl_add_u64 v[20:21], v[158:159], 0, v[20:21]
	v_mov_b32_e32 v20, v224
	v_mov_b32_e32 v21, v225
	v_mov_b32_e32 v22, v226
	v_mov_b32_e32 v23, v227
	s_nop 0
	v_mov_b32_e32 v24, v21
	v_mov_b32_e32 v25, v22
	v_mov_b32_e32 v21, v23
	v_pk_add_f32 v[20:21], v[24:25], v[20:21]
	s_nop 0
	v_add_f32_e32 v19, v20, v21
	v_and_b32_e32 v21, 64, v171
	v_xor_b32_e32 v20, 16, v171
	v_add_u32_e32 v21, 64, v21
	v_cmp_lt_i32_e32 vcc, v20, v21
	s_nop 1
	v_cndmask_b32_e32 v20, v171, v20, vcc
	v_lshlrev_b32_e32 v20, 2, v20
	ds_bpermute_b32 v20, v20, v19
	s_waitcnt lgkmcnt(0)
	v_add_f32_e32 v19, v19, v20
	v_xor_b32_e32 v20, 32, v171
	v_cmp_lt_i32_e32 vcc, v20, v21
	s_nop 1
	v_cndmask_b32_e32 v20, v171, v20, vcc
	v_lshlrev_b32_e32 v20, 2, v20
	ds_bpermute_b32 v20, v20, v19
	s_waitcnt lgkmcnt(0)
	v_add_f32_e32 v19, v19, v20
	v_fmamk_f32 v19, v19, 0x3a800000, v173
	v_cmp_gt_f32_e32 vcc, s64, v19
	v_mul_f32_e32 v20, 0x4b800000, v19
	s_nop 0
	v_cndmask_b32_e32 v19, v19, v20, vcc
	v_rsq_f32_e32 v19, v19
	s_nop 0
	v_mul_f32_e32 v20, 0x45800000, v19
	v_cndmask_b32_e32 v34, v19, v20, vcc
	s_branch .LBB1_664

; __device__ __forceinline__ unsigned cvt_pk_bf16(float lo, float hi) { unsigned r; asm volatile("v_cvt_pk_bf16_f32 %0, %1, %2" : "=v"(r) : "v"(lo), "v"(hi)); return r; }
;     __device__ __forceinline__ void operator()(const f32x4 (&acc)[2][2][4][2], const Unit& u, int wr, int wc, int fr, int fq, LAS unsigned char* lds) const {
;     ...
;         for (int ai = 0; ai < 2; ++ai)
; #pragma unroll
;             for (int m = 0; m < 4; ++m) { const int row = row0 + ai * HALF + m * 16; const size_t off = (size_t)row * D + col0;
;                 float rs = 1.0f; if (MODE == 1) rs = rstd_of4(rss_in, row, fq);
;                 float ss = 0.f;
; #pragma unroll
;                 for (int bj = 0; bj < 2; ++bj) { const size_t o = off + bj * HALF; const u32x4 bw = *(const u32x4*)(base + o);
;                     const float bs[8] = {bflo(bw.x), bfhi(bw.x), bflo(bw.y), bfhi(bw.y), bflo(bw.z), bfhi(bw.z), bflo(bw.w), bfhi(bw.w)};
;                     float hn[8];
;                     if (MODE == 0) {
; #pragma unroll
;                         for (int n = 0; n < 2; ++n)
; #pragma unroll
;                             for (int e = 0; e < 4; ++e) hn[4 * n + e] = bs[4 * n + e] + (acc[ai][bj][m][n][e] + bv[bj][n][e]) * scale;
;                     } else { const u32x4 pw = *(const u32x4*)(pp + o);
;                         const float pv[8] = {bflo(pw.x), bfhi(pw.x), bflo(pw.y), bfhi(pw.y), bflo(pw.z), bfhi(pw.z), bflo(pw.w), bfhi(pw.w)};
; #pragma unroll
;                         for (int n = 0; n < 2; ++n)
; #pragma unroll
;                             for (int e = 0; e < 4; ++e) hn[4 * n + e] = bs[4 * n + e] + fast_sigmoid(acc[ai][bj][m][n][e] * rs) * pv[4 * n + e]; }
;                     u32x4 w; w.x = cvt_pk_bf16(hn[0], hn[1]); w.y = cvt_pk_bf16(hn[2], hn[3]); w.z = cvt_pk_bf16(hn[4], hn[5]); w.w = cvt_pk_bf16(hn[6], hn[7]); *(u32x4*)(hb + o) = w;
;                     const float hr[8] = {bflo(w.x), bfhi(w.x), bflo(w.y), bfhi(w.y), bflo(w.z), bfhi(w.z), bflo(w.w), bfhi(w.w)};
;                     ss += ((hr[0] * hr[0] + hr[1] * hr[1]) + (hr[2] * hr[2] + hr[3] * hr[3])) + ((hr[4] * hr[4] + hr[5] * hr[5]) + (hr[6] * hr[6] + hr[7] * hr[7])); }
;                 ss += __shfl_xor(ss, 16); ss += __shfl_xor(ss, 32);
;                 if (fq == 0) rss_out[(size_t)row * 16 + u.pn * 4 + wc] = ss; }
.LBB1_773:
	v_lshl_add_u32 v158, s74, 8, v161
	v_ashrrev_i32_e32 v159, 31, v158
	v_lshlrev_b64 v[166:167], 10, v[158:159]
	v_lshl_add_u64 v[166:167], v[166:167], 0, v[156:157]
	v_lshlrev_b64 v[176:177], 1, v[166:167]
	v_lshl_add_u64 v[178:179], s[18:19], 0, v[176:177]
	global_load_dwordx4 v[166:169], v[178:179], off
	global_load_dwordx4 v[184:187], v[178:179], off offset:256
	v_or_b32_e32 v228, 16, v158
	v_ashrrev_i32_e32 v229, 31, v228
	v_lshlrev_b64 v[228:229], 10, v[228:229]
	v_lshl_add_u64 v[228:229], v[228:229], 0, v[156:157]
	v_lshlrev_b64 v[228:229], 1, v[228:229]
	v_lshl_add_u64 v[228:229], s[18:19], 0, v[228:229]
	global_load_dwordx4 v[188:191], v[228:229], off
	global_load_dwordx4 v[200:203], v[228:229], off offset:256
	v_or_b32_e32 v228, 32, v158
	v_ashrrev_i32_e32 v229, 31, v228
	v_lshlrev_b64 v[228:229], 10, v[228:229]
	v_lshl_add_u64 v[228:229], v[228:229], 0, v[156:157]
	v_lshlrev_b64 v[228:229], 1, v[228:229]
	v_lshl_add_u64 v[228:229], s[18:19], 0, v[228:229]
	global_load_dwordx4 v[204:207], v[228:229], off
	global_load_dwordx4 v[208:211], v[228:229], off offset:256
	v_or_b32_e32 v228, 48, v158
	v_ashrrev_i32_e32 v229, 31, v228
	v_lshlrev_b64 v[228:229], 10, v[228:229]
	v_lshl_add_u64 v[228:229], v[228:229], 0, v[156:157]
	v_lshlrev_b64 v[228:229], 1, v[228:229]
	v_lshl_add_u64 v[228:229], s[18:19], 0, v[228:229]
	global_load_dwordx4 v[212:215], v[228:229], off
	global_load_dwordx4 v[216:219], v[228:229], off offset:256
	s_waitcnt vmcnt(0)
	v_add_f32_e32 v142, v142, v82
	v_add_f32_e32 v143, v143, v83
	v_add_f32_e32 v144, v144, v84
	v_add_f32_e32 v145, v145, v85
	v_add_f32_e32 v138, v138, v78
	v_add_f32_e32 v139, v139, v79
	v_add_f32_e32 v140, v140, v80
	v_add_f32_e32 v141, v141, v81
	v_lshl_add_u64 v[176:177], s[16:17], 0, v[176:177]
	v_add_f32_e32 v134, v134, v70
	v_add_f32_e32 v136, v136, v72
	v_add_f32_e32 v130, v130, v66
	v_add_f32_e32 v135, v135, v71
	v_add_f32_e32 v137, v137, v73
	v_add_f32_e32 v131, v131, v67
	v_add_f32_e32 v133, v133, v69
	v_lshlrev_b32_e32 v165, 16, v166
	v_and_b32_e32 v166, 0xffff0000, v166
	v_lshlrev_b32_e32 v175, 16, v167
	v_and_b32_e32 v167, 0xffff0000, v167
	v_lshlrev_b32_e32 v180, 16, v168
	v_and_b32_e32 v168, 0xffff0000, v168
	v_lshlrev_b32_e32 v181, 16, v169
	v_and_b32_e32 v169, 0xffff0000, v169
	v_fmac_f32_e32 v165, s65, v142
	v_fmac_f32_e32 v166, s65, v143
	v_fmac_f32_e32 v175, s65, v144
	v_fmac_f32_e32 v167, s65, v145
	v_fmac_f32_e32 v180, s65, v138
	v_fmac_f32_e32 v168, s65, v139
	v_fmac_f32_e32 v181, s65, v140
	v_fmac_f32_e32 v169, s65, v141
	v_cvt_pk_bf16_f32 v138, v165, v166
	v_cvt_pk_bf16_f32 v139, v175, v167
	v_cvt_pk_bf16_f32 v140, v180, v168
	v_cvt_pk_bf16_f32 v141, v181, v169
	global_store_dwordx4 v[176:177], v[138:141], off
	v_mov_b32_e32 v142, v184
	v_mov_b32_e32 v143, v185
	v_mov_b32_e32 v144, v186
	v_mov_b32_e32 v145, v187
	v_lshlrev_b32_e32 v167, 16, v138
	v_and_b32_e32 v138, 0xffff0000, v138
	v_lshlrev_b32_e32 v168, 16, v139
	v_and_b32_e32 v139, 0xffff0000, v139
	v_lshlrev_b32_e32 v169, 16, v140
	v_and_b32_e32 v140, 0xffff0000, v140
	v_lshlrev_b32_e32 v175, 16, v141
	v_and_b32_e32 v141, 0xffff0000, v141
	v_mul_f32_e32 v138, v138, v138
	v_mul_f32_e32 v139, v139, v139
	v_mul_f32_e32 v140, v140, v140
	v_mul_f32_e32 v141, v141, v141
	v_fmac_f32_e32 v138, v167, v167
	v_fmac_f32_e32 v139, v168, v168
	v_fmac_f32_e32 v140, v169, v169
	v_fmac_f32_e32 v141, v175, v175
	v_add_f32_e32 v138, v138, v139
	v_add_f32_e32 v139, v140, v141
	v_add_f32_e32 v138, v138, v139
	v_add_f32_e32 v165, v132, v68
	v_and_b32_e32 v166, 64, v171
	v_xor_b32_e32 v132, 16, v171
	v_add_u32_e32 v166, 64, v166
	v_cmp_lt_i32_e32 vcc, v132, v166
	s_nop 0
	v_lshlrev_b32_e32 v139, 16, v142
	v_and_b32_e32 v140, 0xffff0000, v142
	v_lshlrev_b32_e32 v141, 16, v143
	v_and_b32_e32 v142, 0xffff0000, v143
	v_lshlrev_b32_e32 v143, 16, v144
	v_and_b32_e32 v144, 0xffff0000, v144
	v_lshlrev_b32_e32 v167, 16, v145
	v_and_b32_e32 v145, 0xffff0000, v145
	v_fmac_f32_e32 v139, s65, v134
	v_fmac_f32_e32 v141, s65, v136
	v_fmac_f32_e32 v143, s65, v130
	v_fmac_f32_e32 v140, s65, v135
	v_fmac_f32_e32 v142, s65, v137
	v_fmac_f32_e32 v144, s65, v131
	v_fmac_f32_e32 v167, s65, v165
	v_fmac_f32_e32 v145, s65, v133
	v_cvt_pk_bf16_f32 v134, v139, v140
	v_cvt_pk_bf16_f32 v135, v141, v142
	v_cvt_pk_bf16_f32 v136, v143, v144
	v_cvt_pk_bf16_f32 v137, v167, v145
	v_cndmask_b32_e32 v132, v171, v132, vcc
	v_and_b32_e32 v131, 0xffff0000, v134
	v_and_b32_e32 v139, 0xffff0000, v135
	v_and_b32_e32 v141, 0xffff0000, v136
	v_and_b32_e32 v143, 0xffff0000, v137
	v_lshlrev_b32_e32 v130, 16, v134
	v_lshlrev_b32_e32 v133, 16, v135
	v_lshlrev_b32_e32 v140, 16, v136
	v_lshlrev_b32_e32 v142, 16, v137
	v_mul_f32_e32 v131, v131, v131
	v_mul_f32_e32 v139, v139, v139
	v_mul_f32_e32 v141, v141, v141
	v_mul_f32_e32 v143, v143, v143
	v_fmac_f32_e32 v131, v130, v130
	v_fmac_f32_e32 v139, v133, v133
	v_fmac_f32_e32 v141, v140, v140
	v_fmac_f32_e32 v143, v142, v142
	v_add_f32_e32 v130, v131, v139
	v_add_f32_e32 v131, v141, v143
	v_add_f32_e32 v130, v130, v131
	v_lshlrev_b32_e32 v132, 2, v132
	v_add_f32_e32 v130, v138, v130
	ds_bpermute_b32 v131, v132, v130
	v_xor_b32_e32 v133, 32, v171
	v_cmp_lt_i32_e32 vcc, v133, v166
	global_store_dwordx4 v[176:177], v[134:137], off offset:256
	s_waitcnt lgkmcnt(0)
	v_add_f32_e32 v130, v130, v131
	v_cndmask_b32_e32 v133, v171, v133, vcc
	v_lshlrev_b32_e32 v133, 2, v133
	ds_bpermute_b32 v131, v133, v130
	s_and_saveexec_b64 s[8:9], s[6:7]
	s_cbranch_execz .LBB1_775
	s_waitcnt lgkmcnt(0)
	v_add_f32_e32 v134, v130, v131
	s_lshl_b32 s20, s23, 2
	v_lshlrev_b64 v[130:131], 6, v[158:159]
	s_ashr_i32 s21, s20, 31
	v_lshl_add_u64 v[130:131], s[14:15], 0, v[130:131]
	v_lshl_add_u64 v[130:131], s[20:21], 2, v[130:131]
	s_lshl_b32 s74, s40, 2
	v_lshl_add_u64 v[130:131], v[130:131], 0, s[74:75]
	global_store_dword v[130:131], v134, off
; __device__ __forceinline__ unsigned cvt_pk_bf16(float lo, float hi) { unsigned r; asm volatile("v_cvt_pk_bf16_f32 %0, %1, %2" : "=v"(r) : "v"(lo), "v"(hi)); return r; }
;     __device__ __forceinline__ void operator()(const f32x4 (&acc)[2][2][4][2], const Unit& u, int wr, int wc, int fr, int fq, LAS unsigned char* lds) const {
;     ...
;         for (int ai = 0; ai < 2; ++ai)
; #pragma unroll
;             for (int m = 0; m < 4; ++m) { const int row = row0 + ai * HALF + m * 16; const size_t off = (size_t)row * D + col0;
;                 float rs = 1.0f; if (MODE == 1) rs = rstd_of4(rss_in, row, fq);
;                 float ss = 0.f;
; #pragma unroll
;                 for (int bj = 0; bj < 2; ++bj) { const size_t o = off + bj * HALF; const u32x4 bw = *(const u32x4*)(base + o);
;                     const float bs[8] = {bflo(bw.x), bfhi(bw.x), bflo(bw.y), bfhi(bw.y), bflo(bw.z), bfhi(bw.z), bflo(bw.w), bfhi(bw.w)};
;                     float hn[8];
;                     if (MODE == 0) {
; #pragma unroll
;                         for (int n = 0; n < 2; ++n)
; #pragma unroll
;                             for (int e = 0; e < 4; ++e) hn[4 * n + e] = bs[4 * n + e] + (acc[ai][bj][m][n][e] + bv[bj][n][e]) * scale;
;                     } else { const u32x4 pw = *(const u32x4*)(pp + o);
;                         const float pv[8] = {bflo(pw.x), bfhi(pw.x), bflo(pw.y), bfhi(pw.y), bflo(pw.z), bfhi(pw.z), bflo(pw.w), bfhi(pw.w)};
; #pragma unroll
;                         for (int n = 0; n < 2; ++n)
; #pragma unroll
;                             for (int e = 0; e < 4; ++e) hn[4 * n + e] = bs[4 * n + e] + fast_sigmoid(acc[ai][bj][m][n][e] * rs) * pv[4 * n + e]; }
;                     u32x4 w; w.x = cvt_pk_bf16(hn[0], hn[1]); w.y = cvt_pk_bf16(hn[2], hn[3]); w.z = cvt_pk_bf16(hn[4], hn[5]); w.w = cvt_pk_bf16(hn[6], hn[7]); *(u32x4*)(hb + o) = w;
;                     const float hr[8] = {bflo(w.x), bfhi(w.x), bflo(w.y), bfhi(w.y), bflo(w.z), bfhi(w.z), bflo(w.w), bfhi(w.w)};
;                     ss += ((hr[0] * hr[0] + hr[1] * hr[1]) + (hr[2] * hr[2] + hr[3] * hr[3])) + ((hr[4] * hr[4] + hr[5] * hr[5]) + (hr[6] * hr[6] + hr[7] * hr[7])); }
;                 ss += __shfl_xor(ss, 16); ss += __shfl_xor(ss, 32);
;                 if (fq == 0) rss_out[(size_t)row * 16 + u.pn * 4 + wc] = ss; }
.LBB1_775:
	s_or_b64 exec, exec, s[8:9]
	v_or_b32_e32 v130, 16, v158
	s_waitcnt lgkmcnt(0)
	v_ashrrev_i32_e32 v131, 31, v130
	v_lshlrev_b64 v[134:135], 10, v[130:131]
	v_lshl_add_u64 v[134:135], v[134:135], 0, v[156:157]
	v_lshlrev_b64 v[138:139], 1, v[134:135]
	v_lshl_add_u64 v[140:141], s[18:19], 0, v[138:139]
	v_mov_b32_e32 v134, v188
	v_mov_b32_e32 v135, v189
	v_mov_b32_e32 v136, v190
	v_mov_b32_e32 v137, v191
	v_add_f32_e32 v126, v126, v82
	v_add_f32_e32 v127, v127, v83
	v_add_f32_e32 v128, v128, v84
	v_add_f32_e32 v129, v129, v85
	v_add_f32_e32 v122, v122, v78
	v_add_f32_e32 v123, v123, v79
	v_add_f32_e32 v124, v124, v80
	v_add_f32_e32 v125, v125, v81
	v_lshl_add_u64 v[138:139], s[16:17], 0, v[138:139]
	v_add_f32_e32 v119, v119, v71
	v_add_f32_e32 v121, v121, v73
	v_add_f32_e32 v118, v118, v70
	v_add_f32_e32 v120, v120, v72
	v_add_f32_e32 v114, v114, v66
	v_add_f32_e32 v115, v115, v67
	v_add_f32_e32 v116, v116, v68
	v_add_f32_e32 v117, v117, v69
	s_nop 0
	v_lshlrev_b32_e32 v142, 16, v134
	v_and_b32_e32 v134, 0xffff0000, v134
	v_lshlrev_b32_e32 v143, 16, v135
	v_and_b32_e32 v135, 0xffff0000, v135
	v_lshlrev_b32_e32 v144, 16, v136
	v_and_b32_e32 v136, 0xffff0000, v136
	v_lshlrev_b32_e32 v145, 16, v137
	v_and_b32_e32 v137, 0xffff0000, v137
	v_fmac_f32_e32 v142, s65, v126
	v_fmac_f32_e32 v134, s65, v127
	v_fmac_f32_e32 v143, s65, v128
	v_fmac_f32_e32 v135, s65, v129
	v_fmac_f32_e32 v144, s65, v122
	v_fmac_f32_e32 v136, s65, v123
	v_fmac_f32_e32 v145, s65, v124
	v_fmac_f32_e32 v137, s65, v125
	v_cvt_pk_bf16_f32 v122, v142, v134
	v_cvt_pk_bf16_f32 v123, v143, v135
	v_cvt_pk_bf16_f32 v124, v144, v136
	v_cvt_pk_bf16_f32 v125, v145, v137
	global_store_dwordx4 v[138:139], v[122:125], off
	v_mov_b32_e32 v126, v200
	v_mov_b32_e32 v127, v201
	v_mov_b32_e32 v128, v202
	v_mov_b32_e32 v129, v203
	v_lshlrev_b32_e32 v134, 16, v122
	v_and_b32_e32 v122, 0xffff0000, v122
	v_lshlrev_b32_e32 v135, 16, v123
	v_and_b32_e32 v123, 0xffff0000, v123
	v_lshlrev_b32_e32 v136, 16, v124
	v_and_b32_e32 v124, 0xffff0000, v124
	v_lshlrev_b32_e32 v137, 16, v125
	v_and_b32_e32 v125, 0xffff0000, v125
	v_mul_f32_e32 v122, v122, v122
	v_mul_f32_e32 v123, v123, v123
	v_mul_f32_e32 v124, v124, v124
	v_mul_f32_e32 v125, v125, v125
	v_fmac_f32_e32 v122, v134, v134
	v_fmac_f32_e32 v123, v135, v135
	v_fmac_f32_e32 v124, v136, v136
	v_fmac_f32_e32 v125, v137, v137
	v_add_f32_e32 v122, v122, v123
	v_add_f32_e32 v123, v124, v125
	v_add_f32_e32 v122, v122, v123
	s_nop 0
	v_lshlrev_b32_e32 v123, 16, v126
	v_and_b32_e32 v124, 0xffff0000, v126
	v_and_b32_e32 v126, 0xffff0000, v127
	v_lshlrev_b32_e32 v125, 16, v127
	v_lshlrev_b32_e32 v127, 16, v128
	v_and_b32_e32 v128, 0xffff0000, v128
	v_lshlrev_b32_e32 v134, 16, v129
	v_and_b32_e32 v129, 0xffff0000, v129
	v_fmac_f32_e32 v124, s65, v119
	v_fmac_f32_e32 v126, s65, v121
	v_fmac_f32_e32 v123, s65, v118
	v_fmac_f32_e32 v125, s65, v120
	v_fmac_f32_e32 v127, s65, v114
	v_fmac_f32_e32 v128, s65, v115
	v_fmac_f32_e32 v134, s65, v116
	v_fmac_f32_e32 v129, s65, v117
	v_cvt_pk_bf16_f32 v116, v123, v124
	v_cvt_pk_bf16_f32 v117, v125, v126
	v_cvt_pk_bf16_f32 v118, v127, v128
	v_cvt_pk_bf16_f32 v119, v134, v129
	global_store_dwordx4 v[138:139], v[116:119], off offset:256
	v_and_b32_e32 v115, 0xffff0000, v116
	v_and_b32_e32 v121, 0xffff0000, v117
	v_and_b32_e32 v124, 0xffff0000, v118
	v_and_b32_e32 v126, 0xffff0000, v119
	v_lshlrev_b32_e32 v114, 16, v116
	v_lshlrev_b32_e32 v120, 16, v117
	v_lshlrev_b32_e32 v123, 16, v118
	v_lshlrev_b32_e32 v125, 16, v119
	v_mul_f32_e32 v115, v115, v115
	v_mul_f32_e32 v121, v121, v121
	v_mul_f32_e32 v124, v124, v124
	v_mul_f32_e32 v126, v126, v126
	v_fmac_f32_e32 v115, v114, v114
	v_fmac_f32_e32 v121, v120, v120
	v_fmac_f32_e32 v124, v123, v123
	v_fmac_f32_e32 v126, v125, v125
	v_add_f32_e32 v114, v115, v121
	v_add_f32_e32 v115, v124, v126
	v_add_f32_e32 v114, v114, v115
	v_add_f32_e32 v114, v122, v114
	ds_bpermute_b32 v115, v132, v114
	s_waitcnt lgkmcnt(0)
	v_add_f32_e32 v114, v114, v115
	ds_bpermute_b32 v115, v133, v114
	s_and_saveexec_b64 s[8:9], s[6:7]
	s_cbranch_execz .LBB1_777
	s_waitcnt lgkmcnt(0)
	v_add_f32_e32 v116, v114, v115
	s_lshl_b32 s20, s23, 2
	v_lshlrev_b64 v[114:115], 6, v[130:131]
	s_ashr_i32 s21, s20, 31
	v_lshl_add_u64 v[114:115], s[14:15], 0, v[114:115]
	v_lshl_add_u64 v[114:115], s[20:21], 2, v[114:115]
	s_lshl_b32 s74, s40, 2
	v_lshl_add_u64 v[114:115], v[114:115], 0, s[74:75]
	global_store_dword v[114:115], v116, off
; __device__ __forceinline__ unsigned cvt_pk_bf16(float lo, float hi) { unsigned r; asm volatile("v_cvt_pk_bf16_f32 %0, %1, %2" : "=v"(r) : "v"(lo), "v"(hi)); return r; }
;     __device__ __forceinline__ void operator()(const f32x4 (&acc)[2][2][4][2], const Unit& u, int wr, int wc, int fr, int fq, LAS unsigned char* lds) const {
;     ...
;         for (int ai = 0; ai < 2; ++ai)
; #pragma unroll
;             for (int m = 0; m < 4; ++m) { const int row = row0 + ai * HALF + m * 16; const size_t off = (size_t)row * D + col0;
;                 float rs = 1.0f; if (MODE == 1) rs = rstd_of4(rss_in, row, fq);
;                 float ss = 0.f;
; #pragma unroll
;                 for (int bj = 0; bj < 2; ++bj) { const size_t o = off + bj * HALF; const u32x4 bw = *(const u32x4*)(base + o);
;                     const float bs[8] = {bflo(bw.x), bfhi(bw.x), bflo(bw.y), bfhi(bw.y), bflo(bw.z), bfhi(bw.z), bflo(bw.w), bfhi(bw.w)};
;                     float hn[8];
;                     if (MODE == 0) {
; #pragma unroll
;                         for (int n = 0; n < 2; ++n)
; #pragma unroll
;                             for (int e = 0; e < 4; ++e) hn[4 * n + e] = bs[4 * n + e] + (acc[ai][bj][m][n][e] + bv[bj][n][e]) * scale;
;                     } else { const u32x4 pw = *(const u32x4*)(pp + o);
;                         const float pv[8] = {bflo(pw.x), bfhi(pw.x), bflo(pw.y), bfhi(pw.y), bflo(pw.z), bfhi(pw.z), bflo(pw.w), bfhi(pw.w)};
; #pragma unroll
;                         for (int n = 0; n < 2; ++n)
; #pragma unroll
;                             for (int e = 0; e < 4; ++e) hn[4 * n + e] = bs[4 * n + e] + fast_sigmoid(acc[ai][bj][m][n][e] * rs) * pv[4 * n + e]; }
;                     u32x4 w; w.x = cvt_pk_bf16(hn[0], hn[1]); w.y = cvt_pk_bf16(hn[2], hn[3]); w.z = cvt_pk_bf16(hn[4], hn[5]); w.w = cvt_pk_bf16(hn[6], hn[7]); *(u32x4*)(hb + o) = w;
;                     const float hr[8] = {bflo(w.x), bfhi(w.x), bflo(w.y), bfhi(w.y), bflo(w.z), bfhi(w.z), bflo(w.w), bfhi(w.w)};
;                     ss += ((hr[0] * hr[0] + hr[1] * hr[1]) + (hr[2] * hr[2] + hr[3] * hr[3])) + ((hr[4] * hr[4] + hr[5] * hr[5]) + (hr[6] * hr[6] + hr[7] * hr[7])); }
;                 ss += __shfl_xor(ss, 16); ss += __shfl_xor(ss, 32);
;                 if (fq == 0) rss_out[(size_t)row * 16 + u.pn * 4 + wc] = ss; }
.LBB1_777:
	s_or_b64 exec, exec, s[8:9]
	v_or_b32_e32 v114, 32, v158
	s_waitcnt lgkmcnt(0)
	v_ashrrev_i32_e32 v115, 31, v114
	v_lshlrev_b64 v[116:117], 10, v[114:115]
	v_lshl_add_u64 v[116:117], v[116:117], 0, v[156:157]
	v_lshlrev_b64 v[120:121], 1, v[116:117]
	v_lshl_add_u64 v[122:123], s[18:19], 0, v[120:121]
	v_mov_b32_e32 v116, v204
	v_mov_b32_e32 v117, v205
	v_mov_b32_e32 v118, v206
	v_mov_b32_e32 v119, v207
	v_add_f32_e32 v110, v110, v82
	v_add_f32_e32 v111, v111, v83
	v_add_f32_e32 v112, v112, v84
	v_add_f32_e32 v113, v113, v85
	v_add_f32_e32 v106, v106, v78
	v_add_f32_e32 v107, v107, v79
	v_add_f32_e32 v108, v108, v80
	v_add_f32_e32 v109, v109, v81
	v_lshl_add_u64 v[120:121], s[16:17], 0, v[120:121]
	v_add_f32_e32 v103, v103, v71
	v_add_f32_e32 v105, v105, v73
	v_add_f32_e32 v102, v102, v70
	v_add_f32_e32 v104, v104, v72
	v_add_f32_e32 v98, v98, v66
	v_add_f32_e32 v99, v99, v67
	v_add_f32_e32 v100, v100, v68
	v_add_f32_e32 v101, v101, v69
	s_nop 0
	v_lshlrev_b32_e32 v124, 16, v116
	v_and_b32_e32 v116, 0xffff0000, v116
	v_lshlrev_b32_e32 v125, 16, v117
	v_and_b32_e32 v117, 0xffff0000, v117
	v_lshlrev_b32_e32 v126, 16, v118
	v_and_b32_e32 v118, 0xffff0000, v118
	v_lshlrev_b32_e32 v127, 16, v119
	v_and_b32_e32 v119, 0xffff0000, v119
	v_fmac_f32_e32 v124, s65, v110
	v_fmac_f32_e32 v116, s65, v111
	v_fmac_f32_e32 v125, s65, v112
	v_fmac_f32_e32 v117, s65, v113
	v_fmac_f32_e32 v126, s65, v106
	v_fmac_f32_e32 v118, s65, v107
	v_fmac_f32_e32 v127, s65, v108
	v_fmac_f32_e32 v119, s65, v109
	v_cvt_pk_bf16_f32 v106, v124, v116
	v_cvt_pk_bf16_f32 v107, v125, v117
	v_cvt_pk_bf16_f32 v108, v126, v118
	v_cvt_pk_bf16_f32 v109, v127, v119
	global_store_dwordx4 v[120:121], v[106:109], off
	v_mov_b32_e32 v110, v208
	v_mov_b32_e32 v111, v209
	v_mov_b32_e32 v112, v210
	v_mov_b32_e32 v113, v211
	v_lshlrev_b32_e32 v116, 16, v106
	v_and_b32_e32 v106, 0xffff0000, v106
	v_lshlrev_b32_e32 v117, 16, v107
	v_and_b32_e32 v107, 0xffff0000, v107
	v_lshlrev_b32_e32 v118, 16, v108
	v_and_b32_e32 v108, 0xffff0000, v108
	v_lshlrev_b32_e32 v119, 16, v109
	v_and_b32_e32 v109, 0xffff0000, v109
	v_mul_f32_e32 v106, v106, v106
	v_mul_f32_e32 v107, v107, v107
	v_mul_f32_e32 v108, v108, v108
	v_mul_f32_e32 v109, v109, v109
	v_fmac_f32_e32 v106, v116, v116
	v_fmac_f32_e32 v107, v117, v117
	v_fmac_f32_e32 v108, v118, v118
	v_fmac_f32_e32 v109, v119, v119
	v_add_f32_e32 v106, v106, v107
	v_add_f32_e32 v107, v108, v109
	v_add_f32_e32 v106, v106, v107
	s_nop 0
	v_lshlrev_b32_e32 v107, 16, v110
	v_and_b32_e32 v108, 0xffff0000, v110
	v_and_b32_e32 v110, 0xffff0000, v111
	v_lshlrev_b32_e32 v109, 16, v111
	v_lshlrev_b32_e32 v111, 16, v112
	v_and_b32_e32 v112, 0xffff0000, v112
	v_lshlrev_b32_e32 v116, 16, v113
	v_and_b32_e32 v113, 0xffff0000, v113
	v_fmac_f32_e32 v108, s65, v103
	v_fmac_f32_e32 v110, s65, v105
	v_fmac_f32_e32 v107, s65, v102
	v_fmac_f32_e32 v109, s65, v104
	v_fmac_f32_e32 v111, s65, v98
	v_fmac_f32_e32 v112, s65, v99
	v_fmac_f32_e32 v116, s65, v100
	v_fmac_f32_e32 v113, s65, v101
	v_cvt_pk_bf16_f32 v100, v107, v108
	v_cvt_pk_bf16_f32 v101, v109, v110
	v_cvt_pk_bf16_f32 v102, v111, v112
	v_cvt_pk_bf16_f32 v103, v116, v113
	global_store_dwordx4 v[120:121], v[100:103], off offset:256
	v_and_b32_e32 v99, 0xffff0000, v100
	v_and_b32_e32 v105, 0xffff0000, v101
	v_and_b32_e32 v108, 0xffff0000, v102
	v_and_b32_e32 v110, 0xffff0000, v103
	v_lshlrev_b32_e32 v98, 16, v100
	v_lshlrev_b32_e32 v104, 16, v101
	v_lshlrev_b32_e32 v107, 16, v102
	v_lshlrev_b32_e32 v109, 16, v103
	v_mul_f32_e32 v99, v99, v99
	v_mul_f32_e32 v105, v105, v105
	v_mul_f32_e32 v108, v108, v108
	v_mul_f32_e32 v110, v110, v110
	v_fmac_f32_e32 v99, v98, v98
	v_fmac_f32_e32 v105, v104, v104
	v_fmac_f32_e32 v108, v107, v107
	v_fmac_f32_e32 v110, v109, v109
	v_add_f32_e32 v98, v99, v105
	v_add_f32_e32 v99, v108, v110
	v_add_f32_e32 v98, v98, v99
	v_add_f32_e32 v98, v106, v98
	ds_bpermute_b32 v99, v132, v98
	s_waitcnt lgkmcnt(0)
	v_add_f32_e32 v98, v98, v99
	ds_bpermute_b32 v99, v133, v98
	s_and_saveexec_b64 s[8:9], s[6:7]
	s_cbranch_execz .LBB1_779
	s_waitcnt lgkmcnt(0)
	v_add_f32_e32 v100, v98, v99
	s_lshl_b32 s20, s23, 2
	v_lshlrev_b64 v[98:99], 6, v[114:115]
	s_ashr_i32 s21, s20, 31
	v_lshl_add_u64 v[98:99], s[14:15], 0, v[98:99]
	v_lshl_add_u64 v[98:99], s[20:21], 2, v[98:99]
	s_lshl_b32 s74, s40, 2
	v_lshl_add_u64 v[98:99], v[98:99], 0, s[74:75]
	global_store_dword v[98:99], v100, off
; __device__ __forceinline__ unsigned cvt_pk_bf16(float lo, float hi) { unsigned r; asm volatile("v_cvt_pk_bf16_f32 %0, %1, %2" : "=v"(r) : "v"(lo), "v"(hi)); return r; }
;     __device__ __forceinline__ void operator()(const f32x4 (&acc)[2][2][4][2], const Unit& u, int wr, int wc, int fr, int fq, LAS unsigned char* lds) const {
;     ...
;         for (int ai = 0; ai < 2; ++ai)
; #pragma unroll
;             for (int m = 0; m < 4; ++m) { const int row = row0 + ai * HALF + m * 16; const size_t off = (size_t)row * D + col0;
;                 float rs = 1.0f; if (MODE == 1) rs = rstd_of4(rss_in, row, fq);
;                 float ss = 0.f;
; #pragma unroll
;                 for (int bj = 0; bj < 2; ++bj) { const size_t o = off + bj * HALF; const u32x4 bw = *(const u32x4*)(base + o);
;                     const float bs[8] = {bflo(bw.x), bfhi(bw.x), bflo(bw.y), bfhi(bw.y), bflo(bw.z), bfhi(bw.z), bflo(bw.w), bfhi(bw.w)};
;                     float hn[8];
;                     if (MODE == 0) {
; #pragma unroll
;                         for (int n = 0; n < 2; ++n)
; #pragma unroll
;                             for (int e = 0; e < 4; ++e) hn[4 * n + e] = bs[4 * n + e] + (acc[ai][bj][m][n][e] + bv[bj][n][e]) * scale;
;                     } else { const u32x4 pw = *(const u32x4*)(pp + o);
;                         const float pv[8] = {bflo(pw.x), bfhi(pw.x), bflo(pw.y), bfhi(pw.y), bflo(pw.z), bfhi(pw.z), bflo(pw.w), bfhi(pw.w)};
; #pragma unroll
;                         for (int n = 0; n < 2; ++n)
; #pragma unroll
;                             for (int e = 0; e < 4; ++e) hn[4 * n + e] = bs[4 * n + e] + fast_sigmoid(acc[ai][bj][m][n][e] * rs) * pv[4 * n + e]; }
;                     u32x4 w; w.x = cvt_pk_bf16(hn[0], hn[1]); w.y = cvt_pk_bf16(hn[2], hn[3]); w.z = cvt_pk_bf16(hn[4], hn[5]); w.w = cvt_pk_bf16(hn[6], hn[7]); *(u32x4*)(hb + o) = w;
;                     const float hr[8] = {bflo(w.x), bfhi(w.x), bflo(w.y), bfhi(w.y), bflo(w.z), bfhi(w.z), bflo(w.w), bfhi(w.w)};
;                     ss += ((hr[0] * hr[0] + hr[1] * hr[1]) + (hr[2] * hr[2] + hr[3] * hr[3])) + ((hr[4] * hr[4] + hr[5] * hr[5]) + (hr[6] * hr[6] + hr[7] * hr[7])); }
;                 ss += __shfl_xor(ss, 16); ss += __shfl_xor(ss, 32);
;                 if (fq == 0) rss_out[(size_t)row * 16 + u.pn * 4 + wc] = ss; }
.LBB1_779:
	s_or_b64 exec, exec, s[8:9]
	v_or_b32_e32 v98, 48, v158
	s_waitcnt lgkmcnt(0)
	v_ashrrev_i32_e32 v99, 31, v98
	v_lshlrev_b64 v[100:101], 10, v[98:99]
	v_lshl_add_u64 v[100:101], v[100:101], 0, v[156:157]
	v_lshlrev_b64 v[104:105], 1, v[100:101]
	v_lshl_add_u64 v[106:107], s[18:19], 0, v[104:105]
	v_mov_b32_e32 v100, v212
	v_mov_b32_e32 v101, v213
	v_mov_b32_e32 v102, v214
	v_mov_b32_e32 v103, v215
	v_add_f32_e32 v94, v94, v82
	v_add_f32_e32 v95, v95, v83
	v_add_f32_e32 v96, v96, v84
	v_add_f32_e32 v97, v97, v85
	v_add_f32_e32 v90, v90, v78
	v_add_f32_e32 v91, v91, v79
	v_add_f32_e32 v92, v92, v80
	v_add_f32_e32 v93, v93, v81
	v_lshl_add_u64 v[104:105], s[16:17], 0, v[104:105]
	v_add_f32_e32 v87, v87, v71
	v_add_f32_e32 v89, v89, v73
	v_add_f32_e32 v86, v86, v70
	v_add_f32_e32 v88, v88, v72
	v_add_f32_e32 v74, v74, v66
	v_add_f32_e32 v75, v75, v67
	v_add_f32_e32 v76, v76, v68
	v_add_f32_e32 v77, v77, v69
	s_nop 0
	v_lshlrev_b32_e32 v108, 16, v100
	v_and_b32_e32 v100, 0xffff0000, v100
	v_lshlrev_b32_e32 v109, 16, v101
	v_and_b32_e32 v101, 0xffff0000, v101
	v_lshlrev_b32_e32 v110, 16, v102
	v_and_b32_e32 v102, 0xffff0000, v102
	v_lshlrev_b32_e32 v111, 16, v103
	v_and_b32_e32 v103, 0xffff0000, v103
	v_fmac_f32_e32 v108, s65, v94
	v_fmac_f32_e32 v100, s65, v95
	v_fmac_f32_e32 v109, s65, v96
	v_fmac_f32_e32 v101, s65, v97
	v_fmac_f32_e32 v110, s65, v90
	v_fmac_f32_e32 v102, s65, v91
	v_fmac_f32_e32 v111, s65, v92
	v_fmac_f32_e32 v103, s65, v93
	v_cvt_pk_bf16_f32 v90, v108, v100
	v_cvt_pk_bf16_f32 v91, v109, v101
	v_cvt_pk_bf16_f32 v92, v110, v102
	v_cvt_pk_bf16_f32 v93, v111, v103
	global_store_dwordx4 v[104:105], v[90:93], off
	v_mov_b32_e32 v94, v216
	v_mov_b32_e32 v95, v217
	v_mov_b32_e32 v96, v218
	v_mov_b32_e32 v97, v219
	v_lshlrev_b32_e32 v100, 16, v90
	v_and_b32_e32 v90, 0xffff0000, v90
	v_lshlrev_b32_e32 v101, 16, v91
	v_and_b32_e32 v91, 0xffff0000, v91
	v_lshlrev_b32_e32 v102, 16, v92
	v_and_b32_e32 v92, 0xffff0000, v92
	v_lshlrev_b32_e32 v103, 16, v93
	v_and_b32_e32 v93, 0xffff0000, v93
	v_mul_f32_e32 v90, v90, v90
	v_mul_f32_e32 v91, v91, v91
	v_mul_f32_e32 v92, v92, v92
	v_mul_f32_e32 v93, v93, v93
	v_fmac_f32_e32 v90, v100, v100
	v_fmac_f32_e32 v91, v101, v101
	v_fmac_f32_e32 v92, v102, v102
	v_fmac_f32_e32 v93, v103, v103
	v_add_f32_e32 v90, v90, v91
	v_add_f32_e32 v91, v92, v93
	v_add_f32_e32 v90, v90, v91
	s_nop 0
	v_lshlrev_b32_e32 v91, 16, v94
	v_and_b32_e32 v92, 0xffff0000, v94
	v_and_b32_e32 v94, 0xffff0000, v95
	v_lshlrev_b32_e32 v93, 16, v95
	v_lshlrev_b32_e32 v95, 16, v96
	v_and_b32_e32 v96, 0xffff0000, v96
	v_lshlrev_b32_e32 v100, 16, v97
	v_and_b32_e32 v97, 0xffff0000, v97
	v_fmac_f32_e32 v92, s65, v87
	v_fmac_f32_e32 v94, s65, v89
	v_fmac_f32_e32 v91, s65, v86
	v_fmac_f32_e32 v93, s65, v88
	v_fmac_f32_e32 v95, s65, v74
	v_fmac_f32_e32 v96, s65, v75
	v_fmac_f32_e32 v100, s65, v76
	v_fmac_f32_e32 v97, s65, v77
	v_cvt_pk_bf16_f32 v86, v91, v92
	v_cvt_pk_bf16_f32 v87, v93, v94
	v_cvt_pk_bf16_f32 v88, v95, v96
	v_cvt_pk_bf16_f32 v89, v100, v97
	global_store_dwordx4 v[104:105], v[86:89], off offset:256
	v_and_b32_e32 v75, 0xffff0000, v86
	v_and_b32_e32 v77, 0xffff0000, v87
	v_and_b32_e32 v92, 0xffff0000, v88
	v_and_b32_e32 v94, 0xffff0000, v89
	v_lshlrev_b32_e32 v74, 16, v86
	v_lshlrev_b32_e32 v76, 16, v87
	v_lshlrev_b32_e32 v91, 16, v88
	v_lshlrev_b32_e32 v93, 16, v89
	v_mul_f32_e32 v75, v75, v75
	v_mul_f32_e32 v77, v77, v77
	v_mul_f32_e32 v92, v92, v92
	v_mul_f32_e32 v94, v94, v94
	v_fmac_f32_e32 v75, v74, v74
	v_fmac_f32_e32 v77, v76, v76
	v_fmac_f32_e32 v92, v91, v91
	v_fmac_f32_e32 v94, v93, v93
	v_add_f32_e32 v74, v75, v77
	v_add_f32_e32 v75, v92, v94
	v_add_f32_e32 v74, v74, v75
	v_add_f32_e32 v74, v90, v74
	ds_bpermute_b32 v75, v132, v74
	s_waitcnt lgkmcnt(0)
	v_add_f32_e32 v74, v74, v75
	ds_bpermute_b32 v75, v133, v74
	s_and_saveexec_b64 s[8:9], s[6:7]
	s_cbranch_execz .LBB1_781
	s_waitcnt lgkmcnt(0)
	v_add_f32_e32 v76, v74, v75
	s_lshl_b32 s20, s23, 2
	v_lshlrev_b64 v[74:75], 6, v[98:99]
	s_ashr_i32 s21, s20, 31
	v_lshl_add_u64 v[74:75], s[14:15], 0, v[74:75]
	v_lshl_add_u64 v[74:75], s[20:21], 2, v[74:75]
	s_lshl_b32 s74, s40, 2
	v_lshl_add_u64 v[74:75], v[74:75], 0, s[74:75]
	global_store_dword v[74:75], v76, off
.LBB1_781:
	s_or_b64 exec, exec, s[8:9]
	v_add_u32_e32 v74, 0x80, v158
	s_waitcnt lgkmcnt(0)
	v_ashrrev_i32_e32 v75, 31, v74
	v_lshlrev_b64 v[76:77], 10, v[74:75]
	v_lshl_add_u64 v[76:77], v[76:77], 0, v[156:157]
	v_lshlrev_b64 v[76:77], 1, v[76:77]
	v_lshl_add_u64 v[90:91], s[18:19], 0, v[76:77]
	global_load_dwordx4 v[86:89], v[90:91], off
	global_load_dwordx4 v[184:187], v[90:91], off offset:256
	v_add_u32_e32 v228, 0x90, v158
	v_ashrrev_i32_e32 v229, 31, v228
	v_lshlrev_b64 v[228:229], 10, v[228:229]
	v_lshl_add_u64 v[228:229], v[228:229], 0, v[156:157]
	v_lshlrev_b64 v[228:229], 1, v[228:229]
	v_lshl_add_u64 v[228:229], s[18:19], 0, v[228:229]
	global_load_dwordx4 v[188:191], v[228:229], off
	global_load_dwordx4 v[200:203], v[228:229], off offset:256
	v_add_u32_e32 v228, 0xa0, v158
	v_ashrrev_i32_e32 v229, 31, v228
	v_lshlrev_b64 v[228:229], 10, v[228:229]
	v_lshl_add_u64 v[228:229], v[228:229], 0, v[156:157]
	v_lshlrev_b64 v[228:229], 1, v[228:229]
	v_lshl_add_u64 v[228:229], s[18:19], 0, v[228:229]
	global_load_dwordx4 v[204:207], v[228:229], off
	global_load_dwordx4 v[208:211], v[228:229], off offset:256
	v_add_u32_e32 v228, 0xb0, v158
	v_ashrrev_i32_e32 v229, 31, v228
	v_lshlrev_b64 v[228:229], 10, v[228:229]
	v_lshl_add_u64 v[228:229], v[228:229], 0, v[156:157]
	v_lshlrev_b64 v[228:229], 1, v[228:229]
	v_lshl_add_u64 v[228:229], s[18:19], 0, v[228:229]
	global_load_dwordx4 v[212:215], v[228:229], off
	global_load_dwordx4 v[216:219], v[228:229], off offset:256
	v_add_f32_e32 v62, v62, v82
	v_add_f32_e32 v63, v63, v83
	v_add_f32_e32 v64, v64, v84
	v_add_f32_e32 v65, v65, v85
	v_add_f32_e32 v58, v58, v78
	v_add_f32_e32 v59, v59, v79
	v_add_f32_e32 v60, v60, v80
	v_add_f32_e32 v61, v61, v81
	v_lshl_add_u64 v[76:77], s[16:17], 0, v[76:77]
	v_add_f32_e32 v55, v55, v71
	v_add_f32_e32 v57, v57, v73
	v_add_f32_e32 v54, v54, v70
	v_add_f32_e32 v56, v56, v72
	v_add_f32_e32 v50, v50, v66
	v_add_f32_e32 v51, v51, v67
	v_add_f32_e32 v52, v52, v68
	v_add_f32_e32 v53, v53, v69
	s_waitcnt vmcnt(0)
; __device__ __forceinline__ unsigned cvt_pk_bf16(float lo, float hi) { unsigned r; asm volatile("v_cvt_pk_bf16_f32 %0, %1, %2" : "=v"(r) : "v"(lo), "v"(hi)); return r; }
;     __device__ __forceinline__ void operator()(const f32x4 (&acc)[2][2][4][2], const Unit& u, int wr, int wc, int fr, int fq, LAS unsigned char* lds) const {
;     ...
;         for (int ai = 0; ai < 2; ++ai)
; #pragma unroll
;             for (int m = 0; m < 4; ++m) { const int row = row0 + ai * HALF + m * 16; const size_t off = (size_t)row * D + col0;
;                 float rs = 1.0f; if (MODE == 1) rs = rstd_of4(rss_in, row, fq);
;                 float ss = 0.f;
; #pragma unroll
;                 for (int bj = 0; bj < 2; ++bj) { const size_t o = off + bj * HALF; const u32x4 bw = *(const u32x4*)(base + o);
;                     const float bs[8] = {bflo(bw.x), bfhi(bw.x), bflo(bw.y), bfhi(bw.y), bflo(bw.z), bfhi(bw.z), bflo(bw.w), bfhi(bw.w)};
;                     float hn[8];
;                     if (MODE == 0) {
; #pragma unroll
;                         for (int n = 0; n < 2; ++n)
; #pragma unroll
;                             for (int e = 0; e < 4; ++e) hn[4 * n + e] = bs[4 * n + e] + (acc[ai][bj][m][n][e] + bv[bj][n][e]) * scale;
;                     } else { const u32x4 pw = *(const u32x4*)(pp + o);
;                         const float pv[8] = {bflo(pw.x), bfhi(pw.x), bflo(pw.y), bfhi(pw.y), bflo(pw.z), bfhi(pw.z), bflo(pw.w), bfhi(pw.w)};
; #pragma unroll
;                         for (int n = 0; n < 2; ++n)
; #pragma unroll
;                             for (int e = 0; e < 4; ++e) hn[4 * n + e] = bs[4 * n + e] + fast_sigmoid(acc[ai][bj][m][n][e] * rs) * pv[4 * n + e]; }
;                     u32x4 w; w.x = cvt_pk_bf16(hn[0], hn[1]); w.y = cvt_pk_bf16(hn[2], hn[3]); w.z = cvt_pk_bf16(hn[4], hn[5]); w.w = cvt_pk_bf16(hn[6], hn[7]); *(u32x4*)(hb + o) = w;
;                     const float hr[8] = {bflo(w.x), bfhi(w.x), bflo(w.y), bfhi(w.y), bflo(w.z), bfhi(w.z), bflo(w.w), bfhi(w.w)};
;                     ss += ((hr[0] * hr[0] + hr[1] * hr[1]) + (hr[2] * hr[2] + hr[3] * hr[3])) + ((hr[4] * hr[4] + hr[5] * hr[5]) + (hr[6] * hr[6] + hr[7] * hr[7])); }
;                 ss += __shfl_xor(ss, 16); ss += __shfl_xor(ss, 32);
;                 if (fq == 0) rss_out[(size_t)row * 16 + u.pn * 4 + wc] = ss; }
	v_lshlrev_b32_e32 v92, 16, v86
	v_and_b32_e32 v86, 0xffff0000, v86
	v_lshlrev_b32_e32 v93, 16, v87
	v_and_b32_e32 v87, 0xffff0000, v87
	v_lshlrev_b32_e32 v94, 16, v88
	v_and_b32_e32 v88, 0xffff0000, v88
	v_lshlrev_b32_e32 v95, 16, v89
	v_and_b32_e32 v89, 0xffff0000, v89
	v_fmac_f32_e32 v92, s65, v62
	v_fmac_f32_e32 v86, s65, v63
	v_fmac_f32_e32 v93, s65, v64
	v_fmac_f32_e32 v87, s65, v65
	v_fmac_f32_e32 v94, s65, v58
	v_fmac_f32_e32 v88, s65, v59
	v_fmac_f32_e32 v95, s65, v60
	v_fmac_f32_e32 v89, s65, v61
	v_cvt_pk_bf16_f32 v58, v92, v86
	v_cvt_pk_bf16_f32 v59, v93, v87
	v_cvt_pk_bf16_f32 v60, v94, v88
	v_cvt_pk_bf16_f32 v61, v95, v89
	global_store_dwordx4 v[76:77], v[58:61], off
	v_mov_b32_e32 v62, v184
	v_mov_b32_e32 v63, v185
	v_mov_b32_e32 v64, v186
	v_mov_b32_e32 v65, v187
	v_lshlrev_b32_e32 v86, 16, v58
	v_and_b32_e32 v58, 0xffff0000, v58
	v_lshlrev_b32_e32 v87, 16, v59
	v_and_b32_e32 v59, 0xffff0000, v59
	v_lshlrev_b32_e32 v88, 16, v60
	v_and_b32_e32 v60, 0xffff0000, v60
	v_lshlrev_b32_e32 v89, 16, v61
	v_and_b32_e32 v61, 0xffff0000, v61
	v_mul_f32_e32 v58, v58, v58
	v_mul_f32_e32 v59, v59, v59
	v_mul_f32_e32 v60, v60, v60
	v_mul_f32_e32 v61, v61, v61
	v_fmac_f32_e32 v58, v86, v86
	v_fmac_f32_e32 v59, v87, v87
	v_fmac_f32_e32 v60, v88, v88
	v_fmac_f32_e32 v61, v89, v89
	v_add_f32_e32 v58, v58, v59
	v_add_f32_e32 v59, v60, v61
	v_add_f32_e32 v58, v58, v59
	s_nop 0
	v_lshlrev_b32_e32 v59, 16, v62
	v_and_b32_e32 v60, 0xffff0000, v62
	v_and_b32_e32 v62, 0xffff0000, v63
	v_lshlrev_b32_e32 v61, 16, v63
	v_lshlrev_b32_e32 v63, 16, v64
	v_and_b32_e32 v64, 0xffff0000, v64
	v_lshlrev_b32_e32 v86, 16, v65
	v_and_b32_e32 v65, 0xffff0000, v65
	v_fmac_f32_e32 v60, s65, v55
	v_fmac_f32_e32 v62, s65, v57
	v_fmac_f32_e32 v59, s65, v54
	v_fmac_f32_e32 v61, s65, v56
	v_fmac_f32_e32 v63, s65, v50
	v_fmac_f32_e32 v64, s65, v51
	v_fmac_f32_e32 v86, s65, v52
	v_fmac_f32_e32 v65, s65, v53
	v_cvt_pk_bf16_f32 v52, v59, v60
	v_cvt_pk_bf16_f32 v53, v61, v62
	v_cvt_pk_bf16_f32 v54, v63, v64
	v_cvt_pk_bf16_f32 v55, v86, v65
	global_store_dwordx4 v[76:77], v[52:55], off offset:256
	v_and_b32_e32 v51, 0xffff0000, v52
	v_and_b32_e32 v57, 0xffff0000, v53
	v_and_b32_e32 v60, 0xffff0000, v54
	v_and_b32_e32 v62, 0xffff0000, v55
	v_lshlrev_b32_e32 v50, 16, v52
	v_lshlrev_b32_e32 v56, 16, v53
	v_lshlrev_b32_e32 v59, 16, v54
	v_lshlrev_b32_e32 v61, 16, v55
	v_mul_f32_e32 v51, v51, v51
	v_mul_f32_e32 v57, v57, v57
	v_mul_f32_e32 v60, v60, v60
	v_mul_f32_e32 v62, v62, v62
	v_fmac_f32_e32 v51, v50, v50
	v_fmac_f32_e32 v57, v56, v56
	v_fmac_f32_e32 v60, v59, v59
	v_fmac_f32_e32 v62, v61, v61
	v_add_f32_e32 v50, v51, v57
	v_add_f32_e32 v51, v60, v62
	v_add_f32_e32 v50, v50, v51
	v_add_f32_e32 v50, v58, v50
	ds_bpermute_b32 v51, v132, v50
	s_waitcnt lgkmcnt(0)
	v_add_f32_e32 v50, v50, v51
	ds_bpermute_b32 v51, v133, v50
	s_and_saveexec_b64 s[8:9], s[6:7]
	s_cbranch_execz .LBB1_783
	s_waitcnt lgkmcnt(0)
	v_add_f32_e32 v52, v50, v51
	s_lshl_b32 s20, s23, 2
	v_lshlrev_b64 v[50:51], 6, v[74:75]
	s_ashr_i32 s21, s20, 31
	v_lshl_add_u64 v[50:51], s[14:15], 0, v[50:51]
	v_lshl_add_u64 v[50:51], s[20:21], 2, v[50:51]
	s_lshl_b32 s74, s40, 2
	v_lshl_add_u64 v[50:51], v[50:51], 0, s[74:75]
	global_store_dword v[50:51], v52, off
.LBB1_783:
	s_or_b64 exec, exec, s[8:9]
	v_add_u32_e32 v50, 0x90, v158
	s_waitcnt lgkmcnt(0)
	v_ashrrev_i32_e32 v51, 31, v50
	v_lshlrev_b64 v[52:53], 10, v[50:51]
	v_lshl_add_u64 v[52:53], v[52:53], 0, v[156:157]
	v_lshlrev_b64 v[56:57], 1, v[52:53]
	v_lshl_add_u64 v[58:59], s[18:19], 0, v[56:57]
	v_mov_b32_e32 v52, v188
	v_mov_b32_e32 v53, v189
	v_mov_b32_e32 v54, v190
	v_mov_b32_e32 v55, v191
	v_add_f32_e32 v46, v46, v82
	v_add_f32_e32 v47, v47, v83
	v_add_f32_e32 v48, v48, v84
	v_add_f32_e32 v49, v49, v85
	v_add_f32_e32 v42, v42, v78
	v_add_f32_e32 v43, v43, v79
	v_add_f32_e32 v44, v44, v80
	v_add_f32_e32 v45, v45, v81
	v_lshl_add_u64 v[56:57], s[16:17], 0, v[56:57]
	v_add_f32_e32 v39, v39, v71
	v_add_f32_e32 v41, v41, v73
	v_add_f32_e32 v38, v38, v70
	v_add_f32_e32 v40, v40, v72
	v_add_f32_e32 v34, v34, v66
	v_add_f32_e32 v35, v35, v67
	v_add_f32_e32 v36, v36, v68
	v_add_f32_e32 v37, v37, v69
	s_nop 0
	v_lshlrev_b32_e32 v60, 16, v52
	v_and_b32_e32 v52, 0xffff0000, v52
	v_lshlrev_b32_e32 v61, 16, v53
	v_and_b32_e32 v53, 0xffff0000, v53
	v_lshlrev_b32_e32 v62, 16, v54
	v_and_b32_e32 v54, 0xffff0000, v54
	v_lshlrev_b32_e32 v63, 16, v55
	v_and_b32_e32 v55, 0xffff0000, v55
	v_fmac_f32_e32 v60, s65, v46
	v_fmac_f32_e32 v52, s65, v47
	v_fmac_f32_e32 v61, s65, v48
	v_fmac_f32_e32 v53, s65, v49
	v_fmac_f32_e32 v62, s65, v42
	v_fmac_f32_e32 v54, s65, v43
	v_fmac_f32_e32 v63, s65, v44
	v_fmac_f32_e32 v55, s65, v45
	v_cvt_pk_bf16_f32 v42, v60, v52
	v_cvt_pk_bf16_f32 v43, v61, v53
	v_cvt_pk_bf16_f32 v44, v62, v54
	v_cvt_pk_bf16_f32 v45, v63, v55
	global_store_dwordx4 v[56:57], v[42:45], off
	v_mov_b32_e32 v46, v200
	v_mov_b32_e32 v47, v201
	v_mov_b32_e32 v48, v202
	v_mov_b32_e32 v49, v203
	v_lshlrev_b32_e32 v52, 16, v42
	v_and_b32_e32 v42, 0xffff0000, v42
	v_lshlrev_b32_e32 v53, 16, v43
	v_and_b32_e32 v43, 0xffff0000, v43
	v_lshlrev_b32_e32 v54, 16, v44
	v_and_b32_e32 v44, 0xffff0000, v44
	v_lshlrev_b32_e32 v55, 16, v45
	v_and_b32_e32 v45, 0xffff0000, v45
	v_mul_f32_e32 v42, v42, v42
	v_mul_f32_e32 v43, v43, v43
	v_mul_f32_e32 v44, v44, v44
	v_mul_f32_e32 v45, v45, v45
	v_fmac_f32_e32 v42, v52, v52
	v_fmac_f32_e32 v43, v53, v53
	v_fmac_f32_e32 v44, v54, v54
	v_fmac_f32_e32 v45, v55, v55
	v_add_f32_e32 v42, v42, v43
	v_add_f32_e32 v43, v44, v45
	v_add_f32_e32 v42, v42, v43
	s_nop 0
	v_lshlrev_b32_e32 v43, 16, v46
	v_and_b32_e32 v44, 0xffff0000, v46
	v_and_b32_e32 v46, 0xffff0000, v47
	v_lshlrev_b32_e32 v45, 16, v47
	v_lshlrev_b32_e32 v47, 16, v48
	v_and_b32_e32 v48, 0xffff0000, v48
	v_lshlrev_b32_e32 v52, 16, v49
	v_and_b32_e32 v49, 0xffff0000, v49
	v_fmac_f32_e32 v44, s65, v39
	v_fmac_f32_e32 v46, s65, v41
	v_fmac_f32_e32 v43, s65, v38
	v_fmac_f32_e32 v45, s65, v40
	v_fmac_f32_e32 v47, s65, v34
	v_fmac_f32_e32 v48, s65, v35
	v_fmac_f32_e32 v52, s65, v36
	v_fmac_f32_e32 v49, s65, v37
	v_cvt_pk_bf16_f32 v36, v43, v44
	v_cvt_pk_bf16_f32 v37, v45, v46
	v_cvt_pk_bf16_f32 v38, v47, v48
	v_cvt_pk_bf16_f32 v39, v52, v49
	global_store_dwordx4 v[56:57], v[36:39], off offset:256
	v_and_b32_e32 v35, 0xffff0000, v36
	v_and_b32_e32 v41, 0xffff0000, v37
	v_and_b32_e32 v44, 0xffff0000, v38
	v_and_b32_e32 v46, 0xffff0000, v39
	v_lshlrev_b32_e32 v34, 16, v36
	v_lshlrev_b32_e32 v40, 16, v37
	v_lshlrev_b32_e32 v43, 16, v38
	v_lshlrev_b32_e32 v45, 16, v39
	v_mul_f32_e32 v35, v35, v35
	v_mul_f32_e32 v41, v41, v41
	v_mul_f32_e32 v44, v44, v44
	v_mul_f32_e32 v46, v46, v46
	v_fmac_f32_e32 v35, v34, v34
	v_fmac_f32_e32 v41, v40, v40
	v_fmac_f32_e32 v44, v43, v43
	v_fmac_f32_e32 v46, v45, v45
	v_add_f32_e32 v34, v35, v41
	v_add_f32_e32 v35, v44, v46
	v_add_f32_e32 v34, v34, v35
	v_add_f32_e32 v34, v42, v34
	ds_bpermute_b32 v35, v132, v34
	s_waitcnt lgkmcnt(0)
; __device__ __forceinline__ unsigned cvt_pk_bf16(float lo, float hi) { unsigned r; asm volatile("v_cvt_pk_bf16_f32 %0, %1, %2" : "=v"(r) : "v"(lo), "v"(hi)); return r; }
; __device__ __forceinline__ float bflo(unsigned w) { return __uint_as_float(w << 16); }
;     __device__ __forceinline__ void operator()(const f32x4 (&acc)[2][2][4][2], const Unit& u, int wr, int wc, int fr, int fq, LAS unsigned char* lds) const {
;     ...
;             for (int m = 0; m < 4; ++m) { const int row = row0 + ai * HALF + m * 16; const size_t off = (size_t)row * D + col0;
;                 float rs = 1.0f; if (MODE == 1) rs = rstd_of4(rss_in, row, fq);
;                 float ss = 0.f;
; #pragma unroll
;                 for (int bj = 0; bj < 2; ++bj) { const size_t o = off + bj * HALF; const u32x4 bw = *(const u32x4*)(base + o);
;                     const float bs[8] = {bflo(bw.x), bfhi(bw.x), bflo(bw.y), bfhi(bw.y), bflo(bw.z), bfhi(bw.z), bflo(bw.w), bfhi(bw.w)};
;                     float hn[8];
;                     if (MODE == 0) {
; #pragma unroll
;                         for (int n = 0; n < 2; ++n)
; #pragma unroll
;                             for (int e = 0; e < 4; ++e) hn[4 * n + e] = bs[4 * n + e] + (acc[ai][bj][m][n][e] + bv[bj][n][e]) * scale;
;                     } else { const u32x4 pw = *(const u32x4*)(pp + o);
;                         const float pv[8] = {bflo(pw.x), bfhi(pw.x), bflo(pw.y), bfhi(pw.y), bflo(pw.z), bfhi(pw.z), bflo(pw.w), bfhi(pw.w)};
; #pragma unroll
;                         for (int n = 0; n < 2; ++n)
; #pragma unroll
;                             for (int e = 0; e < 4; ++e) hn[4 * n + e] = bs[4 * n + e] + fast_sigmoid(acc[ai][bj][m][n][e] * rs) * pv[4 * n + e]; }
;                     u32x4 w; w.x = cvt_pk_bf16(hn[0], hn[1]); w.y = cvt_pk_bf16(hn[2], hn[3]); w.z = cvt_pk_bf16(hn[4], hn[5]); w.w = cvt_pk_bf16(hn[6], hn[7]); *(u32x4*)(hb + o) = w;
;                     const float hr[8] = {bflo(w.x), bfhi(w.x), bflo(w.y), bfhi(w.y), bflo(w.z), bfhi(w.z), bflo(w.w), bfhi(w.w)};
;                     ss += ((hr[0] * hr[0] + hr[1] * hr[1]) + (hr[2] * hr[2] + hr[3] * hr[3])) + ((hr[4] * hr[4] + hr[5] * hr[5]) + (hr[6] * hr[6] + hr[7] * hr[7])); }
;                 ss += __shfl_xor(ss, 16); ss += __shfl_xor(ss, 32);
;                 if (fq == 0) rss_out[(size_t)row * 16 + u.pn * 4 + wc] = ss; }
	v_add_f32_e32 v34, v34, v35
	ds_bpermute_b32 v35, v133, v34
	s_and_saveexec_b64 s[8:9], s[6:7]
	s_cbranch_execz .LBB1_785
	s_waitcnt lgkmcnt(0)
	v_add_f32_e32 v36, v34, v35
	s_lshl_b32 s20, s23, 2
	v_lshlrev_b64 v[34:35], 6, v[50:51]
	s_ashr_i32 s21, s20, 31
	v_lshl_add_u64 v[34:35], s[14:15], 0, v[34:35]
	v_lshl_add_u64 v[34:35], s[20:21], 2, v[34:35]
	s_lshl_b32 s74, s40, 2
	v_lshl_add_u64 v[34:35], v[34:35], 0, s[74:75]
	global_store_dword v[34:35], v36, off
.LBB1_785:
	s_or_b64 exec, exec, s[8:9]
	v_add_u32_e32 v34, 0xa0, v158
	s_waitcnt lgkmcnt(0)
	v_ashrrev_i32_e32 v35, 31, v34
	v_lshlrev_b64 v[36:37], 10, v[34:35]
	v_lshl_add_u64 v[36:37], v[36:37], 0, v[156:157]
	v_lshlrev_b64 v[40:41], 1, v[36:37]
	v_lshl_add_u64 v[42:43], s[18:19], 0, v[40:41]
	v_mov_b32_e32 v36, v204
	v_mov_b32_e32 v37, v205
	v_mov_b32_e32 v38, v206
	v_mov_b32_e32 v39, v207
	v_add_f32_e32 v30, v30, v82
	v_add_f32_e32 v31, v31, v83
	v_add_f32_e32 v32, v32, v84
	v_add_f32_e32 v33, v33, v85
	v_add_f32_e32 v26, v26, v78
	v_add_f32_e32 v27, v27, v79
	v_add_f32_e32 v28, v28, v80
	v_add_f32_e32 v29, v29, v81
	v_lshl_add_u64 v[40:41], s[16:17], 0, v[40:41]
	v_add_f32_e32 v23, v23, v71
	v_add_f32_e32 v25, v25, v73
	v_add_f32_e32 v22, v22, v70
	v_add_f32_e32 v24, v24, v72
	v_add_f32_e32 v18, v18, v66
	v_add_f32_e32 v19, v19, v67
	v_add_f32_e32 v20, v20, v68
	v_add_f32_e32 v21, v21, v69
	s_nop 0
	v_lshlrev_b32_e32 v44, 16, v36
	v_and_b32_e32 v36, 0xffff0000, v36
	v_lshlrev_b32_e32 v45, 16, v37
	v_and_b32_e32 v37, 0xffff0000, v37
	v_lshlrev_b32_e32 v46, 16, v38
	v_and_b32_e32 v38, 0xffff0000, v38
	v_lshlrev_b32_e32 v47, 16, v39
	v_and_b32_e32 v39, 0xffff0000, v39
	v_fmac_f32_e32 v44, s65, v30
	v_fmac_f32_e32 v36, s65, v31
	v_fmac_f32_e32 v45, s65, v32
	v_fmac_f32_e32 v37, s65, v33
	v_fmac_f32_e32 v46, s65, v26
	v_fmac_f32_e32 v38, s65, v27
	v_fmac_f32_e32 v47, s65, v28
	v_fmac_f32_e32 v39, s65, v29
	v_cvt_pk_bf16_f32 v26, v44, v36
	v_cvt_pk_bf16_f32 v27, v45, v37
	v_cvt_pk_bf16_f32 v28, v46, v38
	v_cvt_pk_bf16_f32 v29, v47, v39
	global_store_dwordx4 v[40:41], v[26:29], off
	v_mov_b32_e32 v30, v208
	v_mov_b32_e32 v31, v209
	v_mov_b32_e32 v32, v210
	v_mov_b32_e32 v33, v211
	v_lshlrev_b32_e32 v36, 16, v26
	v_and_b32_e32 v26, 0xffff0000, v26
	v_lshlrev_b32_e32 v37, 16, v27
	v_and_b32_e32 v27, 0xffff0000, v27
	v_lshlrev_b32_e32 v38, 16, v28
	v_and_b32_e32 v28, 0xffff0000, v28
	v_lshlrev_b32_e32 v39, 16, v29
	v_and_b32_e32 v29, 0xffff0000, v29
	v_mul_f32_e32 v26, v26, v26
	v_mul_f32_e32 v27, v27, v27
	v_mul_f32_e32 v28, v28, v28
	v_mul_f32_e32 v29, v29, v29
	v_fmac_f32_e32 v26, v36, v36
	v_fmac_f32_e32 v27, v37, v37
	v_fmac_f32_e32 v28, v38, v38
	v_fmac_f32_e32 v29, v39, v39
	v_add_f32_e32 v26, v26, v27
	v_add_f32_e32 v27, v28, v29
	v_add_f32_e32 v26, v26, v27
	s_nop 0
	v_lshlrev_b32_e32 v27, 16, v30
	v_and_b32_e32 v28, 0xffff0000, v30
	v_and_b32_e32 v30, 0xffff0000, v31
	v_lshlrev_b32_e32 v29, 16, v31
	v_lshlrev_b32_e32 v31, 16, v32
	v_and_b32_e32 v32, 0xffff0000, v32
	v_lshlrev_b32_e32 v36, 16, v33
	v_and_b32_e32 v33, 0xffff0000, v33
	v_fmac_f32_e32 v28, s65, v23
	v_fmac_f32_e32 v30, s65, v25
	v_fmac_f32_e32 v27, s65, v22
	v_fmac_f32_e32 v29, s65, v24
	v_fmac_f32_e32 v31, s65, v18
	v_fmac_f32_e32 v32, s65, v19
	v_fmac_f32_e32 v36, s65, v20
	v_fmac_f32_e32 v33, s65, v21
	v_cvt_pk_bf16_f32 v20, v27, v28
	v_cvt_pk_bf16_f32 v21, v29, v30
	v_cvt_pk_bf16_f32 v22, v31, v32
	v_cvt_pk_bf16_f32 v23, v36, v33
	global_store_dwordx4 v[40:41], v[20:23], off offset:256
	v_and_b32_e32 v19, 0xffff0000, v20
	v_and_b32_e32 v25, 0xffff0000, v21
	v_and_b32_e32 v28, 0xffff0000, v22
	v_and_b32_e32 v30, 0xffff0000, v23
	v_lshlrev_b32_e32 v18, 16, v20
	v_lshlrev_b32_e32 v24, 16, v21
	v_lshlrev_b32_e32 v27, 16, v22
	v_lshlrev_b32_e32 v29, 16, v23
	v_mul_f32_e32 v19, v19, v19
	v_mul_f32_e32 v25, v25, v25
	v_mul_f32_e32 v28, v28, v28
	v_mul_f32_e32 v30, v30, v30
	v_fmac_f32_e32 v19, v18, v18
	v_fmac_f32_e32 v25, v24, v24
	v_fmac_f32_e32 v28, v27, v27
	v_fmac_f32_e32 v30, v29, v29
	v_add_f32_e32 v18, v19, v25
	v_add_f32_e32 v19, v28, v30
	v_add_f32_e32 v18, v18, v19
	v_add_f32_e32 v18, v26, v18
	ds_bpermute_b32 v19, v132, v18
	s_waitcnt lgkmcnt(0)
	v_add_f32_e32 v18, v18, v19
	ds_bpermute_b32 v19, v133, v18
	s_and_saveexec_b64 s[8:9], s[6:7]
	s_cbranch_execz .LBB1_787
	s_waitcnt lgkmcnt(0)
	v_add_f32_e32 v20, v18, v19
	s_lshl_b32 s20, s23, 2
	v_lshlrev_b64 v[18:19], 6, v[34:35]
	s_ashr_i32 s21, s20, 31
	v_lshl_add_u64 v[18:19], s[14:15], 0, v[18:19]
	v_lshl_add_u64 v[18:19], s[20:21], 2, v[18:19]
	s_lshl_b32 s74, s40, 2
	v_lshl_add_u64 v[18:19], v[18:19], 0, s[74:75]
	global_store_dword v[18:19], v20, off
; __device__ __forceinline__ unsigned cvt_pk_bf16(float lo, float hi) { unsigned r; asm volatile("v_cvt_pk_bf16_f32 %0, %1, %2" : "=v"(r) : "v"(lo), "v"(hi)); return r; }
; __device__ __forceinline__ float bflo(unsigned w) { return __uint_as_float(w << 16); }
;     __device__ __forceinline__ void operator()(const f32x4 (&acc)[2][2][4][2], const Unit& u, int wr, int wc, int fr, int fq, LAS unsigned char* lds) const {
;     ...
;             for (int m = 0; m < 4; ++m) { const int row = row0 + ai * HALF + m * 16; const size_t off = (size_t)row * D + col0;
;                 float rs = 1.0f; if (MODE == 1) rs = rstd_of4(rss_in, row, fq);
;                 float ss = 0.f;
; #pragma unroll
;                 for (int bj = 0; bj < 2; ++bj) { const size_t o = off + bj * HALF; const u32x4 bw = *(const u32x4*)(base + o);
;                     const float bs[8] = {bflo(bw.x), bfhi(bw.x), bflo(bw.y), bfhi(bw.y), bflo(bw.z), bfhi(bw.z), bflo(bw.w), bfhi(bw.w)};
;                     float hn[8];
;                     if (MODE == 0) {
; #pragma unroll
;                         for (int n = 0; n < 2; ++n)
; #pragma unroll
;                             for (int e = 0; e < 4; ++e) hn[4 * n + e] = bs[4 * n + e] + (acc[ai][bj][m][n][e] + bv[bj][n][e]) * scale;
;                     } else { const u32x4 pw = *(const u32x4*)(pp + o);
;                         const float pv[8] = {bflo(pw.x), bfhi(pw.x), bflo(pw.y), bfhi(pw.y), bflo(pw.z), bfhi(pw.z), bflo(pw.w), bfhi(pw.w)};
; #pragma unroll
;                         for (int n = 0; n < 2; ++n)
; #pragma unroll
;                             for (int e = 0; e < 4; ++e) hn[4 * n + e] = bs[4 * n + e] + fast_sigmoid(acc[ai][bj][m][n][e] * rs) * pv[4 * n + e]; }
;                     u32x4 w; w.x = cvt_pk_bf16(hn[0], hn[1]); w.y = cvt_pk_bf16(hn[2], hn[3]); w.z = cvt_pk_bf16(hn[4], hn[5]); w.w = cvt_pk_bf16(hn[6], hn[7]); *(u32x4*)(hb + o) = w;
;                     const float hr[8] = {bflo(w.x), bfhi(w.x), bflo(w.y), bfhi(w.y), bflo(w.z), bfhi(w.z), bflo(w.w), bfhi(w.w)};
;                     ss += ((hr[0] * hr[0] + hr[1] * hr[1]) + (hr[2] * hr[2] + hr[3] * hr[3])) + ((hr[4] * hr[4] + hr[5] * hr[5]) + (hr[6] * hr[6] + hr[7] * hr[7])); }
;                 ss += __shfl_xor(ss, 16); ss += __shfl_xor(ss, 32);
;                 if (fq == 0) rss_out[(size_t)row * 16 + u.pn * 4 + wc] = ss; }
.LBB1_787:
	s_or_b64 exec, exec, s[8:9]
	v_add_u32_e32 v18, 0xb0, v158
	s_waitcnt lgkmcnt(0)
	v_ashrrev_i32_e32 v19, 31, v18
	v_lshlrev_b64 v[20:21], 10, v[18:19]
	v_lshl_add_u64 v[20:21], v[20:21], 0, v[156:157]
	v_lshlrev_b64 v[24:25], 1, v[20:21]
	v_lshl_add_u64 v[26:27], s[18:19], 0, v[24:25]
	v_mov_b32_e32 v20, v212
	v_mov_b32_e32 v21, v213
	v_mov_b32_e32 v22, v214
	v_mov_b32_e32 v23, v215
	v_add_f32_e32 v14, v14, v82
	v_add_f32_e32 v15, v15, v83
	v_add_f32_e32 v16, v16, v84
	v_add_f32_e32 v17, v17, v85
	v_add_f32_e32 v10, v10, v78
	v_add_f32_e32 v11, v11, v79
	v_add_f32_e32 v12, v12, v80
	v_add_f32_e32 v13, v13, v81
	v_lshl_add_u64 v[24:25], s[16:17], 0, v[24:25]
	v_add_f32_e32 v7, v7, v71
	v_add_f32_e32 v9, v9, v73
	v_add_f32_e32 v6, v6, v70
	v_add_f32_e32 v8, v8, v72
	v_add_f32_e32 v0, v0, v66
	v_add_f32_e32 v1, v1, v67
	v_add_f32_e32 v2, v2, v68
	v_add_f32_e32 v3, v3, v69
	s_nop 0
	v_lshlrev_b32_e32 v28, 16, v20
	v_and_b32_e32 v20, 0xffff0000, v20
	v_lshlrev_b32_e32 v29, 16, v21
	v_and_b32_e32 v21, 0xffff0000, v21
	v_lshlrev_b32_e32 v30, 16, v22
	v_and_b32_e32 v22, 0xffff0000, v22
	v_lshlrev_b32_e32 v31, 16, v23
	v_and_b32_e32 v23, 0xffff0000, v23
	v_fmac_f32_e32 v28, s65, v14
	v_fmac_f32_e32 v20, s65, v15
	v_fmac_f32_e32 v29, s65, v16
	v_fmac_f32_e32 v21, s65, v17
	v_fmac_f32_e32 v30, s65, v10
	v_fmac_f32_e32 v22, s65, v11
	v_fmac_f32_e32 v31, s65, v12
	v_fmac_f32_e32 v23, s65, v13
	v_cvt_pk_bf16_f32 v10, v28, v20
	v_cvt_pk_bf16_f32 v11, v29, v21
	v_cvt_pk_bf16_f32 v12, v30, v22
	v_cvt_pk_bf16_f32 v13, v31, v23
	global_store_dwordx4 v[24:25], v[10:13], off
	v_mov_b32_e32 v14, v216
	v_mov_b32_e32 v15, v217
	v_mov_b32_e32 v16, v218
	v_mov_b32_e32 v17, v219
	v_lshlrev_b32_e32 v20, 16, v10
	v_and_b32_e32 v10, 0xffff0000, v10
	v_lshlrev_b32_e32 v21, 16, v11
	v_and_b32_e32 v11, 0xffff0000, v11
	v_lshlrev_b32_e32 v22, 16, v12
	v_and_b32_e32 v12, 0xffff0000, v12
	v_lshlrev_b32_e32 v23, 16, v13
	v_and_b32_e32 v13, 0xffff0000, v13
	v_mul_f32_e32 v10, v10, v10
	v_mul_f32_e32 v11, v11, v11
	v_mul_f32_e32 v12, v12, v12
	v_mul_f32_e32 v13, v13, v13
	v_fmac_f32_e32 v10, v20, v20
	v_fmac_f32_e32 v11, v21, v21
	v_fmac_f32_e32 v12, v22, v22
	v_fmac_f32_e32 v13, v23, v23
	v_add_f32_e32 v10, v10, v11
	v_add_f32_e32 v11, v12, v13
	v_add_f32_e32 v10, v10, v11
	s_nop 0
	v_lshlrev_b32_e32 v11, 16, v14
	v_and_b32_e32 v12, 0xffff0000, v14
	v_and_b32_e32 v14, 0xffff0000, v15
	v_lshlrev_b32_e32 v13, 16, v15
	v_lshlrev_b32_e32 v15, 16, v16
	v_and_b32_e32 v16, 0xffff0000, v16
	v_lshlrev_b32_e32 v20, 16, v17
	v_and_b32_e32 v17, 0xffff0000, v17
	v_fmac_f32_e32 v12, s65, v7
	v_fmac_f32_e32 v14, s65, v9
	v_fmac_f32_e32 v11, s65, v6
	v_fmac_f32_e32 v13, s65, v8
	v_fmac_f32_e32 v15, s65, v0
	v_fmac_f32_e32 v16, s65, v1
	v_fmac_f32_e32 v20, s65, v2
	v_fmac_f32_e32 v17, s65, v3
	v_cvt_pk_bf16_f32 v6, v11, v12
	v_cvt_pk_bf16_f32 v7, v13, v14
	v_cvt_pk_bf16_f32 v8, v15, v16
	v_cvt_pk_bf16_f32 v9, v20, v17
	global_store_dwordx4 v[24:25], v[6:9], off offset:256
	v_and_b32_e32 v1, 0xffff0000, v6
	v_and_b32_e32 v3, 0xffff0000, v7
	v_and_b32_e32 v12, 0xffff0000, v8
	v_and_b32_e32 v14, 0xffff0000, v9
	v_lshlrev_b32_e32 v0, 16, v6
	v_lshlrev_b32_e32 v2, 16, v7
	v_lshlrev_b32_e32 v11, 16, v8
	v_lshlrev_b32_e32 v13, 16, v9
	v_mul_f32_e32 v1, v1, v1
	v_mul_f32_e32 v3, v3, v3
	v_mul_f32_e32 v12, v12, v12
	v_mul_f32_e32 v14, v14, v14
	v_fmac_f32_e32 v1, v0, v0
	v_fmac_f32_e32 v3, v2, v2
	v_fmac_f32_e32 v12, v11, v11
	v_fmac_f32_e32 v14, v13, v13
	v_add_f32_e32 v0, v1, v3
	v_add_f32_e32 v1, v12, v14
	v_add_f32_e32 v0, v0, v1
	v_add_f32_e32 v0, v10, v0
	ds_bpermute_b32 v1, v132, v0
	s_waitcnt lgkmcnt(0)
	v_add_f32_e32 v0, v0, v1
	ds_bpermute_b32 v1, v133, v0
	s_and_saveexec_b64 s[8:9], s[6:7]
	s_cbranch_execz .LBB1_756
	s_waitcnt lgkmcnt(0)
	v_add_f32_e32 v2, v0, v1
	s_lshl_b32 s16, s23, 2
	v_lshlrev_b64 v[0:1], 6, v[18:19]
	s_ashr_i32 s17, s16, 31
	v_lshl_add_u64 v[0:1], s[14:15], 0, v[0:1]
	v_lshl_add_u64 v[0:1], s[16:17], 2, v[0:1]
	s_lshl_b32 s74, s40, 2
	v_lshl_add_u64 v[0:1], v[0:1], 0, s[74:75]
	global_store_dword v[0:1], v2, off
	s_branch .LBB1_756

;     __device__ __forceinline__ void operator()(const f32x4 (&acc)[2][2][4][2], const Unit& u, int wr, int wc, int fr, int fq, LAS unsigned char* lds) const {
;     ...
;         const int row0 = u.pm * BM + wr * 64 + fr, col0 = u.pn * BM + wc * 32 + 8 * fq;
;         f32x4 bv[2][2];
; #pragma unroll
;         for (int bj = 0; bj < 2; ++bj)
; #pragma unroll
;             for (int n = 0; n < 2; ++n) bv[bj][n] = (MODE == 0 && bias) ? *(const f32x4*)(bias + col0 + bj * HALF + 4 * n) : (f32x4){0.f, 0.f, 0.f, 0.f};
; #pragma unroll
;         for (int ai = 0; ai < 2; ++ai)
; #pragma unroll
;             for (int m = 0; m < 4; ++m) { const int row = row0 + ai * HALF + m * 16; const size_t off = (size_t)row * D + col0;
;                 float rs = 1.0f; if (MODE == 1) rs = rstd_of4(rss_in, row, fq);
;                 float ss = 0.f;
; #pragma unroll
;                 for (int bj = 0; bj < 2; ++bj) { const size_t o = off + bj * HALF; const u32x4 bw = *(const u32x4*)(base + o);
;                     const float bs[8] = {bflo(bw.x), bfhi(bw.x), bflo(bw.y), bfhi(bw.y), bflo(bw.z), bfhi(bw.z), bflo(bw.w), bfhi(bw.w)};
;                     float hn[8];
;                     if (MODE == 0) {
; #pragma unroll
;                         for (int n = 0; n < 2; ++n)
; #pragma unroll
;                             for (int e = 0; e < 4; ++e) hn[4 * n + e] = bs[4 * n + e] + (acc[ai][bj][m][n][e] + bv[bj][n][e]) * scale;
;                     } else { const u32x4 pw = *(const u32x4*)(pp + o);
;                         const float pv[8] = {bflo(pw.x), bfhi(pw.x), bflo(pw.y), bfhi(pw.y), bflo(pw.z), bfhi(pw.z), bflo(pw.w), bfhi(pw.w)};
; #pragma unroll
;                         for (int n = 0; n < 2; ++n)
; #pragma unroll
;                             for (int e = 0; e < 4; ++e) hn[4 * n + e] = bs[4 * n + e] + fast_sigmoid(acc[ai][bj][m][n][e] * rs) * pv[4 * n + e]; }
;                     u32x4 w; w.x = cvt_pk_bf16(hn[0], hn[1]); w.y = cvt_pk_bf16(hn[2], hn[3]); w.z = cvt_pk_bf16(hn[4], hn[5]); w.w = cvt_pk_bf16(hn[6], hn[7]); *(u32x4*)(hb + o) = w;
;                     const float hr[8] = {bflo(w.x), bfhi(w.x), bflo(w.y), bfhi(w.y), bflo(w.z), bfhi(w.z), bflo(w.w), bfhi(w.w)};
;                     ss += ((hr[0] * hr[0] + hr[1] * hr[1]) + (hr[2] * hr[2] + hr[3] * hr[3])) + ((hr[4] * hr[4] + hr[5] * hr[5]) + (hr[6] * hr[6] + hr[7] * hr[7])); }
.LBB1_813:
	v_lshl_add_u32 v158, s26, 8, v161
	v_ashrrev_i32_e32 v159, 31, v158
	v_lshlrev_b64 v[166:167], 10, v[158:159]
	v_lshl_add_u64 v[166:167], v[166:167], 0, v[156:157]
	v_lshlrev_b64 v[176:177], 1, v[166:167]
	v_lshl_add_u64 v[178:179], s[24:25], 0, v[176:177]
	global_load_dwordx4 v[166:169], v[178:179], off
	global_load_dwordx4 v[184:187], v[178:179], off offset:256
	v_or_b32_e32 v228, 16, v158
	v_ashrrev_i32_e32 v229, 31, v228
	v_lshlrev_b64 v[228:229], 10, v[228:229]
	v_lshl_add_u64 v[228:229], v[228:229], 0, v[156:157]
	v_lshlrev_b64 v[228:229], 1, v[228:229]
	v_lshl_add_u64 v[228:229], s[24:25], 0, v[228:229]
	global_load_dwordx4 v[188:191], v[228:229], off
	global_load_dwordx4 v[200:203], v[228:229], off offset:256
	v_or_b32_e32 v228, 32, v158
	v_ashrrev_i32_e32 v229, 31, v228
	v_lshlrev_b64 v[228:229], 10, v[228:229]
	v_lshl_add_u64 v[228:229], v[228:229], 0, v[156:157]
	v_lshlrev_b64 v[228:229], 1, v[228:229]
	v_lshl_add_u64 v[228:229], s[24:25], 0, v[228:229]
	global_load_dwordx4 v[204:207], v[228:229], off
	global_load_dwordx4 v[208:211], v[228:229], off offset:256
	v_or_b32_e32 v228, 48, v158
	v_ashrrev_i32_e32 v229, 31, v228
	v_lshlrev_b64 v[228:229], 10, v[228:229]
	v_lshl_add_u64 v[228:229], v[228:229], 0, v[156:157]
	v_lshlrev_b64 v[228:229], 1, v[228:229]
	v_lshl_add_u64 v[228:229], s[24:25], 0, v[228:229]
	global_load_dwordx4 v[212:215], v[228:229], off
	global_load_dwordx4 v[216:219], v[228:229], off offset:256
	s_waitcnt vmcnt(0)
	v_add_f32_e32 v142, v142, v86
	v_add_f32_e32 v143, v143, v87
	v_add_f32_e32 v144, v144, v88
	v_add_f32_e32 v145, v145, v89
	v_add_f32_e32 v138, v138, v78
	v_add_f32_e32 v139, v139, v79
	v_add_f32_e32 v140, v140, v80
	v_add_f32_e32 v141, v141, v81
	v_lshl_add_u64 v[176:177], s[22:23], 0, v[176:177]
	v_add_f32_e32 v134, v134, v70
	v_add_f32_e32 v136, v136, v72
	v_add_f32_e32 v130, v130, v66
	v_add_f32_e32 v135, v135, v71
	v_add_f32_e32 v137, v137, v73
	v_add_f32_e32 v131, v131, v67
	v_add_f32_e32 v133, v133, v69
	v_lshlrev_b32_e32 v165, 16, v166
	v_and_b32_e32 v166, 0xffff0000, v166
	v_lshlrev_b32_e32 v175, 16, v167
	v_and_b32_e32 v167, 0xffff0000, v167
	v_lshlrev_b32_e32 v180, 16, v168
	v_and_b32_e32 v168, 0xffff0000, v168
	v_lshlrev_b32_e32 v181, 16, v169
	v_and_b32_e32 v169, 0xffff0000, v169
	v_fmac_f32_e32 v165, s11, v142
	v_fmac_f32_e32 v166, s11, v143
	v_fmac_f32_e32 v175, s11, v144
	v_fmac_f32_e32 v167, s11, v145
	v_fmac_f32_e32 v180, s11, v138
	v_fmac_f32_e32 v168, s11, v139
	v_fmac_f32_e32 v181, s11, v140
	v_fmac_f32_e32 v169, s11, v141
	v_cvt_pk_bf16_f32 v138, v165, v166
	v_cvt_pk_bf16_f32 v139, v175, v167
	v_cvt_pk_bf16_f32 v140, v180, v168
	v_cvt_pk_bf16_f32 v141, v181, v169
	global_store_dwordx4 v[176:177], v[138:141], off
	v_mov_b32_e32 v142, v184
	v_mov_b32_e32 v143, v185
	v_mov_b32_e32 v144, v186
	v_mov_b32_e32 v145, v187
	v_lshlrev_b32_e32 v167, 16, v138
	v_and_b32_e32 v138, 0xffff0000, v138
	v_lshlrev_b32_e32 v168, 16, v139
	v_and_b32_e32 v139, 0xffff0000, v139
	v_lshlrev_b32_e32 v169, 16, v140
	v_and_b32_e32 v140, 0xffff0000, v140
	v_lshlrev_b32_e32 v175, 16, v141
	v_and_b32_e32 v141, 0xffff0000, v141
	v_mul_f32_e32 v138, v138, v138
	v_mul_f32_e32 v139, v139, v139
	v_mul_f32_e32 v140, v140, v140
	v_mul_f32_e32 v141, v141, v141
	v_fmac_f32_e32 v138, v167, v167
	v_fmac_f32_e32 v139, v168, v168
	v_fmac_f32_e32 v140, v169, v169
	v_fmac_f32_e32 v141, v175, v175
	v_add_f32_e32 v138, v138, v139
	v_add_f32_e32 v139, v140, v141
	v_add_f32_e32 v138, v138, v139
	v_add_f32_e32 v165, v132, v68
	v_and_b32_e32 v166, 64, v171
	v_xor_b32_e32 v132, 16, v171
	v_add_u32_e32 v166, 64, v166
	v_cmp_lt_i32_e32 vcc, v132, v166
	s_nop 0
	v_lshlrev_b32_e32 v139, 16, v142
	v_and_b32_e32 v140, 0xffff0000, v142
	v_lshlrev_b32_e32 v141, 16, v143
	v_and_b32_e32 v142, 0xffff0000, v143
	v_lshlrev_b32_e32 v143, 16, v144
	v_and_b32_e32 v144, 0xffff0000, v144
	v_lshlrev_b32_e32 v167, 16, v145
	v_and_b32_e32 v145, 0xffff0000, v145
	v_fmac_f32_e32 v139, s11, v134
	v_fmac_f32_e32 v141, s11, v136
	v_fmac_f32_e32 v143, s11, v130
	v_fmac_f32_e32 v140, s11, v135
	v_fmac_f32_e32 v142, s11, v137
	v_fmac_f32_e32 v144, s11, v131
	v_fmac_f32_e32 v167, s11, v165
	v_fmac_f32_e32 v145, s11, v133
	v_cvt_pk_bf16_f32 v134, v139, v140
	v_cvt_pk_bf16_f32 v135, v141, v142
	v_cvt_pk_bf16_f32 v136, v143, v144
	v_cvt_pk_bf16_f32 v137, v167, v145
	v_cndmask_b32_e32 v132, v171, v132, vcc
	v_and_b32_e32 v131, 0xffff0000, v134
	v_and_b32_e32 v139, 0xffff0000, v135
	v_and_b32_e32 v141, 0xffff0000, v136
	v_and_b32_e32 v143, 0xffff0000, v137
	v_lshlrev_b32_e32 v130, 16, v134
	v_lshlrev_b32_e32 v133, 16, v135
	v_lshlrev_b32_e32 v140, 16, v136
	v_lshlrev_b32_e32 v142, 16, v137
	v_mul_f32_e32 v131, v131, v131
	v_mul_f32_e32 v139, v139, v139
	v_mul_f32_e32 v141, v141, v141
	v_mul_f32_e32 v143, v143, v143
	v_fmac_f32_e32 v131, v130, v130
	v_fmac_f32_e32 v139, v133, v133
	v_fmac_f32_e32 v141, v140, v140
	v_fmac_f32_e32 v143, v142, v142
	v_add_f32_e32 v130, v131, v139
	v_add_f32_e32 v131, v141, v143
	v_add_f32_e32 v130, v130, v131
	v_lshlrev_b32_e32 v132, 2, v132
	v_add_f32_e32 v130, v138, v130
	ds_bpermute_b32 v131, v132, v130
	v_xor_b32_e32 v133, 32, v171
	v_cmp_lt_i32_e32 vcc, v133, v166
	global_store_dwordx4 v[176:177], v[134:137], off offset:256
	s_waitcnt lgkmcnt(0)
	v_add_f32_e32 v130, v130, v131
	v_cndmask_b32_e32 v133, v171, v133, vcc
	v_lshlrev_b32_e32 v133, 2, v133
	ds_bpermute_b32 v131, v133, v130
	s_and_saveexec_b64 s[8:9], s[6:7]
	s_cbranch_execz .LBB1_815
	s_waitcnt lgkmcnt(0)
	v_add_f32_e32 v134, v130, v131
	s_lshl_b32 s28, s0, 2
	v_lshlrev_b64 v[130:131], 6, v[158:159]
	s_ashr_i32 s29, s28, 31
	v_lshl_add_u64 v[130:131], s[20:21], 0, v[130:131]
	v_lshl_add_u64 v[130:131], s[28:29], 2, v[130:131]
	s_lshl_b32 s74, s45, 2
	v_lshl_add_u64 v[130:131], v[130:131], 0, s[74:75]
	global_store_dword v[130:131], v134, off
; __device__ __forceinline__ unsigned cvt_pk_bf16(float lo, float hi) { unsigned r; asm volatile("v_cvt_pk_bf16_f32 %0, %1, %2" : "=v"(r) : "v"(lo), "v"(hi)); return r; }
; __device__ __forceinline__ float bflo(unsigned w) { return __uint_as_float(w << 16); }
;     __device__ __forceinline__ void operator()(const f32x4 (&acc)[2][2][4][2], const Unit& u, int wr, int wc, int fr, int fq, LAS unsigned char* lds) const {
;     ...
;             for (int m = 0; m < 4; ++m) { const int row = row0 + ai * HALF + m * 16; const size_t off = (size_t)row * D + col0;
;                 float rs = 1.0f; if (MODE == 1) rs = rstd_of4(rss_in, row, fq);
;                 float ss = 0.f;
; #pragma unroll
;                 for (int bj = 0; bj < 2; ++bj) { const size_t o = off + bj * HALF; const u32x4 bw = *(const u32x4*)(base + o);
;                     const float bs[8] = {bflo(bw.x), bfhi(bw.x), bflo(bw.y), bfhi(bw.y), bflo(bw.z), bfhi(bw.z), bflo(bw.w), bfhi(bw.w)};
;                     float hn[8];
;                     if (MODE == 0) {
; #pragma unroll
;                         for (int n = 0; n < 2; ++n)
; #pragma unroll
;                             for (int e = 0; e < 4; ++e) hn[4 * n + e] = bs[4 * n + e] + (acc[ai][bj][m][n][e] + bv[bj][n][e]) * scale;
;                     } else { const u32x4 pw = *(const u32x4*)(pp + o);
;                         const float pv[8] = {bflo(pw.x), bfhi(pw.x), bflo(pw.y), bfhi(pw.y), bflo(pw.z), bfhi(pw.z), bflo(pw.w), bfhi(pw.w)};
; #pragma unroll
;                         for (int n = 0; n < 2; ++n)
; #pragma unroll
;                             for (int e = 0; e < 4; ++e) hn[4 * n + e] = bs[4 * n + e] + fast_sigmoid(acc[ai][bj][m][n][e] * rs) * pv[4 * n + e]; }
;                     u32x4 w; w.x = cvt_pk_bf16(hn[0], hn[1]); w.y = cvt_pk_bf16(hn[2], hn[3]); w.z = cvt_pk_bf16(hn[4], hn[5]); w.w = cvt_pk_bf16(hn[6], hn[7]); *(u32x4*)(hb + o) = w;
;                     const float hr[8] = {bflo(w.x), bfhi(w.x), bflo(w.y), bfhi(w.y), bflo(w.z), bfhi(w.z), bflo(w.w), bfhi(w.w)};
;                     ss += ((hr[0] * hr[0] + hr[1] * hr[1]) + (hr[2] * hr[2] + hr[3] * hr[3])) + ((hr[4] * hr[4] + hr[5] * hr[5]) + (hr[6] * hr[6] + hr[7] * hr[7])); }
;                 ss += __shfl_xor(ss, 16); ss += __shfl_xor(ss, 32);
;                 if (fq == 0) rss_out[(size_t)row * 16 + u.pn * 4 + wc] = ss; }
.LBB1_815:
	s_or_b64 exec, exec, s[8:9]
	v_or_b32_e32 v130, 16, v158
	s_waitcnt lgkmcnt(0)
	v_ashrrev_i32_e32 v131, 31, v130
	v_lshlrev_b64 v[134:135], 10, v[130:131]
	v_lshl_add_u64 v[134:135], v[134:135], 0, v[156:157]
	v_lshlrev_b64 v[138:139], 1, v[134:135]
	v_lshl_add_u64 v[140:141], s[24:25], 0, v[138:139]
	v_mov_b32_e32 v134, v188
	v_mov_b32_e32 v135, v189
	v_mov_b32_e32 v136, v190
	v_mov_b32_e32 v137, v191
	v_add_f32_e32 v126, v126, v86
	v_add_f32_e32 v127, v127, v87
	v_add_f32_e32 v128, v128, v88
	v_add_f32_e32 v129, v129, v89
	v_add_f32_e32 v122, v122, v78
	v_add_f32_e32 v123, v123, v79
	v_add_f32_e32 v124, v124, v80
	v_add_f32_e32 v125, v125, v81
	v_lshl_add_u64 v[138:139], s[22:23], 0, v[138:139]
	v_add_f32_e32 v119, v119, v71
	v_add_f32_e32 v121, v121, v73
	v_add_f32_e32 v118, v118, v70
	v_add_f32_e32 v120, v120, v72
	v_add_f32_e32 v114, v114, v66
	v_add_f32_e32 v115, v115, v67
	v_add_f32_e32 v116, v116, v68
	v_add_f32_e32 v117, v117, v69
	s_nop 0
	v_lshlrev_b32_e32 v142, 16, v134
	v_and_b32_e32 v134, 0xffff0000, v134
	v_lshlrev_b32_e32 v143, 16, v135
	v_and_b32_e32 v135, 0xffff0000, v135
	v_lshlrev_b32_e32 v144, 16, v136
	v_and_b32_e32 v136, 0xffff0000, v136
	v_lshlrev_b32_e32 v145, 16, v137
	v_and_b32_e32 v137, 0xffff0000, v137
	v_fmac_f32_e32 v142, s11, v126
	v_fmac_f32_e32 v134, s11, v127
	v_fmac_f32_e32 v143, s11, v128
	v_fmac_f32_e32 v135, s11, v129
	v_fmac_f32_e32 v144, s11, v122
	v_fmac_f32_e32 v136, s11, v123
	v_fmac_f32_e32 v145, s11, v124
	v_fmac_f32_e32 v137, s11, v125
	v_cvt_pk_bf16_f32 v122, v142, v134
	v_cvt_pk_bf16_f32 v123, v143, v135
	v_cvt_pk_bf16_f32 v124, v144, v136
	v_cvt_pk_bf16_f32 v125, v145, v137
	global_store_dwordx4 v[138:139], v[122:125], off
	v_mov_b32_e32 v126, v200
	v_mov_b32_e32 v127, v201
	v_mov_b32_e32 v128, v202
	v_mov_b32_e32 v129, v203
	v_lshlrev_b32_e32 v134, 16, v122
	v_and_b32_e32 v122, 0xffff0000, v122
	v_lshlrev_b32_e32 v135, 16, v123
	v_and_b32_e32 v123, 0xffff0000, v123
	v_lshlrev_b32_e32 v136, 16, v124
	v_and_b32_e32 v124, 0xffff0000, v124
	v_lshlrev_b32_e32 v137, 16, v125
	v_and_b32_e32 v125, 0xffff0000, v125
	v_mul_f32_e32 v122, v122, v122
	v_mul_f32_e32 v123, v123, v123
	v_mul_f32_e32 v124, v124, v124
	v_mul_f32_e32 v125, v125, v125
	v_fmac_f32_e32 v122, v134, v134
	v_fmac_f32_e32 v123, v135, v135
	v_fmac_f32_e32 v124, v136, v136
	v_fmac_f32_e32 v125, v137, v137
	v_add_f32_e32 v122, v122, v123
	v_add_f32_e32 v123, v124, v125
	v_add_f32_e32 v122, v122, v123
	s_nop 0
	v_lshlrev_b32_e32 v123, 16, v126
	v_and_b32_e32 v124, 0xffff0000, v126
	v_and_b32_e32 v126, 0xffff0000, v127
	v_lshlrev_b32_e32 v125, 16, v127
	v_lshlrev_b32_e32 v127, 16, v128
	v_and_b32_e32 v128, 0xffff0000, v128
	v_lshlrev_b32_e32 v134, 16, v129
	v_and_b32_e32 v129, 0xffff0000, v129
	v_fmac_f32_e32 v124, s11, v119
	v_fmac_f32_e32 v126, s11, v121
	v_fmac_f32_e32 v123, s11, v118
	v_fmac_f32_e32 v125, s11, v120
	v_fmac_f32_e32 v127, s11, v114
	v_fmac_f32_e32 v128, s11, v115
	v_fmac_f32_e32 v134, s11, v116
	v_fmac_f32_e32 v129, s11, v117
	v_cvt_pk_bf16_f32 v116, v123, v124
	v_cvt_pk_bf16_f32 v117, v125, v126
	v_cvt_pk_bf16_f32 v118, v127, v128
	v_cvt_pk_bf16_f32 v119, v134, v129
	global_store_dwordx4 v[138:139], v[116:119], off offset:256
	v_and_b32_e32 v115, 0xffff0000, v116
	v_and_b32_e32 v121, 0xffff0000, v117
	v_and_b32_e32 v124, 0xffff0000, v118
	v_and_b32_e32 v126, 0xffff0000, v119
	v_lshlrev_b32_e32 v114, 16, v116
	v_lshlrev_b32_e32 v120, 16, v117
	v_lshlrev_b32_e32 v123, 16, v118
	v_lshlrev_b32_e32 v125, 16, v119
	v_mul_f32_e32 v115, v115, v115
	v_mul_f32_e32 v121, v121, v121
	v_mul_f32_e32 v124, v124, v124
	v_mul_f32_e32 v126, v126, v126
	v_fmac_f32_e32 v115, v114, v114
	v_fmac_f32_e32 v121, v120, v120
	v_fmac_f32_e32 v124, v123, v123
	v_fmac_f32_e32 v126, v125, v125
	v_add_f32_e32 v114, v115, v121
	v_add_f32_e32 v115, v124, v126
	v_add_f32_e32 v114, v114, v115
	v_add_f32_e32 v114, v122, v114
	ds_bpermute_b32 v115, v132, v114
	s_waitcnt lgkmcnt(0)
	v_add_f32_e32 v114, v114, v115
	ds_bpermute_b32 v115, v133, v114
	s_and_saveexec_b64 s[8:9], s[6:7]
	s_cbranch_execz .LBB1_817
	s_waitcnt lgkmcnt(0)
	v_add_f32_e32 v116, v114, v115
	s_lshl_b32 s28, s0, 2
	v_lshlrev_b64 v[114:115], 6, v[130:131]
	s_ashr_i32 s29, s28, 31
	v_lshl_add_u64 v[114:115], s[20:21], 0, v[114:115]
	v_lshl_add_u64 v[114:115], s[28:29], 2, v[114:115]
	s_lshl_b32 s74, s45, 2
	v_lshl_add_u64 v[114:115], v[114:115], 0, s[74:75]
	global_store_dword v[114:115], v116, off
; __device__ __forceinline__ unsigned cvt_pk_bf16(float lo, float hi) { unsigned r; asm volatile("v_cvt_pk_bf16_f32 %0, %1, %2" : "=v"(r) : "v"(lo), "v"(hi)); return r; }
; __device__ __forceinline__ float bflo(unsigned w) { return __uint_as_float(w << 16); }
;     __device__ __forceinline__ void operator()(const f32x4 (&acc)[2][2][4][2], const Unit& u, int wr, int wc, int fr, int fq, LAS unsigned char* lds) const {
;     ...
;             for (int m = 0; m < 4; ++m) { const int row = row0 + ai * HALF + m * 16; const size_t off = (size_t)row * D + col0;
;                 float rs = 1.0f; if (MODE == 1) rs = rstd_of4(rss_in, row, fq);
;                 float ss = 0.f;
; #pragma unroll
;                 for (int bj = 0; bj < 2; ++bj) { const size_t o = off + bj * HALF; const u32x4 bw = *(const u32x4*)(base + o);
;                     const float bs[8] = {bflo(bw.x), bfhi(bw.x), bflo(bw.y), bfhi(bw.y), bflo(bw.z), bfhi(bw.z), bflo(bw.w), bfhi(bw.w)};
;                     float hn[8];
;                     if (MODE == 0) {
; #pragma unroll
;                         for (int n = 0; n < 2; ++n)
; #pragma unroll
;                             for (int e = 0; e < 4; ++e) hn[4 * n + e] = bs[4 * n + e] + (acc[ai][bj][m][n][e] + bv[bj][n][e]) * scale;
;                     } else { const u32x4 pw = *(const u32x4*)(pp + o);
;                         const float pv[8] = {bflo(pw.x), bfhi(pw.x), bflo(pw.y), bfhi(pw.y), bflo(pw.z), bfhi(pw.z), bflo(pw.w), bfhi(pw.w)};
; #pragma unroll
;                         for (int n = 0; n < 2; ++n)
; #pragma unroll
;                             for (int e = 0; e < 4; ++e) hn[4 * n + e] = bs[4 * n + e] + fast_sigmoid(acc[ai][bj][m][n][e] * rs) * pv[4 * n + e]; }
;                     u32x4 w; w.x = cvt_pk_bf16(hn[0], hn[1]); w.y = cvt_pk_bf16(hn[2], hn[3]); w.z = cvt_pk_bf16(hn[4], hn[5]); w.w = cvt_pk_bf16(hn[6], hn[7]); *(u32x4*)(hb + o) = w;
;                     const float hr[8] = {bflo(w.x), bfhi(w.x), bflo(w.y), bfhi(w.y), bflo(w.z), bfhi(w.z), bflo(w.w), bfhi(w.w)};
;                     ss += ((hr[0] * hr[0] + hr[1] * hr[1]) + (hr[2] * hr[2] + hr[3] * hr[3])) + ((hr[4] * hr[4] + hr[5] * hr[5]) + (hr[6] * hr[6] + hr[7] * hr[7])); }
;                 ss += __shfl_xor(ss, 16); ss += __shfl_xor(ss, 32);
;                 if (fq == 0) rss_out[(size_t)row * 16 + u.pn * 4 + wc] = ss; }
.LBB1_817:
	s_or_b64 exec, exec, s[8:9]
	v_or_b32_e32 v114, 32, v158
	s_waitcnt lgkmcnt(0)
	v_ashrrev_i32_e32 v115, 31, v114
	v_lshlrev_b64 v[116:117], 10, v[114:115]
	v_lshl_add_u64 v[116:117], v[116:117], 0, v[156:157]
	v_lshlrev_b64 v[120:121], 1, v[116:117]
	v_lshl_add_u64 v[122:123], s[24:25], 0, v[120:121]
	v_mov_b32_e32 v116, v204
	v_mov_b32_e32 v117, v205
	v_mov_b32_e32 v118, v206
	v_mov_b32_e32 v119, v207
	v_add_f32_e32 v110, v110, v86
	v_add_f32_e32 v111, v111, v87
	v_add_f32_e32 v112, v112, v88
	v_add_f32_e32 v113, v113, v89
	v_add_f32_e32 v106, v106, v78
	v_add_f32_e32 v107, v107, v79
	v_add_f32_e32 v108, v108, v80
	v_add_f32_e32 v109, v109, v81
	v_lshl_add_u64 v[120:121], s[22:23], 0, v[120:121]
	v_add_f32_e32 v103, v103, v71
	v_add_f32_e32 v105, v105, v73
	v_add_f32_e32 v102, v102, v70
	v_add_f32_e32 v104, v104, v72
	v_add_f32_e32 v98, v98, v66
	v_add_f32_e32 v99, v99, v67
	v_add_f32_e32 v100, v100, v68
	v_add_f32_e32 v101, v101, v69
	s_nop 0
	v_lshlrev_b32_e32 v124, 16, v116
	v_and_b32_e32 v116, 0xffff0000, v116
	v_lshlrev_b32_e32 v125, 16, v117
	v_and_b32_e32 v117, 0xffff0000, v117
	v_lshlrev_b32_e32 v126, 16, v118
	v_and_b32_e32 v118, 0xffff0000, v118
	v_lshlrev_b32_e32 v127, 16, v119
	v_and_b32_e32 v119, 0xffff0000, v119
	v_fmac_f32_e32 v124, s11, v110
	v_fmac_f32_e32 v116, s11, v111
	v_fmac_f32_e32 v125, s11, v112
	v_fmac_f32_e32 v117, s11, v113
	v_fmac_f32_e32 v126, s11, v106
	v_fmac_f32_e32 v118, s11, v107
	v_fmac_f32_e32 v127, s11, v108
	v_fmac_f32_e32 v119, s11, v109
	v_cvt_pk_bf16_f32 v106, v124, v116
	v_cvt_pk_bf16_f32 v107, v125, v117
	v_cvt_pk_bf16_f32 v108, v126, v118
	v_cvt_pk_bf16_f32 v109, v127, v119
	global_store_dwordx4 v[120:121], v[106:109], off
	v_mov_b32_e32 v110, v208
	v_mov_b32_e32 v111, v209
	v_mov_b32_e32 v112, v210
	v_mov_b32_e32 v113, v211
	v_lshlrev_b32_e32 v116, 16, v106
	v_and_b32_e32 v106, 0xffff0000, v106
	v_lshlrev_b32_e32 v117, 16, v107
	v_and_b32_e32 v107, 0xffff0000, v107
	v_lshlrev_b32_e32 v118, 16, v108
	v_and_b32_e32 v108, 0xffff0000, v108
	v_lshlrev_b32_e32 v119, 16, v109
	v_and_b32_e32 v109, 0xffff0000, v109
	v_mul_f32_e32 v106, v106, v106
	v_mul_f32_e32 v107, v107, v107
	v_mul_f32_e32 v108, v108, v108
	v_mul_f32_e32 v109, v109, v109
	v_fmac_f32_e32 v106, v116, v116
	v_fmac_f32_e32 v107, v117, v117
	v_fmac_f32_e32 v108, v118, v118
	v_fmac_f32_e32 v109, v119, v119
	v_add_f32_e32 v106, v106, v107
	v_add_f32_e32 v107, v108, v109
	v_add_f32_e32 v106, v106, v107
	s_nop 0
	v_lshlrev_b32_e32 v107, 16, v110
	v_and_b32_e32 v108, 0xffff0000, v110
	v_and_b32_e32 v110, 0xffff0000, v111
	v_lshlrev_b32_e32 v109, 16, v111
	v_lshlrev_b32_e32 v111, 16, v112
	v_and_b32_e32 v112, 0xffff0000, v112
	v_lshlrev_b32_e32 v116, 16, v113
	v_and_b32_e32 v113, 0xffff0000, v113
	v_fmac_f32_e32 v108, s11, v103
	v_fmac_f32_e32 v110, s11, v105
	v_fmac_f32_e32 v107, s11, v102
	v_fmac_f32_e32 v109, s11, v104
	v_fmac_f32_e32 v111, s11, v98
	v_fmac_f32_e32 v112, s11, v99
	v_fmac_f32_e32 v116, s11, v100
	v_fmac_f32_e32 v113, s11, v101
	v_cvt_pk_bf16_f32 v100, v107, v108
	v_cvt_pk_bf16_f32 v101, v109, v110
	v_cvt_pk_bf16_f32 v102, v111, v112
	v_cvt_pk_bf16_f32 v103, v116, v113
	global_store_dwordx4 v[120:121], v[100:103], off offset:256
	v_and_b32_e32 v99, 0xffff0000, v100
	v_and_b32_e32 v105, 0xffff0000, v101
	v_and_b32_e32 v108, 0xffff0000, v102
	v_and_b32_e32 v110, 0xffff0000, v103
	v_lshlrev_b32_e32 v98, 16, v100
	v_lshlrev_b32_e32 v104, 16, v101
	v_lshlrev_b32_e32 v107, 16, v102
	v_lshlrev_b32_e32 v109, 16, v103
	v_mul_f32_e32 v99, v99, v99
	v_mul_f32_e32 v105, v105, v105
	v_mul_f32_e32 v108, v108, v108
	v_mul_f32_e32 v110, v110, v110
	v_fmac_f32_e32 v99, v98, v98
	v_fmac_f32_e32 v105, v104, v104
	v_fmac_f32_e32 v108, v107, v107
	v_fmac_f32_e32 v110, v109, v109
	v_add_f32_e32 v98, v99, v105
	v_add_f32_e32 v99, v108, v110
	v_add_f32_e32 v98, v98, v99
	v_add_f32_e32 v98, v106, v98
	ds_bpermute_b32 v99, v132, v98
	s_waitcnt lgkmcnt(0)
	v_add_f32_e32 v98, v98, v99
	ds_bpermute_b32 v99, v133, v98
	s_and_saveexec_b64 s[8:9], s[6:7]
	s_cbranch_execz .LBB1_819
	s_waitcnt lgkmcnt(0)
	v_add_f32_e32 v100, v98, v99
	s_lshl_b32 s28, s0, 2
	v_lshlrev_b64 v[98:99], 6, v[114:115]
	s_ashr_i32 s29, s28, 31
	v_lshl_add_u64 v[98:99], s[20:21], 0, v[98:99]
	v_lshl_add_u64 v[98:99], s[28:29], 2, v[98:99]
	s_lshl_b32 s74, s45, 2
	v_lshl_add_u64 v[98:99], v[98:99], 0, s[74:75]
	global_store_dword v[98:99], v100, off
; __device__ __forceinline__ unsigned cvt_pk_bf16(float lo, float hi) { unsigned r; asm volatile("v_cvt_pk_bf16_f32 %0, %1, %2" : "=v"(r) : "v"(lo), "v"(hi)); return r; }
; __device__ __forceinline__ float bflo(unsigned w) { return __uint_as_float(w << 16); }
;     __device__ __forceinline__ void operator()(const f32x4 (&acc)[2][2][4][2], const Unit& u, int wr, int wc, int fr, int fq, LAS unsigned char* lds) const {
;     ...
;             for (int m = 0; m < 4; ++m) { const int row = row0 + ai * HALF + m * 16; const size_t off = (size_t)row * D + col0;
;                 float rs = 1.0f; if (MODE == 1) rs = rstd_of4(rss_in, row, fq);
;                 float ss = 0.f;
; #pragma unroll
;                 for (int bj = 0; bj < 2; ++bj) { const size_t o = off + bj * HALF; const u32x4 bw = *(const u32x4*)(base + o);
;                     const float bs[8] = {bflo(bw.x), bfhi(bw.x), bflo(bw.y), bfhi(bw.y), bflo(bw.z), bfhi(bw.z), bflo(bw.w), bfhi(bw.w)};
;                     float hn[8];
;                     if (MODE == 0) {
; #pragma unroll
;                         for (int n = 0; n < 2; ++n)
; #pragma unroll
;                             for (int e = 0; e < 4; ++e) hn[4 * n + e] = bs[4 * n + e] + (acc[ai][bj][m][n][e] + bv[bj][n][e]) * scale;
;                     } else { const u32x4 pw = *(const u32x4*)(pp + o);
;                         const float pv[8] = {bflo(pw.x), bfhi(pw.x), bflo(pw.y), bfhi(pw.y), bflo(pw.z), bfhi(pw.z), bflo(pw.w), bfhi(pw.w)};
; #pragma unroll
;                         for (int n = 0; n < 2; ++n)
; #pragma unroll
;                             for (int e = 0; e < 4; ++e) hn[4 * n + e] = bs[4 * n + e] + fast_sigmoid(acc[ai][bj][m][n][e] * rs) * pv[4 * n + e]; }
;                     u32x4 w; w.x = cvt_pk_bf16(hn[0], hn[1]); w.y = cvt_pk_bf16(hn[2], hn[3]); w.z = cvt_pk_bf16(hn[4], hn[5]); w.w = cvt_pk_bf16(hn[6], hn[7]); *(u32x4*)(hb + o) = w;
;                     const float hr[8] = {bflo(w.x), bfhi(w.x), bflo(w.y), bfhi(w.y), bflo(w.z), bfhi(w.z), bflo(w.w), bfhi(w.w)};
;                     ss += ((hr[0] * hr[0] + hr[1] * hr[1]) + (hr[2] * hr[2] + hr[3] * hr[3])) + ((hr[4] * hr[4] + hr[5] * hr[5]) + (hr[6] * hr[6] + hr[7] * hr[7])); }
;                 ss += __shfl_xor(ss, 16); ss += __shfl_xor(ss, 32);
;                 if (fq == 0) rss_out[(size_t)row * 16 + u.pn * 4 + wc] = ss; }
.LBB1_819:
	s_or_b64 exec, exec, s[8:9]
	v_or_b32_e32 v98, 48, v158
	s_waitcnt lgkmcnt(0)
	v_ashrrev_i32_e32 v99, 31, v98
	v_lshlrev_b64 v[100:101], 10, v[98:99]
	v_lshl_add_u64 v[100:101], v[100:101], 0, v[156:157]
	v_lshlrev_b64 v[104:105], 1, v[100:101]
	v_lshl_add_u64 v[106:107], s[24:25], 0, v[104:105]
	v_mov_b32_e32 v100, v212
	v_mov_b32_e32 v101, v213
	v_mov_b32_e32 v102, v214
	v_mov_b32_e32 v103, v215
	v_add_f32_e32 v94, v94, v86
	v_add_f32_e32 v95, v95, v87
	v_add_f32_e32 v96, v96, v88
	v_add_f32_e32 v97, v97, v89
	v_add_f32_e32 v90, v90, v78
	v_add_f32_e32 v91, v91, v79
	v_add_f32_e32 v92, v92, v80
	v_add_f32_e32 v93, v93, v81
	v_lshl_add_u64 v[104:105], s[22:23], 0, v[104:105]
	v_add_f32_e32 v83, v83, v71
	v_add_f32_e32 v85, v85, v73
	v_add_f32_e32 v82, v82, v70
	v_add_f32_e32 v84, v84, v72
	v_add_f32_e32 v74, v74, v66
	v_add_f32_e32 v75, v75, v67
	v_add_f32_e32 v76, v76, v68
	v_add_f32_e32 v77, v77, v69
	s_nop 0
	v_lshlrev_b32_e32 v108, 16, v100
	v_and_b32_e32 v100, 0xffff0000, v100
	v_lshlrev_b32_e32 v109, 16, v101
	v_and_b32_e32 v101, 0xffff0000, v101
	v_lshlrev_b32_e32 v110, 16, v102
	v_and_b32_e32 v102, 0xffff0000, v102
	v_lshlrev_b32_e32 v111, 16, v103
	v_and_b32_e32 v103, 0xffff0000, v103
	v_fmac_f32_e32 v108, s11, v94
	v_fmac_f32_e32 v100, s11, v95
	v_fmac_f32_e32 v109, s11, v96
	v_fmac_f32_e32 v101, s11, v97
	v_fmac_f32_e32 v110, s11, v90
	v_fmac_f32_e32 v102, s11, v91
	v_fmac_f32_e32 v111, s11, v92
	v_fmac_f32_e32 v103, s11, v93
	v_cvt_pk_bf16_f32 v90, v108, v100
	v_cvt_pk_bf16_f32 v91, v109, v101
	v_cvt_pk_bf16_f32 v92, v110, v102
	v_cvt_pk_bf16_f32 v93, v111, v103
	global_store_dwordx4 v[104:105], v[90:93], off
	v_mov_b32_e32 v94, v216
	v_mov_b32_e32 v95, v217
	v_mov_b32_e32 v96, v218
	v_mov_b32_e32 v97, v219
	v_lshlrev_b32_e32 v100, 16, v90
	v_and_b32_e32 v90, 0xffff0000, v90
	v_lshlrev_b32_e32 v101, 16, v91
	v_and_b32_e32 v91, 0xffff0000, v91
	v_lshlrev_b32_e32 v102, 16, v92
	v_and_b32_e32 v92, 0xffff0000, v92
	v_lshlrev_b32_e32 v103, 16, v93
	v_and_b32_e32 v93, 0xffff0000, v93
	v_mul_f32_e32 v90, v90, v90
	v_mul_f32_e32 v91, v91, v91
	v_mul_f32_e32 v92, v92, v92
	v_mul_f32_e32 v93, v93, v93
	v_fmac_f32_e32 v90, v100, v100
	v_fmac_f32_e32 v91, v101, v101
	v_fmac_f32_e32 v92, v102, v102
	v_fmac_f32_e32 v93, v103, v103
	v_add_f32_e32 v90, v90, v91
	v_add_f32_e32 v91, v92, v93
	v_add_f32_e32 v90, v90, v91
	s_nop 0
	v_lshlrev_b32_e32 v91, 16, v94
	v_and_b32_e32 v92, 0xffff0000, v94
	v_and_b32_e32 v94, 0xffff0000, v95
	v_lshlrev_b32_e32 v93, 16, v95
	v_lshlrev_b32_e32 v95, 16, v96
	v_and_b32_e32 v96, 0xffff0000, v96
	v_lshlrev_b32_e32 v100, 16, v97
	v_and_b32_e32 v97, 0xffff0000, v97
	v_fmac_f32_e32 v92, s11, v83
	v_fmac_f32_e32 v94, s11, v85
	v_fmac_f32_e32 v91, s11, v82
	v_fmac_f32_e32 v93, s11, v84
	v_fmac_f32_e32 v95, s11, v74
	v_fmac_f32_e32 v96, s11, v75
	v_fmac_f32_e32 v100, s11, v76
	v_fmac_f32_e32 v97, s11, v77
	v_cvt_pk_bf16_f32 v82, v91, v92
	v_cvt_pk_bf16_f32 v83, v93, v94
	v_cvt_pk_bf16_f32 v84, v95, v96
	v_cvt_pk_bf16_f32 v85, v100, v97
	global_store_dwordx4 v[104:105], v[82:85], off offset:256
	v_and_b32_e32 v75, 0xffff0000, v82
	v_and_b32_e32 v77, 0xffff0000, v83
	v_and_b32_e32 v92, 0xffff0000, v84
	v_and_b32_e32 v94, 0xffff0000, v85
	v_lshlrev_b32_e32 v74, 16, v82
	v_lshlrev_b32_e32 v76, 16, v83
	v_lshlrev_b32_e32 v91, 16, v84
	v_lshlrev_b32_e32 v93, 16, v85
	v_mul_f32_e32 v75, v75, v75
	v_mul_f32_e32 v77, v77, v77
	v_mul_f32_e32 v92, v92, v92
	v_mul_f32_e32 v94, v94, v94
	v_fmac_f32_e32 v75, v74, v74
	v_fmac_f32_e32 v77, v76, v76
	v_fmac_f32_e32 v92, v91, v91
	v_fmac_f32_e32 v94, v93, v93
	v_add_f32_e32 v74, v75, v77
	v_add_f32_e32 v75, v92, v94
	v_add_f32_e32 v74, v74, v75
	v_add_f32_e32 v74, v90, v74
	ds_bpermute_b32 v75, v132, v74
	s_waitcnt lgkmcnt(0)
	v_add_f32_e32 v74, v74, v75
	ds_bpermute_b32 v75, v133, v74
	s_and_saveexec_b64 s[8:9], s[6:7]
	s_cbranch_execz .LBB1_821
	s_waitcnt lgkmcnt(0)
	v_add_f32_e32 v76, v74, v75
	s_lshl_b32 s28, s0, 2
	v_lshlrev_b64 v[74:75], 6, v[98:99]
	s_ashr_i32 s29, s28, 31
	v_lshl_add_u64 v[74:75], s[20:21], 0, v[74:75]
	v_lshl_add_u64 v[74:75], s[28:29], 2, v[74:75]
	s_lshl_b32 s74, s45, 2
	v_lshl_add_u64 v[74:75], v[74:75], 0, s[74:75]
	global_store_dword v[74:75], v76, off
.LBB1_821:
	s_or_b64 exec, exec, s[8:9]
	v_add_u32_e32 v74, 0x80, v158
	s_waitcnt lgkmcnt(0)
	v_ashrrev_i32_e32 v75, 31, v74
	v_lshlrev_b64 v[76:77], 10, v[74:75]
	v_lshl_add_u64 v[76:77], v[76:77], 0, v[156:157]
	v_lshlrev_b64 v[76:77], 1, v[76:77]
	v_lshl_add_u64 v[90:91], s[24:25], 0, v[76:77]
	global_load_dwordx4 v[82:85], v[90:91], off
	global_load_dwordx4 v[184:187], v[90:91], off offset:256
	v_add_u32_e32 v228, 0x90, v158
	v_ashrrev_i32_e32 v229, 31, v228
	v_lshlrev_b64 v[228:229], 10, v[228:229]
	v_lshl_add_u64 v[228:229], v[228:229], 0, v[156:157]
	v_lshlrev_b64 v[228:229], 1, v[228:229]
	v_lshl_add_u64 v[228:229], s[24:25], 0, v[228:229]
	global_load_dwordx4 v[188:191], v[228:229], off
	global_load_dwordx4 v[200:203], v[228:229], off offset:256
	v_add_u32_e32 v228, 0xa0, v158
	v_ashrrev_i32_e32 v229, 31, v228
	v_lshlrev_b64 v[228:229], 10, v[228:229]
	v_lshl_add_u64 v[228:229], v[228:229], 0, v[156:157]
	v_lshlrev_b64 v[228:229], 1, v[228:229]
	v_lshl_add_u64 v[228:229], s[24:25], 0, v[228:229]
	global_load_dwordx4 v[204:207], v[228:229], off
	global_load_dwordx4 v[208:211], v[228:229], off offset:256
	v_add_u32_e32 v228, 0xb0, v158
	v_ashrrev_i32_e32 v229, 31, v228
	v_lshlrev_b64 v[228:229], 10, v[228:229]
	v_lshl_add_u64 v[228:229], v[228:229], 0, v[156:157]
	v_lshlrev_b64 v[228:229], 1, v[228:229]
	v_lshl_add_u64 v[228:229], s[24:25], 0, v[228:229]
	global_load_dwordx4 v[212:215], v[228:229], off
	global_load_dwordx4 v[216:219], v[228:229], off offset:256
	v_add_f32_e32 v62, v62, v86
	v_add_f32_e32 v63, v63, v87
	v_add_f32_e32 v64, v64, v88
	v_add_f32_e32 v65, v65, v89
	v_add_f32_e32 v58, v58, v78
	v_add_f32_e32 v59, v59, v79
	v_add_f32_e32 v60, v60, v80
	v_add_f32_e32 v61, v61, v81
	v_lshl_add_u64 v[76:77], s[22:23], 0, v[76:77]
	v_add_f32_e32 v55, v55, v71
	v_add_f32_e32 v57, v57, v73
	v_add_f32_e32 v54, v54, v70
	v_add_f32_e32 v56, v56, v72
	v_add_f32_e32 v50, v50, v66
	v_add_f32_e32 v51, v51, v67
	v_add_f32_e32 v52, v52, v68
	v_add_f32_e32 v53, v53, v69
	s_waitcnt vmcnt(0)
; __device__ __forceinline__ unsigned cvt_pk_bf16(float lo, float hi) { unsigned r; asm volatile("v_cvt_pk_bf16_f32 %0, %1, %2" : "=v"(r) : "v"(lo), "v"(hi)); return r; }
; __device__ __forceinline__ float bflo(unsigned w) { return __uint_as_float(w << 16); }
;     __device__ __forceinline__ void operator()(const f32x4 (&acc)[2][2][4][2], const Unit& u, int wr, int wc, int fr, int fq, LAS unsigned char* lds) const {
;     ...
;             for (int m = 0; m < 4; ++m) { const int row = row0 + ai * HALF + m * 16; const size_t off = (size_t)row * D + col0;
;                 float rs = 1.0f; if (MODE == 1) rs = rstd_of4(rss_in, row, fq);
;                 float ss = 0.f;
; #pragma unroll
;                 for (int bj = 0; bj < 2; ++bj) { const size_t o = off + bj * HALF; const u32x4 bw = *(const u32x4*)(base + o);
;                     const float bs[8] = {bflo(bw.x), bfhi(bw.x), bflo(bw.y), bfhi(bw.y), bflo(bw.z), bfhi(bw.z), bflo(bw.w), bfhi(bw.w)};
;                     float hn[8];
;                     if (MODE == 0) {
; #pragma unroll
;                         for (int n = 0; n < 2; ++n)
; #pragma unroll
;                             for (int e = 0; e < 4; ++e) hn[4 * n + e] = bs[4 * n + e] + (acc[ai][bj][m][n][e] + bv[bj][n][e]) * scale;
;                     } else { const u32x4 pw = *(const u32x4*)(pp + o);
;                         const float pv[8] = {bflo(pw.x), bfhi(pw.x), bflo(pw.y), bfhi(pw.y), bflo(pw.z), bfhi(pw.z), bflo(pw.w), bfhi(pw.w)};
; #pragma unroll
;                         for (int n = 0; n < 2; ++n)
; #pragma unroll
;                             for (int e = 0; e < 4; ++e) hn[4 * n + e] = bs[4 * n + e] + fast_sigmoid(acc[ai][bj][m][n][e] * rs) * pv[4 * n + e]; }
;                     u32x4 w; w.x = cvt_pk_bf16(hn[0], hn[1]); w.y = cvt_pk_bf16(hn[2], hn[3]); w.z = cvt_pk_bf16(hn[4], hn[5]); w.w = cvt_pk_bf16(hn[6], hn[7]); *(u32x4*)(hb + o) = w;
;                     const float hr[8] = {bflo(w.x), bfhi(w.x), bflo(w.y), bfhi(w.y), bflo(w.z), bfhi(w.z), bflo(w.w), bfhi(w.w)};
;                     ss += ((hr[0] * hr[0] + hr[1] * hr[1]) + (hr[2] * hr[2] + hr[3] * hr[3])) + ((hr[4] * hr[4] + hr[5] * hr[5]) + (hr[6] * hr[6] + hr[7] * hr[7])); }
;                 ss += __shfl_xor(ss, 16); ss += __shfl_xor(ss, 32);
;                 if (fq == 0) rss_out[(size_t)row * 16 + u.pn * 4 + wc] = ss; }
	v_lshlrev_b32_e32 v92, 16, v82
	v_and_b32_e32 v82, 0xffff0000, v82
	v_lshlrev_b32_e32 v93, 16, v83
	v_and_b32_e32 v83, 0xffff0000, v83
	v_lshlrev_b32_e32 v94, 16, v84
	v_and_b32_e32 v84, 0xffff0000, v84
	v_lshlrev_b32_e32 v95, 16, v85
	v_and_b32_e32 v85, 0xffff0000, v85
	v_fmac_f32_e32 v92, s11, v62
	v_fmac_f32_e32 v82, s11, v63
	v_fmac_f32_e32 v93, s11, v64
	v_fmac_f32_e32 v83, s11, v65
	v_fmac_f32_e32 v94, s11, v58
	v_fmac_f32_e32 v84, s11, v59
	v_fmac_f32_e32 v95, s11, v60
	v_fmac_f32_e32 v85, s11, v61
	v_cvt_pk_bf16_f32 v58, v92, v82
	v_cvt_pk_bf16_f32 v59, v93, v83
	v_cvt_pk_bf16_f32 v60, v94, v84
	v_cvt_pk_bf16_f32 v61, v95, v85
	global_store_dwordx4 v[76:77], v[58:61], off
	v_mov_b32_e32 v62, v184
	v_mov_b32_e32 v63, v185
	v_mov_b32_e32 v64, v186
	v_mov_b32_e32 v65, v187
	v_lshlrev_b32_e32 v82, 16, v58
	v_and_b32_e32 v58, 0xffff0000, v58
	v_lshlrev_b32_e32 v83, 16, v59
	v_and_b32_e32 v59, 0xffff0000, v59
	v_lshlrev_b32_e32 v84, 16, v60
	v_and_b32_e32 v60, 0xffff0000, v60
	v_lshlrev_b32_e32 v85, 16, v61
	v_and_b32_e32 v61, 0xffff0000, v61
	v_mul_f32_e32 v58, v58, v58
	v_mul_f32_e32 v59, v59, v59
	v_mul_f32_e32 v60, v60, v60
	v_mul_f32_e32 v61, v61, v61
	v_fmac_f32_e32 v58, v82, v82
	v_fmac_f32_e32 v59, v83, v83
	v_fmac_f32_e32 v60, v84, v84
	v_fmac_f32_e32 v61, v85, v85
	v_add_f32_e32 v58, v58, v59
	v_add_f32_e32 v59, v60, v61
	v_add_f32_e32 v58, v58, v59
	s_nop 0
	v_lshlrev_b32_e32 v59, 16, v62
	v_and_b32_e32 v60, 0xffff0000, v62
	v_and_b32_e32 v62, 0xffff0000, v63
	v_lshlrev_b32_e32 v61, 16, v63
	v_lshlrev_b32_e32 v63, 16, v64
	v_and_b32_e32 v64, 0xffff0000, v64
	v_lshlrev_b32_e32 v82, 16, v65
	v_and_b32_e32 v65, 0xffff0000, v65
	v_fmac_f32_e32 v60, s11, v55
	v_fmac_f32_e32 v62, s11, v57
	v_fmac_f32_e32 v59, s11, v54
	v_fmac_f32_e32 v61, s11, v56
	v_fmac_f32_e32 v63, s11, v50
	v_fmac_f32_e32 v64, s11, v51
	v_fmac_f32_e32 v82, s11, v52
	v_fmac_f32_e32 v65, s11, v53
	v_cvt_pk_bf16_f32 v52, v59, v60
	v_cvt_pk_bf16_f32 v53, v61, v62
	v_cvt_pk_bf16_f32 v54, v63, v64
	v_cvt_pk_bf16_f32 v55, v82, v65
	global_store_dwordx4 v[76:77], v[52:55], off offset:256
	v_and_b32_e32 v51, 0xffff0000, v52
	v_and_b32_e32 v57, 0xffff0000, v53
	v_and_b32_e32 v60, 0xffff0000, v54
	v_and_b32_e32 v62, 0xffff0000, v55
	v_lshlrev_b32_e32 v50, 16, v52
	v_lshlrev_b32_e32 v56, 16, v53
	v_lshlrev_b32_e32 v59, 16, v54
	v_lshlrev_b32_e32 v61, 16, v55
	v_mul_f32_e32 v51, v51, v51
	v_mul_f32_e32 v57, v57, v57
	v_mul_f32_e32 v60, v60, v60
	v_mul_f32_e32 v62, v62, v62
	v_fmac_f32_e32 v51, v50, v50
	v_fmac_f32_e32 v57, v56, v56
	v_fmac_f32_e32 v60, v59, v59
	v_fmac_f32_e32 v62, v61, v61
	v_add_f32_e32 v50, v51, v57
	v_add_f32_e32 v51, v60, v62
	v_add_f32_e32 v50, v50, v51
	v_add_f32_e32 v50, v58, v50
	ds_bpermute_b32 v51, v132, v50
	s_waitcnt lgkmcnt(0)
	v_add_f32_e32 v50, v50, v51
	ds_bpermute_b32 v51, v133, v50
	s_and_saveexec_b64 s[8:9], s[6:7]
	s_cbranch_execz .LBB1_823
	s_waitcnt lgkmcnt(0)
	v_add_f32_e32 v52, v50, v51
	s_lshl_b32 s28, s0, 2
	v_lshlrev_b64 v[50:51], 6, v[74:75]
	s_ashr_i32 s29, s28, 31
	v_lshl_add_u64 v[50:51], s[20:21], 0, v[50:51]
	v_lshl_add_u64 v[50:51], s[28:29], 2, v[50:51]
	s_lshl_b32 s74, s45, 2
	v_lshl_add_u64 v[50:51], v[50:51], 0, s[74:75]
	global_store_dword v[50:51], v52, off
.LBB1_823:
	s_or_b64 exec, exec, s[8:9]
	v_add_u32_e32 v50, 0x90, v158
	s_waitcnt lgkmcnt(0)
	v_ashrrev_i32_e32 v51, 31, v50
	v_lshlrev_b64 v[52:53], 10, v[50:51]
	v_lshl_add_u64 v[52:53], v[52:53], 0, v[156:157]
	v_lshlrev_b64 v[56:57], 1, v[52:53]
	v_lshl_add_u64 v[58:59], s[24:25], 0, v[56:57]
	v_mov_b32_e32 v52, v188
	v_mov_b32_e32 v53, v189
	v_mov_b32_e32 v54, v190
	v_mov_b32_e32 v55, v191
	v_add_f32_e32 v46, v46, v86
	v_add_f32_e32 v47, v47, v87
	v_add_f32_e32 v48, v48, v88
	v_add_f32_e32 v49, v49, v89
	v_add_f32_e32 v42, v42, v78
	v_add_f32_e32 v43, v43, v79
	v_add_f32_e32 v44, v44, v80
	v_add_f32_e32 v45, v45, v81
	v_lshl_add_u64 v[56:57], s[22:23], 0, v[56:57]
	v_add_f32_e32 v39, v39, v71
	v_add_f32_e32 v41, v41, v73
	v_add_f32_e32 v38, v38, v70
	v_add_f32_e32 v40, v40, v72
	v_add_f32_e32 v34, v34, v66
	v_add_f32_e32 v35, v35, v67
	v_add_f32_e32 v36, v36, v68
	v_add_f32_e32 v37, v37, v69
	s_nop 0
	v_lshlrev_b32_e32 v60, 16, v52
	v_and_b32_e32 v52, 0xffff0000, v52
	v_lshlrev_b32_e32 v61, 16, v53
	v_and_b32_e32 v53, 0xffff0000, v53
	v_lshlrev_b32_e32 v62, 16, v54
	v_and_b32_e32 v54, 0xffff0000, v54
	v_lshlrev_b32_e32 v63, 16, v55
	v_and_b32_e32 v55, 0xffff0000, v55
	v_fmac_f32_e32 v60, s11, v46
	v_fmac_f32_e32 v52, s11, v47
	v_fmac_f32_e32 v61, s11, v48
	v_fmac_f32_e32 v53, s11, v49
	v_fmac_f32_e32 v62, s11, v42
	v_fmac_f32_e32 v54, s11, v43
	v_fmac_f32_e32 v63, s11, v44
	v_fmac_f32_e32 v55, s11, v45
	v_cvt_pk_bf16_f32 v42, v60, v52
	v_cvt_pk_bf16_f32 v43, v61, v53
	v_cvt_pk_bf16_f32 v44, v62, v54
	v_cvt_pk_bf16_f32 v45, v63, v55
	global_store_dwordx4 v[56:57], v[42:45], off
	v_mov_b32_e32 v46, v200
	v_mov_b32_e32 v47, v201
	v_mov_b32_e32 v48, v202
	v_mov_b32_e32 v49, v203
	v_lshlrev_b32_e32 v52, 16, v42
	v_and_b32_e32 v42, 0xffff0000, v42
	v_lshlrev_b32_e32 v53, 16, v43
	v_and_b32_e32 v43, 0xffff0000, v43
	v_lshlrev_b32_e32 v54, 16, v44
	v_and_b32_e32 v44, 0xffff0000, v44
	v_lshlrev_b32_e32 v55, 16, v45
	v_and_b32_e32 v45, 0xffff0000, v45
	v_mul_f32_e32 v42, v42, v42
	v_mul_f32_e32 v43, v43, v43
	v_mul_f32_e32 v44, v44, v44
	v_mul_f32_e32 v45, v45, v45
	v_fmac_f32_e32 v42, v52, v52
	v_fmac_f32_e32 v43, v53, v53
	v_fmac_f32_e32 v44, v54, v54
	v_fmac_f32_e32 v45, v55, v55
	v_add_f32_e32 v42, v42, v43
	v_add_f32_e32 v43, v44, v45
	v_add_f32_e32 v42, v42, v43
	s_nop 0
	v_lshlrev_b32_e32 v43, 16, v46
	v_and_b32_e32 v44, 0xffff0000, v46
	v_and_b32_e32 v46, 0xffff0000, v47
	v_lshlrev_b32_e32 v45, 16, v47
	v_lshlrev_b32_e32 v47, 16, v48
	v_and_b32_e32 v48, 0xffff0000, v48
	v_lshlrev_b32_e32 v52, 16, v49
	v_and_b32_e32 v49, 0xffff0000, v49
	v_fmac_f32_e32 v44, s11, v39
	v_fmac_f32_e32 v46, s11, v41
	v_fmac_f32_e32 v43, s11, v38
	v_fmac_f32_e32 v45, s11, v40
	v_fmac_f32_e32 v47, s11, v34
	v_fmac_f32_e32 v48, s11, v35
	v_fmac_f32_e32 v52, s11, v36
	v_fmac_f32_e32 v49, s11, v37
	v_cvt_pk_bf16_f32 v36, v43, v44
	v_cvt_pk_bf16_f32 v37, v45, v46
	v_cvt_pk_bf16_f32 v38, v47, v48
	v_cvt_pk_bf16_f32 v39, v52, v49
	global_store_dwordx4 v[56:57], v[36:39], off offset:256
	v_and_b32_e32 v35, 0xffff0000, v36
	v_and_b32_e32 v41, 0xffff0000, v37
	v_and_b32_e32 v44, 0xffff0000, v38
	v_and_b32_e32 v46, 0xffff0000, v39
	v_lshlrev_b32_e32 v34, 16, v36
	v_lshlrev_b32_e32 v40, 16, v37
	v_lshlrev_b32_e32 v43, 16, v38
	v_lshlrev_b32_e32 v45, 16, v39
	v_mul_f32_e32 v35, v35, v35
	v_mul_f32_e32 v41, v41, v41
	v_mul_f32_e32 v44, v44, v44
	v_mul_f32_e32 v46, v46, v46
	v_fmac_f32_e32 v35, v34, v34
	v_fmac_f32_e32 v41, v40, v40
	v_fmac_f32_e32 v44, v43, v43
	v_fmac_f32_e32 v46, v45, v45
	v_add_f32_e32 v34, v35, v41
	v_add_f32_e32 v35, v44, v46
	v_add_f32_e32 v34, v34, v35
	v_add_f32_e32 v34, v42, v34
	ds_bpermute_b32 v35, v132, v34
	s_waitcnt lgkmcnt(0)
; __device__ __forceinline__ unsigned cvt_pk_bf16(float lo, float hi) { unsigned r; asm volatile("v_cvt_pk_bf16_f32 %0, %1, %2" : "=v"(r) : "v"(lo), "v"(hi)); return r; }
; __device__ __forceinline__ float bflo(unsigned w) { return __uint_as_float(w << 16); }
;     __device__ __forceinline__ void operator()(const f32x4 (&acc)[2][2][4][2], const Unit& u, int wr, int wc, int fr, int fq, LAS unsigned char* lds) const {
;     ...
;             for (int m = 0; m < 4; ++m) { const int row = row0 + ai * HALF + m * 16; const size_t off = (size_t)row * D + col0;
;                 float rs = 1.0f; if (MODE == 1) rs = rstd_of4(rss_in, row, fq);
;                 float ss = 0.f;
; #pragma unroll
;                 for (int bj = 0; bj < 2; ++bj) { const size_t o = off + bj * HALF; const u32x4 bw = *(const u32x4*)(base + o);
;                     const float bs[8] = {bflo(bw.x), bfhi(bw.x), bflo(bw.y), bfhi(bw.y), bflo(bw.z), bfhi(bw.z), bflo(bw.w), bfhi(bw.w)};
;                     float hn[8];
;                     if (MODE == 0) {
; #pragma unroll
;                         for (int n = 0; n < 2; ++n)
; #pragma unroll
;                             for (int e = 0; e < 4; ++e) hn[4 * n + e] = bs[4 * n + e] + (acc[ai][bj][m][n][e] + bv[bj][n][e]) * scale;
;                     } else { const u32x4 pw = *(const u32x4*)(pp + o);
;                         const float pv[8] = {bflo(pw.x), bfhi(pw.x), bflo(pw.y), bfhi(pw.y), bflo(pw.z), bfhi(pw.z), bflo(pw.w), bfhi(pw.w)};
; #pragma unroll
;                         for (int n = 0; n < 2; ++n)
; #pragma unroll
;                             for (int e = 0; e < 4; ++e) hn[4 * n + e] = bs[4 * n + e] + fast_sigmoid(acc[ai][bj][m][n][e] * rs) * pv[4 * n + e]; }
;                     u32x4 w; w.x = cvt_pk_bf16(hn[0], hn[1]); w.y = cvt_pk_bf16(hn[2], hn[3]); w.z = cvt_pk_bf16(hn[4], hn[5]); w.w = cvt_pk_bf16(hn[6], hn[7]); *(u32x4*)(hb + o) = w;
;                     const float hr[8] = {bflo(w.x), bfhi(w.x), bflo(w.y), bfhi(w.y), bflo(w.z), bfhi(w.z), bflo(w.w), bfhi(w.w)};
;                     ss += ((hr[0] * hr[0] + hr[1] * hr[1]) + (hr[2] * hr[2] + hr[3] * hr[3])) + ((hr[4] * hr[4] + hr[5] * hr[5]) + (hr[6] * hr[6] + hr[7] * hr[7])); }
;                 ss += __shfl_xor(ss, 16); ss += __shfl_xor(ss, 32);
;                 if (fq == 0) rss_out[(size_t)row * 16 + u.pn * 4 + wc] = ss; }
	v_add_f32_e32 v34, v34, v35
	ds_bpermute_b32 v35, v133, v34
	s_and_saveexec_b64 s[8:9], s[6:7]
	s_cbranch_execz .LBB1_825
	s_waitcnt lgkmcnt(0)
	v_add_f32_e32 v36, v34, v35
	s_lshl_b32 s28, s0, 2
	v_lshlrev_b64 v[34:35], 6, v[50:51]
	s_ashr_i32 s29, s28, 31
	v_lshl_add_u64 v[34:35], s[20:21], 0, v[34:35]
	v_lshl_add_u64 v[34:35], s[28:29], 2, v[34:35]
	s_lshl_b32 s74, s45, 2
	v_lshl_add_u64 v[34:35], v[34:35], 0, s[74:75]
	global_store_dword v[34:35], v36, off
.LBB1_825:
	s_or_b64 exec, exec, s[8:9]
	v_add_u32_e32 v34, 0xa0, v158
	s_waitcnt lgkmcnt(0)
	v_ashrrev_i32_e32 v35, 31, v34
	v_lshlrev_b64 v[36:37], 10, v[34:35]
	v_lshl_add_u64 v[36:37], v[36:37], 0, v[156:157]
	v_lshlrev_b64 v[40:41], 1, v[36:37]
	v_lshl_add_u64 v[42:43], s[24:25], 0, v[40:41]
	v_mov_b32_e32 v36, v204
	v_mov_b32_e32 v37, v205
	v_mov_b32_e32 v38, v206
	v_mov_b32_e32 v39, v207
	v_add_f32_e32 v30, v30, v86
	v_add_f32_e32 v31, v31, v87
	v_add_f32_e32 v32, v32, v88
	v_add_f32_e32 v33, v33, v89
	v_add_f32_e32 v26, v26, v78
	v_add_f32_e32 v27, v27, v79
	v_add_f32_e32 v28, v28, v80
	v_add_f32_e32 v29, v29, v81
	v_lshl_add_u64 v[40:41], s[22:23], 0, v[40:41]
	v_add_f32_e32 v23, v23, v71
	v_add_f32_e32 v25, v25, v73
	v_add_f32_e32 v22, v22, v70
	v_add_f32_e32 v24, v24, v72
	v_add_f32_e32 v18, v18, v66
	v_add_f32_e32 v19, v19, v67
	v_add_f32_e32 v20, v20, v68
	v_add_f32_e32 v21, v21, v69
	s_nop 0
	v_lshlrev_b32_e32 v44, 16, v36
	v_and_b32_e32 v36, 0xffff0000, v36
	v_lshlrev_b32_e32 v45, 16, v37
	v_and_b32_e32 v37, 0xffff0000, v37
	v_lshlrev_b32_e32 v46, 16, v38
	v_and_b32_e32 v38, 0xffff0000, v38
	v_lshlrev_b32_e32 v47, 16, v39
	v_and_b32_e32 v39, 0xffff0000, v39
	v_fmac_f32_e32 v44, s11, v30
	v_fmac_f32_e32 v36, s11, v31
	v_fmac_f32_e32 v45, s11, v32
	v_fmac_f32_e32 v37, s11, v33
	v_fmac_f32_e32 v46, s11, v26
	v_fmac_f32_e32 v38, s11, v27
	v_fmac_f32_e32 v47, s11, v28
	v_fmac_f32_e32 v39, s11, v29
	v_cvt_pk_bf16_f32 v26, v44, v36
	v_cvt_pk_bf16_f32 v27, v45, v37
	v_cvt_pk_bf16_f32 v28, v46, v38
	v_cvt_pk_bf16_f32 v29, v47, v39
	global_store_dwordx4 v[40:41], v[26:29], off
	v_mov_b32_e32 v30, v208
	v_mov_b32_e32 v31, v209
	v_mov_b32_e32 v32, v210
	v_mov_b32_e32 v33, v211
	v_lshlrev_b32_e32 v36, 16, v26
	v_and_b32_e32 v26, 0xffff0000, v26
	v_lshlrev_b32_e32 v37, 16, v27
	v_and_b32_e32 v27, 0xffff0000, v27
	v_lshlrev_b32_e32 v38, 16, v28
	v_and_b32_e32 v28, 0xffff0000, v28
	v_lshlrev_b32_e32 v39, 16, v29
	v_and_b32_e32 v29, 0xffff0000, v29
	v_mul_f32_e32 v26, v26, v26
	v_mul_f32_e32 v27, v27, v27
	v_mul_f32_e32 v28, v28, v28
	v_mul_f32_e32 v29, v29, v29
	v_fmac_f32_e32 v26, v36, v36
	v_fmac_f32_e32 v27, v37, v37
	v_fmac_f32_e32 v28, v38, v38
	v_fmac_f32_e32 v29, v39, v39
	v_add_f32_e32 v26, v26, v27
	v_add_f32_e32 v27, v28, v29
	v_add_f32_e32 v26, v26, v27
	s_nop 0
	v_lshlrev_b32_e32 v27, 16, v30
	v_and_b32_e32 v28, 0xffff0000, v30
	v_and_b32_e32 v30, 0xffff0000, v31
	v_lshlrev_b32_e32 v29, 16, v31
	v_lshlrev_b32_e32 v31, 16, v32
	v_and_b32_e32 v32, 0xffff0000, v32
	v_lshlrev_b32_e32 v36, 16, v33
	v_and_b32_e32 v33, 0xffff0000, v33
	v_fmac_f32_e32 v28, s11, v23
	v_fmac_f32_e32 v30, s11, v25
	v_fmac_f32_e32 v27, s11, v22
	v_fmac_f32_e32 v29, s11, v24
	v_fmac_f32_e32 v31, s11, v18
	v_fmac_f32_e32 v32, s11, v19
	v_fmac_f32_e32 v36, s11, v20
	v_fmac_f32_e32 v33, s11, v21
	v_cvt_pk_bf16_f32 v20, v27, v28
	v_cvt_pk_bf16_f32 v21, v29, v30
	v_cvt_pk_bf16_f32 v22, v31, v32
	v_cvt_pk_bf16_f32 v23, v36, v33
	global_store_dwordx4 v[40:41], v[20:23], off offset:256
	v_and_b32_e32 v19, 0xffff0000, v20
	v_and_b32_e32 v25, 0xffff0000, v21
	v_and_b32_e32 v28, 0xffff0000, v22
	v_and_b32_e32 v30, 0xffff0000, v23
	v_lshlrev_b32_e32 v18, 16, v20
	v_lshlrev_b32_e32 v24, 16, v21
	v_lshlrev_b32_e32 v27, 16, v22
	v_lshlrev_b32_e32 v29, 16, v23
	v_mul_f32_e32 v19, v19, v19
	v_mul_f32_e32 v25, v25, v25
	v_mul_f32_e32 v28, v28, v28
	v_mul_f32_e32 v30, v30, v30
	v_fmac_f32_e32 v19, v18, v18
	v_fmac_f32_e32 v25, v24, v24
	v_fmac_f32_e32 v28, v27, v27
	v_fmac_f32_e32 v30, v29, v29
	v_add_f32_e32 v18, v19, v25
	v_add_f32_e32 v19, v28, v30
	v_add_f32_e32 v18, v18, v19
	v_add_f32_e32 v18, v26, v18
	ds_bpermute_b32 v19, v132, v18
	s_waitcnt lgkmcnt(0)
	v_add_f32_e32 v18, v18, v19
	ds_bpermute_b32 v19, v133, v18
	s_and_saveexec_b64 s[8:9], s[6:7]
	s_cbranch_execz .LBB1_827
	s_waitcnt lgkmcnt(0)
	v_add_f32_e32 v20, v18, v19
	s_lshl_b32 s28, s0, 2
	v_lshlrev_b64 v[18:19], 6, v[34:35]
	s_ashr_i32 s29, s28, 31
	v_lshl_add_u64 v[18:19], s[20:21], 0, v[18:19]
	v_lshl_add_u64 v[18:19], s[28:29], 2, v[18:19]
	s_lshl_b32 s74, s45, 2
	v_lshl_add_u64 v[18:19], v[18:19], 0, s[74:75]
	global_store_dword v[18:19], v20, off
; __device__ __forceinline__ unsigned cvt_pk_bf16(float lo, float hi) { unsigned r; asm volatile("v_cvt_pk_bf16_f32 %0, %1, %2" : "=v"(r) : "v"(lo), "v"(hi)); return r; }
; __device__ __forceinline__ float bflo(unsigned w) { return __uint_as_float(w << 16); }
;     __device__ __forceinline__ void operator()(const f32x4 (&acc)[2][2][4][2], const Unit& u, int wr, int wc, int fr, int fq, LAS unsigned char* lds) const {
;     ...
;             for (int m = 0; m < 4; ++m) { const int row = row0 + ai * HALF + m * 16; const size_t off = (size_t)row * D + col0;
;                 float rs = 1.0f; if (MODE == 1) rs = rstd_of4(rss_in, row, fq);
;                 float ss = 0.f;
; #pragma unroll
;                 for (int bj = 0; bj < 2; ++bj) { const size_t o = off + bj * HALF; const u32x4 bw = *(const u32x4*)(base + o);
;                     const float bs[8] = {bflo(bw.x), bfhi(bw.x), bflo(bw.y), bfhi(bw.y), bflo(bw.z), bfhi(bw.z), bflo(bw.w), bfhi(bw.w)};
;                     float hn[8];
;                     if (MODE == 0) {
; #pragma unroll
;                         for (int n = 0; n < 2; ++n)
; #pragma unroll
;                             for (int e = 0; e < 4; ++e) hn[4 * n + e] = bs[4 * n + e] + (acc[ai][bj][m][n][e] + bv[bj][n][e]) * scale;
;                     } else { const u32x4 pw = *(const u32x4*)(pp + o);
;                         const float pv[8] = {bflo(pw.x), bfhi(pw.x), bflo(pw.y), bfhi(pw.y), bflo(pw.z), bfhi(pw.z), bflo(pw.w), bfhi(pw.w)};
; #pragma unroll
;                         for (int n = 0; n < 2; ++n)
; #pragma unroll
;                             for (int e = 0; e < 4; ++e) hn[4 * n + e] = bs[4 * n + e] + fast_sigmoid(acc[ai][bj][m][n][e] * rs) * pv[4 * n + e]; }
;                     u32x4 w; w.x = cvt_pk_bf16(hn[0], hn[1]); w.y = cvt_pk_bf16(hn[2], hn[3]); w.z = cvt_pk_bf16(hn[4], hn[5]); w.w = cvt_pk_bf16(hn[6], hn[7]); *(u32x4*)(hb + o) = w;
;                     const float hr[8] = {bflo(w.x), bfhi(w.x), bflo(w.y), bfhi(w.y), bflo(w.z), bfhi(w.z), bflo(w.w), bfhi(w.w)};
;                     ss += ((hr[0] * hr[0] + hr[1] * hr[1]) + (hr[2] * hr[2] + hr[3] * hr[3])) + ((hr[4] * hr[4] + hr[5] * hr[5]) + (hr[6] * hr[6] + hr[7] * hr[7])); }
;                 ss += __shfl_xor(ss, 16); ss += __shfl_xor(ss, 32);
;                 if (fq == 0) rss_out[(size_t)row * 16 + u.pn * 4 + wc] = ss; }
.LBB1_827:
	s_or_b64 exec, exec, s[8:9]
	v_add_u32_e32 v18, 0xb0, v158
	s_waitcnt lgkmcnt(0)
	v_ashrrev_i32_e32 v19, 31, v18
	v_lshlrev_b64 v[20:21], 10, v[18:19]
	v_lshl_add_u64 v[20:21], v[20:21], 0, v[156:157]
	v_lshlrev_b64 v[24:25], 1, v[20:21]
	v_lshl_add_u64 v[26:27], s[24:25], 0, v[24:25]
	v_mov_b32_e32 v20, v212
	v_mov_b32_e32 v21, v213
	v_mov_b32_e32 v22, v214
	v_mov_b32_e32 v23, v215
	v_add_f32_e32 v14, v14, v86
	v_add_f32_e32 v15, v15, v87
	v_add_f32_e32 v16, v16, v88
	v_add_f32_e32 v17, v17, v89
	v_add_f32_e32 v10, v10, v78
	v_add_f32_e32 v11, v11, v79
	v_add_f32_e32 v12, v12, v80
	v_add_f32_e32 v13, v13, v81
	v_lshl_add_u64 v[24:25], s[22:23], 0, v[24:25]
	v_add_f32_e32 v7, v7, v71
	v_add_f32_e32 v9, v9, v73
	v_add_f32_e32 v6, v6, v70
	v_add_f32_e32 v8, v8, v72
	v_add_f32_e32 v0, v0, v66
	v_add_f32_e32 v1, v1, v67
	v_add_f32_e32 v2, v2, v68
	v_add_f32_e32 v3, v3, v69
	s_nop 0
	v_lshlrev_b32_e32 v28, 16, v20
	v_and_b32_e32 v20, 0xffff0000, v20
	v_lshlrev_b32_e32 v29, 16, v21
	v_and_b32_e32 v21, 0xffff0000, v21
	v_lshlrev_b32_e32 v30, 16, v22
	v_and_b32_e32 v22, 0xffff0000, v22
	v_lshlrev_b32_e32 v31, 16, v23
	v_and_b32_e32 v23, 0xffff0000, v23
	v_fmac_f32_e32 v28, s11, v14
	v_fmac_f32_e32 v20, s11, v15
	v_fmac_f32_e32 v29, s11, v16
	v_fmac_f32_e32 v21, s11, v17
	v_fmac_f32_e32 v30, s11, v10
	v_fmac_f32_e32 v22, s11, v11
	v_fmac_f32_e32 v31, s11, v12
	v_fmac_f32_e32 v23, s11, v13
	v_cvt_pk_bf16_f32 v10, v28, v20
	v_cvt_pk_bf16_f32 v11, v29, v21
	v_cvt_pk_bf16_f32 v12, v30, v22
	v_cvt_pk_bf16_f32 v13, v31, v23
	global_store_dwordx4 v[24:25], v[10:13], off
	v_mov_b32_e32 v14, v216
	v_mov_b32_e32 v15, v217
	v_mov_b32_e32 v16, v218
	v_mov_b32_e32 v17, v219
	v_lshlrev_b32_e32 v20, 16, v10
	v_and_b32_e32 v10, 0xffff0000, v10
	v_lshlrev_b32_e32 v21, 16, v11
	v_and_b32_e32 v11, 0xffff0000, v11
	v_lshlrev_b32_e32 v22, 16, v12
	v_and_b32_e32 v12, 0xffff0000, v12
	v_lshlrev_b32_e32 v23, 16, v13
	v_and_b32_e32 v13, 0xffff0000, v13
	v_mul_f32_e32 v10, v10, v10
	v_mul_f32_e32 v11, v11, v11
	v_mul_f32_e32 v12, v12, v12
	v_mul_f32_e32 v13, v13, v13
	v_fmac_f32_e32 v10, v20, v20
	v_fmac_f32_e32 v11, v21, v21
	v_fmac_f32_e32 v12, v22, v22
	v_fmac_f32_e32 v13, v23, v23
	v_add_f32_e32 v10, v10, v11
	v_add_f32_e32 v11, v12, v13
	v_add_f32_e32 v10, v10, v11
	s_nop 0
	v_lshlrev_b32_e32 v11, 16, v14
	v_and_b32_e32 v12, 0xffff0000, v14
	v_and_b32_e32 v14, 0xffff0000, v15
	v_lshlrev_b32_e32 v13, 16, v15
	v_lshlrev_b32_e32 v15, 16, v16
	v_and_b32_e32 v16, 0xffff0000, v16
	v_lshlrev_b32_e32 v20, 16, v17
	v_and_b32_e32 v17, 0xffff0000, v17
	v_fmac_f32_e32 v12, s11, v7
	v_fmac_f32_e32 v14, s11, v9
	v_fmac_f32_e32 v11, s11, v6
	v_fmac_f32_e32 v13, s11, v8
	v_fmac_f32_e32 v15, s11, v0
	v_fmac_f32_e32 v16, s11, v1
	v_fmac_f32_e32 v20, s11, v2
	v_fmac_f32_e32 v17, s11, v3
	v_cvt_pk_bf16_f32 v6, v11, v12
	v_cvt_pk_bf16_f32 v7, v13, v14
	v_cvt_pk_bf16_f32 v8, v15, v16
	v_cvt_pk_bf16_f32 v9, v20, v17
	global_store_dwordx4 v[24:25], v[6:9], off offset:256
	v_and_b32_e32 v1, 0xffff0000, v6
	v_and_b32_e32 v3, 0xffff0000, v7
	v_and_b32_e32 v12, 0xffff0000, v8
	v_and_b32_e32 v14, 0xffff0000, v9
	v_lshlrev_b32_e32 v0, 16, v6
	v_lshlrev_b32_e32 v2, 16, v7
	v_lshlrev_b32_e32 v11, 16, v8
	v_lshlrev_b32_e32 v13, 16, v9
	v_mul_f32_e32 v1, v1, v1
	v_mul_f32_e32 v3, v3, v3
	v_mul_f32_e32 v12, v12, v12
	v_mul_f32_e32 v14, v14, v14
	v_fmac_f32_e32 v1, v0, v0
	v_fmac_f32_e32 v3, v2, v2
	v_fmac_f32_e32 v12, v11, v11
	v_fmac_f32_e32 v14, v13, v13
	v_add_f32_e32 v0, v1, v3
	v_add_f32_e32 v1, v12, v14
	v_add_f32_e32 v0, v0, v1
	v_add_f32_e32 v0, v10, v0
	ds_bpermute_b32 v1, v132, v0
	s_waitcnt lgkmcnt(0)
	v_add_f32_e32 v0, v0, v1
	ds_bpermute_b32 v1, v133, v0
	s_and_saveexec_b64 s[8:9], s[6:7]
	s_cbranch_execz .LBB1_800
	s_waitcnt lgkmcnt(0)
	v_add_f32_e32 v2, v0, v1
	s_lshl_b32 s22, s0, 2
	v_lshlrev_b64 v[0:1], 6, v[18:19]
	s_ashr_i32 s23, s22, 31
	v_lshl_add_u64 v[0:1], s[20:21], 0, v[0:1]
	v_lshl_add_u64 v[0:1], s[22:23], 2, v[0:1]
	s_lshl_b32 s74, s45, 2
	v_lshl_add_u64 v[0:1], v[0:1], 0, s[74:75]
	global_store_dword v[0:1], v2, off
	s_branch .LBB1_800

; #define PG8_STAGE(bufoff, gbase, voff) do { _Pragma("unroll") for (int _i = 0; _i < 2; ++_i) \
;         __builtin_amdgcn_global_load_lds((const unsigned*)((const char*)(gbase) + (voff)[_i]), (LAS unsigned*)(lds + (bufoff) + ldsw + _i * 8192), 16, 0, 0); } while (0)
; #define PG8_LDA(dst, b, h) do { _Pragma("unroll") for (int m = 0; m < 4; ++m) _Pragma("unroll") for (int k = 0; k < 2; ++k) dst[m][k] = *(const LAS bf16x8*)(lds + PG8_SA(b, h) + aoff + m * 2048 + k * 1024); } while (0)
; #define PG8_WAIT_V(n) asm volatile("s_waitcnt vmcnt(" #n ")" ::: "memory")
; template <class Epi, int KK, int LDA, int LDB, int NN, bool AGRP>
; __device__ __forceinline__ void gemm_phase(LAS unsigned char* lds, const bf16_t* gA, const bf16_t* gBt, int G_, int bid_, int tid) {
;     ...
;         for (int t = 0; t < nt; t += 2) {
;             const bool last = (t == nt - 2);
;             const char* a1 = cA + (size_t)(t + 1) * kstep;
;             const char* a2 = last ? nA : cA + (size_t)(t + 2) * kstep; const char* b2 = last ? nB : cB + (size_t)(t + 2) * kstep;
;             const char* a3 = a2 + kstep; const char* b3 = b2 + kstep;
;             PG8_LDB(B0, 0, 0); PG8_SCHED; PG8_LDA(At, 0, 0); PG8_STAGE(PG8_SA(1, 1), a1 + hstepA, voffA);
;             PG8_WAIT_L(8); PG8_BAR; PG8_WAIT_L(0); PG8_MMA(0, 0, At, B0); PG8_BAR; PG8_SCHED;
;             PG8_LDB(B1, 0, 1); PG8_STAGE(PG8_SB(0, 0), b2, voffB);
;             PG8_BAR; PG8_WAIT_L(0); PG8_MMA(0, 1, At, B1); PG8_BAR;
;             PG8_LDA(At, 0, 1); PG8_STAGE(PG8_SA(0, 0), a2, voffA);
;             PG8_BAR; PG8_WAIT_L(0); PG8_MMA(1, 0, At, B0); PG8_BAR; PG8_SCHED;
;             PG8_STAGE(PG8_SB(0, 1), b2 + hstepB, voffB);
;             PG8_WAIT_V(6); PG8_BAR; PG8_MMA(1, 1, At, B1); PG8_BAR;
;             PG8_LDB(B0, 1, 0); PG8_SCHED; PG8_LDA(At, 1, 0); PG8_STAGE(PG8_SA(0, 1), a2 + hstepA, voffA);
;             PG8_WAIT_L(8); PG8_BAR; PG8_WAIT_L(0); PG8_MMA(0, 0, At, B0); PG8_BAR; PG8_SCHED;
;             PG8_LDB(B1, 1, 1); PG8_STAGE(PG8_SB(1, 0), b3, voffB);
;             PG8_BAR; PG8_WAIT_L(0); PG8_MMA(0, 1, At, B1); PG8_BAR;
;             PG8_LDA(At, 1, 1); PG8_STAGE(PG8_SA(1, 0), a3, voffA);
;             PG8_BAR; PG8_WAIT_L(0); PG8_MMA(1, 0, At, B0); PG8_BAR; PG8_SCHED;
;             PG8_STAGE(PG8_SB(1, 1), b3 + hstepB, voffB);
;             PG8_WAIT_V(6); PG8_BAR; PG8_MMA(1, 1, At, B1); PG8_BAR;
.LBB1_843:
	v_add_u32_e32 v146, s17, v151
	ds_read_b128 v[142:145], v146
	ds_read_b128 v[154:157], v146 offset:1024
	ds_read_b128 v[158:161], v146 offset:2048
	ds_read_b128 v[162:165], v146 offset:3072
	s_add_u32 s20, s18, 0xfffc0080
	s_addc_u32 s21, s19, -1
	s_cmp_eq_u32 s57, 12
	s_cselect_b32 s23, s7, s21
	s_cselect_b32 s22, s53, s20
	s_cselect_b32 s21, s9, s56
	s_cselect_b32 s20, s54, s55
	ds_read_b128 v[166:169], v153
	ds_read_b128 v[176:179], v153 offset:1024
	ds_read_b128 v[180:183], v153 offset:2048
	ds_read_b128 v[184:187], v153 offset:3072
	ds_read_b128 v[188:191], v153 offset:4096
	ds_read_b128 v[200:203], v153 offset:5120
	ds_read_b128 v[204:207], v153 offset:6144
	ds_read_b128 v[208:211], v153 offset:7168
	s_waitcnt lgkmcnt(8)
	s_barrier
	s_waitcnt lgkmcnt(0)
	s_setprio 1
	s_waitcnt lgkmcnt(0)
	v_mfma_f32_16x16x32_bf16 v[126:129], v[142:145], v[166:169], v[126:129]
	v_mfma_f32_16x16x32_bf16 v[118:121], v[158:161], v[166:169], v[118:121]
	v_lshl_add_u64 v[146:147], s[18:19], 0, v[140:141]
	s_add_i32 m0, s31, 0xc000
	v_mfma_f32_16x16x32_bf16 v[110:113], v[142:145], v[180:183], v[110:113]
	v_mfma_f32_16x16x32_bf16 v[102:105], v[158:161], v[180:183], v[102:105]
	global_load_lds_dwordx4 v[146:147], off
	v_mfma_f32_16x16x32_bf16 v[94:97], v[142:145], v[188:191], v[94:97]
	v_mfma_f32_16x16x32_bf16 v[86:89], v[158:161], v[188:191], v[86:89]
	v_mfma_f32_16x16x32_bf16 v[78:81], v[142:145], v[204:207], v[78:81]
	v_mfma_f32_16x16x32_bf16 v[70:73], v[158:161], v[204:207], v[70:73]
	v_lshl_add_u64 v[146:147], s[18:19], 0, v[138:139]
	s_add_i32 m0, s31, 0xe000
	v_mfma_f32_16x16x32_bf16 v[126:129], v[154:157], v[176:179], v[126:129]
	v_mfma_f32_16x16x32_bf16 v[118:121], v[162:165], v[176:179], v[118:121]
	global_load_lds_dwordx4 v[146:147], off
	v_mfma_f32_16x16x32_bf16 v[110:113], v[154:157], v[184:187], v[110:113]
	v_mfma_f32_16x16x32_bf16 v[102:105], v[162:165], v[184:187], v[102:105]
	v_mfma_f32_16x16x32_bf16 v[94:97], v[154:157], v[200:203], v[94:97]
	v_mfma_f32_16x16x32_bf16 v[86:89], v[162:165], v[200:203], v[86:89]
	v_mfma_f32_16x16x32_bf16 v[78:81], v[154:157], v[208:211], v[78:81]
	v_mfma_f32_16x16x32_bf16 v[70:73], v[162:165], v[208:211], v[70:73]
	s_setprio 0
	s_barrier
	v_add_u32_e32 v146, s35, v151
	ds_read_b128 v[212:215], v146
	ds_read_b128 v[216:219], v146 offset:1024
	ds_read_b128 v[220:223], v146 offset:2048
	ds_read_b128 v[224:227], v146 offset:3072
	s_barrier
	s_waitcnt lgkmcnt(0)
	s_setprio 1
	s_waitcnt lgkmcnt(0)
	v_mfma_f32_16x16x32_bf16 v[122:125], v[212:215], v[166:169], v[122:125]
	v_mfma_f32_16x16x32_bf16 v[114:117], v[220:223], v[166:169], v[114:117]
	s_mov_b32 m0, s29
	v_lshl_add_u64 v[146:147], s[20:21], 0, v[134:135]
	v_mfma_f32_16x16x32_bf16 v[106:109], v[212:215], v[180:183], v[106:109]
	v_mfma_f32_16x16x32_bf16 v[98:101], v[220:223], v[180:183], v[98:101]
	global_load_lds_dwordx4 v[146:147], off
	v_mfma_f32_16x16x32_bf16 v[90:93], v[212:215], v[188:191], v[90:93]
	v_mfma_f32_16x16x32_bf16 v[82:85], v[220:223], v[188:191], v[82:85]
	v_mfma_f32_16x16x32_bf16 v[74:77], v[212:215], v[204:207], v[74:77]
	v_mfma_f32_16x16x32_bf16 v[66:69], v[220:223], v[204:207], v[66:69]
	v_lshl_add_u64 v[194:195], s[20:21], 0, v[130:131]
	s_mov_b32 m0, s30
	v_mfma_f32_16x16x32_bf16 v[122:125], v[216:219], v[176:179], v[122:125]
	v_mfma_f32_16x16x32_bf16 v[114:117], v[224:227], v[176:179], v[114:117]
	global_load_lds_dwordx4 v[194:195], off
	v_mfma_f32_16x16x32_bf16 v[106:109], v[216:219], v[184:187], v[106:109]
	v_mfma_f32_16x16x32_bf16 v[98:101], v[224:227], v[184:187], v[98:101]
	v_mfma_f32_16x16x32_bf16 v[90:93], v[216:219], v[200:203], v[90:93]
	v_mfma_f32_16x16x32_bf16 v[82:85], v[224:227], v[200:203], v[82:85]
	v_mfma_f32_16x16x32_bf16 v[74:77], v[216:219], v[208:211], v[74:77]
	v_mfma_f32_16x16x32_bf16 v[66:69], v[224:227], v[208:211], v[66:69]
	s_setprio 0
	s_barrier
	ds_read_b128 v[166:169], v153 offset:16384
	ds_read_b128 v[176:179], v153 offset:17408
	ds_read_b128 v[180:183], v153 offset:18432
	ds_read_b128 v[184:187], v153 offset:19456
	ds_read_b128 v[188:191], v153 offset:20480
	ds_read_b128 v[200:203], v153 offset:21504
	ds_read_b128 v[204:207], v153 offset:22528
	ds_read_b128 v[208:211], v153 offset:23552
	s_barrier
	s_waitcnt lgkmcnt(0)
	s_setprio 1
	s_waitcnt lgkmcnt(0)
	v_mfma_f32_16x16x32_bf16 v[62:65], v[142:145], v[166:169], v[62:65]
	v_mfma_f32_16x16x32_bf16 v[54:57], v[158:161], v[166:169], v[54:57]
	s_mov_b32 m0, s31
	v_lshl_add_u64 v[196:197], s[22:23], 0, v[136:137]
	v_mfma_f32_16x16x32_bf16 v[46:49], v[142:145], v[180:183], v[46:49]
	v_mfma_f32_16x16x32_bf16 v[38:41], v[158:161], v[180:183], v[38:41]
	global_load_lds_dwordx4 v[196:197], off
	v_mfma_f32_16x16x32_bf16 v[30:33], v[142:145], v[188:191], v[30:33]
	v_mfma_f32_16x16x32_bf16 v[22:25], v[158:161], v[188:191], v[22:25]
	v_mfma_f32_16x16x32_bf16 v[14:17], v[142:145], v[204:207], v[14:17]
	v_mfma_f32_16x16x32_bf16 v[6:9], v[158:161], v[204:207], v[6:9]
	v_lshl_add_u64 v[228:229], s[22:23], 0, v[132:133]
	s_mov_b32 m0, s34
	v_mfma_f32_16x16x32_bf16 v[62:65], v[154:157], v[176:179], v[62:65]
	v_mfma_f32_16x16x32_bf16 v[54:57], v[162:165], v[176:179], v[54:57]
	global_load_lds_dwordx4 v[228:229], off
	v_mfma_f32_16x16x32_bf16 v[46:49], v[154:157], v[184:187], v[46:49]
	v_mfma_f32_16x16x32_bf16 v[38:41], v[162:165], v[184:187], v[38:41]
	v_mfma_f32_16x16x32_bf16 v[30:33], v[154:157], v[200:203], v[30:33]
	v_mfma_f32_16x16x32_bf16 v[22:25], v[162:165], v[200:203], v[22:25]
	v_mfma_f32_16x16x32_bf16 v[14:17], v[154:157], v[208:211], v[14:17]
	v_mfma_f32_16x16x32_bf16 v[6:9], v[162:165], v[208:211], v[6:9]
	s_setprio 0
	s_barrier
; #define PG8_STAGE(bufoff, gbase, voff) do { _Pragma("unroll") for (int _i = 0; _i < 2; ++_i) \
;         __builtin_amdgcn_global_load_lds((const unsigned*)((const char*)(gbase) + (voff)[_i]), (LAS unsigned*)(lds + (bufoff) + ldsw + _i * 8192), 16, 0, 0); } while (0)
; #define PG8_LDA(dst, b, h) do { _Pragma("unroll") for (int m = 0; m < 4; ++m) _Pragma("unroll") for (int k = 0; k < 2; ++k) dst[m][k] = *(const LAS bf16x8*)(lds + PG8_SA(b, h) + aoff + m * 2048 + k * 1024); } while (0)
; #define PG8_LDB(dst, b, h) do { _Pragma("unroll") for (int n = 0; n < 2; ++n) _Pragma("unroll") for (int k = 0; k < 2; ++k) dst[n][k] = *(const LAS bf16x8*)(lds + PG8_SB(b, h) + boff + n * 2048 + k * 1024); } while (0)
; #define PG8_WAIT_V(n) asm volatile("s_waitcnt vmcnt(" #n ")" ::: "memory")
; #define PG8_WAIT_L(n) asm volatile("s_waitcnt lgkmcnt(" #n ")" ::: "memory")
; #define PG8_BAR __builtin_amdgcn_s_barrier()
; template <class Epi, int KK, int LDA, int LDB, int NN, bool AGRP>
; __device__ __forceinline__ void gemm_phase(LAS unsigned char* lds, const bf16_t* gA, const bf16_t* gBt, int G_, int bid_, int tid) {
;     ...
;             PG8_LDB(B0, 0, 0); PG8_SCHED; PG8_LDA(At, 0, 0); PG8_STAGE(PG8_SA(1, 1), a1 + hstepA, voffA);
;             PG8_WAIT_L(8); PG8_BAR; PG8_WAIT_L(0); PG8_MMA(0, 0, At, B0); PG8_BAR; PG8_SCHED;
;             PG8_LDB(B1, 0, 1); PG8_STAGE(PG8_SB(0, 0), b2, voffB);
;             PG8_BAR; PG8_WAIT_L(0); PG8_MMA(0, 1, At, B1); PG8_BAR;
;             PG8_LDA(At, 0, 1); PG8_STAGE(PG8_SA(0, 0), a2, voffA);
;             PG8_BAR; PG8_WAIT_L(0); PG8_MMA(1, 0, At, B0); PG8_BAR; PG8_SCHED;
;             PG8_STAGE(PG8_SB(0, 1), b2 + hstepB, voffB);
;             PG8_WAIT_V(6); PG8_BAR; PG8_MMA(1, 1, At, B1); PG8_BAR;
;             PG8_LDB(B0, 1, 0); PG8_SCHED; PG8_LDA(At, 1, 0); PG8_STAGE(PG8_SA(0, 1), a2 + hstepA, voffA);
;             PG8_WAIT_L(8); PG8_BAR; PG8_WAIT_L(0); PG8_MMA(0, 0, At, B0); PG8_BAR; PG8_SCHED;
;             PG8_LDB(B1, 1, 1); PG8_STAGE(PG8_SB(1, 0), b3, voffB);
;             PG8_BAR; PG8_WAIT_L(0); PG8_MMA(0, 1, At, B1); PG8_BAR;
;             PG8_LDA(At, 1, 1); PG8_STAGE(PG8_SA(1, 0), a3, voffA);
;             PG8_BAR; PG8_WAIT_L(0); PG8_MMA(1, 0, At, B0); PG8_BAR; PG8_SCHED;
;             PG8_STAGE(PG8_SB(1, 1), b3 + hstepB, voffB);
;             PG8_WAIT_V(6); PG8_BAR; PG8_MMA(1, 1, At, B1); PG8_BAR;
	s_add_u32 s58, s20, 0x40000
	s_addc_u32 s59, s21, 0
	s_waitcnt vmcnt(4)
	s_barrier
	s_setprio 1
	v_mfma_f32_16x16x32_bf16 v[58:61], v[212:215], v[166:169], v[58:61]
	v_mfma_f32_16x16x32_bf16 v[50:53], v[220:223], v[166:169], v[50:53]
	s_mov_b32 m0, s36
	v_lshl_add_u64 v[142:143], s[58:59], 0, v[134:135]
	v_mfma_f32_16x16x32_bf16 v[42:45], v[212:215], v[180:183], v[42:45]
	v_mfma_f32_16x16x32_bf16 v[34:37], v[220:223], v[180:183], v[34:37]
	global_load_lds_dwordx4 v[142:143], off
	v_mfma_f32_16x16x32_bf16 v[26:29], v[212:215], v[188:191], v[26:29]
	v_mfma_f32_16x16x32_bf16 v[18:21], v[220:223], v[188:191], v[18:21]
	v_mfma_f32_16x16x32_bf16 v[10:13], v[212:215], v[204:207], v[10:13]
	v_mfma_f32_16x16x32_bf16 v[0:3], v[220:223], v[204:207], v[0:3]
	v_lshl_add_u64 v[142:143], s[58:59], 0, v[130:131]
	s_mov_b32 m0, s37
	v_mfma_f32_16x16x32_bf16 v[58:61], v[216:219], v[176:179], v[58:61]
	v_mfma_f32_16x16x32_bf16 v[50:53], v[224:227], v[176:179], v[50:53]
	global_load_lds_dwordx4 v[142:143], off
	v_mfma_f32_16x16x32_bf16 v[42:45], v[216:219], v[184:187], v[42:45]
	v_mfma_f32_16x16x32_bf16 v[34:37], v[224:227], v[184:187], v[34:37]
	v_mfma_f32_16x16x32_bf16 v[26:29], v[216:219], v[200:203], v[26:29]
	v_mfma_f32_16x16x32_bf16 v[18:21], v[224:227], v[200:203], v[18:21]
	v_mfma_f32_16x16x32_bf16 v[10:13], v[216:219], v[208:211], v[10:13]
	v_mfma_f32_16x16x32_bf16 v[0:3], v[224:227], v[208:211], v[0:3]
	s_setprio 0
	v_add_u32_e32 v148, s40, v151
	s_barrier
	ds_read_b128 v[142:145], v148
	ds_read_b128 v[154:157], v148 offset:1024
	ds_read_b128 v[158:161], v148 offset:2048
	ds_read_b128 v[162:165], v148 offset:3072
	s_add_u32 s22, s22, 0x40000
	s_addc_u32 s23, s23, 0
	ds_read_b128 v[166:169], v153 offset:32768
	ds_read_b128 v[176:179], v153 offset:33792
	ds_read_b128 v[180:183], v153 offset:34816
	ds_read_b128 v[184:187], v153 offset:35840
	ds_read_b128 v[188:191], v153 offset:36864
	ds_read_b128 v[200:203], v153 offset:37888
	ds_read_b128 v[204:207], v153 offset:38912
	ds_read_b128 v[208:211], v153 offset:39936
	s_waitcnt lgkmcnt(8)
	s_barrier
	s_waitcnt lgkmcnt(0)
	s_setprio 1
	s_waitcnt lgkmcnt(0)
	v_mfma_f32_16x16x32_bf16 v[126:129], v[142:145], v[166:169], v[126:129]
	v_mfma_f32_16x16x32_bf16 v[118:121], v[158:161], v[166:169], v[118:121]
	s_mov_b32 m0, s38
	v_lshl_add_u64 v[212:213], s[22:23], 0, v[136:137]
	v_mfma_f32_16x16x32_bf16 v[110:113], v[142:145], v[180:183], v[110:113]
	v_mfma_f32_16x16x32_bf16 v[102:105], v[158:161], v[180:183], v[102:105]
	global_load_lds_dwordx4 v[212:213], off
	v_mfma_f32_16x16x32_bf16 v[94:97], v[142:145], v[188:191], v[94:97]
	v_mfma_f32_16x16x32_bf16 v[86:89], v[158:161], v[188:191], v[86:89]
	v_mfma_f32_16x16x32_bf16 v[78:81], v[142:145], v[204:207], v[78:81]
	v_mfma_f32_16x16x32_bf16 v[70:73], v[158:161], v[204:207], v[70:73]
	v_lshl_add_u64 v[212:213], s[22:23], 0, v[132:133]
	s_mov_b32 m0, s39
	v_mfma_f32_16x16x32_bf16 v[126:129], v[154:157], v[176:179], v[126:129]
	v_mfma_f32_16x16x32_bf16 v[118:121], v[162:165], v[176:179], v[118:121]
	global_load_lds_dwordx4 v[212:213], off
	v_mfma_f32_16x16x32_bf16 v[110:113], v[154:157], v[184:187], v[110:113]
	v_mfma_f32_16x16x32_bf16 v[102:105], v[162:165], v[184:187], v[102:105]
	v_mfma_f32_16x16x32_bf16 v[94:97], v[154:157], v[200:203], v[94:97]
	v_mfma_f32_16x16x32_bf16 v[86:89], v[162:165], v[200:203], v[86:89]
	v_mfma_f32_16x16x32_bf16 v[78:81], v[154:157], v[208:211], v[78:81]
	v_mfma_f32_16x16x32_bf16 v[70:73], v[162:165], v[208:211], v[70:73]
	s_setprio 0
	s_barrier
	v_add_u32_e32 v148, s45, v151
	ds_read_b128 v[212:215], v148
	ds_read_b128 v[216:219], v148 offset:1024
	ds_read_b128 v[220:223], v148 offset:2048
	ds_read_b128 v[224:227], v148 offset:3072
	s_barrier
	s_waitcnt lgkmcnt(0)
	s_setprio 1
	s_waitcnt lgkmcnt(0)
	v_mfma_f32_16x16x32_bf16 v[122:125], v[212:215], v[166:169], v[122:125]
	v_mfma_f32_16x16x32_bf16 v[114:117], v[220:223], v[166:169], v[114:117]
	s_mov_b32 m0, s41
	v_lshl_add_u64 v[146:147], v[146:147], 0, s[76:77]
	v_mfma_f32_16x16x32_bf16 v[106:109], v[212:215], v[180:183], v[106:109]
	v_mfma_f32_16x16x32_bf16 v[98:101], v[220:223], v[180:183], v[98:101]
	global_load_lds_dwordx4 v[146:147], off
	v_mfma_f32_16x16x32_bf16 v[90:93], v[212:215], v[188:191], v[90:93]
	v_mfma_f32_16x16x32_bf16 v[82:85], v[220:223], v[188:191], v[82:85]
	v_mfma_f32_16x16x32_bf16 v[74:77], v[212:215], v[204:207], v[74:77]
	v_mfma_f32_16x16x32_bf16 v[66:69], v[220:223], v[204:207], v[66:69]
	v_lshl_add_u64 v[146:147], v[194:195], 0, s[76:77]
	s_mov_b32 m0, s42
	v_mfma_f32_16x16x32_bf16 v[122:125], v[216:219], v[176:179], v[122:125]
	v_mfma_f32_16x16x32_bf16 v[114:117], v[224:227], v[176:179], v[114:117]
	global_load_lds_dwordx4 v[146:147], off
	v_mfma_f32_16x16x32_bf16 v[106:109], v[216:219], v[184:187], v[106:109]
	v_mfma_f32_16x16x32_bf16 v[98:101], v[224:227], v[184:187], v[98:101]
	v_mfma_f32_16x16x32_bf16 v[90:93], v[216:219], v[200:203], v[90:93]
	v_mfma_f32_16x16x32_bf16 v[82:85], v[224:227], v[200:203], v[82:85]
	v_mfma_f32_16x16x32_bf16 v[74:77], v[216:219], v[208:211], v[74:77]
	v_mfma_f32_16x16x32_bf16 v[66:69], v[224:227], v[208:211], v[66:69]
	s_setprio 0
	s_barrier
	ds_read_b128 v[166:169], v153 offset:49152
	ds_read_b128 v[176:179], v153 offset:50176
	ds_read_b128 v[180:183], v153 offset:51200
	ds_read_b128 v[184:187], v153 offset:52224
	ds_read_b128 v[188:191], v153 offset:53248
	ds_read_b128 v[200:203], v153 offset:54272
	ds_read_b128 v[204:207], v153 offset:55296
	ds_read_b128 v[208:211], v153 offset:56320
	s_barrier
; #define PG8_STAGE(bufoff, gbase, voff) do { _Pragma("unroll") for (int _i = 0; _i < 2; ++_i) \
;         __builtin_amdgcn_global_load_lds((const unsigned*)((const char*)(gbase) + (voff)[_i]), (LAS unsigned*)(lds + (bufoff) + ldsw + _i * 8192), 16, 0, 0); } while (0)
; #define PG8_WAIT_V(n) asm volatile("s_waitcnt vmcnt(" #n ")" ::: "memory")
; #define PG8_BAR __builtin_amdgcn_s_barrier()
; template <class Epi, int KK, int LDA, int LDB, int NN, bool AGRP>
; __device__ __forceinline__ void gemm_phase(LAS unsigned char* lds, const bf16_t* gA, const bf16_t* gBt, int G_, int bid_, int tid) {
;     ...
;             PG8_LDB(B0, 0, 0); PG8_SCHED; PG8_LDA(At, 0, 0); PG8_STAGE(PG8_SA(1, 1), a1 + hstepA, voffA);
;             PG8_WAIT_L(8); PG8_BAR; PG8_WAIT_L(0); PG8_MMA(0, 0, At, B0); PG8_BAR; PG8_SCHED;
;             PG8_LDB(B1, 0, 1); PG8_STAGE(PG8_SB(0, 0), b2, voffB);
;             PG8_BAR; PG8_WAIT_L(0); PG8_MMA(0, 1, At, B1); PG8_BAR;
;             PG8_LDA(At, 0, 1); PG8_STAGE(PG8_SA(0, 0), a2, voffA);
;             PG8_BAR; PG8_WAIT_L(0); PG8_MMA(1, 0, At, B0); PG8_BAR; PG8_SCHED;
;             PG8_STAGE(PG8_SB(0, 1), b2 + hstepB, voffB);
;             PG8_WAIT_V(6); PG8_BAR; PG8_MMA(1, 1, At, B1); PG8_BAR;
;             PG8_LDB(B0, 1, 0); PG8_SCHED; PG8_LDA(At, 1, 0); PG8_STAGE(PG8_SA(0, 1), a2 + hstepA, voffA);
;             PG8_WAIT_L(8); PG8_BAR; PG8_WAIT_L(0); PG8_MMA(0, 0, At, B0); PG8_BAR; PG8_SCHED;
;             PG8_LDB(B1, 1, 1); PG8_STAGE(PG8_SB(1, 0), b3, voffB);
;             PG8_BAR; PG8_WAIT_L(0); PG8_MMA(0, 1, At, B1); PG8_BAR;
;             PG8_LDA(At, 1, 1); PG8_STAGE(PG8_SA(1, 0), a3, voffA);
;             PG8_BAR; PG8_WAIT_L(0); PG8_MMA(1, 0, At, B0); PG8_BAR; PG8_SCHED;
;             PG8_STAGE(PG8_SB(1, 1), b3 + hstepB, voffB);
;             PG8_WAIT_V(6); PG8_BAR; PG8_MMA(1, 1, At, B1); PG8_BAR;
;     __device__ __forceinline__ void operator()(const f32x4 (&acc)[2][2][4][2], const Unit& u, int wr, int wc, int fr, int fq, LAS unsigned char* lds) const {
;         bf16_t* O = EPP(bf16_t*, 0); const float* rss = EPP(const float*, 1);
;         const int row0 = u.pm * BM + wr * 64 + fr, j0 = u.pn * 128 + wc * 32 + 8 * fq;
; #pragma unroll
;         for (int ai = 0; ai < 2; ++ai)
; #pragma unroll
;             for (int m = 0; m < 4; ++m) { const int row = row0 + ai * HALF + m * 16; const float rs = rstd_of4(rss, row, fq);
	s_waitcnt lgkmcnt(0)
	s_setprio 1
	s_waitcnt lgkmcnt(0)
	v_mfma_f32_16x16x32_bf16 v[62:65], v[142:145], v[166:169], v[62:65]
	v_mfma_f32_16x16x32_bf16 v[54:57], v[158:161], v[166:169], v[54:57]
	s_mov_b32 m0, s43
	v_lshl_add_u64 v[146:147], v[196:197], 0, s[76:77]
	v_mfma_f32_16x16x32_bf16 v[46:49], v[142:145], v[180:183], v[46:49]
	v_mfma_f32_16x16x32_bf16 v[38:41], v[158:161], v[180:183], v[38:41]
	global_load_lds_dwordx4 v[146:147], off
	v_mfma_f32_16x16x32_bf16 v[30:33], v[142:145], v[188:191], v[30:33]
	v_mfma_f32_16x16x32_bf16 v[22:25], v[158:161], v[188:191], v[22:25]
	v_mfma_f32_16x16x32_bf16 v[14:17], v[142:145], v[204:207], v[14:17]
	v_mfma_f32_16x16x32_bf16 v[6:9], v[158:161], v[204:207], v[6:9]
	v_lshl_add_u64 v[146:147], v[228:229], 0, s[76:77]
	s_mov_b32 m0, s44
	v_mfma_f32_16x16x32_bf16 v[62:65], v[154:157], v[176:179], v[62:65]
	v_mfma_f32_16x16x32_bf16 v[54:57], v[162:165], v[176:179], v[54:57]
	global_load_lds_dwordx4 v[146:147], off
	v_mfma_f32_16x16x32_bf16 v[46:49], v[154:157], v[184:187], v[46:49]
	v_mfma_f32_16x16x32_bf16 v[38:41], v[162:165], v[184:187], v[38:41]
	v_mfma_f32_16x16x32_bf16 v[30:33], v[154:157], v[200:203], v[30:33]
	v_mfma_f32_16x16x32_bf16 v[22:25], v[162:165], v[200:203], v[22:25]
	v_mfma_f32_16x16x32_bf16 v[14:17], v[154:157], v[208:211], v[14:17]
	v_mfma_f32_16x16x32_bf16 v[6:9], v[162:165], v[208:211], v[6:9]
	s_setprio 0
	s_barrier
	s_add_u32 s20, s20, 0x40080
	s_addc_u32 s21, s21, 0
	s_waitcnt vmcnt(4)
	s_barrier
	s_setprio 1
	v_mfma_f32_16x16x32_bf16 v[58:61], v[212:215], v[166:169], v[58:61]
	v_mfma_f32_16x16x32_bf16 v[50:53], v[220:223], v[166:169], v[50:53]
	s_mov_b32 m0, s46
	v_lshl_add_u64 v[142:143], s[20:21], 0, v[134:135]
	v_mfma_f32_16x16x32_bf16 v[42:45], v[212:215], v[180:183], v[42:45]
	v_mfma_f32_16x16x32_bf16 v[34:37], v[220:223], v[180:183], v[34:37]
	global_load_lds_dwordx4 v[142:143], off
	v_mfma_f32_16x16x32_bf16 v[26:29], v[212:215], v[188:191], v[26:29]
	v_mfma_f32_16x16x32_bf16 v[18:21], v[220:223], v[188:191], v[18:21]
	v_mfma_f32_16x16x32_bf16 v[10:13], v[212:215], v[204:207], v[10:13]
	v_mfma_f32_16x16x32_bf16 v[0:3], v[220:223], v[204:207], v[0:3]
	v_lshl_add_u64 v[142:143], s[20:21], 0, v[130:131]
	s_mov_b32 m0, s47
	v_mfma_f32_16x16x32_bf16 v[58:61], v[216:219], v[176:179], v[58:61]
	v_mfma_f32_16x16x32_bf16 v[50:53], v[224:227], v[176:179], v[50:53]
	global_load_lds_dwordx4 v[142:143], off
	v_mfma_f32_16x16x32_bf16 v[42:45], v[216:219], v[184:187], v[42:45]
	v_mfma_f32_16x16x32_bf16 v[34:37], v[224:227], v[184:187], v[34:37]
	v_mfma_f32_16x16x32_bf16 v[26:29], v[216:219], v[200:203], v[26:29]
	v_mfma_f32_16x16x32_bf16 v[18:21], v[224:227], v[200:203], v[18:21]
	v_mfma_f32_16x16x32_bf16 v[10:13], v[216:219], v[208:211], v[10:13]
	v_mfma_f32_16x16x32_bf16 v[0:3], v[224:227], v[208:211], v[0:3]
	s_setprio 0
	s_add_i32 s57, s57, 2
	s_add_u32 s55, s55, 0x100
	s_addc_u32 s56, s56, 0
	s_add_u32 s18, s18, 0x100
	s_addc_u32 s19, s19, 0
	s_cmp_gt_u32 s57, 13
	s_barrier
	s_cbranch_scc0 .LBB1_843
	v_mov_b32_e32 v142, s66
	v_mov_b32_e32 v143, s48
	v_and_b32_e32 v148, 64, v171
	ds_read_b32 v142, v142
	ds_read_b32 v143, v143
	v_mov_b32_e32 v144, s49
	v_mov_b32_e32 v145, s50
	v_xor_b32_e32 v147, 16, v171
	v_add_u32_e32 v148, 64, v148
	ds_read_b32 v144, v144
	ds_read_b32 v145, v145
	v_cmp_lt_i32_e32 vcc, v147, v148
	s_waitcnt lgkmcnt(0)
	v_readfirstlane_b32 s7, v142
	v_readfirstlane_b32 s9, v143
	v_cndmask_b32_e32 v147, v171, v147, vcc
	v_lshlrev_b32_e32 v154, 2, v147
	v_xor_b32_e32 v147, 32, v171
	v_cmp_lt_i32_e32 vcc, v147, v148
	v_lshl_or_b32 v156, s52, 7, v152
	v_lshl_add_u32 v146, s16, 8, v150
	v_cndmask_b32_e32 v147, v171, v147, vcc
	v_mov_b32_e32 v142, s7
	v_mov_b32_e32 v143, s9
	v_readfirstlane_b32 s18, v144
	v_readfirstlane_b32 s19, v145
	v_lshlrev_b32_e32 v155, 2, v147
	v_ashrrev_i32_e32 v157, 31, v156
	v_ashrrev_i32_e32 v147, 31, v146
	v_lshl_add_u64 v[144:145], s[18:19], 0, v[4:5]
	v_lshl_add_u64 v[142:143], v[156:157], 1, v[142:143]
	v_lshlrev_b64 v[156:157], 6, v[146:147]
	v_lshl_add_u64 v[156:157], v[144:145], 0, v[156:157]
	global_load_dwordx4 v[156:159], v[156:157], off
	v_or_b32_e32 v162, 16, v146
	v_ashrrev_i32_e32 v163, 31, v162
	v_lshlrev_b64 v[162:163], 6, v[162:163]
	v_lshl_add_u64 v[162:163], v[144:145], 0, v[162:163]
	global_load_dwordx4 v[200:203], v[162:163], off
	v_or_b32_e32 v162, 32, v146
	v_ashrrev_i32_e32 v163, 31, v162
	v_lshlrev_b64 v[162:163], 6, v[162:163]
	v_lshl_add_u64 v[162:163], v[144:145], 0, v[162:163]
	global_load_dwordx4 v[204:207], v[162:163], off
	v_or_b32_e32 v162, 48, v146
	v_ashrrev_i32_e32 v163, 31, v162
	v_lshlrev_b64 v[162:163], 6, v[162:163]
	v_lshl_add_u64 v[162:163], v[144:145], 0, v[162:163]
	global_load_dwordx4 v[208:211], v[162:163], off
	v_add_u32_e32 v162, 0x80, v146
	v_ashrrev_i32_e32 v163, 31, v162
	v_lshlrev_b64 v[162:163], 6, v[162:163]
	v_lshl_add_u64 v[162:163], v[144:145], 0, v[162:163]
	global_load_dwordx4 v[212:215], v[162:163], off
	v_add_u32_e32 v162, 0x90, v146
	v_ashrrev_i32_e32 v163, 31, v162
	v_lshlrev_b64 v[162:163], 6, v[162:163]
	v_lshl_add_u64 v[162:163], v[144:145], 0, v[162:163]
	global_load_dwordx4 v[216:219], v[162:163], off
	v_add_u32_e32 v162, 0xa0, v146
	v_ashrrev_i32_e32 v163, 31, v162
	v_lshlrev_b64 v[162:163], 6, v[162:163]
	v_lshl_add_u64 v[162:163], v[144:145], 0, v[162:163]
	global_load_dwordx4 v[220:223], v[162:163], off
	v_add_u32_e32 v162, 0xb0, v146
	v_ashrrev_i32_e32 v163, 31, v162
	v_lshlrev_b64 v[162:163], 6, v[162:163]
	v_lshl_add_u64 v[162:163], v[144:145], 0, v[162:163]
	global_load_dwordx4 v[224:227], v[162:163], off
	s_mov_b32 s52, s8
	s_mov_b32 s16, s6
	s_mov_b64 s[20:21], s[12:13]
	s_waitcnt vmcnt(0)
; __device__ __forceinline__ unsigned cvt_pk_bf16(float lo, float hi) { unsigned r; asm volatile("v_cvt_pk_bf16_f32 %0, %1, %2" : "=v"(r) : "v"(lo), "v"(hi)); return r; }
; __device__ __forceinline__ float fast_sigmoid(float x) { return __builtin_amdgcn_rcpf(1.0f + __builtin_amdgcn_exp2f(-1.44269504089f * x)); }
;     __device__ __forceinline__ void operator()(const f32x4 (&acc)[2][2][4][2], const Unit& u, int wr, int wc, int fr, int fq, LAS unsigned char* lds) const {
;     ...
;             for (int m = 0; m < 4; ++m) { const int row = row0 + ai * HALF + m * 16; const float rs = rstd_of4(rss, row, fq);
;                 float h[8];
; #pragma unroll
;                 for (int n = 0; n < 2; ++n)
; #pragma unroll
;                     for (int e = 0; e < 4; ++e) { const float gt = acc[ai][0][m][n][e] * rs, up = acc[ai][1][m][n][e] * rs; h[n * 4 + e] = gt * fast_sigmoid(gt) * up; }
;                 u32x4 w; w.x = cvt_pk_bf16(h[0], h[1]); w.y = cvt_pk_bf16(h[2], h[3]); w.z = cvt_pk_bf16(h[4], h[5]); w.w = cvt_pk_bf16(h[6], h[7]);
;                 *(u32x4*)(O + (size_t)row * DFF + j0) = w; }
	v_mov_b32_e32 v160, v157
	v_mov_b32_e32 v161, v158
	v_mov_b32_e32 v157, v159
	v_pk_add_f32 v[156:157], v[160:161], v[156:157]
	s_nop 0
	v_add_f32_e32 v147, v156, v157
	ds_bpermute_b32 v148, v154, v147
	v_mov_b32_e32 v156, v122
	v_mov_b32_e32 v157, v126
	v_mov_b32_e32 v126, v123
	s_waitcnt lgkmcnt(0)
	v_add_f32_e32 v147, v147, v148
	ds_bpermute_b32 v148, v155, v147
	s_waitcnt lgkmcnt(0)
	v_add_f32_e32 v147, v147, v148
	v_fmamk_f32 v147, v147, 0x3a800000, v173
	v_cmp_gt_f32_e32 vcc, s64, v147
	v_mul_f32_e32 v148, 0x4b800000, v147
	s_nop 0
	v_cndmask_b32_e32 v147, v147, v148, vcc
	v_rsq_f32_e32 v147, v147
	s_nop 0
	v_mul_f32_e32 v148, 0x45800000, v147
	v_cndmask_b32_e32 v148, v147, v148, vcc
	v_pk_mul_f32 v[156:157], v[156:157], v[148:149] op_sel_hi:[1,0]
	s_nop 0
	v_mul_f32_e32 v122, 0xbfb8aa3b, v157
	v_exp_f32_e32 v122, v122
	s_nop 0
	v_add_f32_e32 v122, 1.0, v122
	v_rcp_f32_e32 v122, v122
	s_nop 0
	v_mul_f32_e32 v122, v157, v122
	v_mul_f32_e32 v147, v156, v122
	v_pk_mul_f32 v[122:123], v[126:127], v[148:149] op_sel_hi:[1,0]
	s_nop 0
	v_mul_f32_e32 v126, 0xbfb8aa3b, v123
	v_exp_f32_e32 v126, v126
	s_nop 0
	v_add_f32_e32 v126, 1.0, v126
	v_rcp_f32_e32 v126, v126
	s_nop 0
	v_mul_f32_e32 v123, v123, v126
	v_mul_f32_e32 v126, v122, v123
	v_mov_b32_e32 v122, v124
	v_mov_b32_e32 v123, v128
	v_pk_mul_f32 v[122:123], v[122:123], v[148:149] op_sel_hi:[1,0]
	v_mov_b32_e32 v128, v125
	v_mul_f32_e32 v124, 0xbfb8aa3b, v123
	v_exp_f32_e32 v124, v124
	s_nop 0
	v_add_f32_e32 v124, 1.0, v124
	v_rcp_f32_e32 v124, v124
	s_nop 0
	v_mul_f32_e32 v123, v123, v124
	v_mul_f32_e32 v124, v122, v123
	v_pk_mul_f32 v[122:123], v[128:129], v[148:149] op_sel_hi:[1,0]
	s_nop 0
	v_mul_f32_e32 v125, 0xbfb8aa3b, v123
	v_exp_f32_e32 v125, v125
	s_nop 0
	v_add_f32_e32 v125, 1.0, v125
	v_rcp_f32_e32 v125, v125
	s_nop 0
	v_mul_f32_e32 v123, v123, v125
	v_mul_f32_e32 v125, v122, v123
	v_mov_b32_e32 v122, v114
	v_mov_b32_e32 v123, v118
	v_pk_mul_f32 v[122:123], v[122:123], v[148:149] op_sel_hi:[1,0]
	v_mov_b32_e32 v118, v115
	v_mul_f32_e32 v114, 0xbfb8aa3b, v123
	v_exp_f32_e32 v114, v114
	s_nop 0
	v_add_f32_e32 v114, 1.0, v114
	v_rcp_f32_e32 v114, v114
	s_nop 0
	v_mul_f32_e32 v114, v123, v114
	v_mul_f32_e32 v122, v122, v114
	v_pk_mul_f32 v[114:115], v[118:119], v[148:149] op_sel_hi:[1,0]
	s_nop 0
	v_mul_f32_e32 v118, 0xbfb8aa3b, v115
	v_exp_f32_e32 v118, v118
	s_nop 0
	v_add_f32_e32 v118, 1.0, v118
	v_rcp_f32_e32 v118, v118
	s_nop 0
	v_mul_f32_e32 v115, v115, v118
	v_mul_f32_e32 v118, v114, v115
	v_mov_b32_e32 v114, v116
	v_mov_b32_e32 v115, v120
	v_pk_mul_f32 v[114:115], v[114:115], v[148:149] op_sel_hi:[1,0]
	v_mov_b32_e32 v120, v117
	v_mul_f32_e32 v116, 0xbfb8aa3b, v115
	v_exp_f32_e32 v116, v116
	s_nop 0
	v_add_f32_e32 v116, 1.0, v116
	v_rcp_f32_e32 v116, v116
	s_nop 0
	v_mul_f32_e32 v115, v115, v116
	v_mul_f32_e32 v119, v114, v115
	v_pk_mul_f32 v[114:115], v[120:121], v[148:149] op_sel_hi:[1,0]
	s_nop 0
	v_mul_f32_e32 v116, 0xbfb8aa3b, v115
	v_exp_f32_e32 v116, v116
	s_nop 0
	v_add_f32_e32 v116, 1.0, v116
	v_rcp_f32_e32 v116, v116
	s_nop 0
	v_mul_f32_e32 v115, v115, v116
	v_mul_f32_e32 v117, v114, v115
	v_cvt_pk_bf16_f32 v114, v147, v126
	v_cvt_pk_bf16_f32 v115, v124, v125
	v_cvt_pk_bf16_f32 v116, v122, v118
	v_cvt_pk_bf16_f32 v117, v119, v117
	v_mad_i64_i32 v[118:119], s[18:19], v146, s88, v[142:143]
	global_store_dwordx4 v[118:119], v[114:117], off
	s_nop 1
	v_or_b32_e32 v114, 16, v146
	v_ashrrev_i32_e32 v115, 31, v114
	v_lshlrev_b64 v[116:117], 6, v[114:115]
	v_lshl_add_u64 v[116:117], v[144:145], 0, v[116:117]
	v_mov_b32_e32 v116, v200
	v_mov_b32_e32 v117, v201
	v_mov_b32_e32 v118, v202
	v_mov_b32_e32 v119, v203
	s_nop 0
	v_mov_b32_e32 v120, v117
	v_mov_b32_e32 v121, v118
	v_mov_b32_e32 v117, v119
	v_pk_add_f32 v[116:117], v[120:121], v[116:117]
	v_mov_b32_e32 v118, v106
	v_add_f32_e32 v115, v116, v117
	ds_bpermute_b32 v116, v154, v115
	v_mov_b32_e32 v119, v110
	v_mov_b32_e32 v110, v107
	s_waitcnt lgkmcnt(0)
	v_add_f32_e32 v115, v115, v116
	ds_bpermute_b32 v116, v155, v115
	s_waitcnt lgkmcnt(0)
	v_add_f32_e32 v115, v115, v116
	v_fmamk_f32 v115, v115, 0x3a800000, v173
	v_cmp_gt_f32_e32 vcc, s64, v115
	v_mul_f32_e32 v116, 0x4b800000, v115
	s_nop 0
	v_cndmask_b32_e32 v115, v115, v116, vcc
	v_rsq_f32_e32 v115, v115
	s_nop 0
	v_mul_f32_e32 v116, 0x45800000, v115
	v_cndmask_b32_e32 v116, v115, v116, vcc
	v_pk_mul_f32 v[118:119], v[118:119], v[116:117] op_sel_hi:[1,0]
	s_nop 0
	v_mul_f32_e32 v106, 0xbfb8aa3b, v119
	v_exp_f32_e32 v106, v106
	s_nop 0
	v_add_f32_e32 v106, 1.0, v106
	v_rcp_f32_e32 v106, v106
	s_nop 0
	v_mul_f32_e32 v106, v119, v106
	v_mul_f32_e32 v115, v118, v106
	v_pk_mul_f32 v[106:107], v[110:111], v[116:117] op_sel_hi:[1,0]
	s_nop 0
	v_mul_f32_e32 v110, 0xbfb8aa3b, v107
	v_exp_f32_e32 v110, v110
	s_nop 0
	v_add_f32_e32 v110, 1.0, v110
	v_rcp_f32_e32 v110, v110
	s_nop 0
	v_mul_f32_e32 v107, v107, v110
	v_mul_f32_e32 v110, v106, v107
	v_mov_b32_e32 v106, v108
	v_mov_b32_e32 v107, v112
	v_pk_mul_f32 v[106:107], v[106:107], v[116:117] op_sel_hi:[1,0]
	v_mov_b32_e32 v112, v109
	v_mul_f32_e32 v108, 0xbfb8aa3b, v107
	v_exp_f32_e32 v108, v108
	s_nop 0
	v_add_f32_e32 v108, 1.0, v108
	v_rcp_f32_e32 v108, v108
	s_nop 0
	v_mul_f32_e32 v107, v107, v108
	v_mul_f32_e32 v108, v106, v107
	v_pk_mul_f32 v[106:107], v[112:113], v[116:117] op_sel_hi:[1,0]
	s_nop 0
	v_mul_f32_e32 v109, 0xbfb8aa3b, v107
	v_exp_f32_e32 v109, v109
	s_nop 0
	v_add_f32_e32 v109, 1.0, v109
	v_rcp_f32_e32 v109, v109
	s_nop 0
	v_mul_f32_e32 v107, v107, v109
	v_mul_f32_e32 v109, v106, v107
	v_mov_b32_e32 v106, v98
	v_mov_b32_e32 v107, v102
	v_pk_mul_f32 v[106:107], v[106:107], v[116:117] op_sel_hi:[1,0]
; __device__ __forceinline__ unsigned cvt_pk_bf16(float lo, float hi) { unsigned r; asm volatile("v_cvt_pk_bf16_f32 %0, %1, %2" : "=v"(r) : "v"(lo), "v"(hi)); return r; }
; __device__ __forceinline__ float fast_sigmoid(float x) { return __builtin_amdgcn_rcpf(1.0f + __builtin_amdgcn_exp2f(-1.44269504089f * x)); }
;     __device__ __forceinline__ void operator()(const f32x4 (&acc)[2][2][4][2], const Unit& u, int wr, int wc, int fr, int fq, LAS unsigned char* lds) const {
;     ...
;             for (int m = 0; m < 4; ++m) { const int row = row0 + ai * HALF + m * 16; const float rs = rstd_of4(rss, row, fq);
;                 float h[8];
; #pragma unroll
;                 for (int n = 0; n < 2; ++n)
; #pragma unroll
;                     for (int e = 0; e < 4; ++e) { const float gt = acc[ai][0][m][n][e] * rs, up = acc[ai][1][m][n][e] * rs; h[n * 4 + e] = gt * fast_sigmoid(gt) * up; }
;                 u32x4 w; w.x = cvt_pk_bf16(h[0], h[1]); w.y = cvt_pk_bf16(h[2], h[3]); w.z = cvt_pk_bf16(h[4], h[5]); w.w = cvt_pk_bf16(h[6], h[7]);
;                 *(u32x4*)(O + (size_t)row * DFF + j0) = w; }
	v_mov_b32_e32 v102, v99
	v_mul_f32_e32 v98, 0xbfb8aa3b, v107
	v_exp_f32_e32 v98, v98
	s_nop 0
	v_add_f32_e32 v98, 1.0, v98
	v_rcp_f32_e32 v98, v98
	s_nop 0
	v_mul_f32_e32 v98, v107, v98
	v_mul_f32_e32 v106, v106, v98
	v_pk_mul_f32 v[98:99], v[102:103], v[116:117] op_sel_hi:[1,0]
	s_nop 0
	v_mul_f32_e32 v102, 0xbfb8aa3b, v99
	v_exp_f32_e32 v102, v102
	s_nop 0
	v_add_f32_e32 v102, 1.0, v102
	v_rcp_f32_e32 v102, v102
	s_nop 0
	v_mul_f32_e32 v99, v99, v102
	v_mul_f32_e32 v102, v98, v99
	v_mov_b32_e32 v98, v100
	v_mov_b32_e32 v99, v104
	v_pk_mul_f32 v[98:99], v[98:99], v[116:117] op_sel_hi:[1,0]
	v_mov_b32_e32 v104, v101
	v_mul_f32_e32 v100, 0xbfb8aa3b, v99
	v_exp_f32_e32 v100, v100
	s_nop 0
	v_add_f32_e32 v100, 1.0, v100
	v_rcp_f32_e32 v100, v100
	s_nop 0
	v_mul_f32_e32 v99, v99, v100
	v_mul_f32_e32 v103, v98, v99
	v_pk_mul_f32 v[98:99], v[104:105], v[116:117] op_sel_hi:[1,0]
	s_nop 0
	v_mul_f32_e32 v100, 0xbfb8aa3b, v99
	v_exp_f32_e32 v100, v100
	s_nop 0
	v_add_f32_e32 v100, 1.0, v100
	v_rcp_f32_e32 v100, v100
	s_nop 0
	v_mul_f32_e32 v99, v99, v100
	v_mul_f32_e32 v101, v98, v99
	v_cvt_pk_bf16_f32 v98, v115, v110
	v_cvt_pk_bf16_f32 v99, v108, v109
	v_cvt_pk_bf16_f32 v100, v106, v102
	v_cvt_pk_bf16_f32 v101, v103, v101
	v_mad_i64_i32 v[102:103], s[18:19], v114, s88, v[142:143]
	global_store_dwordx4 v[102:103], v[98:101], off
	s_nop 1
	v_or_b32_e32 v98, 32, v146
	v_ashrrev_i32_e32 v99, 31, v98
	v_lshlrev_b64 v[100:101], 6, v[98:99]
	v_lshl_add_u64 v[100:101], v[144:145], 0, v[100:101]
	v_mov_b32_e32 v100, v204
	v_mov_b32_e32 v101, v205
	v_mov_b32_e32 v102, v206
	v_mov_b32_e32 v103, v207
	s_nop 0
	v_mov_b32_e32 v104, v101
	v_mov_b32_e32 v105, v102
	v_mov_b32_e32 v101, v103
	v_pk_add_f32 v[100:101], v[104:105], v[100:101]
	v_mov_b32_e32 v102, v90
	v_add_f32_e32 v99, v100, v101
	ds_bpermute_b32 v100, v154, v99
	v_mov_b32_e32 v103, v94
	v_mov_b32_e32 v94, v91
	s_waitcnt lgkmcnt(0)
	v_add_f32_e32 v99, v99, v100
	ds_bpermute_b32 v100, v155, v99
	s_waitcnt lgkmcnt(0)
	v_add_f32_e32 v99, v99, v100
	v_fmamk_f32 v99, v99, 0x3a800000, v173
	v_cmp_gt_f32_e32 vcc, s64, v99
	v_mul_f32_e32 v100, 0x4b800000, v99
	s_nop 0
	v_cndmask_b32_e32 v99, v99, v100, vcc
	v_rsq_f32_e32 v99, v99
	s_nop 0
	v_mul_f32_e32 v100, 0x45800000, v99
	v_cndmask_b32_e32 v100, v99, v100, vcc
	v_pk_mul_f32 v[102:103], v[102:103], v[100:101] op_sel_hi:[1,0]
	s_nop 0
	v_mul_f32_e32 v90, 0xbfb8aa3b, v103
	v_exp_f32_e32 v90, v90
	s_nop 0
	v_add_f32_e32 v90, 1.0, v90
	v_rcp_f32_e32 v90, v90
	s_nop 0
	v_mul_f32_e32 v90, v103, v90
	v_mul_f32_e32 v99, v102, v90
	v_pk_mul_f32 v[90:91], v[94:95], v[100:101] op_sel_hi:[1,0]
	s_nop 0
	v_mul_f32_e32 v94, 0xbfb8aa3b, v91
	v_exp_f32_e32 v94, v94
	s_nop 0
	v_add_f32_e32 v94, 1.0, v94
	v_rcp_f32_e32 v94, v94
	s_nop 0
	v_mul_f32_e32 v91, v91, v94
	v_mul_f32_e32 v94, v90, v91
	v_mov_b32_e32 v90, v92
	v_mov_b32_e32 v91, v96
	v_pk_mul_f32 v[90:91], v[90:91], v[100:101] op_sel_hi:[1,0]
	v_mov_b32_e32 v96, v93
	v_mul_f32_e32 v92, 0xbfb8aa3b, v91
	v_exp_f32_e32 v92, v92
	s_nop 0
	v_add_f32_e32 v92, 1.0, v92
	v_rcp_f32_e32 v92, v92
	s_nop 0
	v_mul_f32_e32 v91, v91, v92
	v_mul_f32_e32 v92, v90, v91
	v_pk_mul_f32 v[90:91], v[96:97], v[100:101] op_sel_hi:[1,0]
	s_nop 0
	v_mul_f32_e32 v93, 0xbfb8aa3b, v91
	v_exp_f32_e32 v93, v93
	s_nop 0
	v_add_f32_e32 v93, 1.0, v93
	v_rcp_f32_e32 v93, v93
	s_nop 0
	v_mul_f32_e32 v91, v91, v93
	v_mul_f32_e32 v93, v90, v91
	v_mov_b32_e32 v90, v82
	v_mov_b32_e32 v91, v86
	v_pk_mul_f32 v[90:91], v[90:91], v[100:101] op_sel_hi:[1,0]
	v_mov_b32_e32 v86, v83
	v_mul_f32_e32 v82, 0xbfb8aa3b, v91
	v_exp_f32_e32 v82, v82
	s_nop 0
	v_add_f32_e32 v82, 1.0, v82
	v_rcp_f32_e32 v82, v82
	s_nop 0
	v_mul_f32_e32 v82, v91, v82
	v_mul_f32_e32 v90, v90, v82
	v_pk_mul_f32 v[82:83], v[86:87], v[100:101] op_sel_hi:[1,0]
	s_nop 0
	v_mul_f32_e32 v86, 0xbfb8aa3b, v83
	v_exp_f32_e32 v86, v86
	s_nop 0
	v_add_f32_e32 v86, 1.0, v86
	v_rcp_f32_e32 v86, v86
	s_nop 0
	v_mul_f32_e32 v83, v83, v86
	v_mul_f32_e32 v86, v82, v83
	v_mov_b32_e32 v82, v84
	v_mov_b32_e32 v83, v88
	v_pk_mul_f32 v[82:83], v[82:83], v[100:101] op_sel_hi:[1,0]
	v_mov_b32_e32 v88, v85
	v_mul_f32_e32 v84, 0xbfb8aa3b, v83
	v_exp_f32_e32 v84, v84
	s_nop 0
	v_add_f32_e32 v84, 1.0, v84
	v_rcp_f32_e32 v84, v84
	s_nop 0
	v_mul_f32_e32 v83, v83, v84
	v_mul_f32_e32 v87, v82, v83
	v_pk_mul_f32 v[82:83], v[88:89], v[100:101] op_sel_hi:[1,0]
	s_nop 0
	v_mul_f32_e32 v84, 0xbfb8aa3b, v83
	v_exp_f32_e32 v84, v84
	s_nop 0
	v_add_f32_e32 v84, 1.0, v84
	v_rcp_f32_e32 v84, v84
	s_nop 0
	v_mul_f32_e32 v83, v83, v84
	v_mul_f32_e32 v85, v82, v83
	v_cvt_pk_bf16_f32 v82, v99, v94
	v_cvt_pk_bf16_f32 v83, v92, v93
	v_cvt_pk_bf16_f32 v84, v90, v86
	v_cvt_pk_bf16_f32 v85, v87, v85
	v_mad_i64_i32 v[86:87], s[18:19], v98, s88, v[142:143]
	global_store_dwordx4 v[86:87], v[82:85], off
	s_nop 1
	v_or_b32_e32 v82, 48, v146
	v_ashrrev_i32_e32 v83, 31, v82
	v_lshlrev_b64 v[84:85], 6, v[82:83]
	v_lshl_add_u64 v[84:85], v[144:145], 0, v[84:85]
	v_mov_b32_e32 v84, v208
	v_mov_b32_e32 v85, v209
	v_mov_b32_e32 v86, v210
	v_mov_b32_e32 v87, v211
	s_nop 0
	v_mov_b32_e32 v88, v85
	v_mov_b32_e32 v89, v86
	v_mov_b32_e32 v85, v87
	v_pk_add_f32 v[84:85], v[88:89], v[84:85]
	v_mov_b32_e32 v86, v74
	v_add_f32_e32 v83, v84, v85
	ds_bpermute_b32 v84, v154, v83
	v_mov_b32_e32 v87, v78
	v_mov_b32_e32 v78, v75
	s_waitcnt lgkmcnt(0)
	v_add_f32_e32 v83, v83, v84
	ds_bpermute_b32 v84, v155, v83
	s_waitcnt lgkmcnt(0)
; __device__ __forceinline__ unsigned cvt_pk_bf16(float lo, float hi) { unsigned r; asm volatile("v_cvt_pk_bf16_f32 %0, %1, %2" : "=v"(r) : "v"(lo), "v"(hi)); return r; }
; __device__ __forceinline__ float fast_sigmoid(float x) { return __builtin_amdgcn_rcpf(1.0f + __builtin_amdgcn_exp2f(-1.44269504089f * x)); }
;     __device__ __forceinline__ void operator()(const f32x4 (&acc)[2][2][4][2], const Unit& u, int wr, int wc, int fr, int fq, LAS unsigned char* lds) const {
;     ...
;             for (int m = 0; m < 4; ++m) { const int row = row0 + ai * HALF + m * 16; const float rs = rstd_of4(rss, row, fq);
;                 float h[8];
; #pragma unroll
;                 for (int n = 0; n < 2; ++n)
; #pragma unroll
;                     for (int e = 0; e < 4; ++e) { const float gt = acc[ai][0][m][n][e] * rs, up = acc[ai][1][m][n][e] * rs; h[n * 4 + e] = gt * fast_sigmoid(gt) * up; }
;                 u32x4 w; w.x = cvt_pk_bf16(h[0], h[1]); w.y = cvt_pk_bf16(h[2], h[3]); w.z = cvt_pk_bf16(h[4], h[5]); w.w = cvt_pk_bf16(h[6], h[7]);
;                 *(u32x4*)(O + (size_t)row * DFF + j0) = w; }
	v_add_f32_e32 v83, v83, v84
	v_fmamk_f32 v83, v83, 0x3a800000, v173
	v_cmp_gt_f32_e32 vcc, s64, v83
	v_mul_f32_e32 v84, 0x4b800000, v83
	s_nop 0
	v_cndmask_b32_e32 v83, v83, v84, vcc
	v_rsq_f32_e32 v83, v83
	s_nop 0
	v_mul_f32_e32 v84, 0x45800000, v83
	v_cndmask_b32_e32 v84, v83, v84, vcc
	v_pk_mul_f32 v[86:87], v[86:87], v[84:85] op_sel_hi:[1,0]
	s_nop 0
	v_mul_f32_e32 v74, 0xbfb8aa3b, v87
	v_exp_f32_e32 v74, v74
	s_nop 0
	v_add_f32_e32 v74, 1.0, v74
	v_rcp_f32_e32 v74, v74
	s_nop 0
	v_mul_f32_e32 v74, v87, v74
	v_mul_f32_e32 v83, v86, v74
	v_pk_mul_f32 v[74:75], v[78:79], v[84:85] op_sel_hi:[1,0]
	s_nop 0
	v_mul_f32_e32 v78, 0xbfb8aa3b, v75
	v_exp_f32_e32 v78, v78
	s_nop 0
	v_add_f32_e32 v78, 1.0, v78
	v_rcp_f32_e32 v78, v78
	s_nop 0
	v_mul_f32_e32 v75, v75, v78
	v_mul_f32_e32 v78, v74, v75
	v_mov_b32_e32 v74, v76
	v_mov_b32_e32 v75, v80
	v_pk_mul_f32 v[74:75], v[74:75], v[84:85] op_sel_hi:[1,0]
	v_mov_b32_e32 v80, v77
	v_mul_f32_e32 v76, 0xbfb8aa3b, v75
	v_exp_f32_e32 v76, v76
	s_nop 0
	v_add_f32_e32 v76, 1.0, v76
	v_rcp_f32_e32 v76, v76
	s_nop 0
	v_mul_f32_e32 v75, v75, v76
	v_mul_f32_e32 v76, v74, v75
	v_pk_mul_f32 v[74:75], v[80:81], v[84:85] op_sel_hi:[1,0]
	s_nop 0
	v_mul_f32_e32 v77, 0xbfb8aa3b, v75
	v_exp_f32_e32 v77, v77
	s_nop 0
	v_add_f32_e32 v77, 1.0, v77
	v_rcp_f32_e32 v77, v77
	s_nop 0
	v_mul_f32_e32 v75, v75, v77
	v_mul_f32_e32 v77, v74, v75
	v_mov_b32_e32 v74, v66
	v_mov_b32_e32 v75, v70
	v_pk_mul_f32 v[74:75], v[74:75], v[84:85] op_sel_hi:[1,0]
	v_mov_b32_e32 v70, v67
	v_mul_f32_e32 v66, 0xbfb8aa3b, v75
	v_exp_f32_e32 v66, v66
	s_nop 0
	v_add_f32_e32 v66, 1.0, v66
	v_rcp_f32_e32 v66, v66
	s_nop 0
	v_mul_f32_e32 v66, v75, v66
	v_mul_f32_e32 v74, v74, v66
	v_pk_mul_f32 v[66:67], v[70:71], v[84:85] op_sel_hi:[1,0]
	s_nop 0
	v_mul_f32_e32 v70, 0xbfb8aa3b, v67
	v_exp_f32_e32 v70, v70
	s_nop 0
	v_add_f32_e32 v70, 1.0, v70
	v_rcp_f32_e32 v70, v70
	s_nop 0
	v_mul_f32_e32 v67, v67, v70
	v_mul_f32_e32 v70, v66, v67
	v_mov_b32_e32 v66, v68
	v_mov_b32_e32 v67, v72
	v_pk_mul_f32 v[66:67], v[66:67], v[84:85] op_sel_hi:[1,0]
	v_mov_b32_e32 v72, v69
	v_mul_f32_e32 v68, 0xbfb8aa3b, v67
	v_exp_f32_e32 v68, v68
	s_nop 0
	v_add_f32_e32 v68, 1.0, v68
	v_rcp_f32_e32 v68, v68
	s_nop 0
	v_mul_f32_e32 v67, v67, v68
	v_mul_f32_e32 v71, v66, v67
	v_pk_mul_f32 v[66:67], v[72:73], v[84:85] op_sel_hi:[1,0]
	s_nop 0
	v_mul_f32_e32 v68, 0xbfb8aa3b, v67
	v_exp_f32_e32 v68, v68
	s_nop 0
	v_add_f32_e32 v68, 1.0, v68
	v_rcp_f32_e32 v68, v68
	s_nop 0
	v_mul_f32_e32 v67, v67, v68
	v_mul_f32_e32 v69, v66, v67
	v_cvt_pk_bf16_f32 v66, v83, v78
	v_cvt_pk_bf16_f32 v67, v76, v77
	v_cvt_pk_bf16_f32 v68, v74, v70
	v_cvt_pk_bf16_f32 v69, v71, v69
	v_mad_i64_i32 v[70:71], s[18:19], v82, s88, v[142:143]
	global_store_dwordx4 v[70:71], v[66:69], off
	s_nop 1
	v_add_u32_e32 v66, 0x80, v146
	v_ashrrev_i32_e32 v67, 31, v66
	v_lshlrev_b64 v[68:69], 6, v[66:67]
	v_lshl_add_u64 v[68:69], v[144:145], 0, v[68:69]
	v_mov_b32_e32 v68, v212
	v_mov_b32_e32 v69, v213
	v_mov_b32_e32 v70, v214
	v_mov_b32_e32 v71, v215
	s_nop 0
	v_mov_b32_e32 v72, v69
	v_mov_b32_e32 v73, v70
	v_mov_b32_e32 v69, v71
	v_pk_add_f32 v[68:69], v[72:73], v[68:69]
	v_mov_b32_e32 v70, v58
	v_add_f32_e32 v67, v68, v69
	ds_bpermute_b32 v68, v154, v67
	v_mov_b32_e32 v71, v62
	v_mov_b32_e32 v62, v59
	s_waitcnt lgkmcnt(0)
	v_add_f32_e32 v67, v67, v68
	ds_bpermute_b32 v68, v155, v67
	s_waitcnt lgkmcnt(0)
	v_add_f32_e32 v67, v67, v68
	v_fmamk_f32 v67, v67, 0x3a800000, v173
	v_cmp_gt_f32_e32 vcc, s64, v67
	v_mul_f32_e32 v68, 0x4b800000, v67
	s_nop 0
	v_cndmask_b32_e32 v67, v67, v68, vcc
	v_rsq_f32_e32 v67, v67
	s_nop 0
	v_mul_f32_e32 v68, 0x45800000, v67
	v_cndmask_b32_e32 v68, v67, v68, vcc
	v_pk_mul_f32 v[70:71], v[70:71], v[68:69] op_sel_hi:[1,0]
	s_nop 0
	v_mul_f32_e32 v58, 0xbfb8aa3b, v71
	v_exp_f32_e32 v58, v58
	s_nop 0
	v_add_f32_e32 v58, 1.0, v58
	v_rcp_f32_e32 v58, v58
	s_nop 0
	v_mul_f32_e32 v58, v71, v58
	v_mul_f32_e32 v67, v70, v58
	v_pk_mul_f32 v[58:59], v[62:63], v[68:69] op_sel_hi:[1,0]
	s_nop 0
	v_mul_f32_e32 v62, 0xbfb8aa3b, v59
	v_exp_f32_e32 v62, v62
	s_nop 0
	v_add_f32_e32 v62, 1.0, v62
	v_rcp_f32_e32 v62, v62
	s_nop 0
	v_mul_f32_e32 v59, v59, v62
	v_mul_f32_e32 v62, v58, v59
	v_mov_b32_e32 v58, v60
	v_mov_b32_e32 v59, v64
	v_pk_mul_f32 v[58:59], v[58:59], v[68:69] op_sel_hi:[1,0]
	v_mov_b32_e32 v64, v61
	v_mul_f32_e32 v60, 0xbfb8aa3b, v59
	v_exp_f32_e32 v60, v60
	s_nop 0
	v_add_f32_e32 v60, 1.0, v60
	v_rcp_f32_e32 v60, v60
	s_nop 0
	v_mul_f32_e32 v59, v59, v60
	v_mul_f32_e32 v60, v58, v59
	v_pk_mul_f32 v[58:59], v[64:65], v[68:69] op_sel_hi:[1,0]
	s_nop 0
	v_mul_f32_e32 v61, 0xbfb8aa3b, v59
	v_exp_f32_e32 v61, v61
	s_nop 0
	v_add_f32_e32 v61, 1.0, v61
	v_rcp_f32_e32 v61, v61
	s_nop 0
	v_mul_f32_e32 v59, v59, v61
	v_mul_f32_e32 v61, v58, v59
	v_mov_b32_e32 v58, v50
	v_mov_b32_e32 v59, v54
	v_pk_mul_f32 v[58:59], v[58:59], v[68:69] op_sel_hi:[1,0]
	v_mov_b32_e32 v54, v51
	v_mul_f32_e32 v50, 0xbfb8aa3b, v59
	v_exp_f32_e32 v50, v50
	s_nop 0
	v_add_f32_e32 v50, 1.0, v50
	v_rcp_f32_e32 v50, v50
	s_nop 0
	v_mul_f32_e32 v50, v59, v50
	v_mul_f32_e32 v58, v58, v50
	v_pk_mul_f32 v[50:51], v[54:55], v[68:69] op_sel_hi:[1,0]
	s_nop 0
	v_mul_f32_e32 v54, 0xbfb8aa3b, v51
	v_exp_f32_e32 v54, v54
	s_nop 0
	v_add_f32_e32 v54, 1.0, v54
	v_rcp_f32_e32 v54, v54
	s_nop 0
	v_mul_f32_e32 v51, v51, v54
	v_mul_f32_e32 v54, v50, v51
	v_mov_b32_e32 v50, v52
	v_mov_b32_e32 v51, v56
	v_pk_mul_f32 v[50:51], v[50:51], v[68:69] op_sel_hi:[1,0]
	v_mov_b32_e32 v56, v53
	v_mul_f32_e32 v52, 0xbfb8aa3b, v51
	v_exp_f32_e32 v52, v52
	s_nop 0
	v_add_f32_e32 v52, 1.0, v52
	v_rcp_f32_e32 v52, v52
	s_nop 0
	v_mul_f32_e32 v51, v51, v52
	v_mul_f32_e32 v55, v50, v51
	v_pk_mul_f32 v[50:51], v[56:57], v[68:69] op_sel_hi:[1,0]
	s_nop 0
	v_mul_f32_e32 v52, 0xbfb8aa3b, v51
	v_exp_f32_e32 v52, v52
	s_nop 0
	v_add_f32_e32 v52, 1.0, v52
	v_rcp_f32_e32 v52, v52
	s_nop 0
	v_mul_f32_e32 v51, v51, v52
	v_mul_f32_e32 v53, v50, v51
	v_cvt_pk_bf16_f32 v50, v67, v62
	v_cvt_pk_bf16_f32 v51, v60, v61
	v_cvt_pk_bf16_f32 v52, v58, v54
	v_cvt_pk_bf16_f32 v53, v55, v53
	v_mad_i64_i32 v[54:55], s[18:19], v66, s88, v[142:143]
	global_store_dwordx4 v[54:55], v[50:53], off
	s_nop 1
	v_add_u32_e32 v50, 0x90, v146
	v_ashrrev_i32_e32 v51, 31, v50
	v_lshlrev_b64 v[52:53], 6, v[50:51]
	v_lshl_add_u64 v[52:53], v[144:145], 0, v[52:53]
	v_mov_b32_e32 v52, v216
	v_mov_b32_e32 v53, v217
	v_mov_b32_e32 v54, v218
	v_mov_b32_e32 v55, v219
	s_nop 0
	v_mov_b32_e32 v56, v53
	v_mov_b32_e32 v57, v54
	v_mov_b32_e32 v53, v55
	v_pk_add_f32 v[52:53], v[56:57], v[52:53]
	v_mov_b32_e32 v54, v42
	v_add_f32_e32 v51, v52, v53
	ds_bpermute_b32 v52, v154, v51
	v_mov_b32_e32 v55, v46
	v_mov_b32_e32 v46, v43
	s_waitcnt lgkmcnt(0)
; __device__ __forceinline__ unsigned cvt_pk_bf16(float lo, float hi) { unsigned r; asm volatile("v_cvt_pk_bf16_f32 %0, %1, %2" : "=v"(r) : "v"(lo), "v"(hi)); return r; }
; __device__ __forceinline__ float fast_sigmoid(float x) { return __builtin_amdgcn_rcpf(1.0f + __builtin_amdgcn_exp2f(-1.44269504089f * x)); }
;     __device__ __forceinline__ void operator()(const f32x4 (&acc)[2][2][4][2], const Unit& u, int wr, int wc, int fr, int fq, LAS unsigned char* lds) const {
;     ...
;             for (int m = 0; m < 4; ++m) { const int row = row0 + ai * HALF + m * 16; const float rs = rstd_of4(rss, row, fq);
;                 float h[8];
; #pragma unroll
;                 for (int n = 0; n < 2; ++n)
; #pragma unroll
;                     for (int e = 0; e < 4; ++e) { const float gt = acc[ai][0][m][n][e] * rs, up = acc[ai][1][m][n][e] * rs; h[n * 4 + e] = gt * fast_sigmoid(gt) * up; }
;                 u32x4 w; w.x = cvt_pk_bf16(h[0], h[1]); w.y = cvt_pk_bf16(h[2], h[3]); w.z = cvt_pk_bf16(h[4], h[5]); w.w = cvt_pk_bf16(h[6], h[7]);
;                 *(u32x4*)(O + (size_t)row * DFF + j0) = w; }
	v_add_f32_e32 v51, v51, v52
	ds_bpermute_b32 v52, v155, v51
	s_waitcnt lgkmcnt(0)
	v_add_f32_e32 v51, v51, v52
	v_fmamk_f32 v51, v51, 0x3a800000, v173
	v_cmp_gt_f32_e32 vcc, s64, v51
	v_mul_f32_e32 v52, 0x4b800000, v51
	s_nop 0
	v_cndmask_b32_e32 v51, v51, v52, vcc
	v_rsq_f32_e32 v51, v51
	s_nop 0
	v_mul_f32_e32 v52, 0x45800000, v51
	v_cndmask_b32_e32 v52, v51, v52, vcc
	v_pk_mul_f32 v[54:55], v[54:55], v[52:53] op_sel_hi:[1,0]
	s_nop 0
	v_mul_f32_e32 v42, 0xbfb8aa3b, v55
	v_exp_f32_e32 v42, v42
	s_nop 0
	v_add_f32_e32 v42, 1.0, v42
	v_rcp_f32_e32 v42, v42
	s_nop 0
	v_mul_f32_e32 v42, v55, v42
	v_mul_f32_e32 v51, v54, v42
	v_pk_mul_f32 v[42:43], v[46:47], v[52:53] op_sel_hi:[1,0]
	s_nop 0
	v_mul_f32_e32 v46, 0xbfb8aa3b, v43
	v_exp_f32_e32 v46, v46
	s_nop 0
	v_add_f32_e32 v46, 1.0, v46
	v_rcp_f32_e32 v46, v46
	s_nop 0
	v_mul_f32_e32 v43, v43, v46
	v_mul_f32_e32 v46, v42, v43
	v_mov_b32_e32 v42, v44
	v_mov_b32_e32 v43, v48
	v_pk_mul_f32 v[42:43], v[42:43], v[52:53] op_sel_hi:[1,0]
	v_mov_b32_e32 v48, v45
	v_mul_f32_e32 v44, 0xbfb8aa3b, v43
	v_exp_f32_e32 v44, v44
	s_nop 0
	v_add_f32_e32 v44, 1.0, v44
	v_rcp_f32_e32 v44, v44
	s_nop 0
	v_mul_f32_e32 v43, v43, v44
	v_mul_f32_e32 v44, v42, v43
	v_pk_mul_f32 v[42:43], v[48:49], v[52:53] op_sel_hi:[1,0]
	s_nop 0
	v_mul_f32_e32 v45, 0xbfb8aa3b, v43
	v_exp_f32_e32 v45, v45
	s_nop 0
	v_add_f32_e32 v45, 1.0, v45
	v_rcp_f32_e32 v45, v45
	s_nop 0
	v_mul_f32_e32 v43, v43, v45
	v_mul_f32_e32 v45, v42, v43
	v_mov_b32_e32 v42, v34
	v_mov_b32_e32 v43, v38
	v_pk_mul_f32 v[42:43], v[42:43], v[52:53] op_sel_hi:[1,0]
	v_mov_b32_e32 v38, v35
	v_mul_f32_e32 v34, 0xbfb8aa3b, v43
	v_exp_f32_e32 v34, v34
	s_nop 0
	v_add_f32_e32 v34, 1.0, v34
	v_rcp_f32_e32 v34, v34
	s_nop 0
	v_mul_f32_e32 v34, v43, v34
	v_mul_f32_e32 v42, v42, v34
	v_pk_mul_f32 v[34:35], v[38:39], v[52:53] op_sel_hi:[1,0]
	s_nop 0
	v_mul_f32_e32 v38, 0xbfb8aa3b, v35
	v_exp_f32_e32 v38, v38
	s_nop 0
	v_add_f32_e32 v38, 1.0, v38
	v_rcp_f32_e32 v38, v38
	s_nop 0
	v_mul_f32_e32 v35, v35, v38
	v_mul_f32_e32 v38, v34, v35
	v_mov_b32_e32 v34, v36
	v_mov_b32_e32 v35, v40
	v_pk_mul_f32 v[34:35], v[34:35], v[52:53] op_sel_hi:[1,0]
	v_mov_b32_e32 v40, v37
	v_mul_f32_e32 v36, 0xbfb8aa3b, v35
	v_exp_f32_e32 v36, v36
	s_nop 0
	v_add_f32_e32 v36, 1.0, v36
	v_rcp_f32_e32 v36, v36
	s_nop 0
	v_mul_f32_e32 v35, v35, v36
	v_mul_f32_e32 v39, v34, v35
	v_pk_mul_f32 v[34:35], v[40:41], v[52:53] op_sel_hi:[1,0]
	s_nop 0
	v_mul_f32_e32 v36, 0xbfb8aa3b, v35
	v_exp_f32_e32 v36, v36
	s_nop 0
	v_add_f32_e32 v36, 1.0, v36
	v_rcp_f32_e32 v36, v36
	s_nop 0
	v_mul_f32_e32 v35, v35, v36
	v_mul_f32_e32 v37, v34, v35
	v_cvt_pk_bf16_f32 v34, v51, v46
	v_cvt_pk_bf16_f32 v35, v44, v45
	v_cvt_pk_bf16_f32 v36, v42, v38
	v_cvt_pk_bf16_f32 v37, v39, v37
	v_mad_i64_i32 v[38:39], s[18:19], v50, s88, v[142:143]
	global_store_dwordx4 v[38:39], v[34:37], off
	s_nop 1
	v_add_u32_e32 v34, 0xa0, v146
	v_ashrrev_i32_e32 v35, 31, v34
	v_lshlrev_b64 v[36:37], 6, v[34:35]
	v_lshl_add_u64 v[36:37], v[144:145], 0, v[36:37]
	v_mov_b32_e32 v36, v220
	v_mov_b32_e32 v37, v221
	v_mov_b32_e32 v38, v222
	v_mov_b32_e32 v39, v223
	s_nop 0
	v_mov_b32_e32 v40, v37
	v_mov_b32_e32 v41, v38
	v_mov_b32_e32 v37, v39
	v_pk_add_f32 v[36:37], v[40:41], v[36:37]
	v_mov_b32_e32 v38, v26
	v_add_f32_e32 v35, v36, v37
	ds_bpermute_b32 v36, v154, v35
	v_mov_b32_e32 v39, v30
	v_mov_b32_e32 v30, v27
	s_waitcnt lgkmcnt(0)
	v_add_f32_e32 v35, v35, v36
	ds_bpermute_b32 v36, v155, v35
	s_waitcnt lgkmcnt(0)
; __device__ __forceinline__ unsigned cvt_pk_bf16(float lo, float hi) { unsigned r; asm volatile("v_cvt_pk_bf16_f32 %0, %1, %2" : "=v"(r) : "v"(lo), "v"(hi)); return r; }
; __device__ __forceinline__ float fast_sigmoid(float x) { return __builtin_amdgcn_rcpf(1.0f + __builtin_amdgcn_exp2f(-1.44269504089f * x)); }
; #define PG8_WAIT_V(n) asm volatile("s_waitcnt vmcnt(" #n ")" ::: "memory")
; #define PG8_BAR __builtin_amdgcn_s_barrier()
; template <class Epi, int KK, int LDA, int LDB, int NN, bool AGRP>
; __device__ __forceinline__ void gemm_phase(LAS unsigned char* lds, const bf16_t* gA, const bf16_t* gBt, int G_, int bid_, int tid) {
;     ...
;     PG8_WAIT_V(0);
;     if (wr == 0) PG8_BAR;
;     PG8_BAR;
;     __device__ __forceinline__ void operator()(const f32x4 (&acc)[2][2][4][2], const Unit& u, int wr, int wc, int fr, int fq, LAS unsigned char* lds) const {
;     ...
;             for (int m = 0; m < 4; ++m) { const int row = row0 + ai * HALF + m * 16; const float rs = rstd_of4(rss, row, fq);
;                 float h[8];
; #pragma unroll
;                 for (int n = 0; n < 2; ++n)
; #pragma unroll
;                     for (int e = 0; e < 4; ++e) { const float gt = acc[ai][0][m][n][e] * rs, up = acc[ai][1][m][n][e] * rs; h[n * 4 + e] = gt * fast_sigmoid(gt) * up; }
;                 u32x4 w; w.x = cvt_pk_bf16(h[0], h[1]); w.y = cvt_pk_bf16(h[2], h[3]); w.z = cvt_pk_bf16(h[4], h[5]); w.w = cvt_pk_bf16(h[6], h[7]);
;                 *(u32x4*)(O + (size_t)row * DFF + j0) = w; }
	v_add_f32_e32 v35, v35, v36
	v_fmamk_f32 v35, v35, 0x3a800000, v173
	v_cmp_gt_f32_e32 vcc, s64, v35
	v_mul_f32_e32 v36, 0x4b800000, v35
	s_nop 0
	v_cndmask_b32_e32 v35, v35, v36, vcc
	v_rsq_f32_e32 v35, v35
	s_nop 0
	v_mul_f32_e32 v36, 0x45800000, v35
	v_cndmask_b32_e32 v36, v35, v36, vcc
	v_pk_mul_f32 v[38:39], v[38:39], v[36:37] op_sel_hi:[1,0]
	s_nop 0
	v_mul_f32_e32 v26, 0xbfb8aa3b, v39
	v_exp_f32_e32 v26, v26
	s_nop 0
	v_add_f32_e32 v26, 1.0, v26
	v_rcp_f32_e32 v26, v26
	s_nop 0
	v_mul_f32_e32 v26, v39, v26
	v_mul_f32_e32 v35, v38, v26
	v_pk_mul_f32 v[26:27], v[30:31], v[36:37] op_sel_hi:[1,0]
	s_nop 0
	v_mul_f32_e32 v30, 0xbfb8aa3b, v27
	v_exp_f32_e32 v30, v30
	s_nop 0
	v_add_f32_e32 v30, 1.0, v30
	v_rcp_f32_e32 v30, v30
	s_nop 0
	v_mul_f32_e32 v27, v27, v30
	v_mul_f32_e32 v30, v26, v27
	v_mov_b32_e32 v26, v28
	v_mov_b32_e32 v27, v32
	v_pk_mul_f32 v[26:27], v[26:27], v[36:37] op_sel_hi:[1,0]
	v_mov_b32_e32 v32, v29
	v_mul_f32_e32 v28, 0xbfb8aa3b, v27
	v_exp_f32_e32 v28, v28
	s_nop 0
	v_add_f32_e32 v28, 1.0, v28
	v_rcp_f32_e32 v28, v28
	s_nop 0
	v_mul_f32_e32 v27, v27, v28
	v_mul_f32_e32 v28, v26, v27
	v_pk_mul_f32 v[26:27], v[32:33], v[36:37] op_sel_hi:[1,0]
	s_nop 0
	v_mul_f32_e32 v29, 0xbfb8aa3b, v27
	v_exp_f32_e32 v29, v29
	s_nop 0
	v_add_f32_e32 v29, 1.0, v29
	v_rcp_f32_e32 v29, v29
	s_nop 0
	v_mul_f32_e32 v27, v27, v29
	v_mul_f32_e32 v29, v26, v27
	v_mov_b32_e32 v26, v18
	v_mov_b32_e32 v27, v22
	v_pk_mul_f32 v[26:27], v[26:27], v[36:37] op_sel_hi:[1,0]
	v_mov_b32_e32 v22, v19
	v_mul_f32_e32 v18, 0xbfb8aa3b, v27
	v_exp_f32_e32 v18, v18
	s_nop 0
	v_add_f32_e32 v18, 1.0, v18
	v_rcp_f32_e32 v18, v18
	s_nop 0
	v_mul_f32_e32 v18, v27, v18
	v_mul_f32_e32 v26, v26, v18
	v_pk_mul_f32 v[18:19], v[22:23], v[36:37] op_sel_hi:[1,0]
	s_nop 0
	v_mul_f32_e32 v22, 0xbfb8aa3b, v19
	v_exp_f32_e32 v22, v22
	s_nop 0
	v_add_f32_e32 v22, 1.0, v22
	v_rcp_f32_e32 v22, v22
	s_nop 0
	v_mul_f32_e32 v19, v19, v22
	v_mul_f32_e32 v22, v18, v19
	v_mov_b32_e32 v18, v20
	v_mov_b32_e32 v19, v24
	v_pk_mul_f32 v[18:19], v[18:19], v[36:37] op_sel_hi:[1,0]
	v_mov_b32_e32 v24, v21
	v_mul_f32_e32 v20, 0xbfb8aa3b, v19
	v_exp_f32_e32 v20, v20
	s_nop 0
	v_add_f32_e32 v20, 1.0, v20
	v_rcp_f32_e32 v20, v20
	s_nop 0
	v_mul_f32_e32 v19, v19, v20
	v_mul_f32_e32 v23, v18, v19
	v_pk_mul_f32 v[18:19], v[24:25], v[36:37] op_sel_hi:[1,0]
	s_nop 0
	v_mul_f32_e32 v20, 0xbfb8aa3b, v19
	v_exp_f32_e32 v20, v20
	s_nop 0
	v_add_f32_e32 v20, 1.0, v20
	v_rcp_f32_e32 v20, v20
	s_nop 0
	v_mul_f32_e32 v19, v19, v20
	v_mul_f32_e32 v21, v18, v19
	v_cvt_pk_bf16_f32 v18, v35, v30
	v_cvt_pk_bf16_f32 v19, v28, v29
	v_cvt_pk_bf16_f32 v20, v26, v22
	v_cvt_pk_bf16_f32 v21, v23, v21
	v_mad_i64_i32 v[22:23], s[18:19], v34, s88, v[142:143]
	global_store_dwordx4 v[22:23], v[18:21], off
	s_nop 1
	v_add_u32_e32 v18, 0xb0, v146
	v_ashrrev_i32_e32 v19, 31, v18
	v_lshlrev_b64 v[20:21], 6, v[18:19]
	v_lshl_add_u64 v[20:21], v[144:145], 0, v[20:21]
	v_mov_b32_e32 v20, v224
	v_mov_b32_e32 v21, v225
	v_mov_b32_e32 v22, v226
	v_mov_b32_e32 v23, v227
	s_nop 0
	v_mov_b32_e32 v24, v21
	v_mov_b32_e32 v25, v22
	v_mov_b32_e32 v21, v23
	v_pk_add_f32 v[20:21], v[24:25], v[20:21]
	v_mov_b32_e32 v22, v10
	v_add_f32_e32 v19, v20, v21
	ds_bpermute_b32 v20, v154, v19
	v_mov_b32_e32 v23, v14
	v_mov_b32_e32 v14, v11
	s_waitcnt lgkmcnt(0)
	v_add_f32_e32 v19, v19, v20
	ds_bpermute_b32 v20, v155, v19
	s_waitcnt lgkmcnt(0)
	v_add_f32_e32 v19, v19, v20
	v_fmamk_f32 v19, v19, 0x3a800000, v173
	v_cmp_gt_f32_e32 vcc, s64, v19
	v_mul_f32_e32 v20, 0x4b800000, v19
	s_nop 0
	v_cndmask_b32_e32 v19, v19, v20, vcc
	v_rsq_f32_e32 v19, v19
	s_nop 0
	v_mul_f32_e32 v20, 0x45800000, v19
	v_cndmask_b32_e32 v20, v19, v20, vcc
	v_pk_mul_f32 v[22:23], v[22:23], v[20:21] op_sel_hi:[1,0]
	s_and_b64 vcc, exec, s[10:11]
	v_mul_f32_e32 v10, 0xbfb8aa3b, v23
	v_exp_f32_e32 v10, v10
	s_nop 0
	v_add_f32_e32 v10, 1.0, v10
	v_rcp_f32_e32 v10, v10
	s_nop 0
	v_mul_f32_e32 v10, v23, v10
	v_mul_f32_e32 v19, v22, v10
	v_pk_mul_f32 v[10:11], v[14:15], v[20:21] op_sel_hi:[1,0]
	s_nop 0
	v_mul_f32_e32 v14, 0xbfb8aa3b, v11
	v_exp_f32_e32 v14, v14
	s_nop 0
	v_add_f32_e32 v14, 1.0, v14
	v_rcp_f32_e32 v14, v14
	s_nop 0
	v_mul_f32_e32 v11, v11, v14
	v_mul_f32_e32 v14, v10, v11
	v_mov_b32_e32 v10, v12
	v_mov_b32_e32 v11, v16
	v_pk_mul_f32 v[10:11], v[10:11], v[20:21] op_sel_hi:[1,0]
	v_mov_b32_e32 v16, v13
	v_mul_f32_e32 v12, 0xbfb8aa3b, v11
	v_exp_f32_e32 v12, v12
	s_nop 0
	v_add_f32_e32 v12, 1.0, v12
	v_rcp_f32_e32 v12, v12
	s_nop 0
	v_mul_f32_e32 v11, v11, v12
	v_mul_f32_e32 v12, v10, v11
	v_pk_mul_f32 v[10:11], v[16:17], v[20:21] op_sel_hi:[1,0]
	s_nop 0
	v_mul_f32_e32 v13, 0xbfb8aa3b, v11
	v_exp_f32_e32 v13, v13
	s_nop 0
	v_add_f32_e32 v13, 1.0, v13
	v_rcp_f32_e32 v13, v13
	s_nop 0
	v_mul_f32_e32 v11, v11, v13
	v_mul_f32_e32 v13, v10, v11
	v_mov_b32_e32 v10, v0
	v_mov_b32_e32 v11, v6
	v_pk_mul_f32 v[10:11], v[10:11], v[20:21] op_sel_hi:[1,0]
	v_mov_b32_e32 v6, v1
	v_mul_f32_e32 v0, 0xbfb8aa3b, v11
	v_exp_f32_e32 v0, v0
	s_nop 0
	v_add_f32_e32 v0, 1.0, v0
	v_rcp_f32_e32 v0, v0
	s_nop 0
	v_mul_f32_e32 v0, v11, v0
	v_mul_f32_e32 v10, v10, v0
	v_pk_mul_f32 v[0:1], v[6:7], v[20:21] op_sel_hi:[1,0]
	s_nop 0
	v_mul_f32_e32 v6, 0xbfb8aa3b, v1
	v_exp_f32_e32 v6, v6
	s_nop 0
	v_add_f32_e32 v6, 1.0, v6
	v_rcp_f32_e32 v6, v6
	s_nop 0
	v_mul_f32_e32 v1, v1, v6
	v_mul_f32_e32 v6, v0, v1
	v_mov_b32_e32 v0, v2
	v_mov_b32_e32 v1, v8
	v_pk_mul_f32 v[0:1], v[0:1], v[20:21] op_sel_hi:[1,0]
	v_mov_b32_e32 v8, v3
	v_mul_f32_e32 v2, 0xbfb8aa3b, v1
	v_exp_f32_e32 v2, v2
	s_nop 0
	v_add_f32_e32 v2, 1.0, v2
	v_rcp_f32_e32 v2, v2
	s_nop 0
	v_mul_f32_e32 v1, v1, v2
	v_mul_f32_e32 v7, v0, v1
	v_pk_mul_f32 v[0:1], v[8:9], v[20:21] op_sel_hi:[1,0]
	s_nop 0
	v_mul_f32_e32 v2, 0xbfb8aa3b, v1
	v_exp_f32_e32 v2, v2
	s_nop 0
	v_add_f32_e32 v2, 1.0, v2
	v_rcp_f32_e32 v2, v2
	s_nop 0
	v_mul_f32_e32 v1, v1, v2
	v_mul_f32_e32 v3, v0, v1
	v_cvt_pk_bf16_f32 v0, v19, v14
	v_cvt_pk_bf16_f32 v1, v12, v13
	v_cvt_pk_bf16_f32 v2, v10, v6
	v_cvt_pk_bf16_f32 v3, v7, v3
	v_mad_i64_i32 v[6:7], s[18:19], v18, s88, v[142:143]
	s_mov_b64 s[18:19], s[14:15]
	global_store_dwordx4 v[6:7], v[0:3], off
	s_cbranch_vccz .LBB1_840
	s_waitcnt vmcnt(0)
	s_cmpk_gt_u32 s24, 0xff
	s_cbranch_scc1 .LBB1_847
	s_barrier
